# FFN-up epilogue: dead DPP zero-inits removed; last PLE phase: dead bf16 residual-copy stores removed; retention consts moved to s84-87
# speedup vs baseline: 1.0181x; 1.0181x over previous
; __device__ __forceinline__ u32x2 pack4(f32x4 v) { return (u32x2){pk2(v[0], v[1]), pk2(v[2], v[3])}; }
; #define EPI_LOAD_RR(ssp) float rr[8]; _Pragma("unroll") for (int it = 0; it < 8; ++it) rr[it] = (ssp)[EPI_IT_ROW(it)]; _Pragma("unroll") for (int it = 0; it < 8; ++it) rr[it] = rms_r(rr[it])
;     __device__ __forceinline__ void operator()(AccRef acc, const Unit& u, int wr, int wc, int fr, int fq) const {
;         asm volatile("" : "+v"(fr), "+v"(fq));
;         const int j0 = u.pn * 128 + wc * 32 + 8 * fq;
;         u32x2 pa[2][2][4][2];
;         { EPI_LOAD_RR(ss);
; #pragma unroll
;           for (int it = 0; it < 8; ++it)
; #pragma unroll
;               for (int bj = 0; bj < 2; ++bj)
; #pragma unroll
;                   for (int n = 0; n < 2; ++n) pa[it >> 2][bj][it & 3][n] = pack4(acc[it >> 2][bj][it & 3][n] * rr[it]); }
.LBB0_549:
	s_lshl_b32 s69, s6, 8
	v_mov_b32_e32 v166, v151
	v_mov_b32_e32 v185, v153
	s_add_i32 s69, s69, s65
	s_lshl_b32 s0, s0, 7
	v_add_u32_e32 v146, s69, v166
	v_ashrrev_i32_e32 v147, 31, v146
	v_lshl_add_u64 v[148:149], v[146:147], 2, s[22:23]
	global_load_dword v136, v[148:149], off
	v_add_u32_e32 v148, 16, v146
	v_add_u32_e32 v170, 32, v146
	v_ashrrev_i32_e32 v149, 31, v148
	v_ashrrev_i32_e32 v171, 31, v170
	v_add_u32_e32 v172, 48, v146
	v_add_u32_e32 v174, 0x80, v146
	v_add_u32_e32 v178, 0x90, v146
	v_add_u32_e32 v180, 0xa0, v146
	v_add_u32_e32 v182, 0xb0, v146
	v_lshl_add_u64 v[168:169], v[148:149], 2, s[22:23]
	v_lshl_add_u64 v[170:171], v[170:171], 2, s[22:23]
	v_ashrrev_i32_e32 v173, 31, v172
	v_ashrrev_i32_e32 v175, 31, v174
	v_ashrrev_i32_e32 v179, 31, v178
	v_ashrrev_i32_e32 v181, 31, v180
	v_ashrrev_i32_e32 v183, 31, v182
	v_lshl_add_u64 v[172:173], v[172:173], 2, s[22:23]
	v_lshl_add_u64 v[174:175], v[174:175], 2, s[22:23]
	v_lshl_add_u64 v[178:179], v[178:179], 2, s[22:23]
	v_lshl_add_u64 v[180:181], v[180:181], 2, s[22:23]
	v_lshl_add_u64 v[182:183], v[182:183], 2, s[22:23]
	global_load_dword v147, v[168:169], off
	global_load_dword v149, v[170:171], off
	global_load_dword v150, v[172:173], off
	global_load_dword v152, v[174:175], off
	global_load_dword v167, v[178:179], off
	s_nop 0
	global_load_dword v169, v[180:181], off
	global_load_dword v170, v[182:183], off
	s_or_b32 s0, s0, s78
	s_waitcnt vmcnt(0)
	v_fmamk_f32 v136, v136, 0x3a800000, v165
	v_rsq_f32_e32 v168, v136
	v_fmamk_f32 v136, v147, 0x3a800000, v165
	v_fmamk_f32 v147, v149, 0x3a800000, v165
	v_fmamk_f32 v149, v150, 0x3a800000, v165
	v_fmamk_f32 v150, v152, 0x3a800000, v165
	v_fmamk_f32 v152, v167, 0x3a800000, v165
	v_fmamk_f32 v167, v169, 0x3a800000, v165
	v_rsq_f32_e32 v172, v136
	v_fmamk_f32 v169, v170, 0x3a800000, v165
	v_rsq_f32_e32 v180, v147
	v_rsq_f32_e32 v184, v150
	v_rsq_f32_e32 v150, v167
	v_rsq_f32_e32 v182, v149
	v_rsq_f32_e32 v152, v152
	v_rsq_f32_e32 v136, v169
	v_pk_mul_f32 v[90:91], v[90:91], v[172:173] op_sel_hi:[1,0]
	v_pk_mul_f32 v[88:89], v[88:89], v[172:173] op_sel_hi:[1,0]
	v_pk_mul_f32 v[110:111], v[110:111], v[168:169] op_sel_hi:[1,0]
	v_pk_mul_f32 v[108:109], v[108:109], v[168:169] op_sel_hi:[1,0]
	v_pk_mul_f32 v[104:105], v[104:105], v[172:173] op_sel_hi:[1,0]
	v_pk_mul_f32 v[100:101], v[100:101], v[180:181] op_sel_hi:[1,0]
	v_cvt_pk_bf16_f32 v89, v88, v89
	v_cvt_pk_bf16_f32 v88, v90, v91
	v_pk_mul_f32 v[90:91], v[82:83], v[180:181] op_sel_hi:[1,0]
	v_pk_mul_f32 v[72:73], v[72:73], v[180:181] op_sel_hi:[1,0]
	v_pk_mul_f32 v[42:43], v[42:43], v[184:185] op_sel_hi:[1,0]
	v_pk_mul_f32 v[10:11], v[10:11], v[150:151] op_sel_hi:[1,0]
	v_pk_mul_f32 v[8:9], v[8:9], v[150:151] op_sel_hi:[1,0]
	v_cvt_pk_bf16_f32 v170, v108, v109
	v_cvt_pk_bf16_f32 v171, v110, v111
	v_pk_mul_f32 v[108:109], v[114:115], v[172:173] op_sel_hi:[1,0]
	v_pk_mul_f32 v[110:111], v[112:113], v[172:173] op_sel_hi:[1,0]
	v_pk_mul_f32 v[106:107], v[106:107], v[172:173] op_sel_hi:[1,0]
	v_pk_mul_f32 v[98:99], v[98:99], v[172:173] op_sel_hi:[1,0]
	v_pk_mul_f32 v[96:97], v[96:97], v[172:173] op_sel_hi:[1,0]
	v_pk_mul_f32 v[102:103], v[102:103], v[180:181] op_sel_hi:[1,0]
	v_cvt_pk_bf16_f32 v167, v104, v105
	v_cvt_pk_bf16_f32 v173, v100, v101
	v_pk_mul_f32 v[80:81], v[80:81], v[180:181] op_sel_hi:[1,0]
	v_cvt_pk_bf16_f32 v83, v90, v91
	v_pk_mul_f32 v[74:75], v[74:75], v[180:181] op_sel_hi:[1,0]
	v_cvt_pk_bf16_f32 v90, v72, v73
	v_pk_mul_f32 v[72:73], v[86:87], v[182:183] op_sel_hi:[1,0]
	v_pk_mul_f32 v[40:41], v[40:41], v[184:185] op_sel_hi:[1,0]
	v_cvt_pk_bf16_f32 v101, v42, v43
	v_pk_mul_f32 v[42:43], v[52:53], v[152:153] op_sel_hi:[1,0]
	v_pk_mul_f32 v[26:27], v[26:27], v[152:153] op_sel_hi:[1,0]
	v_pk_mul_f32 v[24:25], v[24:25], v[152:153] op_sel_hi:[1,0]
	v_cvt_pk_bf16_f32 v104, v8, v9
	v_cvt_pk_bf16_f32 v105, v10, v11
	v_pk_mul_f32 v[8:9], v[22:23], v[136:137] op_sel_hi:[1,0]
	v_pk_mul_f32 v[10:11], v[20:21], v[136:137] op_sel_hi:[1,0]
	v_pk_mul_f32 v[126:127], v[126:127], v[168:169] op_sel_hi:[1,0]
	v_pk_mul_f32 v[124:125], v[124:125], v[168:169] op_sel_hi:[1,0]
	v_pk_mul_f32 v[122:123], v[122:123], v[168:169] op_sel_hi:[1,0]
	v_pk_mul_f32 v[120:121], v[120:121], v[168:169] op_sel_hi:[1,0]
	v_pk_mul_f32 v[118:119], v[118:119], v[168:169] op_sel_hi:[1,0]
	v_pk_mul_f32 v[116:117], v[116:117], v[168:169] op_sel_hi:[1,0]
	v_pk_mul_f32 v[94:95], v[94:95], v[180:181] op_sel_hi:[1,0]
	v_pk_mul_f32 v[92:93], v[92:93], v[180:181] op_sel_hi:[1,0]
	v_cvt_pk_bf16_f32 v174, v108, v109
	v_cvt_pk_bf16_f32 v172, v102, v103
	v_cvt_pk_bf16_f32 v82, v80, v81
	v_cvt_pk_bf16_f32 v91, v74, v75
	v_pk_mul_f32 v[74:75], v[84:85], v[182:183] op_sel_hi:[1,0]
	v_cvt_pk_bf16_f32 v81, v72, v73
	v_pk_mul_f32 v[72:73], v[78:79], v[182:183] op_sel_hi:[1,0]
	v_pk_mul_f32 v[58:59], v[58:59], v[184:185] op_sel_hi:[1,0]
	v_pk_mul_f32 v[56:57], v[56:57], v[184:185] op_sel_hi:[1,0]
	v_cvt_pk_bf16_f32 v100, v40, v41
	v_pk_mul_f32 v[40:41], v[54:55], v[152:153] op_sel_hi:[1,0]
	v_cvt_pk_bf16_f32 v112, v42, v43
	v_pk_mul_f32 v[42:43], v[44:45], v[152:153] op_sel_hi:[1,0]
	v_cvt_pk_bf16_f32 v102, v24, v25
	v_cvt_pk_bf16_f32 v103, v26, v27
	v_pk_mul_f32 v[24:25], v[38:39], v[150:151] op_sel_hi:[1,0]
	v_pk_mul_f32 v[26:27], v[36:37], v[150:151] op_sel_hi:[1,0]
	v_cvt_pk_bf16_f32 v108, v10, v11
	v_cvt_pk_bf16_f32 v109, v8, v9
	v_pk_mul_f32 v[8:9], v[14:15], v[136:137] op_sel_hi:[1,0]
	v_pk_mul_f32 v[10:11], v[12:13], v[136:137] op_sel_hi:[1,0]
	v_pk_mul_f32 v[6:7], v[6:7], v[136:137] op_sel_hi:[1,0]
	v_pk_mul_f32 v[4:5], v[4:5], v[136:137] op_sel_hi:[1,0]
	v_pk_mul_f32 v[2:3], v[2:3], v[136:137] op_sel_hi:[1,0]
; __device__ __forceinline__ f32x4 ror1v(f32x4 v) { return (f32x4){dpp_ror1(v[0]), dpp_ror1(v[1]), dpp_ror1(v[2]), dpp_ror1(v[3])}; }
; __device__ __forceinline__ f32x4 ror2v(f32x4 v) { return (f32x4){dpp_ror2(v[0]), dpp_ror2(v[1]), dpp_ror2(v[2]), dpp_ror2(v[3])}; }
; __device__ __forceinline__ f32x4 unpack4(u32x2 w) { return (f32x4){bflo(w.x), bfhi(w.x), bflo(w.y), bfhi(w.y)}; }
;     __device__ __forceinline__ void operator()(AccRef acc, const Unit& u, int wr, int wc, int fr, int fq) const {
;     ...
;         for (int ai = 0; ai < 2; ++ai) {
;             const int rowg = u.pm * 256 + ai * 128 + wr * 64; const int grp = rowg >> 6;
; #pragma unroll
;             for (int n = 0; n < 2; ++n) { const unsigned jn = (unsigned)(j0 + 4 * n);
;                 f32x4 cu[4];
;                 {
;                     const f32x4 wu0 = *(const f32x4*)(cw + (DFF + jn)), wu1 = *(const f32x4*)(cw + (UPN + DFF + jn)), wu2 = *(const f32x4*)(cw + (2 * UPN + DFF + jn)), bu = *(const f32x4*)(cb + (DFF + jn));
;                     f32x4 pu1 = (f32x4){0.f, 0.f, 0.f, 0.f}, pu2 = pu1;
; #pragma unroll
;                     for (int m = 0; m < 4; ++m) {
;                         const f32x4 au = unpack4(pa[ai][1][m][n]);
;                         const f32x4 ru1 = ror1v(au), ru2 = ror2v(au);
;                         const f32x4 u1 = fr >= 1 ? ru1 : pu1, u2 = fr >= 2 ? ru2 : pu2;
;                         if (m == 0 && fr < 2) *(f32x4*)(edge + (unsigned)((grp * 4 + fr) * UPN + DFF + jn)) = au;
;                         if (m == 3 && fr >= 14) *(f32x4*)(edge + (unsigned)((grp * 4 + (fr - 12)) * UPN + DFF + jn)) = au;
;                         cu[m] = bu + wu0 * u2 + wu1 * u1 + wu2 * au;
;                         pu1 = ru1; pu2 = ru2; }
	v_pk_mul_f32 v[0:1], v[0:1], v[136:137] op_sel_hi:[1,0]
	v_lshl_add_u32 v44, v185, 3, s0
	v_cvt_pk_bf16_f32 v190, v124, v125
	v_cvt_pk_bf16_f32 v189, v126, v127
	v_cvt_pk_bf16_f32 v169, v120, v121
	v_cvt_pk_bf16_f32 v168, v122, v123
	v_cvt_pk_bf16_f32 v126, v116, v117
	v_cvt_pk_bf16_f32 v179, v118, v119
	v_cvt_pk_bf16_f32 v175, v110, v111
	v_cvt_pk_bf16_f32 v149, v106, v107
	v_cvt_pk_bf16_f32 v178, v96, v97
	v_cvt_pk_bf16_f32 v177, v98, v99
	v_cvt_pk_bf16_f32 v127, v92, v93
	v_cvt_pk_bf16_f32 v147, v94, v95
	v_cvt_pk_bf16_f32 v80, v74, v75
	v_pk_mul_f32 v[74:75], v[76:77], v[182:183] op_sel_hi:[1,0]
	v_cvt_pk_bf16_f32 v125, v72, v73
	v_pk_mul_f32 v[72:73], v[70:71], v[182:183] op_sel_hi:[1,0]
	v_cvt_pk_bf16_f32 v124, v74, v75
	v_pk_mul_f32 v[68:69], v[68:69], v[182:183] op_sel_hi:[1,0]
	v_cvt_pk_bf16_f32 v71, v72, v73
	v_pk_mul_f32 v[66:67], v[66:67], v[182:183] op_sel_hi:[1,0]
	v_cvt_pk_bf16_f32 v70, v68, v69
	v_pk_mul_f32 v[64:65], v[64:65], v[182:183] op_sel_hi:[1,0]
	v_cvt_pk_bf16_f32 v85, v66, v67
	v_pk_mul_f32 v[62:63], v[62:63], v[184:185] op_sel_hi:[1,0]
	v_cvt_pk_bf16_f32 v84, v64, v65
	v_pk_mul_f32 v[60:61], v[60:61], v[184:185] op_sel_hi:[1,0]
	v_cvt_pk_bf16_f32 v115, v62, v63
	v_cvt_pk_bf16_f32 v98, v56, v57
	v_cvt_pk_bf16_f32 v99, v58, v59
	v_pk_mul_f32 v[50:51], v[50:51], v[184:185] op_sel_hi:[1,0]
	v_cvt_pk_bf16_f32 v114, v60, v61
	v_pk_mul_f32 v[48:49], v[48:49], v[184:185] op_sel_hi:[1,0]
	v_cvt_pk_bf16_f32 v117, v50, v51
	v_cvt_pk_bf16_f32 v113, v40, v41
	v_pk_mul_f32 v[40:41], v[46:47], v[152:153] op_sel_hi:[1,0]
	v_cvt_pk_bf16_f32 v116, v48, v49
	v_cvt_pk_bf16_f32 v96, v42, v43
	v_pk_mul_f32 v[34:35], v[34:35], v[152:153] op_sel_hi:[1,0]
	v_cvt_pk_bf16_f32 v97, v40, v41
	v_pk_mul_f32 v[32:33], v[32:33], v[152:153] op_sel_hi:[1,0]
	v_cvt_pk_bf16_f32 v119, v34, v35
	v_cvt_pk_bf16_f32 v110, v26, v27
	v_cvt_pk_bf16_f32 v111, v24, v25
	v_pk_mul_f32 v[24:25], v[30:31], v[150:151] op_sel_hi:[1,0]
	v_cvt_pk_bf16_f32 v118, v32, v33
	v_pk_mul_f32 v[26:27], v[28:29], v[150:151] op_sel_hi:[1,0]
	v_cvt_pk_bf16_f32 v95, v24, v25
	v_pk_mul_f32 v[18:19], v[18:19], v[150:151] op_sel_hi:[1,0]
	v_cvt_pk_bf16_f32 v94, v26, v27
	v_pk_mul_f32 v[16:17], v[16:17], v[150:151] op_sel_hi:[1,0]
	v_cvt_pk_bf16_f32 v121, v18, v19
	v_cvt_pk_bf16_f32 v92, v10, v11
	v_cvt_pk_bf16_f32 v93, v8, v9
	v_cvt_pk_bf16_f32 v122, v4, v5
	v_cvt_pk_bf16_f32 v123, v6, v7
	s_nop 0
	v_cvt_pk_bf16_f32 v120, v16, v17
	v_cvt_pk_bf16_f32 v106, v0, v1
	v_cvt_pk_bf16_f32 v107, v2, v3
	v_add_u32_e32 v136, 0xb00, v44
	v_lshlrev_b64 v[12:13], 2, v[136:137]
	v_add_u32_e32 v136, 0x2100, v44
	v_lshl_add_u64 v[54:55], v[136:137], 2, s[66:67]
	v_add_u32_e32 v136, 0x3700, v44
	v_lshl_add_u64 v[52:53], s[66:67], 0, v[12:13]
	v_lshl_add_u64 v[56:57], v[136:137], 2, s[66:67]
	v_lshl_add_u64 v[58:59], s[36:37], 0, v[12:13]
	global_load_dwordx4 v[8:11], v[52:53], off
	global_load_dwordx4 v[0:3], v[54:55], off
	global_load_dwordx4 v[4:7], v[56:57], off
	global_load_dwordx4 v[12:15], v[58:59], off
	s_ashr_i32 s6, s69, 4
	v_add_u32_e32 v16, s6, v166
	v_mul_lo_u32 v152, v16, s87
	v_lshlrev_b32_e32 v36, 16, v126
	v_and_b32_e32 v37, 0xffff0000, v126
	v_lshlrev_b32_e32 v38, 16, v179
	v_and_b32_e32 v39, 0xffff0000, v179
	s_nop 1
	v_cmp_lt_i32_e64 s[10:11], 1, v166
	v_cmp_gt_i32_e64 s[12:13], 2, v166
	v_add_u32_e32 v78, 0xb00, v152
	v_mov_b32_dpp v191, v36 row_ror:1 row_mask:0xf bank_mask:0xf
	v_mov_b32_dpp v194, v37 row_ror:1 row_mask:0xf bank_mask:0xf
	v_mov_b32_dpp v192, v38 row_ror:1 row_mask:0xf bank_mask:0xf
	v_mov_b32_dpp v196, v39 row_ror:1 row_mask:0xf bank_mask:0xf
	v_mov_b32_dpp v193, v36 row_ror:2 row_mask:0xf bank_mask:0xf
	v_mov_b32_dpp v197, v37 row_ror:2 row_mask:0xf bank_mask:0xf
	v_mov_b32_dpp v201, v38 row_ror:2 row_mask:0xf bank_mask:0xf
	v_mov_b32_dpp v204, v39 row_ror:2 row_mask:0xf bank_mask:0xf
	s_and_saveexec_b64 s[0:1], s[12:13]
	s_cbranch_execz .LBB0_551
	v_add_u32_e32 v136, v78, v44
	v_lshl_add_u64 v[16:17], v[136:137], 2, s[28:29]
	global_store_dwordx4 v[16:17], v[36:39], off
.LBB0_551:
	s_or_b64 exec, exec, s[0:1]
	v_add_u32_e32 v126, -12, v166
	v_add_u32_e32 v16, s6, v126
	v_mul_lo_u32 v150, v16, s87
	v_lshlrev_b32_e32 v68, 16, v178
	v_and_b32_e32 v69, 0xffff0000, v178
	v_lshlrev_b32_e32 v66, 16, v177
	v_and_b32_e32 v67, 0xffff0000, v177
	s_nop 1
	v_lshlrev_b32_e32 v62, 16, v82
	v_and_b32_e32 v63, 0xffff0000, v82
	v_lshlrev_b32_e32 v50, 16, v83
	v_and_b32_e32 v51, 0xffff0000, v83
	s_nop 1
	v_lshlrev_b32_e32 v16, 16, v70
	v_and_b32_e32 v17, 0xffff0000, v70
	v_lshlrev_b32_e32 v18, 16, v71
	v_and_b32_e32 v19, 0xffff0000, v71
	s_nop 1
	v_cmp_lt_i32_e32 vcc, 13, v166
	v_add_u32_e32 v86, 0xb00, v150
	v_mov_b32_dpp v195, v68 row_ror:1 row_mask:0xf bank_mask:0xf
	v_mov_b32_dpp v200, v69 row_ror:1 row_mask:0xf bank_mask:0xf
	v_mov_b32_dpp v198, v66 row_ror:1 row_mask:0xf bank_mask:0xf
	v_mov_b32_dpp v202, v67 row_ror:1 row_mask:0xf bank_mask:0xf
	v_mov_b32_dpp v199, v68 row_ror:2 row_mask:0xf bank_mask:0xf
	v_mov_b32_dpp v203, v69 row_ror:2 row_mask:0xf bank_mask:0xf
	v_mov_b32_dpp v205, v66 row_ror:2 row_mask:0xf bank_mask:0xf
	v_mov_b32_dpp v206, v67 row_ror:2 row_mask:0xf bank_mask:0xf
	v_mov_b32_dpp v79, v62 row_ror:1 row_mask:0xf bank_mask:0xf
	v_mov_b32_dpp v87, v63 row_ror:1 row_mask:0xf bank_mask:0xf
	v_mov_b32_dpp v82, v50 row_ror:1 row_mask:0xf bank_mask:0xf
	v_mov_b32_dpp v177, v51 row_ror:1 row_mask:0xf bank_mask:0xf
	v_mov_b32_dpp v83, v62 row_ror:2 row_mask:0xf bank_mask:0xf
	v_mov_b32_dpp v178, v63 row_ror:2 row_mask:0xf bank_mask:0xf
	v_mov_b32_dpp v179, v50 row_ror:2 row_mask:0xf bank_mask:0xf
	v_mov_b32_dpp v180, v51 row_ror:2 row_mask:0xf bank_mask:0xf
	v_mov_b32_dpp v181, v16 row_ror:1 row_mask:0xf bank_mask:0xf
	v_mov_b32_dpp v184, v17 row_ror:1 row_mask:0xf bank_mask:0xf
	v_mov_b32_dpp v182, v18 row_ror:1 row_mask:0xf bank_mask:0xf
	v_mov_b32_dpp v185, v19 row_ror:1 row_mask:0xf bank_mask:0xf
	v_mov_b32_dpp v183, v16 row_ror:2 row_mask:0xf bank_mask:0xf
	v_mov_b32_dpp v186, v17 row_ror:2 row_mask:0xf bank_mask:0xf
	v_mov_b32_dpp v187, v18 row_ror:2 row_mask:0xf bank_mask:0xf
	v_mov_b32_dpp v188, v19 row_ror:2 row_mask:0xf bank_mask:0xf
	s_and_saveexec_b64 s[0:1], vcc
	s_cbranch_execz .LBB0_553
	v_add_u32_e32 v136, v86, v44
	v_lshl_add_u64 v[20:21], v[136:137], 2, s[28:29]
	global_store_dwordx4 v[20:21], v[16:19], off
; __device__ __forceinline__ f32x4 gelu4(f32x4 v) { const f32x2 a = gelu_pk((f32x2){v[0], v[1]}), b = gelu_pk((f32x2){v[2], v[3]}); return (f32x4){a.x, a.y, b.x, b.y}; }
; __device__ __forceinline__ f32x4 ror1v(f32x4 v) { return (f32x4){dpp_ror1(v[0]), dpp_ror1(v[1]), dpp_ror1(v[2]), dpp_ror1(v[3])}; }
; __device__ __forceinline__ f32x4 ror2v(f32x4 v) { return (f32x4){dpp_ror2(v[0]), dpp_ror2(v[1]), dpp_ror2(v[2]), dpp_ror2(v[3])}; }
; __device__ __forceinline__ u32x2 pack4(f32x4 v) { return (u32x2){pk2(v[0], v[1]), pk2(v[2], v[3])}; }
; __device__ __forceinline__ f32x2 gelu_pk(f32x2 v) {
;     const f32x2 av = __builtin_elementwise_abs(v), d = av * 0.2316418882f + 1.0f;
;     f32x2 t; t.x = __builtin_amdgcn_rcpf(d.x); t.y = __builtin_amdgcn_rcpf(d.y);
;     f32x2 q = t * 0.5307027145f + (-0.7265760135f); q = q * t + 0.7107068705f; q = q * t + (-0.142248368f); q = q * t + 0.127414796f; q = q * t;
;     const f32x2 s = (v * v) * (-0.72134752044f);
;     f32x2 e; e.x = __builtin_amdgcn_exp2f(s.x); e.y = __builtin_amdgcn_exp2f(s.y);
;     const f32x2 m = v * (q * e), r = v - m;
;     f32x2 o; o.x = v.x < 0.f ? m.x : r.x; o.y = v.y < 0.f ? m.y : r.y; return o;
; }
;     __device__ __forceinline__ void operator()(AccRef acc, const Unit& u, int wr, int wc, int fr, int fq) const {
;     ...
;                 {
;                     const f32x4 wg0 = *(const f32x4*)(cw + jn), wg1 = *(const f32x4*)(cw + (UPN + jn)), wg2 = *(const f32x4*)(cw + (2 * UPN + jn)), bg = *(const f32x4*)(cb + jn);
;                     f32x4 pg1 = (f32x4){0.f, 0.f, 0.f, 0.f}, pg2 = pg1;
; #pragma unroll
;                     for (int m = 0; m < 4; ++m) { const int row = rowg + m * 16 + fr;
;                         const f32x4 ag = unpack4(pa[ai][0][m][n]);
;                         const f32x4 rg1 = ror1v(ag), rg2 = ror2v(ag);
;                         const f32x4 g1 = fr >= 1 ? rg1 : pg1, g2 = fr >= 2 ? rg2 : pg2;
;                         if (m == 0 && fr < 2) *(f32x4*)(edge + (unsigned)((grp * 4 + fr) * UPN + jn)) = ag;
;                         if (m == 3 && fr >= 14) *(f32x4*)(edge + (unsigned)((grp * 4 + (fr - 12)) * UPN + jn)) = ag;
;                         const f32x4 o = gelu4(bg + wg0 * g2 + wg1 * g1 + wg2 * ag) * cu[m];
;                         if (!(m == 0 && fr < 2)) *(u32x2*)(act + (unsigned)(row * DFF + jn)) = pack4(o);
.LBB0_553:
	s_or_b64 exec, exec, s[0:1]
	v_mov_b32_e32 v45, v137
	v_add_u32_e32 v136, 0x1600, v44
	v_lshlrev_b64 v[32:33], 2, v[44:45]
	v_lshl_add_u64 v[60:61], v[136:137], 2, s[66:67]
	v_add_u32_e32 v136, 0x2c00, v44
	v_lshl_add_u64 v[46:47], s[66:67], 0, v[32:33]
	v_lshl_add_u64 v[64:65], v[136:137], 2, s[66:67]
	v_lshl_add_u64 v[48:49], s[36:37], 0, v[32:33]
	global_load_dwordx4 v[28:31], v[46:47], off
	global_load_dwordx4 v[20:23], v[60:61], off
	global_load_dwordx4 v[24:27], v[64:65], off
	global_load_dwordx4 v[32:35], v[48:49], off
	v_lshlrev_b32_e32 v40, 16, v190
	v_and_b32_e32 v41, 0xffff0000, v190
	v_lshlrev_b32_e32 v42, 16, v189
	v_and_b32_e32 v43, 0xffff0000, v189
	s_nop 1
	v_cmp_lt_i32_e64 s[8:9], 0, v166
	v_cmp_lt_i32_e64 s[6:7], 1, v166
	v_mov_b32_dpp v70, v40 row_ror:1 row_mask:0xf bank_mask:0xf
	v_mov_b32_dpp v71, v41 row_ror:1 row_mask:0xf bank_mask:0xf
	v_mov_b32_dpp v72, v42 row_ror:1 row_mask:0xf bank_mask:0xf
	v_mov_b32_dpp v73, v43 row_ror:1 row_mask:0xf bank_mask:0xf
	v_mov_b32_dpp v74, v40 row_ror:2 row_mask:0xf bank_mask:0xf
	v_mov_b32_dpp v75, v41 row_ror:2 row_mask:0xf bank_mask:0xf
	v_mov_b32_dpp v76, v42 row_ror:2 row_mask:0xf bank_mask:0xf
	v_mov_b32_dpp v77, v43 row_ror:2 row_mask:0xf bank_mask:0xf
	s_and_saveexec_b64 s[0:1], s[10:11]
	s_xor_b64 s[76:77], exec, s[0:1]
	s_cbranch_execz .LBB0_555
	v_cndmask_b32_e64 v213, 0, v204, s[6:7]
	v_cndmask_b32_e64 v212, 0, v201, s[6:7]
	v_cndmask_b32_e64 v211, 0, v196, s[8:9]
	v_cndmask_b32_e64 v210, 0, v192, s[8:9]
	s_waitcnt vmcnt(4)
	v_pk_fma_f32 v[212:213], v[10:11], v[212:213], v[14:15]
	v_cndmask_b32_e64 v215, 0, v197, s[6:7]
	v_pk_fma_f32 v[210:211], v[2:3], v[210:211], v[212:213]
	v_cndmask_b32_e64 v214, 0, v193, s[6:7]
	v_pk_fma_f32 v[38:39], v[6:7], v[38:39], v[210:211]
	s_waitcnt vmcnt(0)
	v_pk_fma_f32 v[210:211], v[28:29], v[74:75], v[32:33]
	v_cndmask_b32_e64 v209, 0, v194, s[8:9]
	v_pk_fma_f32 v[210:211], v[20:21], v[70:71], v[210:211]
	v_cndmask_b32_e64 v208, 0, v191, s[8:9]
	v_pk_fma_f32 v[40:41], v[24:25], v[40:41], v[210:211]
	v_pk_fma_f32 v[214:215], v[8:9], v[214:215], v[12:13]
	v_and_b32_e32 v213, 0x7fffffff, v41
	v_and_b32_e32 v212, 0x7fffffff, v40
	v_pk_fma_f32 v[212:213], v[212:213], s[42:43], 1.0 op_sel_hi:[1,0,0]
	v_pk_fma_f32 v[208:209], v[0:1], v[208:209], v[214:215]
	v_rcp_f32_e32 v212, v212
	v_rcp_f32_e32 v213, v213
	v_pk_mul_f32 v[210:211], v[40:41], v[40:41]
	v_mov_b64_e32 v[214:215], s[54:55]
	v_pk_mul_f32 v[210:211], v[210:211], s[38:39] op_sel_hi:[1,0]
	v_pk_fma_f32 v[216:217], v[212:213], s[52:53], v[214:215] op_sel_hi:[1,0,0]
	v_exp_f32_e32 v210, v210
	v_exp_f32_e32 v211, v211
	v_pk_fma_f32 v[216:217], v[212:213], v[216:217], s[56:57] op_sel_hi:[1,1,0]
	v_pk_fma_f32 v[36:37], v[4:5], v[36:37], v[208:209]
	v_pk_fma_f32 v[216:217], v[212:213], v[216:217], s[62:63] op_sel_hi:[1,1,0]
	v_pk_fma_f32 v[208:209], v[30:31], v[76:77], v[34:35]
	v_pk_fma_f32 v[216:217], v[212:213], v[216:217], s[64:65] op_sel_hi:[1,1,0]
	v_pk_fma_f32 v[208:209], v[22:23], v[72:73], v[208:209]
	v_pk_mul_f32 v[212:213], v[212:213], v[216:217]
	v_cmp_gt_f32_e64 s[0:1], 0, v40
	v_pk_mul_f32 v[210:211], v[210:211], v[212:213]
	v_pk_fma_f32 v[42:43], v[26:27], v[42:43], v[208:209]
	v_pk_mul_f32 v[212:213], v[40:41], v[210:211]
	v_pk_fma_f32 v[210:211], v[40:41], v[210:211], v[40:41] neg_lo:[1,0,0] neg_hi:[1,0,0]
	v_pk_mul_f32 v[208:209], v[42:43], v[42:43]
	v_cndmask_b32_e64 v40, v210, v212, s[0:1]
	v_cmp_gt_f32_e64 s[0:1], 0, v41
	v_and_b32_e32 v210, 0x7fffffff, v42
	v_pk_mul_f32 v[208:209], v[208:209], s[38:39] op_sel_hi:[1,0]
	v_cndmask_b32_e64 v41, v211, v213, s[0:1]
	v_and_b32_e32 v211, 0x7fffffff, v43
	v_pk_fma_f32 v[210:211], v[210:211], s[42:43], 1.0 op_sel_hi:[1,0,0]
	v_exp_f32_e32 v208, v208
	v_rcp_f32_e32 v210, v210
	v_rcp_f32_e32 v211, v211
	v_exp_f32_e32 v209, v209
	v_cmp_gt_f32_e64 s[0:1], 0, v42
	v_pk_mul_f32 v[36:37], v[36:37], v[40:41]
	v_pk_fma_f32 v[212:213], v[210:211], s[52:53], v[214:215] op_sel_hi:[1,0,0]
	v_cvt_pk_bf16_f32 v36, v36, v37
	s_nop 0
	v_pk_fma_f32 v[212:213], v[210:211], v[212:213], s[56:57] op_sel_hi:[1,1,0]
	s_nop 0
	v_pk_fma_f32 v[212:213], v[210:211], v[212:213], s[62:63] op_sel_hi:[1,1,0]
	s_nop 0
	v_pk_fma_f32 v[212:213], v[210:211], v[212:213], s[64:65] op_sel_hi:[1,1,0]
	s_nop 0
	v_pk_mul_f32 v[210:211], v[210:211], v[212:213]
	s_nop 0
	v_pk_mul_f32 v[208:209], v[208:209], v[210:211]
	s_nop 0
	v_pk_mul_f32 v[210:211], v[42:43], v[208:209]
	v_pk_fma_f32 v[208:209], v[42:43], v[208:209], v[42:43] neg_lo:[1,0,0] neg_hi:[1,0,0]
	s_nop 0
	v_cndmask_b32_e64 v42, v208, v210, s[0:1]
	v_cmp_gt_f32_e64 s[0:1], 0, v43
	s_nop 1
	v_cndmask_b32_e64 v43, v209, v211, s[0:1]
	v_pk_mul_f32 v[38:39], v[38:39], v[42:43]
	s_nop 0
	v_cvt_pk_bf16_f32 v37, v38, v39
	v_mad_u64_u32 v[38:39], s[0:1], v146, s88, v[44:45]
	v_mov_b32_e32 v39, v137
	v_lshl_add_u64 v[38:39], v[38:39], 1, s[26:27]
	global_store_dwordx2 v[38:39], v[36:37], off

; __device__ __forceinline__ f32x2 gelu_pk(f32x2 v) {
;     __device__ __forceinline__ void operator()(AccRef acc, const Unit& u, int wr, int wc, int fr, int fq) const {
;     ...
;             for (int n = 0; n < 2; ++n) { const unsigned jn = (unsigned)(j0 + 4 * n);
;                 f32x4 cu[4];
;                 {
;                     const f32x4 wu0 = *(const f32x4*)(cw + (DFF + jn)), wu1 = *(const f32x4*)(cw + (UPN + DFF + jn)), wu2 = *(const f32x4*)(cw + (2 * UPN + DFF + jn)), bu = *(const f32x4*)(cb + (DFF + jn));
;                     f32x4 pu1 = (f32x4){0.f, 0.f, 0.f, 0.f}, pu2 = pu1;
; #pragma unroll
;                     for (int m = 0; m < 4; ++m) {
;                         const f32x4 au = unpack4(pa[ai][1][m][n]);
;                         const f32x4 ru1 = ror1v(au), ru2 = ror2v(au);
;                         const f32x4 u1 = fr >= 1 ? ru1 : pu1, u2 = fr >= 2 ? ru2 : pu2;
;                         if (m == 0 && fr < 2) *(f32x4*)(edge + (unsigned)((grp * 4 + fr) * UPN + DFF + jn)) = au;
;                         if (m == 3 && fr >= 14) *(f32x4*)(edge + (unsigned)((grp * 4 + (fr - 12)) * UPN + DFF + jn)) = au;
;                         cu[m] = bu + wu0 * u2 + wu1 * u1 + wu2 * au;
;                         pu1 = ru1; pu2 = ru2; }
;                 }
;                 {
;                     const f32x4 wg0 = *(const f32x4*)(cw + jn), wg1 = *(const f32x4*)(cw + (UPN + jn)), wg2 = *(const f32x4*)(cw + (2 * UPN + jn)), bg = *(const f32x4*)(cb + jn);
;                     f32x4 pg1 = (f32x4){0.f, 0.f, 0.f, 0.f}, pg2 = pg1;
; #pragma unroll
;                     for (int m = 0; m < 4; ++m) { const int row = rowg + m * 16 + fr;
;                         const f32x4 ag = unpack4(pa[ai][0][m][n]);
;                         const f32x4 rg1 = ror1v(ag), rg2 = ror2v(ag);
;                         const f32x4 g1 = fr >= 1 ? rg1 : pg1, g2 = fr >= 2 ? rg2 : pg2;
;                         if (m == 0 && fr < 2) *(f32x4*)(edge + (unsigned)((grp * 4 + fr) * UPN + jn)) = ag;
;                         if (m == 3 && fr >= 14) *(f32x4*)(edge + (unsigned)((grp * 4 + (fr - 12)) * UPN + jn)) = ag;
;                         const f32x4 o = gelu4(bg + wg0 * g2 + wg1 * g1 + wg2 * ag) * cu[m];
;                         if (!(m == 0 && fr < 2)) *(u32x2*)(act + (unsigned)(row * DFF + jn)) = pack4(o);
;                         pg1 = rg1; pg2 = rg2; }
.LBB0_557:
	s_or_b64 exec, exec, s[0:1]
	s_nop 0
	v_cndmask_b32_e64 v43, v197, v203, s[6:7]
	v_cndmask_b32_e64 v42, v193, v199, s[6:7]
	v_cndmask_b32_e64 v37, v194, v200, s[8:9]
	v_cndmask_b32_e64 v36, v191, v195, s[8:9]
	v_cndmask_b32_e64 v41, v204, v206, s[6:7]
	v_cndmask_b32_e64 v40, v201, v205, s[6:7]
	s_waitcnt vmcnt(4)
	v_pk_fma_f32 v[42:43], v[8:9], v[42:43], v[12:13]
	v_cndmask_b32_e64 v39, v196, v202, s[8:9]
	v_cndmask_b32_e64 v38, v192, v198, s[8:9]
	v_pk_fma_f32 v[40:41], v[10:11], v[40:41], v[14:15]
	v_pk_fma_f32 v[36:37], v[0:1], v[36:37], v[42:43]
	v_pk_fma_f32 v[38:39], v[2:3], v[38:39], v[40:41]
	v_pk_fma_f32 v[36:37], v[4:5], v[68:69], v[36:37]
	v_cndmask_b32_e64 v69, v203, v178, s[6:7]
	v_cndmask_b32_e64 v68, v199, v83, s[6:7]
	v_pk_fma_f32 v[38:39], v[6:7], v[66:67], v[38:39]
	v_cndmask_b32_e64 v41, v200, v87, s[8:9]
	v_cndmask_b32_e64 v40, v195, v79, s[8:9]
	v_cndmask_b32_e64 v67, v206, v180, s[6:7]
	v_cndmask_b32_e64 v66, v205, v179, s[6:7]
	v_pk_fma_f32 v[68:69], v[8:9], v[68:69], v[12:13]
	v_cndmask_b32_e64 v43, v202, v177, s[8:9]
	v_cndmask_b32_e64 v42, v198, v82, s[8:9]
	v_pk_fma_f32 v[66:67], v[10:11], v[66:67], v[14:15]
	v_pk_fma_f32 v[40:41], v[0:1], v[40:41], v[68:69]
	v_pk_fma_f32 v[42:43], v[2:3], v[42:43], v[66:67]
	v_pk_fma_f32 v[68:69], v[4:5], v[62:63], v[40:41]
	v_lshlrev_b32_e32 v40, 16, v175
	v_and_b32_e32 v41, 0xffff0000, v175
	v_mov_b32_e32 v193, v137
	v_mov_b32_e32 v194, v137
	v_pk_fma_f32 v[190:191], v[6:7], v[50:51], v[42:43]
	v_lshlrev_b32_e32 v42, 16, v174
	v_and_b32_e32 v43, 0xffff0000, v174
	v_mov_b32_e32 v174, v137
	v_mov_b32_e32 v175, v137
	v_mov_b32_dpp v193, v40 row_ror:2 row_mask:0xf bank_mask:0xf
	v_mov_b32_dpp v194, v41 row_ror:2 row_mask:0xf bank_mask:0xf
	v_mov_b32_dpp v174, v40 row_ror:1 row_mask:0xf bank_mask:0xf
	v_mov_b32_dpp v175, v41 row_ror:1 row_mask:0xf bank_mask:0xf
	v_cndmask_b32_e64 v67, v75, v194, s[6:7]
	v_cndmask_b32_e64 v66, v74, v193, s[6:7]
	v_cndmask_b32_e64 v63, v71, v175, s[8:9]
	v_cndmask_b32_e64 v62, v70, v174, s[8:9]
	s_waitcnt vmcnt(0)
	v_pk_fma_f32 v[66:67], v[28:29], v[66:67], v[32:33]
	v_mov_b32_e32 v195, v137
	v_pk_fma_f32 v[62:63], v[20:21], v[62:63], v[66:67]
	v_mov_b32_e32 v196, v137
	v_pk_fma_f32 v[40:41], v[24:25], v[40:41], v[62:63]
	v_mov_b32_e32 v189, v137
	v_and_b32_e32 v67, 0x7fffffff, v41
	v_and_b32_e32 v66, 0x7fffffff, v40
	v_pk_fma_f32 v[66:67], v[66:67], s[42:43], 1.0 op_sel_hi:[1,0,0]
	v_mov_b32_e32 v192, v137
	v_mov_b32_dpp v195, v42 row_ror:2 row_mask:0xf bank_mask:0xf
	v_mov_b32_dpp v196, v43 row_ror:2 row_mask:0xf bank_mask:0xf
	v_rcp_f32_e32 v66, v66
	v_rcp_f32_e32 v67, v67
	v_mov_b32_dpp v189, v42 row_ror:1 row_mask:0xf bank_mask:0xf
	v_mov_b32_dpp v192, v43 row_ror:1 row_mask:0xf bank_mask:0xf
	v_cndmask_b32_e64 v71, v77, v196, s[6:7]
	v_cndmask_b32_e64 v70, v76, v195, s[6:7]
	v_cndmask_b32_e64 v51, v73, v192, s[8:9]
	v_cndmask_b32_e64 v50, v72, v189, s[8:9]
	v_pk_fma_f32 v[70:71], v[30:31], v[70:71], v[34:35]
	v_pk_mul_f32 v[62:63], v[40:41], v[40:41]
	v_pk_fma_f32 v[50:51], v[22:23], v[50:51], v[70:71]
	v_mov_b64_e32 v[70:71], s[54:55]
	v_pk_mul_f32 v[62:63], v[62:63], s[38:39] op_sel_hi:[1,0]
	v_pk_fma_f32 v[72:73], v[66:67], s[52:53], v[70:71] op_sel_hi:[1,0,0]
	v_exp_f32_e32 v62, v62
	v_exp_f32_e32 v63, v63
	v_pk_fma_f32 v[72:73], v[66:67], v[72:73], s[56:57] op_sel_hi:[1,1,0]
	v_cmp_gt_f32_e64 s[0:1], 0, v40
	v_pk_fma_f32 v[72:73], v[66:67], v[72:73], s[62:63] op_sel_hi:[1,1,0]
	v_pk_fma_f32 v[42:43], v[26:27], v[42:43], v[50:51]
	v_pk_fma_f32 v[72:73], v[66:67], v[72:73], s[64:65] op_sel_hi:[1,1,0]
	v_pk_mul_f32 v[50:51], v[42:43], v[42:43]
	v_pk_mul_f32 v[66:67], v[66:67], v[72:73]
	v_pk_mul_f32 v[50:51], v[50:51], s[38:39] op_sel_hi:[1,0]
	v_pk_mul_f32 v[62:63], v[62:63], v[66:67]
	v_exp_f32_e32 v50, v50
	v_pk_mul_f32 v[66:67], v[40:41], v[62:63]
	v_pk_fma_f32 v[62:63], v[40:41], v[62:63], v[40:41] neg_lo:[1,0,0] neg_hi:[1,0,0]
	v_exp_f32_e32 v51, v51
	v_cndmask_b32_e64 v40, v62, v66, s[0:1]
	v_cmp_gt_f32_e64 s[0:1], 0, v41
	v_and_b32_e32 v62, 0x7fffffff, v42
	v_mul_lo_u32 v45, v148, s88
	v_cndmask_b32_e64 v41, v63, v67, s[0:1]
	v_and_b32_e32 v63, 0x7fffffff, v43
	v_pk_fma_f32 v[62:63], v[62:63], s[42:43], 1.0 op_sel_hi:[1,0,0]
	v_cmp_gt_f32_e64 s[0:1], 0, v42
	v_rcp_f32_e32 v62, v62
	v_rcp_f32_e32 v63, v63
	v_pk_mul_f32 v[36:37], v[36:37], v[40:41]
	v_add_u32_e32 v136, v45, v44
	v_cvt_pk_bf16_f32 v36, v36, v37
	v_pk_fma_f32 v[66:67], v[62:63], s[52:53], v[70:71] op_sel_hi:[1,0,0]
	s_nop 1
	v_pk_fma_f32 v[66:67], v[62:63], v[66:67], s[56:57] op_sel_hi:[1,1,0]
	s_nop 1
	v_pk_fma_f32 v[66:67], v[62:63], v[66:67], s[62:63] op_sel_hi:[1,1,0]
	s_nop 0
	v_pk_fma_f32 v[66:67], v[62:63], v[66:67], s[64:65] op_sel_hi:[1,1,0]
	s_nop 0
	v_pk_mul_f32 v[62:63], v[62:63], v[66:67]
	s_nop 1
	v_pk_mul_f32 v[50:51], v[50:51], v[62:63]
	v_mov_b32_e32 v67, 0
	v_pk_mul_f32 v[62:63], v[42:43], v[50:51]
	v_pk_fma_f32 v[50:51], v[42:43], v[50:51], v[42:43] neg_lo:[1,0,0] neg_hi:[1,0,0]
	s_nop 0
	v_cndmask_b32_e64 v42, v50, v62, s[0:1]
	v_cmp_gt_f32_e64 s[0:1], 0, v43
	s_nop 1
	v_cndmask_b32_e64 v43, v51, v63, s[0:1]
	v_pk_mul_f32 v[38:39], v[38:39], v[42:43]
	s_nop 1
	v_cvt_pk_bf16_f32 v37, v38, v39
	v_lshl_add_u64 v[38:39], v[136:137], 1, s[26:27]
	global_store_dwordx2 v[38:39], v[36:37], off
	v_lshlrev_b32_e32 v36, 16, v173
	v_and_b32_e32 v37, 0xffff0000, v173
	s_nop 1
	v_mov_b32_dpp v43, v36 row_ror:2 row_mask:0xf bank_mask:0xf
	v_mov_b32_dpp v40, v36 row_ror:1 row_mask:0xf bank_mask:0xf
	v_mov_b32_dpp v63, v37 row_ror:2 row_mask:0xf bank_mask:0xf
	v_mov_b32_dpp v41, v37 row_ror:1 row_mask:0xf bank_mask:0xf
	v_cndmask_b32_e64 v77, v194, v63, s[6:7]
; __device__ __forceinline__ f32x2 gelu_pk(f32x2 v) {
;     __device__ __forceinline__ void operator()(AccRef acc, const Unit& u, int wr, int wc, int fr, int fq) const {
;     ...
;             for (int n = 0; n < 2; ++n) { const unsigned jn = (unsigned)(j0 + 4 * n);
;                 f32x4 cu[4];
;                 {
;                     const f32x4 wu0 = *(const f32x4*)(cw + (DFF + jn)), wu1 = *(const f32x4*)(cw + (UPN + DFF + jn)), wu2 = *(const f32x4*)(cw + (2 * UPN + DFF + jn)), bu = *(const f32x4*)(cb + (DFF + jn));
;                     f32x4 pu1 = (f32x4){0.f, 0.f, 0.f, 0.f}, pu2 = pu1;
; #pragma unroll
;                     for (int m = 0; m < 4; ++m) {
;                         const f32x4 au = unpack4(pa[ai][1][m][n]);
;                         const f32x4 ru1 = ror1v(au), ru2 = ror2v(au);
;                         const f32x4 u1 = fr >= 1 ? ru1 : pu1, u2 = fr >= 2 ? ru2 : pu2;
;                         if (m == 0 && fr < 2) *(f32x4*)(edge + (unsigned)((grp * 4 + fr) * UPN + DFF + jn)) = au;
;                         if (m == 3 && fr >= 14) *(f32x4*)(edge + (unsigned)((grp * 4 + (fr - 12)) * UPN + DFF + jn)) = au;
;                         cu[m] = bu + wu0 * u2 + wu1 * u1 + wu2 * au;
;                         pu1 = ru1; pu2 = ru2; }
;                 }
;                 {
;                     const f32x4 wg0 = *(const f32x4*)(cw + jn), wg1 = *(const f32x4*)(cw + (UPN + jn)), wg2 = *(const f32x4*)(cw + (2 * UPN + jn)), bg = *(const f32x4*)(cb + jn);
;                     f32x4 pg1 = (f32x4){0.f, 0.f, 0.f, 0.f}, pg2 = pg1;
; #pragma unroll
;                     for (int m = 0; m < 4; ++m) { const int row = rowg + m * 16 + fr;
;                         const f32x4 ag = unpack4(pa[ai][0][m][n]);
;                         const f32x4 rg1 = ror1v(ag), rg2 = ror2v(ag);
;                         const f32x4 g1 = fr >= 1 ? rg1 : pg1, g2 = fr >= 2 ? rg2 : pg2;
;                         if (m == 0 && fr < 2) *(f32x4*)(edge + (unsigned)((grp * 4 + fr) * UPN + jn)) = ag;
;                         if (m == 3 && fr >= 14) *(f32x4*)(edge + (unsigned)((grp * 4 + (fr - 12)) * UPN + jn)) = ag;
;                         const f32x4 o = gelu4(bg + wg0 * g2 + wg1 * g1 + wg2 * ag) * cu[m];
;                         if (!(m == 0 && fr < 2)) *(u32x2*)(act + (unsigned)(row * DFF + jn)) = pack4(o);
;                         pg1 = rg1; pg2 = rg2; }
	v_cndmask_b32_e64 v76, v193, v43, s[6:7]
	v_cndmask_b32_e64 v75, v175, v41, s[8:9]
	v_cndmask_b32_e64 v74, v174, v40, s[8:9]
	v_pk_fma_f32 v[76:77], v[28:29], v[76:77], v[32:33]
	v_lshlrev_b32_e32 v38, 16, v172
	v_pk_fma_f32 v[74:75], v[20:21], v[74:75], v[76:77]
	v_and_b32_e32 v39, 0xffff0000, v172
	v_pk_fma_f32 v[36:37], v[24:25], v[36:37], v[74:75]
	s_nop 1
	v_and_b32_e32 v77, 0x7fffffff, v37
	v_and_b32_e32 v76, 0x7fffffff, v36
	v_pk_fma_f32 v[76:77], v[76:77], s[42:43], 1.0 op_sel_hi:[1,0,0]
	v_mov_b32_dpp v50, v38 row_ror:2 row_mask:0xf bank_mask:0xf
	v_rcp_f32_e32 v76, v76
	v_rcp_f32_e32 v77, v77
	v_mov_b32_dpp v66, v39 row_ror:2 row_mask:0xf bank_mask:0xf
	v_mov_b32_dpp v42, v38 row_ror:1 row_mask:0xf bank_mask:0xf
	v_mov_b32_dpp v62, v39 row_ror:1 row_mask:0xf bank_mask:0xf
	v_cndmask_b32_e64 v173, v196, v66, s[6:7]
	v_cndmask_b32_e64 v172, v195, v50, s[6:7]
	v_cndmask_b32_e64 v73, v192, v62, s[8:9]
	v_cndmask_b32_e64 v72, v189, v42, s[8:9]
	v_pk_fma_f32 v[172:173], v[30:31], v[172:173], v[34:35]
	v_pk_mul_f32 v[74:75], v[36:37], v[36:37]
	v_pk_fma_f32 v[72:73], v[22:23], v[72:73], v[172:173]
	v_pk_mul_f32 v[74:75], v[74:75], s[38:39] op_sel_hi:[1,0]
	v_pk_fma_f32 v[172:173], v[76:77], s[52:53], v[70:71] op_sel_hi:[1,0,0]
	v_exp_f32_e32 v74, v74
	v_exp_f32_e32 v75, v75
	v_pk_fma_f32 v[172:173], v[76:77], v[172:173], s[56:57] op_sel_hi:[1,1,0]
	v_cmp_gt_f32_e64 s[0:1], 0, v36
	v_pk_fma_f32 v[172:173], v[76:77], v[172:173], s[62:63] op_sel_hi:[1,1,0]
	v_pk_fma_f32 v[38:39], v[26:27], v[38:39], v[72:73]
	v_pk_fma_f32 v[172:173], v[76:77], v[172:173], s[64:65] op_sel_hi:[1,1,0]
	v_pk_mul_f32 v[72:73], v[38:39], v[38:39]
	v_pk_mul_f32 v[76:77], v[76:77], v[172:173]
	v_pk_mul_f32 v[72:73], v[72:73], s[38:39] op_sel_hi:[1,0]
	v_pk_mul_f32 v[74:75], v[74:75], v[76:77]
	v_exp_f32_e32 v72, v72
	v_pk_mul_f32 v[76:77], v[36:37], v[74:75]
	v_pk_fma_f32 v[74:75], v[36:37], v[74:75], v[36:37] neg_lo:[1,0,0] neg_hi:[1,0,0]
	v_exp_f32_e32 v73, v73
	v_cndmask_b32_e64 v36, v74, v76, s[0:1]
	v_cmp_gt_f32_e64 s[0:1], 0, v37
	v_and_b32_e32 v74, 0x7fffffff, v38
	v_add_u32_e32 v51, 0xb000, v45
	v_cndmask_b32_e64 v37, v75, v77, s[0:1]
	v_and_b32_e32 v75, 0x7fffffff, v39
	v_pk_fma_f32 v[74:75], v[74:75], s[42:43], 1.0 op_sel_hi:[1,0,0]
	v_cmp_gt_f32_e64 s[0:1], 0, v38
	v_rcp_f32_e32 v74, v74
	v_rcp_f32_e32 v75, v75
	v_pk_mul_f32 v[36:37], v[68:69], v[36:37]
	v_add_u32_e32 v136, v51, v44
	v_cvt_pk_bf16_f32 v36, v36, v37
	v_pk_fma_f32 v[70:71], v[74:75], s[52:53], v[70:71] op_sel_hi:[1,0,0]
	s_nop 1
	v_pk_fma_f32 v[70:71], v[74:75], v[70:71], s[56:57] op_sel_hi:[1,1,0]
	s_nop 1
	v_pk_fma_f32 v[70:71], v[74:75], v[70:71], s[62:63] op_sel_hi:[1,1,0]
	s_nop 0
	v_pk_fma_f32 v[70:71], v[74:75], v[70:71], s[64:65] op_sel_hi:[1,1,0]
	s_nop 0
	v_pk_mul_f32 v[70:71], v[74:75], v[70:71]
	s_nop 1
	v_pk_mul_f32 v[70:71], v[72:73], v[70:71]
	s_nop 0
	v_pk_mul_f32 v[72:73], v[38:39], v[70:71]
	v_pk_fma_f32 v[70:71], v[38:39], v[70:71], v[38:39] neg_lo:[1,0,0] neg_hi:[1,0,0]
	s_nop 0
	v_cndmask_b32_e64 v38, v70, v72, s[0:1]
	v_cmp_gt_f32_e64 s[0:1], 0, v39
	s_nop 1
	v_cndmask_b32_e64 v39, v71, v73, s[0:1]
	v_pk_mul_f32 v[38:39], v[190:191], v[38:39]
	s_nop 1
	v_cvt_pk_bf16_f32 v37, v38, v39
	v_lshl_add_u64 v[38:39], v[136:137], 1, s[26:27]
	global_store_dwordx2 v[38:39], v[36:37], off
	v_lshlrev_b32_e32 v36, 16, v80
	v_and_b32_e32 v37, 0xffff0000, v80
	v_lshlrev_b32_e32 v38, 16, v81
	v_and_b32_e32 v39, 0xffff0000, v81
	s_nop 1
	v_mov_b32_dpp v67, v36 row_ror:1 row_mask:0xf bank_mask:0xf
	v_mov_b32_dpp v68, v37 row_ror:1 row_mask:0xf bank_mask:0xf
	v_mov_b32_dpp v69, v38 row_ror:1 row_mask:0xf bank_mask:0xf
	v_mov_b32_dpp v72, v39 row_ror:1 row_mask:0xf bank_mask:0xf
	v_mov_b32_dpp v70, v36 row_ror:2 row_mask:0xf bank_mask:0xf
	v_mov_b32_dpp v73, v37 row_ror:2 row_mask:0xf bank_mask:0xf
	v_mov_b32_dpp v71, v38 row_ror:2 row_mask:0xf bank_mask:0xf
	v_mov_b32_dpp v74, v39 row_ror:2 row_mask:0xf bank_mask:0xf
	s_and_saveexec_b64 s[0:1], vcc
	s_cbranch_execz .LBB0_559
	v_add_u32_e32 v136, v150, v44
	v_lshl_add_u64 v[76:77], v[136:137], 2, s[28:29]
	global_store_dwordx4 v[76:77], v[36:39], off
.LBB0_559:
	s_or_b64 exec, exec, s[0:1]
	v_cndmask_b32_e64 v77, v62, v72, s[8:9]
	v_cndmask_b32_e64 v76, v42, v69, s[8:9]
	v_cndmask_b32_e64 v62, v43, v70, s[6:7]
	v_cndmask_b32_e64 v42, v50, v71, s[6:7]
	v_cndmask_b32_e64 v71, v180, v188, s[6:7]
	v_cndmask_b32_e64 v70, v179, v187, s[6:7]
	v_cndmask_b32_e64 v41, v41, v68, s[8:9]
	v_cndmask_b32_e64 v69, v177, v185, s[8:9]
	v_cndmask_b32_e64 v68, v82, v182, s[8:9]
	v_pk_fma_f32 v[10:11], v[10:11], v[70:71], v[14:15]
	v_cndmask_b32_e64 v63, v63, v73, s[6:7]
	v_pk_fma_f32 v[2:3], v[2:3], v[68:69], v[10:11]
	v_cndmask_b32_e64 v40, v40, v67, s[8:9]
	v_pk_fma_f32 v[2:3], v[6:7], v[18:19], v[2:3]
	v_pk_fma_f32 v[6:7], v[28:29], v[62:63], v[32:33]
	v_cndmask_b32_e64 v73, v178, v186, s[6:7]
	v_pk_fma_f32 v[6:7], v[20:21], v[40:41], v[6:7]
	v_cndmask_b32_e64 v72, v83, v183, s[6:7]
	v_pk_fma_f32 v[6:7], v[24:25], v[36:37], v[6:7]
	v_pk_fma_f32 v[8:9], v[8:9], v[72:73], v[12:13]
	v_and_b32_e32 v13, 0x7fffffff, v7
	v_and_b32_e32 v12, 0x7fffffff, v6
	v_pk_fma_f32 v[12:13], v[12:13], s[42:43], 1.0 op_sel_hi:[1,0,0]
	v_cndmask_b32_e64 v43, v66, v74, s[6:7]
	v_rcp_f32_e32 v12, v12
	v_rcp_f32_e32 v13, v13
	v_cndmask_b32_e64 v67, v87, v184, s[8:9]
	v_cndmask_b32_e64 v66, v79, v181, s[8:9]
	v_pk_fma_f32 v[0:1], v[0:1], v[66:67], v[8:9]
	v_pk_mul_f32 v[10:11], v[6:7], v[6:7]
	v_mov_b64_e32 v[14:15], s[54:55]
	v_pk_fma_f32 v[0:1], v[4:5], v[16:17], v[0:1]
	v_pk_mul_f32 v[10:11], v[10:11], s[38:39] op_sel_hi:[1,0]
	v_pk_fma_f32 v[16:17], v[12:13], s[52:53], v[14:15] op_sel_hi:[1,0,0]
; __device__ __forceinline__ f32x2 gelu_pk(f32x2 v) {
;     __device__ __forceinline__ void operator()(AccRef acc, const Unit& u, int wr, int wc, int fr, int fq) const {
;     ...
;             for (int n = 0; n < 2; ++n) { const unsigned jn = (unsigned)(j0 + 4 * n);
;                 f32x4 cu[4];
;                 {
;                     const f32x4 wu0 = *(const f32x4*)(cw + (DFF + jn)), wu1 = *(const f32x4*)(cw + (UPN + DFF + jn)), wu2 = *(const f32x4*)(cw + (2 * UPN + DFF + jn)), bu = *(const f32x4*)(cb + (DFF + jn));
;                     f32x4 pu1 = (f32x4){0.f, 0.f, 0.f, 0.f}, pu2 = pu1;
; #pragma unroll
;                     for (int m = 0; m < 4; ++m) {
;                         const f32x4 au = unpack4(pa[ai][1][m][n]);
;                         const f32x4 ru1 = ror1v(au), ru2 = ror2v(au);
;                         const f32x4 u1 = fr >= 1 ? ru1 : pu1, u2 = fr >= 2 ? ru2 : pu2;
;                         if (m == 0 && fr < 2) *(f32x4*)(edge + (unsigned)((grp * 4 + fr) * UPN + DFF + jn)) = au;
;                         if (m == 3 && fr >= 14) *(f32x4*)(edge + (unsigned)((grp * 4 + (fr - 12)) * UPN + DFF + jn)) = au;
;                         cu[m] = bu + wu0 * u2 + wu1 * u1 + wu2 * au;
;                         pu1 = ru1; pu2 = ru2; }
;                 }
;                 {
;                     const f32x4 wg0 = *(const f32x4*)(cw + jn), wg1 = *(const f32x4*)(cw + (UPN + jn)), wg2 = *(const f32x4*)(cw + (2 * UPN + jn)), bg = *(const f32x4*)(cb + jn);
;                     f32x4 pg1 = (f32x4){0.f, 0.f, 0.f, 0.f}, pg2 = pg1;
; #pragma unroll
;                     for (int m = 0; m < 4; ++m) { const int row = rowg + m * 16 + fr;
;                         const f32x4 ag = unpack4(pa[ai][0][m][n]);
;                         const f32x4 rg1 = ror1v(ag), rg2 = ror2v(ag);
;                         const f32x4 g1 = fr >= 1 ? rg1 : pg1, g2 = fr >= 2 ? rg2 : pg2;
;                         if (m == 0 && fr < 2) *(f32x4*)(edge + (unsigned)((grp * 4 + fr) * UPN + jn)) = ag;
;                         if (m == 3 && fr >= 14) *(f32x4*)(edge + (unsigned)((grp * 4 + (fr - 12)) * UPN + jn)) = ag;
;                         const f32x4 o = gelu4(bg + wg0 * g2 + wg1 * g1 + wg2 * ag) * cu[m];
;                         if (!(m == 0 && fr < 2)) *(u32x2*)(act + (unsigned)(row * DFF + jn)) = pack4(o);
;                         pg1 = rg1; pg2 = rg2; }
	v_exp_f32_e32 v10, v10
	v_exp_f32_e32 v11, v11
	v_pk_fma_f32 v[16:17], v[12:13], v[16:17], s[56:57] op_sel_hi:[1,1,0]
	v_pk_fma_f32 v[4:5], v[30:31], v[42:43], v[34:35]
	v_pk_fma_f32 v[16:17], v[12:13], v[16:17], s[62:63] op_sel_hi:[1,1,0]
	v_pk_fma_f32 v[4:5], v[22:23], v[76:77], v[4:5]
	v_pk_fma_f32 v[16:17], v[12:13], v[16:17], s[64:65] op_sel_hi:[1,1,0]
	v_cmp_gt_f32_e64 s[0:1], 0, v6
	v_pk_mul_f32 v[12:13], v[12:13], v[16:17]
	v_pk_fma_f32 v[4:5], v[26:27], v[38:39], v[4:5]
	v_pk_mul_f32 v[10:11], v[10:11], v[12:13]
	v_pk_mul_f32 v[8:9], v[4:5], v[4:5]
	v_pk_mul_f32 v[12:13], v[6:7], v[10:11]
	v_pk_fma_f32 v[10:11], v[6:7], v[10:11], v[6:7] neg_lo:[1,0,0] neg_hi:[1,0,0]
	v_pk_mul_f32 v[8:9], v[8:9], s[38:39] op_sel_hi:[1,0]
	v_cndmask_b32_e64 v6, v10, v12, s[0:1]
	v_cmp_gt_f32_e64 s[0:1], 0, v7
	v_and_b32_e32 v10, 0x7fffffff, v4
	v_exp_f32_e32 v8, v8
	v_cndmask_b32_e64 v7, v11, v13, s[0:1]
	v_and_b32_e32 v11, 0x7fffffff, v5
	v_pk_fma_f32 v[10:11], v[10:11], s[42:43], 1.0 op_sel_hi:[1,0,0]
	v_exp_f32_e32 v9, v9
	v_rcp_f32_e32 v10, v10
	v_rcp_f32_e32 v11, v11
	v_cmp_gt_f32_e64 s[0:1], 0, v4
	v_add_u32_e32 v148, 0xb000, v51
	v_pk_mul_f32 v[0:1], v[0:1], v[6:7]
	v_pk_fma_f32 v[12:13], v[10:11], s[52:53], v[14:15] op_sel_hi:[1,0,0]
	v_add_u32_e32 v136, v148, v44
	v_pk_fma_f32 v[12:13], v[10:11], v[12:13], s[56:57] op_sel_hi:[1,1,0]
	v_cvt_pk_bf16_f32 v0, v0, v1
	v_lshlrev_b32_e32 v36, 16, v170
	v_pk_fma_f32 v[12:13], v[10:11], v[12:13], s[62:63] op_sel_hi:[1,1,0]
	v_and_b32_e32 v37, 0xffff0000, v170
	v_pk_fma_f32 v[12:13], v[10:11], v[12:13], s[64:65] op_sel_hi:[1,1,0]
	v_lshlrev_b32_e32 v38, 16, v171
	v_pk_mul_f32 v[10:11], v[10:11], v[12:13]
	v_and_b32_e32 v39, 0xffff0000, v171
	v_pk_mul_f32 v[8:9], v[8:9], v[10:11]
	s_nop 1
	v_pk_mul_f32 v[10:11], v[4:5], v[8:9]
	v_pk_fma_f32 v[8:9], v[4:5], v[8:9], v[4:5] neg_lo:[1,0,0] neg_hi:[1,0,0]
	s_nop 1
	v_cndmask_b32_e64 v4, v8, v10, s[0:1]
	v_cmp_gt_f32_e64 s[0:1], 0, v5
	s_nop 1
	v_cndmask_b32_e64 v5, v9, v11, s[0:1]
	v_pk_mul_f32 v[2:3], v[2:3], v[4:5]
	s_nop 1
	v_cvt_pk_bf16_f32 v1, v2, v3
	v_lshl_add_u64 v[2:3], v[136:137], 1, s[26:27]
	v_add_u32_e32 v136, 0xb04, v44
	v_lshlrev_b64 v[12:13], 2, v[136:137]
	v_add_u32_e32 v136, 0x2104, v44
	v_lshl_add_u64 v[66:67], v[136:137], 2, s[66:67]
	v_add_u32_e32 v136, 0x3704, v44
	global_store_dwordx2 v[2:3], v[0:1], off
	v_lshl_add_u64 v[62:63], s[66:67], 0, v[12:13]
	v_lshl_add_u64 v[68:69], v[136:137], 2, s[66:67]
	v_lshl_add_u64 v[70:71], s[36:37], 0, v[12:13]
	global_load_dwordx4 v[8:11], v[62:63], off
	global_load_dwordx4 v[0:3], v[66:67], off
	global_load_dwordx4 v[4:7], v[68:69], off
	global_load_dwordx4 v[12:15], v[70:71], off
	s_nop 1
	v_or_b32_e32 v50, 4, v44
	v_mov_b32_dpp v188, v36 row_ror:1 row_mask:0xf bank_mask:0xf
	v_mov_b32_dpp v194, v37 row_ror:1 row_mask:0xf bank_mask:0xf
	v_mov_b32_dpp v191, v38 row_ror:1 row_mask:0xf bank_mask:0xf
	v_mov_b32_dpp v197, v39 row_ror:1 row_mask:0xf bank_mask:0xf
	v_mov_b32_dpp v192, v36 row_ror:2 row_mask:0xf bank_mask:0xf
	v_mov_b32_dpp v198, v37 row_ror:2 row_mask:0xf bank_mask:0xf
	v_mov_b32_dpp v200, v38 row_ror:2 row_mask:0xf bank_mask:0xf
	v_mov_b32_dpp v202, v39 row_ror:2 row_mask:0xf bank_mask:0xf
	s_and_saveexec_b64 s[0:1], s[12:13]
	s_cbranch_execz .LBB0_561
	v_add_u32_e32 v136, v50, v78
	v_lshl_add_u64 v[16:17], v[136:137], 2, s[28:29]
	global_store_dwordx4 v[16:17], v[36:39], off
.LBB0_561:
	s_or_b64 exec, exec, s[0:1]
	v_lshlrev_b32_e32 v82, 16, v89
	v_and_b32_e32 v83, 0xffff0000, v89
	v_lshlrev_b32_e32 v80, 16, v88
	v_and_b32_e32 v81, 0xffff0000, v88
	s_nop 1
	v_lshlrev_b32_e32 v78, 16, v90
	v_and_b32_e32 v79, 0xffff0000, v90
	v_lshlrev_b32_e32 v76, 16, v91
	v_and_b32_e32 v77, 0xffff0000, v91
	s_nop 1
	v_lshlrev_b32_e32 v16, 16, v84
	v_and_b32_e32 v17, 0xffff0000, v84
	v_lshlrev_b32_e32 v18, 16, v85
	v_and_b32_e32 v19, 0xffff0000, v85
	s_nop 1
	v_mov_b32_dpp v187, v82 row_ror:1 row_mask:0xf bank_mask:0xf
	v_mov_b32_dpp v193, v83 row_ror:1 row_mask:0xf bank_mask:0xf
	v_mov_b32_dpp v189, v80 row_ror:1 row_mask:0xf bank_mask:0xf
	v_mov_b32_dpp v195, v81 row_ror:1 row_mask:0xf bank_mask:0xf
	v_mov_b32_dpp v190, v82 row_ror:2 row_mask:0xf bank_mask:0xf
	v_mov_b32_dpp v196, v83 row_ror:2 row_mask:0xf bank_mask:0xf
	v_mov_b32_dpp v199, v80 row_ror:2 row_mask:0xf bank_mask:0xf
	v_mov_b32_dpp v201, v81 row_ror:2 row_mask:0xf bank_mask:0xf
	v_mov_b32_dpp v170, v78 row_ror:1 row_mask:0xf bank_mask:0xf
	v_mov_b32_dpp v173, v79 row_ror:1 row_mask:0xf bank_mask:0xf
	v_mov_b32_dpp v171, v76 row_ror:1 row_mask:0xf bank_mask:0xf
	v_mov_b32_dpp v174, v77 row_ror:1 row_mask:0xf bank_mask:0xf
	v_mov_b32_dpp v172, v78 row_ror:2 row_mask:0xf bank_mask:0xf
	v_mov_b32_dpp v175, v79 row_ror:2 row_mask:0xf bank_mask:0xf
	v_mov_b32_dpp v177, v76 row_ror:2 row_mask:0xf bank_mask:0xf
	v_mov_b32_dpp v178, v77 row_ror:2 row_mask:0xf bank_mask:0xf
	v_mov_b32_dpp v179, v16 row_ror:1 row_mask:0xf bank_mask:0xf
	v_mov_b32_dpp v182, v17 row_ror:1 row_mask:0xf bank_mask:0xf
	v_mov_b32_dpp v180, v18 row_ror:1 row_mask:0xf bank_mask:0xf
	v_mov_b32_dpp v183, v19 row_ror:1 row_mask:0xf bank_mask:0xf
	v_mov_b32_dpp v181, v16 row_ror:2 row_mask:0xf bank_mask:0xf
	v_mov_b32_dpp v184, v17 row_ror:2 row_mask:0xf bank_mask:0xf
	v_mov_b32_dpp v185, v18 row_ror:2 row_mask:0xf bank_mask:0xf
	v_mov_b32_dpp v186, v19 row_ror:2 row_mask:0xf bank_mask:0xf
	s_and_saveexec_b64 s[0:1], vcc
	s_cbranch_execz .LBB0_563
	v_add_u32_e32 v136, v86, v50
	v_lshl_add_u64 v[20:21], v[136:137], 2, s[28:29]
	global_store_dwordx4 v[20:21], v[16:19], off
; __device__ __forceinline__ f32x2 gelu_pk(f32x2 v) {
;     const f32x2 av = __builtin_elementwise_abs(v), d = av * 0.2316418882f + 1.0f;
;     f32x2 t; t.x = __builtin_amdgcn_rcpf(d.x); t.y = __builtin_amdgcn_rcpf(d.y);
;     __device__ __forceinline__ void operator()(AccRef acc, const Unit& u, int wr, int wc, int fr, int fq) const {
;     ...
;                     const f32x4 wu0 = *(const f32x4*)(cw + (DFF + jn)), wu1 = *(const f32x4*)(cw + (UPN + DFF + jn)), wu2 = *(const f32x4*)(cw + (2 * UPN + DFF + jn)), bu = *(const f32x4*)(cb + (DFF + jn));
;                     f32x4 pu1 = (f32x4){0.f, 0.f, 0.f, 0.f}, pu2 = pu1;
; #pragma unroll
;                     for (int m = 0; m < 4; ++m) {
;                         const f32x4 au = unpack4(pa[ai][1][m][n]);
;                         const f32x4 ru1 = ror1v(au), ru2 = ror2v(au);
;                         const f32x4 u1 = fr >= 1 ? ru1 : pu1, u2 = fr >= 2 ? ru2 : pu2;
;                         if (m == 0 && fr < 2) *(f32x4*)(edge + (unsigned)((grp * 4 + fr) * UPN + DFF + jn)) = au;
;                         if (m == 3 && fr >= 14) *(f32x4*)(edge + (unsigned)((grp * 4 + (fr - 12)) * UPN + DFF + jn)) = au;
;                         cu[m] = bu + wu0 * u2 + wu1 * u1 + wu2 * au;
;                         pu1 = ru1; pu2 = ru2; }
;                 }
;                 {
;                     const f32x4 wg0 = *(const f32x4*)(cw + jn), wg1 = *(const f32x4*)(cw + (UPN + jn)), wg2 = *(const f32x4*)(cw + (2 * UPN + jn)), bg = *(const f32x4*)(cb + jn);
;                     f32x4 pg1 = (f32x4){0.f, 0.f, 0.f, 0.f}, pg2 = pg1;
; #pragma unroll
;                     for (int m = 0; m < 4; ++m) { const int row = rowg + m * 16 + fr;
;                         const f32x4 ag = unpack4(pa[ai][0][m][n]);
;                         const f32x4 rg1 = ror1v(ag), rg2 = ror2v(ag);
;                         const f32x4 g1 = fr >= 1 ? rg1 : pg1, g2 = fr >= 2 ? rg2 : pg2;
;                         if (m == 0 && fr < 2) *(f32x4*)(edge + (unsigned)((grp * 4 + fr) * UPN + jn)) = ag;
;                         if (m == 3 && fr >= 14) *(f32x4*)(edge + (unsigned)((grp * 4 + (fr - 12)) * UPN + jn)) = ag;
;                         const f32x4 o = gelu4(bg + wg0 * g2 + wg1 * g1 + wg2 * ag) * cu[m];
;                         if (!(m == 0 && fr < 2)) *(u32x2*)(act + (unsigned)(row * DFF + jn)) = pack4(o);
;                         pg1 = rg1; pg2 = rg2; }
.LBB0_563:
	s_or_b64 exec, exec, s[0:1]
	v_add_u32_e32 v136, 0x1604, v44
	v_lshl_add_u64 v[72:73], v[136:137], 2, s[66:67]
	v_add_u32_e32 v136, 0x2c04, v44
	global_load_dwordx4 v[20:23], v[46:47], off offset:16
	v_lshl_add_u64 v[74:75], v[136:137], 2, s[66:67]
	global_load_dwordx4 v[28:31], v[72:73], off
	global_load_dwordx4 v[24:27], v[74:75], off
	global_load_dwordx4 v[32:35], v[48:49], off offset:16
	v_lshlrev_b32_e32 v40, 16, v169
	v_and_b32_e32 v41, 0xffff0000, v169
	v_lshlrev_b32_e32 v42, 16, v168
	v_and_b32_e32 v43, 0xffff0000, v168
	s_nop 1
	v_mov_b32_dpp v84, v40 row_ror:1 row_mask:0xf bank_mask:0xf
	v_mov_b32_dpp v85, v41 row_ror:1 row_mask:0xf bank_mask:0xf
	v_mov_b32_dpp v86, v42 row_ror:1 row_mask:0xf bank_mask:0xf
	v_mov_b32_dpp v87, v43 row_ror:1 row_mask:0xf bank_mask:0xf
	v_mov_b32_dpp v88, v40 row_ror:2 row_mask:0xf bank_mask:0xf
	v_mov_b32_dpp v89, v41 row_ror:2 row_mask:0xf bank_mask:0xf
	v_mov_b32_dpp v90, v42 row_ror:2 row_mask:0xf bank_mask:0xf
	v_mov_b32_dpp v91, v43 row_ror:2 row_mask:0xf bank_mask:0xf
	s_and_saveexec_b64 s[0:1], s[10:11]
	s_xor_b64 s[76:77], exec, s[0:1]
	s_cbranch_execz .LBB0_565
	v_cndmask_b32_e64 v207, 0, v202, s[6:7]
	v_cndmask_b32_e64 v206, 0, v200, s[6:7]
	v_cndmask_b32_e64 v205, 0, v197, s[8:9]
	v_cndmask_b32_e64 v204, 0, v191, s[8:9]
	s_waitcnt vmcnt(4)
	v_pk_fma_f32 v[206:207], v[10:11], v[206:207], v[14:15]
	v_cndmask_b32_e64 v209, 0, v198, s[6:7]
	v_pk_fma_f32 v[204:205], v[2:3], v[204:205], v[206:207]
	v_cndmask_b32_e64 v208, 0, v192, s[6:7]
	v_pk_fma_f32 v[38:39], v[6:7], v[38:39], v[204:205]
	s_waitcnt vmcnt(0)
	v_pk_fma_f32 v[204:205], v[20:21], v[88:89], v[32:33]
	v_cndmask_b32_e64 v169, 0, v194, s[8:9]
	v_pk_fma_f32 v[204:205], v[28:29], v[84:85], v[204:205]
	v_cndmask_b32_e64 v168, 0, v188, s[8:9]
	v_pk_fma_f32 v[40:41], v[24:25], v[40:41], v[204:205]
	v_pk_fma_f32 v[208:209], v[8:9], v[208:209], v[12:13]
	v_and_b32_e32 v207, 0x7fffffff, v41
	v_and_b32_e32 v206, 0x7fffffff, v40
	v_pk_fma_f32 v[206:207], v[206:207], s[42:43], 1.0 op_sel_hi:[1,0,0]
	v_pk_fma_f32 v[168:169], v[0:1], v[168:169], v[208:209]
	v_rcp_f32_e32 v206, v206
	v_rcp_f32_e32 v207, v207
	v_pk_mul_f32 v[204:205], v[40:41], v[40:41]
	v_mov_b64_e32 v[208:209], s[54:55]
	v_pk_mul_f32 v[204:205], v[204:205], s[38:39] op_sel_hi:[1,0]
	v_pk_fma_f32 v[210:211], v[206:207], s[52:53], v[208:209] op_sel_hi:[1,0,0]
	v_exp_f32_e32 v204, v204
	v_exp_f32_e32 v205, v205
	v_pk_fma_f32 v[210:211], v[206:207], v[210:211], s[56:57] op_sel_hi:[1,1,0]
	v_pk_fma_f32 v[36:37], v[4:5], v[36:37], v[168:169]
	v_pk_fma_f32 v[210:211], v[206:207], v[210:211], s[62:63] op_sel_hi:[1,1,0]
	v_pk_fma_f32 v[168:169], v[22:23], v[90:91], v[34:35]
	v_pk_fma_f32 v[210:211], v[206:207], v[210:211], s[64:65] op_sel_hi:[1,1,0]
	v_pk_fma_f32 v[168:169], v[30:31], v[86:87], v[168:169]
	v_pk_mul_f32 v[206:207], v[206:207], v[210:211]
	v_cmp_gt_f32_e64 s[0:1], 0, v40
	v_pk_mul_f32 v[204:205], v[204:205], v[206:207]
	v_pk_fma_f32 v[42:43], v[26:27], v[42:43], v[168:169]
	v_pk_mul_f32 v[206:207], v[40:41], v[204:205]
	v_pk_fma_f32 v[204:205], v[40:41], v[204:205], v[40:41] neg_lo:[1,0,0] neg_hi:[1,0,0]
	v_pk_mul_f32 v[168:169], v[42:43], v[42:43]
	v_cndmask_b32_e64 v40, v204, v206, s[0:1]
	v_cmp_gt_f32_e64 s[0:1], 0, v41
	v_and_b32_e32 v204, 0x7fffffff, v42
	v_pk_mul_f32 v[168:169], v[168:169], s[38:39] op_sel_hi:[1,0]
	v_cndmask_b32_e64 v41, v205, v207, s[0:1]
	v_and_b32_e32 v205, 0x7fffffff, v43
	v_pk_fma_f32 v[204:205], v[204:205], s[42:43], 1.0 op_sel_hi:[1,0,0]
	v_exp_f32_e32 v168, v168
	v_rcp_f32_e32 v204, v204
	v_rcp_f32_e32 v205, v205
	v_exp_f32_e32 v169, v169
	v_cmp_gt_f32_e64 s[0:1], 0, v42
	v_pk_mul_f32 v[36:37], v[36:37], v[40:41]
	v_pk_fma_f32 v[206:207], v[204:205], s[52:53], v[208:209] op_sel_hi:[1,0,0]
	v_cvt_pk_bf16_f32 v36, v36, v37
	s_nop 0
	v_pk_fma_f32 v[206:207], v[204:205], v[206:207], s[56:57] op_sel_hi:[1,1,0]
	s_nop 0
	v_pk_fma_f32 v[206:207], v[204:205], v[206:207], s[62:63] op_sel_hi:[1,1,0]
	s_nop 0
	v_pk_fma_f32 v[206:207], v[204:205], v[206:207], s[64:65] op_sel_hi:[1,1,0]
	s_nop 0
	v_pk_mul_f32 v[204:205], v[204:205], v[206:207]
	s_nop 0
	v_pk_mul_f32 v[168:169], v[168:169], v[204:205]
	s_nop 0
	v_pk_mul_f32 v[204:205], v[42:43], v[168:169]
	v_pk_fma_f32 v[168:169], v[42:43], v[168:169], v[42:43] neg_lo:[1,0,0] neg_hi:[1,0,0]
	s_nop 0
	v_cndmask_b32_e64 v42, v168, v204, s[0:1]
	v_cmp_gt_f32_e64 s[0:1], 0, v43
	s_nop 1
	v_cndmask_b32_e64 v43, v169, v205, s[0:1]
	v_pk_mul_f32 v[38:39], v[38:39], v[42:43]
	s_nop 0
	v_cvt_pk_bf16_f32 v37, v38, v39
	v_mad_u64_u32 v[38:39], s[0:1], v146, s88, v[50:51]
	v_mov_b32_e32 v39, v137
	v_lshl_add_u64 v[38:39], v[38:39], 1, s[26:27]
	global_store_dwordx2 v[38:39], v[36:37], off

; __device__ __forceinline__ f32x2 gelu_pk(f32x2 v) {
;     __device__ __forceinline__ void operator()(AccRef acc, const Unit& u, int wr, int wc, int fr, int fq) const {
;     ...
;             for (int n = 0; n < 2; ++n) { const unsigned jn = (unsigned)(j0 + 4 * n);
;                 f32x4 cu[4];
;                 {
;                     const f32x4 wu0 = *(const f32x4*)(cw + (DFF + jn)), wu1 = *(const f32x4*)(cw + (UPN + DFF + jn)), wu2 = *(const f32x4*)(cw + (2 * UPN + DFF + jn)), bu = *(const f32x4*)(cb + (DFF + jn));
;                     f32x4 pu1 = (f32x4){0.f, 0.f, 0.f, 0.f}, pu2 = pu1;
; #pragma unroll
;                     for (int m = 0; m < 4; ++m) {
;                         const f32x4 au = unpack4(pa[ai][1][m][n]);
;                         const f32x4 ru1 = ror1v(au), ru2 = ror2v(au);
;                         const f32x4 u1 = fr >= 1 ? ru1 : pu1, u2 = fr >= 2 ? ru2 : pu2;
;                         if (m == 0 && fr < 2) *(f32x4*)(edge + (unsigned)((grp * 4 + fr) * UPN + DFF + jn)) = au;
;                         if (m == 3 && fr >= 14) *(f32x4*)(edge + (unsigned)((grp * 4 + (fr - 12)) * UPN + DFF + jn)) = au;
;                         cu[m] = bu + wu0 * u2 + wu1 * u1 + wu2 * au;
;                         pu1 = ru1; pu2 = ru2; }
;                 }
;                 {
;                     const f32x4 wg0 = *(const f32x4*)(cw + jn), wg1 = *(const f32x4*)(cw + (UPN + jn)), wg2 = *(const f32x4*)(cw + (2 * UPN + jn)), bg = *(const f32x4*)(cb + jn);
;                     f32x4 pg1 = (f32x4){0.f, 0.f, 0.f, 0.f}, pg2 = pg1;
; #pragma unroll
;                     for (int m = 0; m < 4; ++m) { const int row = rowg + m * 16 + fr;
;                         const f32x4 ag = unpack4(pa[ai][0][m][n]);
;                         const f32x4 rg1 = ror1v(ag), rg2 = ror2v(ag);
;                         const f32x4 g1 = fr >= 1 ? rg1 : pg1, g2 = fr >= 2 ? rg2 : pg2;
;                         if (m == 0 && fr < 2) *(f32x4*)(edge + (unsigned)((grp * 4 + fr) * UPN + jn)) = ag;
;                         if (m == 3 && fr >= 14) *(f32x4*)(edge + (unsigned)((grp * 4 + (fr - 12)) * UPN + jn)) = ag;
;                         const f32x4 o = gelu4(bg + wg0 * g2 + wg1 * g1 + wg2 * ag) * cu[m];
;                         if (!(m == 0 && fr < 2)) *(u32x2*)(act + (unsigned)(row * DFF + jn)) = pack4(o);
;                         pg1 = rg1; pg2 = rg2; }
.LBB0_567:
	s_or_b64 exec, exec, s[0:1]
	s_nop 0
	v_cndmask_b32_e64 v41, v202, v201, s[6:7]
	v_cndmask_b32_e64 v40, v200, v199, s[6:7]
	v_cndmask_b32_e64 v43, v198, v196, s[6:7]
	v_cndmask_b32_e64 v42, v192, v190, s[6:7]
	v_cndmask_b32_e64 v37, v194, v193, s[8:9]
	v_cndmask_b32_e64 v36, v188, v187, s[8:9]
	v_cndmask_b32_e64 v39, v197, v195, s[8:9]
	v_cndmask_b32_e64 v38, v191, v189, s[8:9]
	s_waitcnt vmcnt(4)
	v_pk_fma_f32 v[42:43], v[8:9], v[42:43], v[12:13]
	v_pk_fma_f32 v[40:41], v[10:11], v[40:41], v[14:15]
	v_pk_fma_f32 v[36:37], v[0:1], v[36:37], v[42:43]
	v_pk_fma_f32 v[38:39], v[2:3], v[38:39], v[40:41]
	v_pk_fma_f32 v[36:37], v[4:5], v[82:83], v[36:37]
	v_pk_fma_f32 v[38:39], v[6:7], v[80:81], v[38:39]
	v_cndmask_b32_e64 v81, v201, v178, s[6:7]
	v_cndmask_b32_e64 v80, v199, v177, s[6:7]
	v_cndmask_b32_e64 v83, v196, v175, s[6:7]
	v_cndmask_b32_e64 v82, v190, v172, s[6:7]
	v_cndmask_b32_e64 v41, v193, v173, s[8:9]
	v_cndmask_b32_e64 v40, v187, v170, s[8:9]
	v_cndmask_b32_e64 v43, v195, v174, s[8:9]
	v_cndmask_b32_e64 v42, v189, v171, s[8:9]
	v_pk_fma_f32 v[82:83], v[8:9], v[82:83], v[12:13]
	v_pk_fma_f32 v[80:81], v[10:11], v[80:81], v[14:15]
	v_pk_fma_f32 v[40:41], v[0:1], v[40:41], v[82:83]
	v_pk_fma_f32 v[42:43], v[2:3], v[42:43], v[80:81]
	v_pk_fma_f32 v[80:81], v[4:5], v[78:79], v[40:41]
	v_pk_fma_f32 v[82:83], v[6:7], v[76:77], v[42:43]
	v_lshlrev_b32_e32 v40, 16, v167
	v_and_b32_e32 v41, 0xffff0000, v167
	v_lshlrev_b32_e32 v42, 16, v149
	v_and_b32_e32 v43, 0xffff0000, v149
	v_mov_b32_e32 v146, v137
	v_mov_b32_e32 v149, v137
	v_mov_b32_e32 v168, v137
	v_mov_b32_e32 v169, v137
	v_mov_b32_dpp v146, v40 row_ror:1 row_mask:0xf bank_mask:0xf
	v_mov_b32_dpp v149, v41 row_ror:1 row_mask:0xf bank_mask:0xf
	v_mov_b32_dpp v168, v40 row_ror:2 row_mask:0xf bank_mask:0xf
	v_mov_b32_dpp v169, v41 row_ror:2 row_mask:0xf bank_mask:0xf
	v_cndmask_b32_e64 v79, v85, v149, s[8:9]
	v_cndmask_b32_e64 v78, v84, v146, s[8:9]
	v_cndmask_b32_e64 v85, v89, v169, s[6:7]
	v_cndmask_b32_e64 v84, v88, v168, s[6:7]
	s_waitcnt vmcnt(0)
	v_pk_fma_f32 v[84:85], v[20:21], v[84:85], v[32:33]
	v_mov_b32_e32 v152, v137
	v_pk_fma_f32 v[78:79], v[28:29], v[78:79], v[84:85]
	v_mov_b32_e32 v167, v137
	v_pk_fma_f32 v[40:41], v[24:25], v[40:41], v[78:79]
	v_mov_b32_e32 v187, v137
	v_and_b32_e32 v85, 0x7fffffff, v41
	v_and_b32_e32 v84, 0x7fffffff, v40
	v_mov_b32_e32 v188, v137
	v_pk_fma_f32 v[84:85], v[84:85], s[42:43], 1.0 op_sel_hi:[1,0,0]
	v_mov_b32_dpp v152, v42 row_ror:1 row_mask:0xf bank_mask:0xf
	v_mov_b32_dpp v167, v43 row_ror:1 row_mask:0xf bank_mask:0xf
	v_mov_b32_dpp v187, v42 row_ror:2 row_mask:0xf bank_mask:0xf
	v_mov_b32_dpp v188, v43 row_ror:2 row_mask:0xf bank_mask:0xf
	v_rcp_f32_e32 v84, v84
	v_rcp_f32_e32 v85, v85
	v_cndmask_b32_e64 v77, v87, v167, s[8:9]
	v_cndmask_b32_e64 v76, v86, v152, s[8:9]
	v_cndmask_b32_e64 v87, v91, v188, s[6:7]
	v_cndmask_b32_e64 v86, v90, v187, s[6:7]
	v_pk_fma_f32 v[86:87], v[22:23], v[86:87], v[34:35]
	v_pk_mul_f32 v[78:79], v[40:41], v[40:41]
	v_pk_fma_f32 v[76:77], v[30:31], v[76:77], v[86:87]
	v_mov_b64_e32 v[86:87], s[54:55]
	v_pk_mul_f32 v[78:79], v[78:79], s[38:39] op_sel_hi:[1,0]
	v_pk_fma_f32 v[88:89], v[84:85], s[52:53], v[86:87] op_sel_hi:[1,0,0]
	v_exp_f32_e32 v78, v78
	v_exp_f32_e32 v79, v79
	v_pk_fma_f32 v[88:89], v[84:85], v[88:89], s[56:57] op_sel_hi:[1,1,0]
	v_cmp_gt_f32_e64 s[0:1], 0, v40
	v_pk_fma_f32 v[88:89], v[84:85], v[88:89], s[62:63] op_sel_hi:[1,1,0]
	v_pk_fma_f32 v[42:43], v[26:27], v[42:43], v[76:77]
	v_pk_fma_f32 v[88:89], v[84:85], v[88:89], s[64:65] op_sel_hi:[1,1,0]
	v_pk_mul_f32 v[76:77], v[42:43], v[42:43]
	v_pk_mul_f32 v[84:85], v[84:85], v[88:89]
	v_pk_mul_f32 v[76:77], v[76:77], s[38:39] op_sel_hi:[1,0]
	v_pk_mul_f32 v[78:79], v[78:79], v[84:85]
	v_exp_f32_e32 v76, v76
	v_pk_mul_f32 v[84:85], v[40:41], v[78:79]
	v_pk_fma_f32 v[78:79], v[40:41], v[78:79], v[40:41] neg_lo:[1,0,0] neg_hi:[1,0,0]
	v_exp_f32_e32 v77, v77
	v_cndmask_b32_e64 v40, v78, v84, s[0:1]
	v_cmp_gt_f32_e64 s[0:1], 0, v41
	v_and_b32_e32 v78, 0x7fffffff, v42
	v_add_u32_e32 v136, v45, v50
	v_cndmask_b32_e64 v41, v79, v85, s[0:1]
	v_and_b32_e32 v79, 0x7fffffff, v43
	v_pk_fma_f32 v[78:79], v[78:79], s[42:43], 1.0 op_sel_hi:[1,0,0]
	v_cmp_gt_f32_e64 s[0:1], 0, v42
	v_rcp_f32_e32 v78, v78
	v_rcp_f32_e32 v79, v79
	v_pk_mul_f32 v[36:37], v[36:37], v[40:41]
	s_nop 1
	v_cvt_pk_bf16_f32 v36, v36, v37
	v_pk_fma_f32 v[84:85], v[78:79], s[52:53], v[86:87] op_sel_hi:[1,0,0]
	s_nop 1
	v_pk_fma_f32 v[84:85], v[78:79], v[84:85], s[56:57] op_sel_hi:[1,1,0]
	s_nop 1
	v_pk_fma_f32 v[84:85], v[78:79], v[84:85], s[62:63] op_sel_hi:[1,1,0]
	s_nop 0
	v_pk_fma_f32 v[84:85], v[78:79], v[84:85], s[64:65] op_sel_hi:[1,1,0]
	s_nop 0
	v_pk_mul_f32 v[78:79], v[78:79], v[84:85]
	s_nop 0
	v_pk_mul_f32 v[76:77], v[76:77], v[78:79]
	s_nop 0
	v_pk_mul_f32 v[78:79], v[42:43], v[76:77]
	v_pk_fma_f32 v[76:77], v[42:43], v[76:77], v[42:43] neg_lo:[1,0,0] neg_hi:[1,0,0]
	s_nop 0
	v_cndmask_b32_e64 v42, v76, v78, s[0:1]
	v_cmp_gt_f32_e64 s[0:1], 0, v43
	s_nop 1
	v_cndmask_b32_e64 v43, v77, v79, s[0:1]
	v_pk_mul_f32 v[38:39], v[38:39], v[42:43]
	s_nop 1
	v_cvt_pk_bf16_f32 v37, v38, v39
	v_lshl_add_u64 v[38:39], v[136:137], 1, s[26:27]
	global_store_dwordx2 v[38:39], v[36:37], off
	v_lshlrev_b32_e32 v36, 16, v127
	v_and_b32_e32 v37, 0xffff0000, v127
	s_nop 1
	v_mov_b32_dpp v43, v36 row_ror:2 row_mask:0xf bank_mask:0xf
	v_mov_b32_dpp v40, v36 row_ror:1 row_mask:0xf bank_mask:0xf
	v_mov_b32_dpp v77, v37 row_ror:2 row_mask:0xf bank_mask:0xf
	v_mov_b32_dpp v41, v37 row_ror:1 row_mask:0xf bank_mask:0xf
	v_cndmask_b32_e64 v91, v169, v77, s[6:7]
	v_cndmask_b32_e64 v90, v168, v43, s[6:7]
; __device__ __forceinline__ f32x2 gelu_pk(f32x2 v) {
;     __device__ __forceinline__ void operator()(AccRef acc, const Unit& u, int wr, int wc, int fr, int fq) const {
;     ...
;             for (int n = 0; n < 2; ++n) { const unsigned jn = (unsigned)(j0 + 4 * n);
;                 f32x4 cu[4];
;                 {
;                     const f32x4 wu0 = *(const f32x4*)(cw + (DFF + jn)), wu1 = *(const f32x4*)(cw + (UPN + DFF + jn)), wu2 = *(const f32x4*)(cw + (2 * UPN + DFF + jn)), bu = *(const f32x4*)(cb + (DFF + jn));
;                     f32x4 pu1 = (f32x4){0.f, 0.f, 0.f, 0.f}, pu2 = pu1;
; #pragma unroll
;                     for (int m = 0; m < 4; ++m) {
;                         const f32x4 au = unpack4(pa[ai][1][m][n]);
;                         const f32x4 ru1 = ror1v(au), ru2 = ror2v(au);
;                         const f32x4 u1 = fr >= 1 ? ru1 : pu1, u2 = fr >= 2 ? ru2 : pu2;
;                         if (m == 0 && fr < 2) *(f32x4*)(edge + (unsigned)((grp * 4 + fr) * UPN + DFF + jn)) = au;
;                         if (m == 3 && fr >= 14) *(f32x4*)(edge + (unsigned)((grp * 4 + (fr - 12)) * UPN + DFF + jn)) = au;
;                         cu[m] = bu + wu0 * u2 + wu1 * u1 + wu2 * au;
;                         pu1 = ru1; pu2 = ru2; }
;                 }
;                 {
;                     const f32x4 wg0 = *(const f32x4*)(cw + jn), wg1 = *(const f32x4*)(cw + (UPN + jn)), wg2 = *(const f32x4*)(cw + (2 * UPN + jn)), bg = *(const f32x4*)(cb + jn);
;                     f32x4 pg1 = (f32x4){0.f, 0.f, 0.f, 0.f}, pg2 = pg1;
; #pragma unroll
;                     for (int m = 0; m < 4; ++m) { const int row = rowg + m * 16 + fr;
;                         const f32x4 ag = unpack4(pa[ai][0][m][n]);
;                         const f32x4 rg1 = ror1v(ag), rg2 = ror2v(ag);
;                         const f32x4 g1 = fr >= 1 ? rg1 : pg1, g2 = fr >= 2 ? rg2 : pg2;
;                         if (m == 0 && fr < 2) *(f32x4*)(edge + (unsigned)((grp * 4 + fr) * UPN + jn)) = ag;
;                         if (m == 3 && fr >= 14) *(f32x4*)(edge + (unsigned)((grp * 4 + (fr - 12)) * UPN + jn)) = ag;
;                         const f32x4 o = gelu4(bg + wg0 * g2 + wg1 * g1 + wg2 * ag) * cu[m];
;                         if (!(m == 0 && fr < 2)) *(u32x2*)(act + (unsigned)(row * DFF + jn)) = pack4(o);
;                         pg1 = rg1; pg2 = rg2; }
	v_cndmask_b32_e64 v89, v149, v41, s[8:9]
	v_cndmask_b32_e64 v88, v146, v40, s[8:9]
	v_pk_fma_f32 v[90:91], v[20:21], v[90:91], v[32:33]
	v_lshlrev_b32_e32 v38, 16, v147
	v_pk_fma_f32 v[88:89], v[28:29], v[88:89], v[90:91]
	v_and_b32_e32 v39, 0xffff0000, v147
	v_pk_fma_f32 v[36:37], v[24:25], v[36:37], v[88:89]
	s_nop 1
	v_and_b32_e32 v91, 0x7fffffff, v37
	v_and_b32_e32 v90, 0x7fffffff, v36
	v_pk_fma_f32 v[90:91], v[90:91], s[42:43], 1.0 op_sel_hi:[1,0,0]
	v_mov_b32_dpp v45, v38 row_ror:2 row_mask:0xf bank_mask:0xf
	v_rcp_f32_e32 v90, v90
	v_rcp_f32_e32 v91, v91
	v_mov_b32_dpp v78, v39 row_ror:2 row_mask:0xf bank_mask:0xf
	v_mov_b32_dpp v42, v38 row_ror:1 row_mask:0xf bank_mask:0xf
	v_mov_b32_dpp v76, v39 row_ror:1 row_mask:0xf bank_mask:0xf
	v_cndmask_b32_e64 v147, v188, v78, s[6:7]
	v_cndmask_b32_e64 v146, v187, v45, s[6:7]
	v_cndmask_b32_e64 v85, v167, v76, s[8:9]
	v_cndmask_b32_e64 v84, v152, v42, s[8:9]
	v_pk_fma_f32 v[146:147], v[22:23], v[146:147], v[34:35]
	v_pk_mul_f32 v[88:89], v[36:37], v[36:37]
	v_pk_fma_f32 v[84:85], v[30:31], v[84:85], v[146:147]
	v_pk_mul_f32 v[88:89], v[88:89], s[38:39] op_sel_hi:[1,0]
	v_pk_fma_f32 v[146:147], v[90:91], s[52:53], v[86:87] op_sel_hi:[1,0,0]
	v_exp_f32_e32 v88, v88
	v_exp_f32_e32 v89, v89
	v_pk_fma_f32 v[146:147], v[90:91], v[146:147], s[56:57] op_sel_hi:[1,1,0]
	v_cmp_gt_f32_e64 s[0:1], 0, v36
	v_pk_fma_f32 v[146:147], v[90:91], v[146:147], s[62:63] op_sel_hi:[1,1,0]
	v_pk_fma_f32 v[38:39], v[26:27], v[38:39], v[84:85]
	v_pk_fma_f32 v[146:147], v[90:91], v[146:147], s[64:65] op_sel_hi:[1,1,0]
	v_pk_mul_f32 v[84:85], v[38:39], v[38:39]
	v_pk_mul_f32 v[90:91], v[90:91], v[146:147]
	v_pk_mul_f32 v[84:85], v[84:85], s[38:39] op_sel_hi:[1,0]
	v_pk_mul_f32 v[88:89], v[88:89], v[90:91]
	v_exp_f32_e32 v84, v84
	v_pk_mul_f32 v[90:91], v[36:37], v[88:89]
	v_pk_fma_f32 v[88:89], v[36:37], v[88:89], v[36:37] neg_lo:[1,0,0] neg_hi:[1,0,0]
	v_exp_f32_e32 v85, v85
	v_cndmask_b32_e64 v36, v88, v90, s[0:1]
	v_cmp_gt_f32_e64 s[0:1], 0, v37
	v_and_b32_e32 v88, 0x7fffffff, v38
	v_add_u32_e32 v136, v51, v50
	v_cndmask_b32_e64 v37, v89, v91, s[0:1]
	v_and_b32_e32 v89, 0x7fffffff, v39
	v_pk_fma_f32 v[88:89], v[88:89], s[42:43], 1.0 op_sel_hi:[1,0,0]
	v_cmp_gt_f32_e64 s[0:1], 0, v38
	v_rcp_f32_e32 v88, v88
	v_rcp_f32_e32 v89, v89
	v_pk_mul_f32 v[36:37], v[80:81], v[36:37]
	s_nop 1
	v_cvt_pk_bf16_f32 v36, v36, v37
	v_pk_fma_f32 v[86:87], v[88:89], s[52:53], v[86:87] op_sel_hi:[1,0,0]
	s_nop 1
	v_pk_fma_f32 v[86:87], v[88:89], v[86:87], s[56:57] op_sel_hi:[1,1,0]
	s_nop 1
	v_pk_fma_f32 v[86:87], v[88:89], v[86:87], s[62:63] op_sel_hi:[1,1,0]
	s_nop 1
	v_pk_fma_f32 v[86:87], v[88:89], v[86:87], s[64:65] op_sel_hi:[1,1,0]
	s_nop 0
	v_pk_mul_f32 v[86:87], v[88:89], v[86:87]
	s_nop 0
	v_pk_mul_f32 v[84:85], v[84:85], v[86:87]
	s_nop 0
	v_pk_mul_f32 v[86:87], v[38:39], v[84:85]
	v_pk_fma_f32 v[84:85], v[38:39], v[84:85], v[38:39] neg_lo:[1,0,0] neg_hi:[1,0,0]
	s_nop 0
	v_cndmask_b32_e64 v38, v84, v86, s[0:1]
	v_cmp_gt_f32_e64 s[0:1], 0, v39
	s_nop 1
	s_nop 0
	v_cndmask_b32_e64 v39, v85, v87, s[0:1]
	v_pk_mul_f32 v[38:39], v[82:83], v[38:39]
	s_nop 1
	v_cvt_pk_bf16_f32 v37, v38, v39
	v_lshl_add_u64 v[38:39], v[136:137], 1, s[26:27]
	global_store_dwordx2 v[38:39], v[36:37], off
	v_lshlrev_b32_e32 v36, 16, v124
	v_and_b32_e32 v37, 0xffff0000, v124
	v_lshlrev_b32_e32 v38, 16, v125
	v_and_b32_e32 v39, 0xffff0000, v125
	s_nop 1
	v_mov_b32_dpp v51, v36 row_ror:1 row_mask:0xf bank_mask:0xf
	v_mov_b32_dpp v79, v37 row_ror:1 row_mask:0xf bank_mask:0xf
	v_mov_b32_dpp v80, v38 row_ror:1 row_mask:0xf bank_mask:0xf
	v_mov_b32_dpp v83, v39 row_ror:1 row_mask:0xf bank_mask:0xf
	v_mov_b32_dpp v81, v36 row_ror:2 row_mask:0xf bank_mask:0xf
	v_mov_b32_dpp v84, v37 row_ror:2 row_mask:0xf bank_mask:0xf
	v_mov_b32_dpp v82, v38 row_ror:2 row_mask:0xf bank_mask:0xf
	v_mov_b32_dpp v85, v39 row_ror:2 row_mask:0xf bank_mask:0xf
	s_and_saveexec_b64 s[0:1], vcc
	s_cbranch_execz .LBB0_569
	v_add_u32_e32 v136, v50, v150
	v_lshl_add_u64 v[86:87], v[136:137], 2, s[28:29]
	global_store_dwordx4 v[86:87], v[36:39], off
.LBB0_569:
	s_or_b64 exec, exec, s[0:1]
	v_cndmask_b32_e64 v87, v76, v83, s[8:9]
	v_cndmask_b32_e64 v86, v42, v80, s[8:9]
	v_cndmask_b32_e64 v42, v45, v82, s[6:7]
	v_cndmask_b32_e64 v83, v178, v186, s[6:7]
	v_cndmask_b32_e64 v82, v177, v185, s[6:7]
	v_cndmask_b32_e64 v76, v43, v81, s[6:7]
	v_cndmask_b32_e64 v81, v174, v183, s[8:9]
	v_cndmask_b32_e64 v80, v171, v180, s[8:9]
	v_pk_fma_f32 v[10:11], v[10:11], v[82:83], v[14:15]
	v_cndmask_b32_e64 v77, v77, v84, s[6:7]
	v_pk_fma_f32 v[2:3], v[2:3], v[80:81], v[10:11]
	v_cndmask_b32_e64 v41, v41, v79, s[8:9]
	v_cndmask_b32_e64 v40, v40, v51, s[8:9]
	v_pk_fma_f32 v[2:3], v[6:7], v[18:19], v[2:3]
	v_pk_fma_f32 v[6:7], v[20:21], v[76:77], v[32:33]
	v_cndmask_b32_e64 v43, v78, v85, s[6:7]
	v_pk_fma_f32 v[6:7], v[28:29], v[40:41], v[6:7]
	v_cndmask_b32_e64 v85, v175, v184, s[6:7]
	v_cndmask_b32_e64 v84, v172, v181, s[6:7]
	v_pk_fma_f32 v[6:7], v[24:25], v[36:37], v[6:7]
	v_pk_fma_f32 v[8:9], v[8:9], v[84:85], v[12:13]
	v_and_b32_e32 v13, 0x7fffffff, v7
	v_and_b32_e32 v12, 0x7fffffff, v6
	v_pk_fma_f32 v[12:13], v[12:13], s[42:43], 1.0 op_sel_hi:[1,0,0]
	v_cndmask_b32_e64 v79, v173, v182, s[8:9]
	v_rcp_f32_e32 v12, v12
	v_rcp_f32_e32 v13, v13
	v_cndmask_b32_e64 v78, v170, v179, s[8:9]
	v_pk_fma_f32 v[0:1], v[0:1], v[78:79], v[8:9]
	v_pk_mul_f32 v[10:11], v[6:7], v[6:7]
	v_mov_b64_e32 v[14:15], s[54:55]
	v_pk_fma_f32 v[0:1], v[4:5], v[16:17], v[0:1]
	v_pk_mul_f32 v[10:11], v[10:11], s[38:39] op_sel_hi:[1,0]
	v_pk_fma_f32 v[16:17], v[12:13], s[52:53], v[14:15] op_sel_hi:[1,0,0]
	v_exp_f32_e32 v10, v10
; __device__ __forceinline__ f32x2 gelu_pk(f32x2 v) {
;     __device__ __forceinline__ void operator()(AccRef acc, const Unit& u, int wr, int wc, int fr, int fq) const {
;     ...
;             for (int n = 0; n < 2; ++n) { const unsigned jn = (unsigned)(j0 + 4 * n);
;                 f32x4 cu[4];
;                 {
;                     const f32x4 wu0 = *(const f32x4*)(cw + (DFF + jn)), wu1 = *(const f32x4*)(cw + (UPN + DFF + jn)), wu2 = *(const f32x4*)(cw + (2 * UPN + DFF + jn)), bu = *(const f32x4*)(cb + (DFF + jn));
;                     f32x4 pu1 = (f32x4){0.f, 0.f, 0.f, 0.f}, pu2 = pu1;
; #pragma unroll
;                     for (int m = 0; m < 4; ++m) {
;                         const f32x4 au = unpack4(pa[ai][1][m][n]);
;                         const f32x4 ru1 = ror1v(au), ru2 = ror2v(au);
;                         const f32x4 u1 = fr >= 1 ? ru1 : pu1, u2 = fr >= 2 ? ru2 : pu2;
;                         if (m == 0 && fr < 2) *(f32x4*)(edge + (unsigned)((grp * 4 + fr) * UPN + DFF + jn)) = au;
;                         if (m == 3 && fr >= 14) *(f32x4*)(edge + (unsigned)((grp * 4 + (fr - 12)) * UPN + DFF + jn)) = au;
;                         cu[m] = bu + wu0 * u2 + wu1 * u1 + wu2 * au;
;                         pu1 = ru1; pu2 = ru2; }
;                 }
;                 {
;                     const f32x4 wg0 = *(const f32x4*)(cw + jn), wg1 = *(const f32x4*)(cw + (UPN + jn)), wg2 = *(const f32x4*)(cw + (2 * UPN + jn)), bg = *(const f32x4*)(cb + jn);
;                     f32x4 pg1 = (f32x4){0.f, 0.f, 0.f, 0.f}, pg2 = pg1;
; #pragma unroll
;                     for (int m = 0; m < 4; ++m) { const int row = rowg + m * 16 + fr;
;                         const f32x4 ag = unpack4(pa[ai][0][m][n]);
;                         const f32x4 rg1 = ror1v(ag), rg2 = ror2v(ag);
;                         const f32x4 g1 = fr >= 1 ? rg1 : pg1, g2 = fr >= 2 ? rg2 : pg2;
;                         if (m == 0 && fr < 2) *(f32x4*)(edge + (unsigned)((grp * 4 + fr) * UPN + jn)) = ag;
;                         if (m == 3 && fr >= 14) *(f32x4*)(edge + (unsigned)((grp * 4 + (fr - 12)) * UPN + jn)) = ag;
;                         const f32x4 o = gelu4(bg + wg0 * g2 + wg1 * g1 + wg2 * ag) * cu[m];
;                         if (!(m == 0 && fr < 2)) *(u32x2*)(act + (unsigned)(row * DFF + jn)) = pack4(o);
;                         pg1 = rg1; pg2 = rg2; }
	v_exp_f32_e32 v11, v11
	v_pk_fma_f32 v[16:17], v[12:13], v[16:17], s[56:57] op_sel_hi:[1,1,0]
	v_pk_fma_f32 v[4:5], v[22:23], v[42:43], v[34:35]
	v_pk_fma_f32 v[16:17], v[12:13], v[16:17], s[62:63] op_sel_hi:[1,1,0]
	v_pk_fma_f32 v[4:5], v[30:31], v[86:87], v[4:5]
	v_pk_fma_f32 v[16:17], v[12:13], v[16:17], s[64:65] op_sel_hi:[1,1,0]
	v_cmp_gt_f32_e64 s[0:1], 0, v6
	v_pk_mul_f32 v[12:13], v[12:13], v[16:17]
	v_pk_fma_f32 v[4:5], v[26:27], v[38:39], v[4:5]
	v_pk_mul_f32 v[10:11], v[10:11], v[12:13]
	v_pk_mul_f32 v[8:9], v[4:5], v[4:5]
	v_pk_mul_f32 v[12:13], v[6:7], v[10:11]
	v_pk_fma_f32 v[10:11], v[6:7], v[10:11], v[6:7] neg_lo:[1,0,0] neg_hi:[1,0,0]
	v_pk_mul_f32 v[8:9], v[8:9], s[38:39] op_sel_hi:[1,0]
	v_cndmask_b32_e64 v6, v10, v12, s[0:1]
	v_cmp_gt_f32_e64 s[0:1], 0, v7
	v_and_b32_e32 v10, 0x7fffffff, v4
	v_exp_f32_e32 v8, v8
	v_cndmask_b32_e64 v7, v11, v13, s[0:1]
	v_and_b32_e32 v11, 0x7fffffff, v5
	v_pk_fma_f32 v[10:11], v[10:11], s[42:43], 1.0 op_sel_hi:[1,0,0]
	v_exp_f32_e32 v9, v9
	v_rcp_f32_e32 v10, v10
	v_rcp_f32_e32 v11, v11
	v_cmp_gt_f32_e64 s[0:1], 0, v4
	v_pk_mul_f32 v[0:1], v[0:1], v[6:7]
	v_add_u32_e32 v136, v148, v50
	v_pk_fma_f32 v[12:13], v[10:11], s[52:53], v[14:15] op_sel_hi:[1,0,0]
	v_cvt_pk_bf16_f32 v0, v0, v1
	s_addk_i32 s69, 0x80
	v_pk_fma_f32 v[12:13], v[10:11], v[12:13], s[56:57] op_sel_hi:[1,1,0]
	s_ashr_i32 s71, s69, 4
	v_pk_fma_f32 v[12:13], v[10:11], v[12:13], s[62:63] op_sel_hi:[1,1,0]
	v_add_u32_e32 v16, s71, v166
	v_pk_fma_f32 v[12:13], v[10:11], v[12:13], s[64:65] op_sel_hi:[1,1,0]
	v_mul_lo_u32 v80, v16, s87
	v_pk_mul_f32 v[10:11], v[10:11], v[12:13]
	v_lshlrev_b32_e32 v36, 16, v116
	v_pk_mul_f32 v[8:9], v[8:9], v[10:11]
	v_and_b32_e32 v37, 0xffff0000, v116
	v_pk_mul_f32 v[10:11], v[4:5], v[8:9]
	v_pk_fma_f32 v[8:9], v[4:5], v[8:9], v[4:5] neg_lo:[1,0,0] neg_hi:[1,0,0]
	v_lshlrev_b32_e32 v38, 16, v117
	v_cndmask_b32_e64 v4, v8, v10, s[0:1]
	v_cmp_gt_f32_e64 s[0:1], 0, v5
	v_and_b32_e32 v39, 0xffff0000, v117
	s_nop 1
	v_cndmask_b32_e64 v5, v9, v11, s[0:1]
	v_pk_mul_f32 v[2:3], v[2:3], v[4:5]
	s_nop 1
	v_cvt_pk_bf16_f32 v1, v2, v3
	v_lshl_add_u64 v[2:3], v[136:137], 1, s[26:27]
	global_store_dwordx2 v[2:3], v[0:1], off
	global_load_dwordx4 v[8:11], v[52:53], off
	global_load_dwordx4 v[4:7], v[54:55], off
	s_nop 0
	global_load_dwordx4 v[0:3], v[56:57], off
	global_load_dwordx4 v[12:15], v[58:59], off
	s_nop 1
	v_add_u32_e32 v45, 0xb00, v80
	v_mov_b32_dpp v124, v36 row_ror:1 row_mask:0xf bank_mask:0xf
	v_mov_b32_dpp v146, v37 row_ror:1 row_mask:0xf bank_mask:0xf
	v_mov_b32_dpp v125, v38 row_ror:1 row_mask:0xf bank_mask:0xf
	v_mov_b32_dpp v149, v39 row_ror:1 row_mask:0xf bank_mask:0xf
	v_mov_b32_dpp v127, v36 row_ror:2 row_mask:0xf bank_mask:0xf
	v_mov_b32_dpp v150, v37 row_ror:2 row_mask:0xf bank_mask:0xf
	v_mov_b32_dpp v169, v38 row_ror:2 row_mask:0xf bank_mask:0xf
	v_mov_b32_dpp v171, v39 row_ror:2 row_mask:0xf bank_mask:0xf
	s_and_saveexec_b64 s[0:1], s[12:13]
	s_cbranch_execz .LBB0_571
	v_add_u32_e32 v136, v45, v44
	v_lshl_add_u64 v[16:17], v[136:137], 2, s[28:29]
	global_store_dwordx4 v[16:17], v[36:39], off
.LBB0_571:
	s_or_b64 exec, exec, s[0:1]
	v_add_u32_e32 v16, s71, v126
	v_mul_lo_u32 v51, v16, s87
	v_lshlrev_b32_e32 v58, 16, v118
	v_and_b32_e32 v59, 0xffff0000, v118
	v_lshlrev_b32_e32 v56, 16, v119
	v_and_b32_e32 v57, 0xffff0000, v119
	s_nop 1
	v_lshlrev_b32_e32 v54, 16, v120
	v_and_b32_e32 v55, 0xffff0000, v120
	v_lshlrev_b32_e32 v52, 16, v121
	v_and_b32_e32 v53, 0xffff0000, v121
	s_nop 1
	v_lshlrev_b32_e32 v16, 16, v122
	v_and_b32_e32 v17, 0xffff0000, v122
	v_lshlrev_b32_e32 v18, 16, v123
	v_and_b32_e32 v19, 0xffff0000, v123
	s_nop 1
	v_add_u32_e32 v81, 0xb00, v51
	v_mov_b32_dpp v126, v58 row_ror:1 row_mask:0xf bank_mask:0xf
	v_mov_b32_dpp v152, v59 row_ror:1 row_mask:0xf bank_mask:0xf
	v_mov_b32_dpp v147, v56 row_ror:1 row_mask:0xf bank_mask:0xf
	v_mov_b32_dpp v167, v57 row_ror:1 row_mask:0xf bank_mask:0xf
	v_mov_b32_dpp v148, v58 row_ror:2 row_mask:0xf bank_mask:0xf
	v_mov_b32_dpp v168, v59 row_ror:2 row_mask:0xf bank_mask:0xf
	v_mov_b32_dpp v170, v56 row_ror:2 row_mask:0xf bank_mask:0xf
	v_mov_b32_dpp v172, v57 row_ror:2 row_mask:0xf bank_mask:0xf
	v_mov_b32_dpp v83, v54 row_ror:1 row_mask:0xf bank_mask:0xf
	v_mov_b32_dpp v86, v55 row_ror:1 row_mask:0xf bank_mask:0xf
	v_mov_b32_dpp v84, v52 row_ror:1 row_mask:0xf bank_mask:0xf
	v_mov_b32_dpp v87, v53 row_ror:1 row_mask:0xf bank_mask:0xf
	v_mov_b32_dpp v85, v54 row_ror:2 row_mask:0xf bank_mask:0xf
	v_mov_b32_dpp v88, v55 row_ror:2 row_mask:0xf bank_mask:0xf
	v_mov_b32_dpp v89, v52 row_ror:2 row_mask:0xf bank_mask:0xf
	v_mov_b32_dpp v90, v53 row_ror:2 row_mask:0xf bank_mask:0xf
	v_mov_b32_dpp v91, v16 row_ror:1 row_mask:0xf bank_mask:0xf
	v_mov_b32_dpp v118, v17 row_ror:1 row_mask:0xf bank_mask:0xf
	v_mov_b32_dpp v116, v18 row_ror:1 row_mask:0xf bank_mask:0xf
	v_mov_b32_dpp v119, v19 row_ror:1 row_mask:0xf bank_mask:0xf
	v_mov_b32_dpp v117, v16 row_ror:2 row_mask:0xf bank_mask:0xf
	v_mov_b32_dpp v120, v17 row_ror:2 row_mask:0xf bank_mask:0xf
	v_mov_b32_dpp v121, v18 row_ror:2 row_mask:0xf bank_mask:0xf
	v_mov_b32_dpp v122, v19 row_ror:2 row_mask:0xf bank_mask:0xf
	s_and_saveexec_b64 s[0:1], vcc
	s_cbranch_execz .LBB0_573
	v_add_u32_e32 v136, v81, v44
	v_lshl_add_u64 v[20:21], v[136:137], 2, s[28:29]
	global_store_dwordx4 v[20:21], v[16:19], off
; __device__ __forceinline__ f32x2 gelu_pk(f32x2 v) {
;     const f32x2 av = __builtin_elementwise_abs(v), d = av * 0.2316418882f + 1.0f;
;     f32x2 t; t.x = __builtin_amdgcn_rcpf(d.x); t.y = __builtin_amdgcn_rcpf(d.y);
;     __device__ __forceinline__ void operator()(AccRef acc, const Unit& u, int wr, int wc, int fr, int fq) const {
;     ...
;                     const f32x4 wu0 = *(const f32x4*)(cw + (DFF + jn)), wu1 = *(const f32x4*)(cw + (UPN + DFF + jn)), wu2 = *(const f32x4*)(cw + (2 * UPN + DFF + jn)), bu = *(const f32x4*)(cb + (DFF + jn));
;                     f32x4 pu1 = (f32x4){0.f, 0.f, 0.f, 0.f}, pu2 = pu1;
; #pragma unroll
;                     for (int m = 0; m < 4; ++m) {
;                         const f32x4 au = unpack4(pa[ai][1][m][n]);
;                         const f32x4 ru1 = ror1v(au), ru2 = ror2v(au);
;                         const f32x4 u1 = fr >= 1 ? ru1 : pu1, u2 = fr >= 2 ? ru2 : pu2;
;                         if (m == 0 && fr < 2) *(f32x4*)(edge + (unsigned)((grp * 4 + fr) * UPN + DFF + jn)) = au;
;                         if (m == 3 && fr >= 14) *(f32x4*)(edge + (unsigned)((grp * 4 + (fr - 12)) * UPN + DFF + jn)) = au;
;                         cu[m] = bu + wu0 * u2 + wu1 * u1 + wu2 * au;
;                         pu1 = ru1; pu2 = ru2; }
;                 }
;                 {
;                     const f32x4 wg0 = *(const f32x4*)(cw + jn), wg1 = *(const f32x4*)(cw + (UPN + jn)), wg2 = *(const f32x4*)(cw + (2 * UPN + jn)), bg = *(const f32x4*)(cb + jn);
;                     f32x4 pg1 = (f32x4){0.f, 0.f, 0.f, 0.f}, pg2 = pg1;
; #pragma unroll
;                     for (int m = 0; m < 4; ++m) { const int row = rowg + m * 16 + fr;
;                         const f32x4 ag = unpack4(pa[ai][0][m][n]);
;                         const f32x4 rg1 = ror1v(ag), rg2 = ror2v(ag);
;                         const f32x4 g1 = fr >= 1 ? rg1 : pg1, g2 = fr >= 2 ? rg2 : pg2;
;                         if (m == 0 && fr < 2) *(f32x4*)(edge + (unsigned)((grp * 4 + fr) * UPN + jn)) = ag;
;                         if (m == 3 && fr >= 14) *(f32x4*)(edge + (unsigned)((grp * 4 + (fr - 12)) * UPN + jn)) = ag;
;                         const f32x4 o = gelu4(bg + wg0 * g2 + wg1 * g1 + wg2 * ag) * cu[m];
;                         if (!(m == 0 && fr < 2)) *(u32x2*)(act + (unsigned)(row * DFF + jn)) = pack4(o);
;                         pg1 = rg1; pg2 = rg2; }
.LBB0_573:
	s_or_b64 exec, exec, s[0:1]
	global_load_dwordx4 v[28:31], v[46:47], off
	global_load_dwordx4 v[24:27], v[60:61], off
	global_load_dwordx4 v[20:23], v[64:65], off
	global_load_dwordx4 v[32:35], v[48:49], off
	v_add_u32_e32 v123, s69, v166
	v_lshlrev_b32_e32 v40, 16, v114
	v_and_b32_e32 v41, 0xffff0000, v114
	v_lshlrev_b32_e32 v42, 16, v115
	v_and_b32_e32 v43, 0xffff0000, v115
	s_nop 1
	v_mov_b32_dpp v60, v40 row_ror:1 row_mask:0xf bank_mask:0xf
	v_mov_b32_dpp v61, v41 row_ror:1 row_mask:0xf bank_mask:0xf
	v_mov_b32_dpp v64, v42 row_ror:1 row_mask:0xf bank_mask:0xf
	v_mov_b32_dpp v65, v43 row_ror:1 row_mask:0xf bank_mask:0xf
	v_mov_b32_dpp v76, v40 row_ror:2 row_mask:0xf bank_mask:0xf
	v_mov_b32_dpp v77, v41 row_ror:2 row_mask:0xf bank_mask:0xf
	v_mov_b32_dpp v78, v42 row_ror:2 row_mask:0xf bank_mask:0xf
	v_mov_b32_dpp v79, v43 row_ror:2 row_mask:0xf bank_mask:0xf
	v_mul_lo_u32 v82, v123, s88
	s_and_saveexec_b64 s[0:1], s[10:11]
	s_xor_b64 s[76:77], exec, s[0:1]
	s_cbranch_execz .LBB0_575
	v_cndmask_b32_e64 v179, 0, v171, s[6:7]
	v_cndmask_b32_e64 v178, 0, v169, s[6:7]
	v_cndmask_b32_e64 v175, 0, v149, s[8:9]
	v_cndmask_b32_e64 v174, 0, v125, s[8:9]
	s_waitcnt vmcnt(4)
	v_pk_fma_f32 v[178:179], v[10:11], v[178:179], v[14:15]
	v_cndmask_b32_e64 v181, 0, v150, s[6:7]
	v_pk_fma_f32 v[174:175], v[6:7], v[174:175], v[178:179]
	v_cndmask_b32_e64 v180, 0, v127, s[6:7]
	v_pk_fma_f32 v[38:39], v[2:3], v[38:39], v[174:175]
	s_waitcnt vmcnt(0)
	v_pk_fma_f32 v[174:175], v[28:29], v[76:77], v[32:33]
	v_cndmask_b32_e64 v115, 0, v146, s[8:9]
	v_pk_fma_f32 v[174:175], v[24:25], v[60:61], v[174:175]
	v_cndmask_b32_e64 v114, 0, v124, s[8:9]
	v_pk_fma_f32 v[40:41], v[20:21], v[40:41], v[174:175]
	v_pk_fma_f32 v[180:181], v[8:9], v[180:181], v[12:13]
	v_and_b32_e32 v179, 0x7fffffff, v41
	v_and_b32_e32 v178, 0x7fffffff, v40
	v_pk_fma_f32 v[178:179], v[178:179], s[42:43], 1.0 op_sel_hi:[1,0,0]
	v_pk_fma_f32 v[114:115], v[4:5], v[114:115], v[180:181]
	v_rcp_f32_e32 v178, v178
	v_rcp_f32_e32 v179, v179
	v_pk_mul_f32 v[174:175], v[40:41], v[40:41]
	v_mov_b64_e32 v[180:181], s[54:55]
	v_pk_mul_f32 v[174:175], v[174:175], s[38:39] op_sel_hi:[1,0]
	v_pk_fma_f32 v[182:183], v[178:179], s[52:53], v[180:181] op_sel_hi:[1,0,0]
	v_exp_f32_e32 v174, v174
	v_exp_f32_e32 v175, v175
	v_pk_fma_f32 v[182:183], v[178:179], v[182:183], s[56:57] op_sel_hi:[1,1,0]
	v_pk_fma_f32 v[36:37], v[0:1], v[36:37], v[114:115]
	v_pk_fma_f32 v[182:183], v[178:179], v[182:183], s[62:63] op_sel_hi:[1,1,0]
	v_pk_fma_f32 v[114:115], v[30:31], v[78:79], v[34:35]
	v_pk_fma_f32 v[182:183], v[178:179], v[182:183], s[64:65] op_sel_hi:[1,1,0]
	v_pk_fma_f32 v[114:115], v[26:27], v[64:65], v[114:115]
	v_pk_mul_f32 v[178:179], v[178:179], v[182:183]
	v_cmp_gt_f32_e64 s[0:1], 0, v40
	v_pk_mul_f32 v[174:175], v[174:175], v[178:179]
	v_pk_fma_f32 v[42:43], v[22:23], v[42:43], v[114:115]
	v_pk_mul_f32 v[178:179], v[40:41], v[174:175]
	v_pk_fma_f32 v[174:175], v[40:41], v[174:175], v[40:41] neg_lo:[1,0,0] neg_hi:[1,0,0]
	v_pk_mul_f32 v[114:115], v[42:43], v[42:43]
	v_cndmask_b32_e64 v40, v174, v178, s[0:1]
	v_cmp_gt_f32_e64 s[0:1], 0, v41
	v_and_b32_e32 v174, 0x7fffffff, v42
	v_pk_mul_f32 v[114:115], v[114:115], s[38:39] op_sel_hi:[1,0]
	v_cndmask_b32_e64 v41, v175, v179, s[0:1]
	v_and_b32_e32 v175, 0x7fffffff, v43
	v_pk_fma_f32 v[174:175], v[174:175], s[42:43], 1.0 op_sel_hi:[1,0,0]
	v_exp_f32_e32 v114, v114
	v_rcp_f32_e32 v174, v174
	v_rcp_f32_e32 v175, v175
	v_exp_f32_e32 v115, v115
	v_cmp_gt_f32_e64 s[0:1], 0, v42
	v_mul_lo_u32 v82, v123, s88
	v_pk_fma_f32 v[178:179], v[174:175], s[52:53], v[180:181] op_sel_hi:[1,0,0]
	v_pk_mul_f32 v[36:37], v[36:37], v[40:41]
	v_pk_fma_f32 v[178:179], v[174:175], v[178:179], s[56:57] op_sel_hi:[1,1,0]
	v_add_u32_e32 v136, v82, v44
	v_pk_fma_f32 v[178:179], v[174:175], v[178:179], s[62:63] op_sel_hi:[1,1,0]
	v_cvt_pk_bf16_f32 v36, v36, v37
	s_nop 0
	v_pk_fma_f32 v[178:179], v[174:175], v[178:179], s[64:65] op_sel_hi:[1,1,0]
	s_nop 0
	v_pk_mul_f32 v[174:175], v[174:175], v[178:179]
	s_nop 0
	v_pk_mul_f32 v[114:115], v[114:115], v[174:175]
	s_nop 0
	v_pk_mul_f32 v[174:175], v[42:43], v[114:115]
	v_pk_fma_f32 v[114:115], v[42:43], v[114:115], v[42:43] neg_lo:[1,0,0] neg_hi:[1,0,0]
	s_nop 0
	v_cndmask_b32_e64 v42, v114, v174, s[0:1]
	v_cmp_gt_f32_e64 s[0:1], 0, v43
	s_nop 1
	v_cndmask_b32_e64 v43, v115, v175, s[0:1]
	v_pk_mul_f32 v[38:39], v[38:39], v[42:43]
	s_nop 0
	v_cvt_pk_bf16_f32 v37, v38, v39
	v_lshl_add_u64 v[38:39], v[136:137], 1, s[26:27]
	global_store_dwordx2 v[38:39], v[36:37], off

; __device__ __forceinline__ f32x2 gelu_pk(f32x2 v) {
;     __device__ __forceinline__ void operator()(AccRef acc, const Unit& u, int wr, int wc, int fr, int fq) const {
;     ...
;             for (int n = 0; n < 2; ++n) { const unsigned jn = (unsigned)(j0 + 4 * n);
;                 f32x4 cu[4];
;                 {
;                     const f32x4 wu0 = *(const f32x4*)(cw + (DFF + jn)), wu1 = *(const f32x4*)(cw + (UPN + DFF + jn)), wu2 = *(const f32x4*)(cw + (2 * UPN + DFF + jn)), bu = *(const f32x4*)(cb + (DFF + jn));
;                     f32x4 pu1 = (f32x4){0.f, 0.f, 0.f, 0.f}, pu2 = pu1;
; #pragma unroll
;                     for (int m = 0; m < 4; ++m) {
;                         const f32x4 au = unpack4(pa[ai][1][m][n]);
;                         const f32x4 ru1 = ror1v(au), ru2 = ror2v(au);
;                         const f32x4 u1 = fr >= 1 ? ru1 : pu1, u2 = fr >= 2 ? ru2 : pu2;
;                         if (m == 0 && fr < 2) *(f32x4*)(edge + (unsigned)((grp * 4 + fr) * UPN + DFF + jn)) = au;
;                         if (m == 3 && fr >= 14) *(f32x4*)(edge + (unsigned)((grp * 4 + (fr - 12)) * UPN + DFF + jn)) = au;
;                         cu[m] = bu + wu0 * u2 + wu1 * u1 + wu2 * au;
;                         pu1 = ru1; pu2 = ru2; }
;                 }
;                 {
;                     const f32x4 wg0 = *(const f32x4*)(cw + jn), wg1 = *(const f32x4*)(cw + (UPN + jn)), wg2 = *(const f32x4*)(cw + (2 * UPN + jn)), bg = *(const f32x4*)(cb + jn);
;                     f32x4 pg1 = (f32x4){0.f, 0.f, 0.f, 0.f}, pg2 = pg1;
; #pragma unroll
;                     for (int m = 0; m < 4; ++m) { const int row = rowg + m * 16 + fr;
;                         const f32x4 ag = unpack4(pa[ai][0][m][n]);
;                         const f32x4 rg1 = ror1v(ag), rg2 = ror2v(ag);
;                         const f32x4 g1 = fr >= 1 ? rg1 : pg1, g2 = fr >= 2 ? rg2 : pg2;
;                         if (m == 0 && fr < 2) *(f32x4*)(edge + (unsigned)((grp * 4 + fr) * UPN + jn)) = ag;
;                         if (m == 3 && fr >= 14) *(f32x4*)(edge + (unsigned)((grp * 4 + (fr - 12)) * UPN + jn)) = ag;
;                         const f32x4 o = gelu4(bg + wg0 * g2 + wg1 * g1 + wg2 * ag) * cu[m];
;                         if (!(m == 0 && fr < 2)) *(u32x2*)(act + (unsigned)(row * DFF + jn)) = pack4(o);
;                         pg1 = rg1; pg2 = rg2; }
.LBB0_577:
	s_or_b64 exec, exec, s[0:1]
	s_nop 0
	v_cndmask_b32_e64 v41, v171, v172, s[6:7]
	v_cndmask_b32_e64 v40, v169, v170, s[6:7]
	v_cndmask_b32_e64 v43, v150, v168, s[6:7]
	v_cndmask_b32_e64 v42, v127, v148, s[6:7]
	v_cndmask_b32_e64 v37, v146, v152, s[8:9]
	v_cndmask_b32_e64 v36, v124, v126, s[8:9]
	v_cndmask_b32_e64 v39, v149, v167, s[8:9]
	v_cndmask_b32_e64 v38, v125, v147, s[8:9]
	s_waitcnt vmcnt(4)
	v_pk_fma_f32 v[42:43], v[8:9], v[42:43], v[12:13]
	v_pk_fma_f32 v[40:41], v[10:11], v[40:41], v[14:15]
	v_pk_fma_f32 v[36:37], v[4:5], v[36:37], v[42:43]
	v_pk_fma_f32 v[38:39], v[6:7], v[38:39], v[40:41]
	v_pk_fma_f32 v[36:37], v[0:1], v[58:59], v[36:37]
	v_pk_fma_f32 v[38:39], v[2:3], v[56:57], v[38:39]
	v_cndmask_b32_e64 v57, v172, v90, s[6:7]
	v_cndmask_b32_e64 v56, v170, v89, s[6:7]
	v_cndmask_b32_e64 v59, v168, v88, s[6:7]
	v_cndmask_b32_e64 v58, v148, v85, s[6:7]
	v_cndmask_b32_e64 v41, v152, v86, s[8:9]
	v_cndmask_b32_e64 v40, v126, v83, s[8:9]
	v_cndmask_b32_e64 v43, v167, v87, s[8:9]
	v_cndmask_b32_e64 v42, v147, v84, s[8:9]
	v_pk_fma_f32 v[58:59], v[8:9], v[58:59], v[12:13]
	v_pk_fma_f32 v[56:57], v[10:11], v[56:57], v[14:15]
	v_pk_fma_f32 v[40:41], v[4:5], v[40:41], v[58:59]
	v_pk_fma_f32 v[42:43], v[6:7], v[42:43], v[56:57]
	v_pk_fma_f32 v[56:57], v[0:1], v[54:55], v[40:41]
	v_pk_fma_f32 v[58:59], v[2:3], v[52:53], v[42:43]
	v_lshlrev_b32_e32 v40, 16, v112
	v_and_b32_e32 v41, 0xffff0000, v112
	v_lshlrev_b32_e32 v42, 16, v113
	v_and_b32_e32 v43, 0xffff0000, v113
	v_mov_b32_e32 v112, v137
	v_mov_b32_e32 v113, v137
	v_mov_b32_e32 v123, v137
	v_mov_b32_e32 v124, v137
	v_mov_b32_dpp v112, v40 row_ror:1 row_mask:0xf bank_mask:0xf
	v_mov_b32_dpp v113, v41 row_ror:1 row_mask:0xf bank_mask:0xf
	v_mov_b32_dpp v123, v40 row_ror:2 row_mask:0xf bank_mask:0xf
	v_mov_b32_dpp v124, v41 row_ror:2 row_mask:0xf bank_mask:0xf
	v_cndmask_b32_e64 v55, v61, v113, s[8:9]
	v_cndmask_b32_e64 v54, v60, v112, s[8:9]
	v_cndmask_b32_e64 v61, v77, v124, s[6:7]
	v_cndmask_b32_e64 v60, v76, v123, s[6:7]
	s_waitcnt vmcnt(0)
	v_pk_fma_f32 v[60:61], v[28:29], v[60:61], v[32:33]
	v_mov_b32_e32 v114, v137
	v_pk_fma_f32 v[54:55], v[24:25], v[54:55], v[60:61]
	v_mov_b32_e32 v115, v137
	v_pk_fma_f32 v[40:41], v[20:21], v[40:41], v[54:55]
	v_mov_b32_e32 v125, v137
	v_and_b32_e32 v61, 0x7fffffff, v41
	v_and_b32_e32 v60, 0x7fffffff, v40
	v_pk_fma_f32 v[60:61], v[60:61], s[42:43], 1.0 op_sel_hi:[1,0,0]
	v_mov_b32_e32 v126, v137
	v_rcp_f32_e32 v60, v60
	v_rcp_f32_e32 v61, v61
	v_mov_b32_dpp v114, v42 row_ror:1 row_mask:0xf bank_mask:0xf
	v_mov_b32_dpp v115, v43 row_ror:1 row_mask:0xf bank_mask:0xf
	v_mov_b32_dpp v125, v42 row_ror:2 row_mask:0xf bank_mask:0xf
	v_mov_b32_dpp v126, v43 row_ror:2 row_mask:0xf bank_mask:0xf
	v_cndmask_b32_e64 v53, v65, v115, s[8:9]
	v_cndmask_b32_e64 v52, v64, v114, s[8:9]
	v_cndmask_b32_e64 v65, v79, v126, s[6:7]
	v_cndmask_b32_e64 v64, v78, v125, s[6:7]
	v_pk_fma_f32 v[64:65], v[30:31], v[64:65], v[34:35]
	v_pk_mul_f32 v[54:55], v[40:41], v[40:41]
	v_mov_b64_e32 v[76:77], s[54:55]
	v_pk_fma_f32 v[52:53], v[26:27], v[52:53], v[64:65]
	v_pk_mul_f32 v[54:55], v[54:55], s[38:39] op_sel_hi:[1,0]
	v_pk_fma_f32 v[64:65], v[60:61], s[52:53], v[76:77] op_sel_hi:[1,0,0]
	v_exp_f32_e32 v54, v54
	v_exp_f32_e32 v55, v55
	v_pk_fma_f32 v[64:65], v[60:61], v[64:65], s[56:57] op_sel_hi:[1,1,0]
	v_cmp_gt_f32_e64 s[0:1], 0, v40
	v_pk_fma_f32 v[64:65], v[60:61], v[64:65], s[62:63] op_sel_hi:[1,1,0]
	v_pk_fma_f32 v[42:43], v[22:23], v[42:43], v[52:53]
	v_pk_fma_f32 v[64:65], v[60:61], v[64:65], s[64:65] op_sel_hi:[1,1,0]
	v_pk_mul_f32 v[52:53], v[42:43], v[42:43]
	v_pk_mul_f32 v[60:61], v[60:61], v[64:65]
	v_pk_mul_f32 v[52:53], v[52:53], s[38:39] op_sel_hi:[1,0]
	v_pk_mul_f32 v[54:55], v[54:55], v[60:61]
	v_exp_f32_e32 v52, v52
	v_pk_mul_f32 v[60:61], v[40:41], v[54:55]
	v_pk_fma_f32 v[54:55], v[40:41], v[54:55], v[40:41] neg_lo:[1,0,0] neg_hi:[1,0,0]
	v_exp_f32_e32 v53, v53
	v_cndmask_b32_e64 v40, v54, v60, s[0:1]
	v_cmp_gt_f32_e64 s[0:1], 0, v41
	v_and_b32_e32 v54, 0x7fffffff, v42
	v_add_u32_e32 v64, 0xb000, v82
	v_cndmask_b32_e64 v41, v55, v61, s[0:1]
	v_and_b32_e32 v55, 0x7fffffff, v43
	v_pk_fma_f32 v[54:55], v[54:55], s[42:43], 1.0 op_sel_hi:[1,0,0]
	v_cmp_gt_f32_e64 s[0:1], 0, v42
	v_rcp_f32_e32 v54, v54
	v_rcp_f32_e32 v55, v55
	v_pk_mul_f32 v[36:37], v[36:37], v[40:41]
	v_add_u32_e32 v136, v64, v44
	v_cvt_pk_bf16_f32 v36, v36, v37
	v_pk_fma_f32 v[60:61], v[54:55], s[52:53], v[76:77] op_sel_hi:[1,0,0]
	s_nop 1
	v_pk_fma_f32 v[60:61], v[54:55], v[60:61], s[56:57] op_sel_hi:[1,1,0]
	s_nop 1
	v_pk_fma_f32 v[60:61], v[54:55], v[60:61], s[62:63] op_sel_hi:[1,1,0]
	v_add_u32_e32 v65, 0x16000, v82
	v_pk_fma_f32 v[60:61], v[54:55], v[60:61], s[64:65] op_sel_hi:[1,1,0]
	s_nop 0
	v_pk_mul_f32 v[54:55], v[54:55], v[60:61]
	s_nop 0
	v_pk_mul_f32 v[52:53], v[52:53], v[54:55]
	s_nop 0
	v_pk_mul_f32 v[54:55], v[42:43], v[52:53]
	v_pk_fma_f32 v[52:53], v[42:43], v[52:53], v[42:43] neg_lo:[1,0,0] neg_hi:[1,0,0]
	s_nop 0
	v_cndmask_b32_e64 v42, v52, v54, s[0:1]
	v_cmp_gt_f32_e64 s[0:1], 0, v43
	s_nop 1
	v_cndmask_b32_e64 v43, v53, v55, s[0:1]
	v_pk_mul_f32 v[38:39], v[38:39], v[42:43]
	s_nop 1
	v_cvt_pk_bf16_f32 v37, v38, v39
	v_lshl_add_u64 v[38:39], v[136:137], 1, s[26:27]
	global_store_dwordx2 v[38:39], v[36:37], off
	v_lshlrev_b32_e32 v36, 16, v110
	v_and_b32_e32 v37, 0xffff0000, v110
	v_lshlrev_b32_e32 v38, 16, v111
	v_mov_b32_dpp v43, v36 row_ror:2 row_mask:0xf bank_mask:0xf
	v_mov_b32_dpp v54, v37 row_ror:2 row_mask:0xf bank_mask:0xf
	v_and_b32_e32 v39, 0xffff0000, v111
	v_mov_b32_dpp v40, v36 row_ror:1 row_mask:0xf bank_mask:0xf
; __device__ __forceinline__ f32x2 gelu_pk(f32x2 v) {
;     __device__ __forceinline__ void operator()(AccRef acc, const Unit& u, int wr, int wc, int fr, int fq) const {
;     ...
;             for (int n = 0; n < 2; ++n) { const unsigned jn = (unsigned)(j0 + 4 * n);
;                 f32x4 cu[4];
;                 {
;                     const f32x4 wu0 = *(const f32x4*)(cw + (DFF + jn)), wu1 = *(const f32x4*)(cw + (UPN + DFF + jn)), wu2 = *(const f32x4*)(cw + (2 * UPN + DFF + jn)), bu = *(const f32x4*)(cb + (DFF + jn));
;                     f32x4 pu1 = (f32x4){0.f, 0.f, 0.f, 0.f}, pu2 = pu1;
; #pragma unroll
;                     for (int m = 0; m < 4; ++m) {
;                         const f32x4 au = unpack4(pa[ai][1][m][n]);
;                         const f32x4 ru1 = ror1v(au), ru2 = ror2v(au);
;                         const f32x4 u1 = fr >= 1 ? ru1 : pu1, u2 = fr >= 2 ? ru2 : pu2;
;                         if (m == 0 && fr < 2) *(f32x4*)(edge + (unsigned)((grp * 4 + fr) * UPN + DFF + jn)) = au;
;                         if (m == 3 && fr >= 14) *(f32x4*)(edge + (unsigned)((grp * 4 + (fr - 12)) * UPN + DFF + jn)) = au;
;                         cu[m] = bu + wu0 * u2 + wu1 * u1 + wu2 * au;
;                         pu1 = ru1; pu2 = ru2; }
;                 }
;                 {
;                     const f32x4 wg0 = *(const f32x4*)(cw + jn), wg1 = *(const f32x4*)(cw + (UPN + jn)), wg2 = *(const f32x4*)(cw + (2 * UPN + jn)), bg = *(const f32x4*)(cb + jn);
;                     f32x4 pg1 = (f32x4){0.f, 0.f, 0.f, 0.f}, pg2 = pg1;
; #pragma unroll
;                     for (int m = 0; m < 4; ++m) { const int row = rowg + m * 16 + fr;
;                         const f32x4 ag = unpack4(pa[ai][0][m][n]);
;                         const f32x4 rg1 = ror1v(ag), rg2 = ror2v(ag);
;                         const f32x4 g1 = fr >= 1 ? rg1 : pg1, g2 = fr >= 2 ? rg2 : pg2;
;                         if (m == 0 && fr < 2) *(f32x4*)(edge + (unsigned)((grp * 4 + fr) * UPN + jn)) = ag;
;                         if (m == 3 && fr >= 14) *(f32x4*)(edge + (unsigned)((grp * 4 + (fr - 12)) * UPN + jn)) = ag;
;                         const f32x4 o = gelu4(bg + wg0 * g2 + wg1 * g1 + wg2 * ag) * cu[m];
;                         if (!(m == 0 && fr < 2)) *(u32x2*)(act + (unsigned)(row * DFF + jn)) = pack4(o);
;                         pg1 = rg1; pg2 = rg2; }
	v_mov_b32_dpp v41, v37 row_ror:1 row_mask:0xf bank_mask:0xf
	v_cndmask_b32_e64 v111, v124, v54, s[6:7]
	v_cndmask_b32_e64 v110, v123, v43, s[6:7]
	v_cndmask_b32_e64 v79, v113, v41, s[8:9]
	v_cndmask_b32_e64 v78, v112, v40, s[8:9]
	v_pk_fma_f32 v[110:111], v[28:29], v[110:111], v[32:33]
	s_nop 1
	v_pk_fma_f32 v[78:79], v[24:25], v[78:79], v[110:111]
	s_nop 1
	v_pk_fma_f32 v[36:37], v[20:21], v[36:37], v[78:79]
	s_nop 1
	v_and_b32_e32 v111, 0x7fffffff, v37
	v_and_b32_e32 v110, 0x7fffffff, v36
	v_pk_fma_f32 v[110:111], v[110:111], s[42:43], 1.0 op_sel_hi:[1,0,0]
	v_mov_b32_dpp v52, v38 row_ror:2 row_mask:0xf bank_mask:0xf
	v_rcp_f32_e32 v110, v110
	v_rcp_f32_e32 v111, v111
	v_mov_b32_dpp v55, v39 row_ror:2 row_mask:0xf bank_mask:0xf
	v_mov_b32_dpp v42, v38 row_ror:1 row_mask:0xf bank_mask:0xf
	v_mov_b32_dpp v53, v39 row_ror:1 row_mask:0xf bank_mask:0xf
	v_cndmask_b32_e64 v113, v126, v55, s[6:7]
	v_cndmask_b32_e64 v112, v125, v52, s[6:7]
	v_cndmask_b32_e64 v61, v115, v53, s[8:9]
	v_cndmask_b32_e64 v60, v114, v42, s[8:9]
	v_pk_fma_f32 v[112:113], v[30:31], v[112:113], v[34:35]
	v_pk_mul_f32 v[78:79], v[36:37], v[36:37]
	v_pk_fma_f32 v[60:61], v[26:27], v[60:61], v[112:113]
	v_pk_mul_f32 v[78:79], v[78:79], s[38:39] op_sel_hi:[1,0]
	v_pk_fma_f32 v[112:113], v[110:111], s[52:53], v[76:77] op_sel_hi:[1,0,0]
	v_exp_f32_e32 v78, v78
	v_exp_f32_e32 v79, v79
	v_pk_fma_f32 v[112:113], v[110:111], v[112:113], s[56:57] op_sel_hi:[1,1,0]
	v_cmp_gt_f32_e64 s[0:1], 0, v36
	v_pk_fma_f32 v[112:113], v[110:111], v[112:113], s[62:63] op_sel_hi:[1,1,0]
	v_pk_fma_f32 v[38:39], v[22:23], v[38:39], v[60:61]
	v_pk_fma_f32 v[112:113], v[110:111], v[112:113], s[64:65] op_sel_hi:[1,1,0]
	v_pk_mul_f32 v[60:61], v[38:39], v[38:39]
	v_pk_mul_f32 v[110:111], v[110:111], v[112:113]
	v_pk_mul_f32 v[60:61], v[60:61], s[38:39] op_sel_hi:[1,0]
	v_pk_mul_f32 v[78:79], v[78:79], v[110:111]
	v_exp_f32_e32 v60, v60
	v_pk_mul_f32 v[110:111], v[36:37], v[78:79]
	v_pk_fma_f32 v[78:79], v[36:37], v[78:79], v[36:37] neg_lo:[1,0,0] neg_hi:[1,0,0]
	v_exp_f32_e32 v61, v61
	v_cndmask_b32_e64 v36, v78, v110, s[0:1]
	v_cmp_gt_f32_e64 s[0:1], 0, v37
	v_and_b32_e32 v78, 0x7fffffff, v38
	v_add_u32_e32 v136, v65, v44
	v_cndmask_b32_e64 v37, v79, v111, s[0:1]
	v_and_b32_e32 v79, 0x7fffffff, v39
	v_pk_fma_f32 v[78:79], v[78:79], s[42:43], 1.0 op_sel_hi:[1,0,0]
	v_cmp_gt_f32_e64 s[0:1], 0, v38
	v_rcp_f32_e32 v78, v78
	v_rcp_f32_e32 v79, v79
	v_pk_mul_f32 v[36:37], v[56:57], v[36:37]
	s_nop 1
	v_cvt_pk_bf16_f32 v36, v36, v37
	v_pk_fma_f32 v[76:77], v[78:79], s[52:53], v[76:77] op_sel_hi:[1,0,0]
	s_nop 1
	v_pk_fma_f32 v[76:77], v[78:79], v[76:77], s[56:57] op_sel_hi:[1,1,0]
	s_nop 0
	v_pk_fma_f32 v[76:77], v[78:79], v[76:77], s[62:63] op_sel_hi:[1,1,0]
	s_nop 0
	v_pk_fma_f32 v[76:77], v[78:79], v[76:77], s[64:65] op_sel_hi:[1,1,0]
	s_nop 0
	v_pk_mul_f32 v[76:77], v[78:79], v[76:77]
	s_nop 0
	v_pk_mul_f32 v[60:61], v[60:61], v[76:77]
	s_nop 0
	v_pk_mul_f32 v[76:77], v[38:39], v[60:61]
	v_pk_fma_f32 v[60:61], v[38:39], v[60:61], v[38:39] neg_lo:[1,0,0] neg_hi:[1,0,0]
	s_nop 0
	v_cndmask_b32_e64 v38, v60, v76, s[0:1]
	v_cmp_gt_f32_e64 s[0:1], 0, v39
	s_nop 1
	v_cndmask_b32_e64 v39, v61, v77, s[0:1]
	v_pk_mul_f32 v[38:39], v[58:59], v[38:39]
	s_nop 1
	v_cvt_pk_bf16_f32 v37, v38, v39
	v_lshl_add_u64 v[38:39], v[136:137], 1, s[26:27]
	global_store_dwordx2 v[38:39], v[36:37], off
	v_lshlrev_b32_e32 v36, 16, v108
	v_and_b32_e32 v37, 0xffff0000, v108
	v_lshlrev_b32_e32 v38, 16, v109
	v_and_b32_e32 v39, 0xffff0000, v109
	s_nop 1
	v_mov_b32_dpp v56, v36 row_ror:1 row_mask:0xf bank_mask:0xf
	v_mov_b32_dpp v57, v37 row_ror:1 row_mask:0xf bank_mask:0xf
	v_mov_b32_dpp v58, v38 row_ror:1 row_mask:0xf bank_mask:0xf
	v_mov_b32_dpp v61, v39 row_ror:1 row_mask:0xf bank_mask:0xf
	v_mov_b32_dpp v59, v36 row_ror:2 row_mask:0xf bank_mask:0xf
	v_mov_b32_dpp v76, v37 row_ror:2 row_mask:0xf bank_mask:0xf
	v_mov_b32_dpp v60, v38 row_ror:2 row_mask:0xf bank_mask:0xf
	v_mov_b32_dpp v77, v39 row_ror:2 row_mask:0xf bank_mask:0xf
	s_and_saveexec_b64 s[0:1], vcc
	s_cbranch_execz .LBB0_579
	v_add_u32_e32 v136, v51, v44
	v_lshl_add_u64 v[78:79], v[136:137], 2, s[28:29]
	global_store_dwordx4 v[78:79], v[36:39], off
.LBB0_579:
	s_or_b64 exec, exec, s[0:1]
	v_cndmask_b32_e64 v78, v42, v58, s[8:9]
	v_cndmask_b32_e64 v40, v40, v56, s[8:9]
	v_cndmask_b32_e64 v56, v43, v59, s[6:7]
	v_cndmask_b32_e64 v59, v90, v122, s[6:7]
	v_cndmask_b32_e64 v58, v89, v121, s[6:7]
	v_cndmask_b32_e64 v41, v41, v57, s[8:9]
	v_cndmask_b32_e64 v57, v54, v76, s[6:7]
	v_cndmask_b32_e64 v43, v55, v77, s[6:7]
	v_cndmask_b32_e64 v55, v87, v119, s[8:9]
	v_cndmask_b32_e64 v54, v84, v116, s[8:9]
	v_pk_fma_f32 v[10:11], v[10:11], v[58:59], v[14:15]
	v_cndmask_b32_e64 v79, v53, v61, s[8:9]
	v_pk_fma_f32 v[6:7], v[6:7], v[54:55], v[10:11]
	v_cndmask_b32_e64 v42, v52, v60, s[6:7]
	v_pk_fma_f32 v[2:3], v[2:3], v[18:19], v[6:7]
	v_pk_fma_f32 v[6:7], v[28:29], v[56:57], v[32:33]
	v_cndmask_b32_e64 v61, v88, v120, s[6:7]
	v_pk_fma_f32 v[6:7], v[24:25], v[40:41], v[6:7]
	v_cndmask_b32_e64 v60, v85, v117, s[6:7]
	v_pk_fma_f32 v[6:7], v[20:21], v[36:37], v[6:7]
	v_pk_fma_f32 v[8:9], v[8:9], v[60:61], v[12:13]
	v_and_b32_e32 v13, 0x7fffffff, v7
	v_and_b32_e32 v12, 0x7fffffff, v6
	v_pk_fma_f32 v[12:13], v[12:13], s[42:43], 1.0 op_sel_hi:[1,0,0]
	v_cndmask_b32_e64 v53, v86, v118, s[8:9]
	v_rcp_f32_e32 v12, v12
	v_rcp_f32_e32 v13, v13
	v_cndmask_b32_e64 v52, v83, v91, s[8:9]
	v_pk_fma_f32 v[4:5], v[4:5], v[52:53], v[8:9]
	v_pk_mul_f32 v[10:11], v[6:7], v[6:7]
	v_mov_b64_e32 v[14:15], s[54:55]
	v_pk_fma_f32 v[0:1], v[0:1], v[16:17], v[4:5]
	v_pk_mul_f32 v[10:11], v[10:11], s[38:39] op_sel_hi:[1,0]
; __device__ __forceinline__ f32x2 gelu_pk(f32x2 v) {
;     __device__ __forceinline__ void operator()(AccRef acc, const Unit& u, int wr, int wc, int fr, int fq) const {
;     ...
;             for (int n = 0; n < 2; ++n) { const unsigned jn = (unsigned)(j0 + 4 * n);
;                 f32x4 cu[4];
;                 {
;                     const f32x4 wu0 = *(const f32x4*)(cw + (DFF + jn)), wu1 = *(const f32x4*)(cw + (UPN + DFF + jn)), wu2 = *(const f32x4*)(cw + (2 * UPN + DFF + jn)), bu = *(const f32x4*)(cb + (DFF + jn));
;                     f32x4 pu1 = (f32x4){0.f, 0.f, 0.f, 0.f}, pu2 = pu1;
; #pragma unroll
;                     for (int m = 0; m < 4; ++m) {
;                         const f32x4 au = unpack4(pa[ai][1][m][n]);
;                         const f32x4 ru1 = ror1v(au), ru2 = ror2v(au);
;                         const f32x4 u1 = fr >= 1 ? ru1 : pu1, u2 = fr >= 2 ? ru2 : pu2;
;                         if (m == 0 && fr < 2) *(f32x4*)(edge + (unsigned)((grp * 4 + fr) * UPN + DFF + jn)) = au;
;                         if (m == 3 && fr >= 14) *(f32x4*)(edge + (unsigned)((grp * 4 + (fr - 12)) * UPN + DFF + jn)) = au;
;                         cu[m] = bu + wu0 * u2 + wu1 * u1 + wu2 * au;
;                         pu1 = ru1; pu2 = ru2; }
;                 }
;                 {
;                     const f32x4 wg0 = *(const f32x4*)(cw + jn), wg1 = *(const f32x4*)(cw + (UPN + jn)), wg2 = *(const f32x4*)(cw + (2 * UPN + jn)), bg = *(const f32x4*)(cb + jn);
;                     f32x4 pg1 = (f32x4){0.f, 0.f, 0.f, 0.f}, pg2 = pg1;
; #pragma unroll
;                     for (int m = 0; m < 4; ++m) { const int row = rowg + m * 16 + fr;
;                         const f32x4 ag = unpack4(pa[ai][0][m][n]);
;                         const f32x4 rg1 = ror1v(ag), rg2 = ror2v(ag);
;                         const f32x4 g1 = fr >= 1 ? rg1 : pg1, g2 = fr >= 2 ? rg2 : pg2;
;                         if (m == 0 && fr < 2) *(f32x4*)(edge + (unsigned)((grp * 4 + fr) * UPN + jn)) = ag;
;                         if (m == 3 && fr >= 14) *(f32x4*)(edge + (unsigned)((grp * 4 + (fr - 12)) * UPN + jn)) = ag;
;                         const f32x4 o = gelu4(bg + wg0 * g2 + wg1 * g1 + wg2 * ag) * cu[m];
;                         if (!(m == 0 && fr < 2)) *(u32x2*)(act + (unsigned)(row * DFF + jn)) = pack4(o);
;                         pg1 = rg1; pg2 = rg2; }
	v_pk_fma_f32 v[16:17], v[12:13], s[52:53], v[14:15] op_sel_hi:[1,0,0]
	v_exp_f32_e32 v10, v10
	v_exp_f32_e32 v11, v11
	v_pk_fma_f32 v[16:17], v[12:13], v[16:17], s[56:57] op_sel_hi:[1,1,0]
	v_pk_fma_f32 v[4:5], v[30:31], v[42:43], v[34:35]
	v_pk_fma_f32 v[16:17], v[12:13], v[16:17], s[62:63] op_sel_hi:[1,1,0]
	v_pk_fma_f32 v[4:5], v[26:27], v[78:79], v[4:5]
	v_pk_fma_f32 v[16:17], v[12:13], v[16:17], s[64:65] op_sel_hi:[1,1,0]
	v_cmp_gt_f32_e64 s[0:1], 0, v6
	v_pk_mul_f32 v[12:13], v[12:13], v[16:17]
	v_pk_fma_f32 v[4:5], v[22:23], v[38:39], v[4:5]
	v_pk_mul_f32 v[10:11], v[10:11], v[12:13]
	v_pk_mul_f32 v[8:9], v[4:5], v[4:5]
	v_pk_mul_f32 v[12:13], v[6:7], v[10:11]
	v_pk_fma_f32 v[10:11], v[6:7], v[10:11], v[6:7] neg_lo:[1,0,0] neg_hi:[1,0,0]
	v_pk_mul_f32 v[8:9], v[8:9], s[38:39] op_sel_hi:[1,0]
	v_cndmask_b32_e64 v6, v10, v12, s[0:1]
	v_cmp_gt_f32_e64 s[0:1], 0, v7
	v_and_b32_e32 v10, 0x7fffffff, v4
	v_exp_f32_e32 v8, v8
	v_cndmask_b32_e64 v7, v11, v13, s[0:1]
	v_and_b32_e32 v11, 0x7fffffff, v5
	v_pk_fma_f32 v[10:11], v[10:11], s[42:43], 1.0 op_sel_hi:[1,0,0]
	v_exp_f32_e32 v9, v9
	v_rcp_f32_e32 v10, v10
	v_rcp_f32_e32 v11, v11
	v_cmp_gt_f32_e64 s[0:1], 0, v4
	v_add_u32_e32 v76, 0x21000, v82
	v_pk_mul_f32 v[0:1], v[0:1], v[6:7]
	v_pk_fma_f32 v[12:13], v[10:11], s[52:53], v[14:15] op_sel_hi:[1,0,0]
	v_add_u32_e32 v136, v76, v44
	v_pk_fma_f32 v[12:13], v[10:11], v[12:13], s[56:57] op_sel_hi:[1,1,0]
	v_cvt_pk_bf16_f32 v0, v0, v1
	v_lshlrev_b32_e32 v36, 16, v100
	v_pk_fma_f32 v[12:13], v[10:11], v[12:13], s[62:63] op_sel_hi:[1,1,0]
	v_and_b32_e32 v37, 0xffff0000, v100
	v_pk_fma_f32 v[12:13], v[10:11], v[12:13], s[64:65] op_sel_hi:[1,1,0]
	v_lshlrev_b32_e32 v38, 16, v101
	v_pk_mul_f32 v[10:11], v[10:11], v[12:13]
	v_and_b32_e32 v39, 0xffff0000, v101
	v_pk_mul_f32 v[8:9], v[8:9], v[10:11]
	s_nop 1
	v_pk_mul_f32 v[10:11], v[4:5], v[8:9]
	v_pk_fma_f32 v[8:9], v[4:5], v[8:9], v[4:5] neg_lo:[1,0,0] neg_hi:[1,0,0]
	s_nop 1
	v_cndmask_b32_e64 v4, v8, v10, s[0:1]
	v_cmp_gt_f32_e64 s[0:1], 0, v5
	s_nop 1
	v_cndmask_b32_e64 v5, v9, v11, s[0:1]
	v_pk_mul_f32 v[2:3], v[2:3], v[4:5]
	s_nop 1
	v_cvt_pk_bf16_f32 v1, v2, v3
	v_lshl_add_u64 v[2:3], v[136:137], 1, s[26:27]
	global_store_dwordx2 v[2:3], v[0:1], off
	global_load_dwordx4 v[8:11], v[62:63], off
	global_load_dwordx4 v[4:7], v[66:67], off
	s_nop 0
	global_load_dwordx4 v[0:3], v[68:69], off
	global_load_dwordx4 v[12:15], v[70:71], off
	s_nop 1
	v_mov_b32_dpp v89, v36 row_ror:1 row_mask:0xf bank_mask:0xf
	v_mov_b32_dpp v108, v37 row_ror:1 row_mask:0xf bank_mask:0xf
	v_mov_b32_dpp v100, v38 row_ror:1 row_mask:0xf bank_mask:0xf
	v_mov_b32_dpp v110, v39 row_ror:1 row_mask:0xf bank_mask:0xf
	v_mov_b32_dpp v101, v36 row_ror:2 row_mask:0xf bank_mask:0xf
	v_mov_b32_dpp v111, v37 row_ror:2 row_mask:0xf bank_mask:0xf
	v_mov_b32_dpp v113, v38 row_ror:2 row_mask:0xf bank_mask:0xf
	v_mov_b32_dpp v115, v39 row_ror:2 row_mask:0xf bank_mask:0xf
	s_and_saveexec_b64 s[0:1], s[12:13]
	s_cbranch_execz .LBB0_581
	v_add_u32_e32 v136, v50, v45
	v_lshl_add_u64 v[16:17], v[136:137], 2, s[28:29]
	global_store_dwordx4 v[16:17], v[36:39], off
.LBB0_581:
	s_or_b64 exec, exec, s[0:1]
	v_lshlrev_b32_e32 v56, 16, v102
	v_and_b32_e32 v57, 0xffff0000, v102
	v_lshlrev_b32_e32 v54, 16, v103
	v_and_b32_e32 v55, 0xffff0000, v103
	s_nop 1
	v_lshlrev_b32_e32 v52, 16, v104
	v_and_b32_e32 v53, 0xffff0000, v104
	v_lshlrev_b32_e32 v44, 16, v105
	v_and_b32_e32 v45, 0xffff0000, v105
	s_nop 1
	v_lshlrev_b32_e32 v16, 16, v106
	v_and_b32_e32 v17, 0xffff0000, v106
	v_lshlrev_b32_e32 v18, 16, v107
	v_and_b32_e32 v19, 0xffff0000, v107
	s_nop 1
	v_mov_b32_dpp v88, v56 row_ror:1 row_mask:0xf bank_mask:0xf
	v_mov_b32_dpp v102, v57 row_ror:1 row_mask:0xf bank_mask:0xf
	v_mov_b32_dpp v90, v54 row_ror:1 row_mask:0xf bank_mask:0xf
	v_mov_b32_dpp v103, v55 row_ror:1 row_mask:0xf bank_mask:0xf
	v_mov_b32_dpp v91, v56 row_ror:2 row_mask:0xf bank_mask:0xf
	v_mov_b32_dpp v109, v57 row_ror:2 row_mask:0xf bank_mask:0xf
	v_mov_b32_dpp v112, v54 row_ror:2 row_mask:0xf bank_mask:0xf
	v_mov_b32_dpp v114, v55 row_ror:2 row_mask:0xf bank_mask:0xf
	v_mov_b32_dpp v62, v52 row_ror:1 row_mask:0xf bank_mask:0xf
	v_mov_b32_dpp v67, v53 row_ror:1 row_mask:0xf bank_mask:0xf
	v_mov_b32_dpp v63, v44 row_ror:1 row_mask:0xf bank_mask:0xf
	v_mov_b32_dpp v68, v45 row_ror:1 row_mask:0xf bank_mask:0xf
	v_mov_b32_dpp v66, v52 row_ror:2 row_mask:0xf bank_mask:0xf
	v_mov_b32_dpp v69, v53 row_ror:2 row_mask:0xf bank_mask:0xf
	v_mov_b32_dpp v70, v44 row_ror:2 row_mask:0xf bank_mask:0xf
	v_mov_b32_dpp v71, v45 row_ror:2 row_mask:0xf bank_mask:0xf
	v_mov_b32_dpp v77, v16 row_ror:1 row_mask:0xf bank_mask:0xf
	v_mov_b32_dpp v83, v17 row_ror:1 row_mask:0xf bank_mask:0xf
	v_mov_b32_dpp v78, v18 row_ror:1 row_mask:0xf bank_mask:0xf
	v_mov_b32_dpp v84, v19 row_ror:1 row_mask:0xf bank_mask:0xf
	v_mov_b32_dpp v79, v16 row_ror:2 row_mask:0xf bank_mask:0xf
	v_mov_b32_dpp v85, v17 row_ror:2 row_mask:0xf bank_mask:0xf
	v_mov_b32_dpp v86, v18 row_ror:2 row_mask:0xf bank_mask:0xf
	v_mov_b32_dpp v87, v19 row_ror:2 row_mask:0xf bank_mask:0xf
	s_and_saveexec_b64 s[0:1], vcc
	s_cbranch_execz .LBB0_583
	v_add_u32_e32 v136, v81, v50
	v_lshl_add_u64 v[20:21], v[136:137], 2, s[28:29]
	global_store_dwordx4 v[20:21], v[16:19], off
; __device__ __forceinline__ f32x2 gelu_pk(f32x2 v) {
;     const f32x2 av = __builtin_elementwise_abs(v), d = av * 0.2316418882f + 1.0f;
;     f32x2 t; t.x = __builtin_amdgcn_rcpf(d.x); t.y = __builtin_amdgcn_rcpf(d.y);
;     __device__ __forceinline__ void operator()(AccRef acc, const Unit& u, int wr, int wc, int fr, int fq) const {
;     ...
;                     const f32x4 wu0 = *(const f32x4*)(cw + (DFF + jn)), wu1 = *(const f32x4*)(cw + (UPN + DFF + jn)), wu2 = *(const f32x4*)(cw + (2 * UPN + DFF + jn)), bu = *(const f32x4*)(cb + (DFF + jn));
;                     f32x4 pu1 = (f32x4){0.f, 0.f, 0.f, 0.f}, pu2 = pu1;
; #pragma unroll
;                     for (int m = 0; m < 4; ++m) {
;                         const f32x4 au = unpack4(pa[ai][1][m][n]);
;                         const f32x4 ru1 = ror1v(au), ru2 = ror2v(au);
;                         const f32x4 u1 = fr >= 1 ? ru1 : pu1, u2 = fr >= 2 ? ru2 : pu2;
;                         if (m == 0 && fr < 2) *(f32x4*)(edge + (unsigned)((grp * 4 + fr) * UPN + DFF + jn)) = au;
;                         if (m == 3 && fr >= 14) *(f32x4*)(edge + (unsigned)((grp * 4 + (fr - 12)) * UPN + DFF + jn)) = au;
;                         cu[m] = bu + wu0 * u2 + wu1 * u1 + wu2 * au;
;                         pu1 = ru1; pu2 = ru2; }
;                 }
;                 {
;                     const f32x4 wg0 = *(const f32x4*)(cw + jn), wg1 = *(const f32x4*)(cw + (UPN + jn)), wg2 = *(const f32x4*)(cw + (2 * UPN + jn)), bg = *(const f32x4*)(cb + jn);
;                     f32x4 pg1 = (f32x4){0.f, 0.f, 0.f, 0.f}, pg2 = pg1;
; #pragma unroll
;                     for (int m = 0; m < 4; ++m) { const int row = rowg + m * 16 + fr;
;                         const f32x4 ag = unpack4(pa[ai][0][m][n]);
;                         const f32x4 rg1 = ror1v(ag), rg2 = ror2v(ag);
;                         const f32x4 g1 = fr >= 1 ? rg1 : pg1, g2 = fr >= 2 ? rg2 : pg2;
;                         if (m == 0 && fr < 2) *(f32x4*)(edge + (unsigned)((grp * 4 + fr) * UPN + jn)) = ag;
;                         if (m == 3 && fr >= 14) *(f32x4*)(edge + (unsigned)((grp * 4 + (fr - 12)) * UPN + jn)) = ag;
;                         const f32x4 o = gelu4(bg + wg0 * g2 + wg1 * g1 + wg2 * ag) * cu[m];
;                         if (!(m == 0 && fr < 2)) *(u32x2*)(act + (unsigned)(row * DFF + jn)) = pack4(o);
;                         pg1 = rg1; pg2 = rg2; }
.LBB0_583:
	s_or_b64 exec, exec, s[0:1]
	global_load_dwordx4 v[28:31], v[46:47], off offset:16
	global_load_dwordx4 v[24:27], v[72:73], off
	global_load_dwordx4 v[20:23], v[74:75], off
	global_load_dwordx4 v[32:35], v[48:49], off offset:16
	v_lshlrev_b32_e32 v40, 16, v98
	v_and_b32_e32 v41, 0xffff0000, v98
	v_lshlrev_b32_e32 v42, 16, v99
	v_and_b32_e32 v43, 0xffff0000, v99
	s_nop 1
	v_mov_b32_dpp v46, v40 row_ror:1 row_mask:0xf bank_mask:0xf
	v_mov_b32_dpp v47, v41 row_ror:1 row_mask:0xf bank_mask:0xf
	v_mov_b32_dpp v48, v42 row_ror:1 row_mask:0xf bank_mask:0xf
	v_mov_b32_dpp v49, v43 row_ror:1 row_mask:0xf bank_mask:0xf
	v_mov_b32_dpp v58, v40 row_ror:2 row_mask:0xf bank_mask:0xf
	v_mov_b32_dpp v59, v41 row_ror:2 row_mask:0xf bank_mask:0xf
	v_mov_b32_dpp v60, v42 row_ror:2 row_mask:0xf bank_mask:0xf
	v_mov_b32_dpp v61, v43 row_ror:2 row_mask:0xf bank_mask:0xf
	s_and_saveexec_b64 s[0:1], s[10:11]
	s_xor_b64 s[10:11], exec, s[0:1]
	s_cbranch_execz .LBB0_585
	v_cndmask_b32_e64 v81, 0, v115, s[6:7]
	v_cndmask_b32_e64 v80, 0, v113, s[6:7]
	v_cndmask_b32_e64 v75, 0, v110, s[8:9]
	v_cndmask_b32_e64 v74, 0, v100, s[8:9]
	s_waitcnt vmcnt(4)
	v_pk_fma_f32 v[80:81], v[10:11], v[80:81], v[14:15]
	v_cndmask_b32_e64 v99, 0, v111, s[6:7]
	v_pk_fma_f32 v[74:75], v[6:7], v[74:75], v[80:81]
	v_cndmask_b32_e64 v98, 0, v101, s[6:7]
	v_pk_fma_f32 v[38:39], v[2:3], v[38:39], v[74:75]
	s_waitcnt vmcnt(0)
	v_pk_fma_f32 v[74:75], v[28:29], v[58:59], v[32:33]
	v_cndmask_b32_e64 v73, 0, v108, s[8:9]
	v_pk_fma_f32 v[74:75], v[24:25], v[46:47], v[74:75]
	v_cndmask_b32_e64 v72, 0, v89, s[8:9]
	v_pk_fma_f32 v[40:41], v[20:21], v[40:41], v[74:75]
	v_pk_fma_f32 v[98:99], v[8:9], v[98:99], v[12:13]
	v_and_b32_e32 v81, 0x7fffffff, v41
	v_and_b32_e32 v80, 0x7fffffff, v40
	v_pk_fma_f32 v[80:81], v[80:81], s[42:43], 1.0 op_sel_hi:[1,0,0]
	v_pk_fma_f32 v[72:73], v[4:5], v[72:73], v[98:99]
	v_rcp_f32_e32 v80, v80
	v_rcp_f32_e32 v81, v81
	v_pk_mul_f32 v[74:75], v[40:41], v[40:41]
	v_mov_b64_e32 v[98:99], s[54:55]
	v_pk_mul_f32 v[74:75], v[74:75], s[38:39] op_sel_hi:[1,0]
	v_pk_fma_f32 v[104:105], v[80:81], s[52:53], v[98:99] op_sel_hi:[1,0,0]
	v_exp_f32_e32 v74, v74
	v_exp_f32_e32 v75, v75
	v_pk_fma_f32 v[104:105], v[80:81], v[104:105], s[56:57] op_sel_hi:[1,1,0]
	v_pk_fma_f32 v[36:37], v[0:1], v[36:37], v[72:73]
	v_pk_fma_f32 v[104:105], v[80:81], v[104:105], s[62:63] op_sel_hi:[1,1,0]
	v_pk_fma_f32 v[72:73], v[30:31], v[60:61], v[34:35]
	v_pk_fma_f32 v[104:105], v[80:81], v[104:105], s[64:65] op_sel_hi:[1,1,0]
	v_pk_fma_f32 v[72:73], v[26:27], v[48:49], v[72:73]
	v_pk_mul_f32 v[80:81], v[80:81], v[104:105]
	v_cmp_gt_f32_e64 s[0:1], 0, v40
	v_pk_mul_f32 v[74:75], v[74:75], v[80:81]
	v_pk_fma_f32 v[42:43], v[22:23], v[42:43], v[72:73]
	v_pk_mul_f32 v[80:81], v[40:41], v[74:75]
	v_pk_fma_f32 v[74:75], v[40:41], v[74:75], v[40:41] neg_lo:[1,0,0] neg_hi:[1,0,0]
	v_pk_mul_f32 v[72:73], v[42:43], v[42:43]
	v_cndmask_b32_e64 v40, v74, v80, s[0:1]
	v_cmp_gt_f32_e64 s[0:1], 0, v41
	v_and_b32_e32 v74, 0x7fffffff, v42
	v_pk_mul_f32 v[72:73], v[72:73], s[38:39] op_sel_hi:[1,0]
	v_cndmask_b32_e64 v41, v75, v81, s[0:1]
	v_and_b32_e32 v75, 0x7fffffff, v43
	v_pk_fma_f32 v[74:75], v[74:75], s[42:43], 1.0 op_sel_hi:[1,0,0]
	v_exp_f32_e32 v72, v72
	v_rcp_f32_e32 v74, v74
	v_rcp_f32_e32 v75, v75
	v_exp_f32_e32 v73, v73
	v_cmp_gt_f32_e64 s[0:1], 0, v42
	v_pk_mul_f32 v[36:37], v[36:37], v[40:41]
	v_pk_fma_f32 v[80:81], v[74:75], s[52:53], v[98:99] op_sel_hi:[1,0,0]
	v_add_u32_e32 v136, v82, v50
	v_pk_fma_f32 v[80:81], v[74:75], v[80:81], s[56:57] op_sel_hi:[1,1,0]
	v_cvt_pk_bf16_f32 v36, v36, v37
	s_nop 0
	v_pk_fma_f32 v[80:81], v[74:75], v[80:81], s[62:63] op_sel_hi:[1,1,0]
	s_nop 0
	v_pk_fma_f32 v[80:81], v[74:75], v[80:81], s[64:65] op_sel_hi:[1,1,0]
	s_nop 0
	v_pk_mul_f32 v[74:75], v[74:75], v[80:81]
	s_nop 0
	v_pk_mul_f32 v[72:73], v[72:73], v[74:75]
	s_nop 0
	v_pk_mul_f32 v[74:75], v[42:43], v[72:73]
	v_pk_fma_f32 v[72:73], v[42:43], v[72:73], v[42:43] neg_lo:[1,0,0] neg_hi:[1,0,0]
	s_nop 0
	v_cndmask_b32_e64 v42, v72, v74, s[0:1]
	v_cmp_gt_f32_e64 s[0:1], 0, v43
	s_nop 1
	v_cndmask_b32_e64 v43, v73, v75, s[0:1]
	v_pk_mul_f32 v[38:39], v[38:39], v[42:43]
	s_nop 0
	v_cvt_pk_bf16_f32 v37, v38, v39
	v_lshl_add_u64 v[38:39], v[136:137], 1, s[26:27]
	global_store_dwordx2 v[38:39], v[36:37], off

; __device__ __forceinline__ f32x2 gelu_pk(f32x2 v) {
;     __device__ __forceinline__ void operator()(AccRef acc, const Unit& u, int wr, int wc, int fr, int fq) const {
;     ...
;             for (int n = 0; n < 2; ++n) { const unsigned jn = (unsigned)(j0 + 4 * n);
;                 f32x4 cu[4];
;                 {
;                     const f32x4 wu0 = *(const f32x4*)(cw + (DFF + jn)), wu1 = *(const f32x4*)(cw + (UPN + DFF + jn)), wu2 = *(const f32x4*)(cw + (2 * UPN + DFF + jn)), bu = *(const f32x4*)(cb + (DFF + jn));
;                     f32x4 pu1 = (f32x4){0.f, 0.f, 0.f, 0.f}, pu2 = pu1;
; #pragma unroll
;                     for (int m = 0; m < 4; ++m) {
;                         const f32x4 au = unpack4(pa[ai][1][m][n]);
;                         const f32x4 ru1 = ror1v(au), ru2 = ror2v(au);
;                         const f32x4 u1 = fr >= 1 ? ru1 : pu1, u2 = fr >= 2 ? ru2 : pu2;
;                         if (m == 0 && fr < 2) *(f32x4*)(edge + (unsigned)((grp * 4 + fr) * UPN + DFF + jn)) = au;
;                         if (m == 3 && fr >= 14) *(f32x4*)(edge + (unsigned)((grp * 4 + (fr - 12)) * UPN + DFF + jn)) = au;
;                         cu[m] = bu + wu0 * u2 + wu1 * u1 + wu2 * au;
;                         pu1 = ru1; pu2 = ru2; }
;                 }
;                 {
;                     const f32x4 wg0 = *(const f32x4*)(cw + jn), wg1 = *(const f32x4*)(cw + (UPN + jn)), wg2 = *(const f32x4*)(cw + (2 * UPN + jn)), bg = *(const f32x4*)(cb + jn);
;                     f32x4 pg1 = (f32x4){0.f, 0.f, 0.f, 0.f}, pg2 = pg1;
; #pragma unroll
;                     for (int m = 0; m < 4; ++m) { const int row = rowg + m * 16 + fr;
;                         const f32x4 ag = unpack4(pa[ai][0][m][n]);
;                         const f32x4 rg1 = ror1v(ag), rg2 = ror2v(ag);
;                         const f32x4 g1 = fr >= 1 ? rg1 : pg1, g2 = fr >= 2 ? rg2 : pg2;
;                         if (m == 0 && fr < 2) *(f32x4*)(edge + (unsigned)((grp * 4 + fr) * UPN + jn)) = ag;
;                         if (m == 3 && fr >= 14) *(f32x4*)(edge + (unsigned)((grp * 4 + (fr - 12)) * UPN + jn)) = ag;
;                         const f32x4 o = gelu4(bg + wg0 * g2 + wg1 * g1 + wg2 * ag) * cu[m];
;                         if (!(m == 0 && fr < 2)) *(u32x2*)(act + (unsigned)(row * DFF + jn)) = pack4(o);
;                         pg1 = rg1; pg2 = rg2; }
.LBB0_587:
	s_or_b64 exec, exec, s[0:1]
	s_nop 0
	v_cndmask_b32_e64 v41, v115, v114, s[6:7]
	v_cndmask_b32_e64 v40, v113, v112, s[6:7]
	v_cndmask_b32_e64 v43, v111, v109, s[6:7]
	v_cndmask_b32_e64 v42, v101, v91, s[6:7]
	v_cndmask_b32_e64 v37, v108, v102, s[8:9]
	v_cndmask_b32_e64 v36, v89, v88, s[8:9]
	v_cndmask_b32_e64 v39, v110, v103, s[8:9]
	v_cndmask_b32_e64 v38, v100, v90, s[8:9]
	s_waitcnt vmcnt(4)
	v_pk_fma_f32 v[42:43], v[8:9], v[42:43], v[12:13]
	v_pk_fma_f32 v[40:41], v[10:11], v[40:41], v[14:15]
	v_pk_fma_f32 v[36:37], v[4:5], v[36:37], v[42:43]
	v_pk_fma_f32 v[38:39], v[6:7], v[38:39], v[40:41]
	v_pk_fma_f32 v[36:37], v[0:1], v[56:57], v[36:37]
	v_pk_fma_f32 v[38:39], v[2:3], v[54:55], v[38:39]
	v_cndmask_b32_e64 v55, v114, v71, s[6:7]
	v_cndmask_b32_e64 v54, v112, v70, s[6:7]
	v_cndmask_b32_e64 v57, v109, v69, s[6:7]
	v_cndmask_b32_e64 v56, v91, v66, s[6:7]
	v_cndmask_b32_e64 v41, v102, v67, s[8:9]
	v_cndmask_b32_e64 v40, v88, v62, s[8:9]
	v_cndmask_b32_e64 v43, v103, v68, s[8:9]
	v_cndmask_b32_e64 v42, v90, v63, s[8:9]
	v_pk_fma_f32 v[56:57], v[8:9], v[56:57], v[12:13]
	v_pk_fma_f32 v[54:55], v[10:11], v[54:55], v[14:15]
	v_pk_fma_f32 v[40:41], v[4:5], v[40:41], v[56:57]
	v_pk_fma_f32 v[42:43], v[6:7], v[42:43], v[54:55]
	v_pk_fma_f32 v[52:53], v[0:1], v[52:53], v[40:41]
	v_pk_fma_f32 v[54:55], v[2:3], v[44:45], v[42:43]
	v_lshlrev_b32_e32 v40, 16, v96
	v_and_b32_e32 v41, 0xffff0000, v96
	v_lshlrev_b32_e32 v42, 16, v97
	v_and_b32_e32 v43, 0xffff0000, v97
	v_mov_b32_e32 v74, v137
	v_mov_b32_e32 v75, v137
	v_mov_b32_e32 v80, v137
	v_mov_b32_e32 v81, v137
	v_mov_b32_e32 v72, v137
	v_mov_b32_e32 v73, v137
	v_mov_b32_dpp v74, v42 row_ror:1 row_mask:0xf bank_mask:0xf
	v_mov_b32_dpp v75, v43 row_ror:1 row_mask:0xf bank_mask:0xf
	v_mov_b32_dpp v80, v40 row_ror:2 row_mask:0xf bank_mask:0xf
	v_mov_b32_dpp v81, v41 row_ror:2 row_mask:0xf bank_mask:0xf
	v_mov_b32_dpp v72, v40 row_ror:1 row_mask:0xf bank_mask:0xf
	v_mov_b32_dpp v73, v41 row_ror:1 row_mask:0xf bank_mask:0xf
	v_cndmask_b32_e64 v45, v49, v75, s[8:9]
	v_cndmask_b32_e64 v44, v48, v74, s[8:9]
	v_cndmask_b32_e64 v49, v59, v81, s[6:7]
	v_cndmask_b32_e64 v48, v58, v80, s[6:7]
	v_cndmask_b32_e64 v47, v47, v73, s[8:9]
	v_cndmask_b32_e64 v46, v46, v72, s[8:9]
	s_waitcnt vmcnt(0)
	v_pk_fma_f32 v[48:49], v[28:29], v[48:49], v[32:33]
	v_mov_b32_e32 v82, v137
	v_pk_fma_f32 v[46:47], v[24:25], v[46:47], v[48:49]
	v_mov_b32_e32 v88, v137
	v_pk_fma_f32 v[40:41], v[20:21], v[40:41], v[46:47]
	v_mov_b32_dpp v82, v42 row_ror:2 row_mask:0xf bank_mask:0xf
	v_and_b32_e32 v49, 0x7fffffff, v41
	v_and_b32_e32 v48, 0x7fffffff, v40
	v_pk_fma_f32 v[48:49], v[48:49], s[42:43], 1.0 op_sel_hi:[1,0,0]
	v_mov_b32_dpp v88, v43 row_ror:2 row_mask:0xf bank_mask:0xf
	v_rcp_f32_e32 v48, v48
	v_rcp_f32_e32 v49, v49
	v_cndmask_b32_e64 v57, v61, v88, s[6:7]
	v_cndmask_b32_e64 v56, v60, v82, s[6:7]
	v_pk_fma_f32 v[56:57], v[30:31], v[56:57], v[34:35]
	v_pk_mul_f32 v[46:47], v[40:41], v[40:41]
	v_pk_fma_f32 v[44:45], v[26:27], v[44:45], v[56:57]
	v_mov_b64_e32 v[56:57], s[54:55]
	v_pk_mul_f32 v[46:47], v[46:47], s[38:39] op_sel_hi:[1,0]
	v_pk_fma_f32 v[58:59], v[48:49], s[52:53], v[56:57] op_sel_hi:[1,0,0]
	v_exp_f32_e32 v46, v46
	v_exp_f32_e32 v47, v47
	v_pk_fma_f32 v[58:59], v[48:49], v[58:59], s[56:57] op_sel_hi:[1,1,0]
	v_cmp_gt_f32_e64 s[0:1], 0, v40
	v_pk_fma_f32 v[58:59], v[48:49], v[58:59], s[62:63] op_sel_hi:[1,1,0]
	v_pk_fma_f32 v[42:43], v[22:23], v[42:43], v[44:45]
	v_pk_fma_f32 v[58:59], v[48:49], v[58:59], s[64:65] op_sel_hi:[1,1,0]
	v_pk_mul_f32 v[44:45], v[42:43], v[42:43]
	v_pk_mul_f32 v[48:49], v[48:49], v[58:59]
	v_pk_mul_f32 v[44:45], v[44:45], s[38:39] op_sel_hi:[1,0]
	v_pk_mul_f32 v[46:47], v[46:47], v[48:49]
	v_exp_f32_e32 v44, v44
	v_pk_mul_f32 v[48:49], v[40:41], v[46:47]
	v_pk_fma_f32 v[46:47], v[40:41], v[46:47], v[40:41] neg_lo:[1,0,0] neg_hi:[1,0,0]
	v_exp_f32_e32 v45, v45
	v_cndmask_b32_e64 v40, v46, v48, s[0:1]
	v_cmp_gt_f32_e64 s[0:1], 0, v41
	v_and_b32_e32 v46, 0x7fffffff, v42
	v_add_u32_e32 v136, v64, v50
	v_cndmask_b32_e64 v41, v47, v49, s[0:1]
	v_and_b32_e32 v47, 0x7fffffff, v43
	v_pk_fma_f32 v[46:47], v[46:47], s[42:43], 1.0 op_sel_hi:[1,0,0]
	v_cmp_gt_f32_e64 s[0:1], 0, v42
	v_rcp_f32_e32 v46, v46
	v_rcp_f32_e32 v47, v47
	v_pk_mul_f32 v[36:37], v[36:37], v[40:41]
	s_nop 1
	v_cvt_pk_bf16_f32 v36, v36, v37
	v_pk_fma_f32 v[48:49], v[46:47], s[52:53], v[56:57] op_sel_hi:[1,0,0]
	s_nop 1
	v_pk_fma_f32 v[48:49], v[46:47], v[48:49], s[56:57] op_sel_hi:[1,1,0]
	s_nop 0
	v_pk_fma_f32 v[48:49], v[46:47], v[48:49], s[62:63] op_sel_hi:[1,1,0]
	s_nop 0
	v_pk_fma_f32 v[48:49], v[46:47], v[48:49], s[64:65] op_sel_hi:[1,1,0]
	s_nop 0
	v_pk_mul_f32 v[46:47], v[46:47], v[48:49]
	s_nop 0
	v_pk_mul_f32 v[44:45], v[44:45], v[46:47]
	s_nop 0
	v_pk_mul_f32 v[46:47], v[42:43], v[44:45]
; __device__ __forceinline__ f32x2 gelu_pk(f32x2 v) {
;     __device__ __forceinline__ void operator()(AccRef acc, const Unit& u, int wr, int wc, int fr, int fq) const {
;     ...
;             for (int n = 0; n < 2; ++n) { const unsigned jn = (unsigned)(j0 + 4 * n);
;                 f32x4 cu[4];
;                 {
;                     const f32x4 wu0 = *(const f32x4*)(cw + (DFF + jn)), wu1 = *(const f32x4*)(cw + (UPN + DFF + jn)), wu2 = *(const f32x4*)(cw + (2 * UPN + DFF + jn)), bu = *(const f32x4*)(cb + (DFF + jn));
;                     f32x4 pu1 = (f32x4){0.f, 0.f, 0.f, 0.f}, pu2 = pu1;
; #pragma unroll
;                     for (int m = 0; m < 4; ++m) {
;                         const f32x4 au = unpack4(pa[ai][1][m][n]);
;                         const f32x4 ru1 = ror1v(au), ru2 = ror2v(au);
;                         const f32x4 u1 = fr >= 1 ? ru1 : pu1, u2 = fr >= 2 ? ru2 : pu2;
;                         if (m == 0 && fr < 2) *(f32x4*)(edge + (unsigned)((grp * 4 + fr) * UPN + DFF + jn)) = au;
;                         if (m == 3 && fr >= 14) *(f32x4*)(edge + (unsigned)((grp * 4 + (fr - 12)) * UPN + DFF + jn)) = au;
;                         cu[m] = bu + wu0 * u2 + wu1 * u1 + wu2 * au;
;                         pu1 = ru1; pu2 = ru2; }
;                 }
;                 {
;                     const f32x4 wg0 = *(const f32x4*)(cw + jn), wg1 = *(const f32x4*)(cw + (UPN + jn)), wg2 = *(const f32x4*)(cw + (2 * UPN + jn)), bg = *(const f32x4*)(cb + jn);
;                     f32x4 pg1 = (f32x4){0.f, 0.f, 0.f, 0.f}, pg2 = pg1;
; #pragma unroll
;                     for (int m = 0; m < 4; ++m) { const int row = rowg + m * 16 + fr;
;                         const f32x4 ag = unpack4(pa[ai][0][m][n]);
;                         const f32x4 rg1 = ror1v(ag), rg2 = ror2v(ag);
;                         const f32x4 g1 = fr >= 1 ? rg1 : pg1, g2 = fr >= 2 ? rg2 : pg2;
;                         if (m == 0 && fr < 2) *(f32x4*)(edge + (unsigned)((grp * 4 + fr) * UPN + jn)) = ag;
;                         if (m == 3 && fr >= 14) *(f32x4*)(edge + (unsigned)((grp * 4 + (fr - 12)) * UPN + jn)) = ag;
;                         const f32x4 o = gelu4(bg + wg0 * g2 + wg1 * g1 + wg2 * ag) * cu[m];
;                         if (!(m == 0 && fr < 2)) *(u32x2*)(act + (unsigned)(row * DFF + jn)) = pack4(o);
;                         pg1 = rg1; pg2 = rg2; }
	v_pk_fma_f32 v[44:45], v[42:43], v[44:45], v[42:43] neg_lo:[1,0,0] neg_hi:[1,0,0]
	s_nop 0
	v_cndmask_b32_e64 v42, v44, v46, s[0:1]
	v_cmp_gt_f32_e64 s[0:1], 0, v43
	s_nop 1
	v_cndmask_b32_e64 v43, v45, v47, s[0:1]
	v_pk_mul_f32 v[38:39], v[38:39], v[42:43]
	s_nop 1
	v_cvt_pk_bf16_f32 v37, v38, v39
	v_lshl_add_u64 v[38:39], v[136:137], 1, s[26:27]
	global_store_dwordx2 v[38:39], v[36:37], off
	v_lshlrev_b32_e32 v36, 16, v94
	v_and_b32_e32 v37, 0xffff0000, v94
	v_lshlrev_b32_e32 v38, 16, v95
	v_mov_b32_dpp v44, v36 row_ror:2 row_mask:0xf bank_mask:0xf
	v_mov_b32_dpp v46, v37 row_ror:2 row_mask:0xf bank_mask:0xf
	v_mov_b32_dpp v40, v36 row_ror:1 row_mask:0xf bank_mask:0xf
	v_mov_b32_dpp v41, v37 row_ror:1 row_mask:0xf bank_mask:0xf
	v_cndmask_b32_e64 v61, v81, v46, s[6:7]
	v_cndmask_b32_e64 v60, v80, v44, s[6:7]
	v_cndmask_b32_e64 v59, v73, v41, s[8:9]
	v_cndmask_b32_e64 v58, v72, v40, s[8:9]
	v_pk_fma_f32 v[60:61], v[28:29], v[60:61], v[32:33]
	v_and_b32_e32 v39, 0xffff0000, v95
	v_pk_fma_f32 v[58:59], v[24:25], v[58:59], v[60:61]
	s_nop 1
	v_pk_fma_f32 v[36:37], v[20:21], v[36:37], v[58:59]
	s_nop 1
	v_and_b32_e32 v61, 0x7fffffff, v37
	v_and_b32_e32 v60, 0x7fffffff, v36
	v_pk_fma_f32 v[60:61], v[60:61], s[42:43], 1.0 op_sel_hi:[1,0,0]
	s_nop 1
	v_rcp_f32_e32 v60, v60
	v_rcp_f32_e32 v61, v61
	v_mov_b32_dpp v45, v38 row_ror:2 row_mask:0xf bank_mask:0xf
	v_mov_b32_dpp v47, v39 row_ror:2 row_mask:0xf bank_mask:0xf
	v_mov_b32_dpp v42, v38 row_ror:1 row_mask:0xf bank_mask:0xf
	v_mov_b32_dpp v43, v39 row_ror:1 row_mask:0xf bank_mask:0xf
	v_cndmask_b32_e64 v73, v88, v47, s[6:7]
	v_cndmask_b32_e64 v72, v82, v45, s[6:7]
	v_cndmask_b32_e64 v49, v75, v43, s[8:9]
	v_cndmask_b32_e64 v48, v74, v42, s[8:9]
	v_pk_fma_f32 v[72:73], v[30:31], v[72:73], v[34:35]
	v_pk_mul_f32 v[58:59], v[36:37], v[36:37]
	v_pk_fma_f32 v[48:49], v[26:27], v[48:49], v[72:73]
	v_pk_mul_f32 v[58:59], v[58:59], s[38:39] op_sel_hi:[1,0]
	v_pk_fma_f32 v[72:73], v[60:61], s[52:53], v[56:57] op_sel_hi:[1,0,0]
	v_exp_f32_e32 v58, v58
	v_exp_f32_e32 v59, v59
	v_pk_fma_f32 v[72:73], v[60:61], v[72:73], s[56:57] op_sel_hi:[1,1,0]
	v_cmp_gt_f32_e64 s[0:1], 0, v36
	v_pk_fma_f32 v[72:73], v[60:61], v[72:73], s[62:63] op_sel_hi:[1,1,0]
	v_pk_fma_f32 v[38:39], v[22:23], v[38:39], v[48:49]
	v_pk_fma_f32 v[72:73], v[60:61], v[72:73], s[64:65] op_sel_hi:[1,1,0]
	v_pk_mul_f32 v[48:49], v[38:39], v[38:39]
	v_pk_mul_f32 v[60:61], v[60:61], v[72:73]
	v_pk_mul_f32 v[48:49], v[48:49], s[38:39] op_sel_hi:[1,0]
	v_pk_mul_f32 v[58:59], v[58:59], v[60:61]
	v_exp_f32_e32 v48, v48
	v_pk_mul_f32 v[60:61], v[36:37], v[58:59]
	v_pk_fma_f32 v[58:59], v[36:37], v[58:59], v[36:37] neg_lo:[1,0,0] neg_hi:[1,0,0]
	v_exp_f32_e32 v49, v49
	v_cndmask_b32_e64 v36, v58, v60, s[0:1]
	v_cmp_gt_f32_e64 s[0:1], 0, v37
	v_and_b32_e32 v58, 0x7fffffff, v38
	v_add_u32_e32 v136, v65, v50
	v_cndmask_b32_e64 v37, v59, v61, s[0:1]
	v_and_b32_e32 v59, 0x7fffffff, v39
	v_pk_fma_f32 v[58:59], v[58:59], s[42:43], 1.0 op_sel_hi:[1,0,0]
	v_cmp_gt_f32_e64 s[0:1], 0, v38
	v_rcp_f32_e32 v58, v58
	v_rcp_f32_e32 v59, v59
	v_pk_mul_f32 v[36:37], v[52:53], v[36:37]
	s_nop 1
	v_cvt_pk_bf16_f32 v36, v36, v37
	v_pk_fma_f32 v[56:57], v[58:59], s[52:53], v[56:57] op_sel_hi:[1,0,0]
	s_nop 1
	v_pk_fma_f32 v[56:57], v[58:59], v[56:57], s[56:57] op_sel_hi:[1,1,0]
	s_nop 0
	v_pk_fma_f32 v[56:57], v[58:59], v[56:57], s[62:63] op_sel_hi:[1,1,0]
	s_nop 0
	v_pk_fma_f32 v[56:57], v[58:59], v[56:57], s[64:65] op_sel_hi:[1,1,0]
	s_nop 0
	v_pk_mul_f32 v[56:57], v[58:59], v[56:57]
	s_nop 0
	v_pk_mul_f32 v[48:49], v[48:49], v[56:57]
	s_nop 0
	v_pk_mul_f32 v[56:57], v[38:39], v[48:49]
	v_pk_fma_f32 v[48:49], v[38:39], v[48:49], v[38:39] neg_lo:[1,0,0] neg_hi:[1,0,0]
	s_nop 0
	v_cndmask_b32_e64 v38, v48, v56, s[0:1]
	v_cmp_gt_f32_e64 s[0:1], 0, v39
	s_nop 1
	v_cndmask_b32_e64 v39, v49, v57, s[0:1]
	v_pk_mul_f32 v[38:39], v[54:55], v[38:39]
	s_nop 1
	v_cvt_pk_bf16_f32 v37, v38, v39
	v_lshl_add_u64 v[38:39], v[136:137], 1, s[26:27]
	global_store_dwordx2 v[38:39], v[36:37], off
	v_lshlrev_b32_e32 v36, 16, v92
	v_and_b32_e32 v37, 0xffff0000, v92
	v_lshlrev_b32_e32 v38, 16, v93
	v_and_b32_e32 v39, 0xffff0000, v93
	s_nop 1
	v_mov_b32_dpp v48, v36 row_ror:1 row_mask:0xf bank_mask:0xf
	v_mov_b32_dpp v49, v37 row_ror:1 row_mask:0xf bank_mask:0xf
	v_mov_b32_dpp v52, v38 row_ror:1 row_mask:0xf bank_mask:0xf
	v_mov_b32_dpp v53, v39 row_ror:1 row_mask:0xf bank_mask:0xf
	v_mov_b32_dpp v54, v36 row_ror:2 row_mask:0xf bank_mask:0xf
	v_mov_b32_dpp v56, v37 row_ror:2 row_mask:0xf bank_mask:0xf
	v_mov_b32_dpp v55, v38 row_ror:2 row_mask:0xf bank_mask:0xf
	v_mov_b32_dpp v57, v39 row_ror:2 row_mask:0xf bank_mask:0xf
	s_and_saveexec_b64 s[0:1], vcc
	s_cbranch_execz .LBB0_589
	v_add_u32_e32 v136, v50, v51
	v_lshl_add_u64 v[58:59], v[136:137], 2, s[28:29]
	global_store_dwordx4 v[58:59], v[36:39], off

; #define LAS __attribute__((address_space(3)))
; __device__ __forceinline__ float rms_r(float ss) { return __builtin_amdgcn_rsqf(ss * (1.0f / DM) + RMS_EPS); }
; #define LDS_BAR() do { asm volatile("s_waitcnt lgkmcnt(0)" ::: "memory"); __builtin_amdgcn_s_barrier(); asm volatile("" ::: "memory"); } while (0)
; #define RET_STAGE(Kd, Vd) do { _Pragma("unroll") for (int uu = 0; uu < 4; ++uu) { const int c8 = lc8 + 8 * uu; *(LAS u32x4*)(Ql + ls * 264 + 8 * c8) = pq[uu]; *(LAS u32x4*)((Kd) + ls * 264 + 8 * c8) = pkv[uu]; } \
;         _Pragma("unroll") for (int uu = 0; uu < 2; ++uu) { const int c8 = lc8 + 8 * uu; *(LAS u32x4*)((Vd) + ls * 136 + 8 * c8) = pv[uu]; } } while (0)
; __device__ __forceinline__ void ret_unit(LAS unsigned char* lds, bf16_t* QKV, float* gn, int b, int h, int vs, bool commit, const float* s00p, const float* ss3, bool skel = false) {
;     const int tid = threadIdx.x, lane = tid & 63, w = tid >> 6, fr = lane & 15, fq = lane >> 4;
;     LAS bf16_t* Kb = (LAS bf16_t*)lds;
;     LAS bf16_t* Ql = Kb + 2 * 64 * 264;
;     LAS bf16_t* Vb = Ql + 64 * 264;
;     LAS bf16_t* Pl = Vb + 2 * 64 * 136;
;     LAS float* st = (LAS float*)(Pl + 64 * 72);
;     const float l2g = __builtin_amdgcn_logf(1.0f - __builtin_amdgcn_exp2f(-5.0f - (float)h));
;     const float cd = __builtin_amdgcn_exp2f(64.f * l2g);
;     f32x4 state[16];
; #pragma unroll
;     for (int m = 0; m < 16; ++m) state[m] = (f32x4){0.f, 0.f, 0.f, 0.f};
;     const float s00 = s00p[b * 4 + h] * rms_r(ss3[(size_t)b * SEQ]) * rms_r(ss3[(size_t)b * SEQ]) * 0.0625f;
;     const int si = w & 3, ti0 = 2 * (w >> 2);
;     u32x4 pq[4], pkv[4], pv[2];
;     const int ls = tid & 63, lc8 = tid >> 6;
;     ...
;     RET_LOAD(0);
;     LDS_BAR();
;     RET_STAGE(Kb, Vb);
;     RET_LOAD(1);
;     if (tid < 128) st[tid] = 0.f;
;     LDS_BAR();
.LBB0_1130:
	v_readlane_b32 s52, v254, 6
	s_cmp_lt_i32 s52, 10
	s_cselect_b64 s[6:7], -1, 0
	s_add_u32 s0, s50, 0x180000
	s_addc_u32 s1, s51, 0
	s_and_b64 s[34:35], s[6:7], s[4:5]
	s_xor_b64 s[4:5], s[34:35], -1
	s_cmpk_gt_i32 s2, 0xff
	s_cselect_b64 s[6:7], -1, 0
	s_or_b64 s[4:5], s[4:5], s[6:7]
	v_readlane_b32 s53, v254, 7
	v_readlane_b32 s54, v254, 8
	v_readlane_b32 s55, v254, 9
	s_and_b64 vcc, exec, s[4:5]
	s_cbranch_vccnz .LBB0_1160
	v_and_b32_e32 v128, 63, v176
	s_add_u32 s33, s50, 0x60000
	v_mul_u32_u24_e32 v2, 0x108, v128
	s_addc_u32 s70, s51, 0
	v_bfe_u32 v3, v176, 6, 2
	s_add_i32 s38, 0, 0x10800
	v_lshlrev_b32_e32 v4, 1, v2
	v_lshlrev_b32_e32 v2, 4, v224
	v_and_b32_e32 v130, 15, v176
	v_add3_u32 v129, s38, v4, v2
	v_add3_u32 v131, 0, v4, v2
	v_mul_u32_u24_e32 v4, 0x110, v128
	s_add_i32 s8, 0, 0x18c00
	v_lshlrev_b32_e32 v6, 4, v3
	s_waitcnt lgkmcnt(0)
	v_bfe_u32 v1, v176, 4, 2
	v_add3_u32 v135, s8, v4, v2
	v_or_b32_e32 v4, v6, v130
	s_waitcnt vmcnt(0)
	v_lshlrev_b32_e32 v10, 5, v224
	v_and_b32_e32 v12, 1, v176
	v_mul_u32_u24_e32 v163, 0x210, v4
	v_lshlrev_b32_e32 v4, 2, v1
	v_add_u32_e32 v11, s8, v10
	v_lshlrev_b32_e32 v132, 2, v12
	v_lshrrev_b32_e32 v12, 3, v176
	s_movk_i32 s8, 0x60
	v_lshlrev_b32_e32 v5, 2, v176
	s_add_i32 s71, 0, 0x23800
	v_lshlrev_b32_e32 v164, 3, v1
	v_and_b32_e32 v7, 48, v176
	v_or_b32_e32 v1, v6, v4
	v_and_or_b32 v12, v12, s8, v130
	v_add_u32_e32 v162, s71, v5
	s_movk_i32 s42, 0x210
	v_add_u32_e32 v8, s38, v7
	s_add_i32 s9, 0, 0x21400
	v_lshlrev_b32_e32 v6, 5, v3
	v_and_b32_e32 v5, 12, v5
	v_or_b32_e32 v14, 16, v12
	v_or_b32_e32 v15, 2, v1
	v_or_b32_e32 v16, 3, v1
	v_add3_u32 v6, s9, v6, v164
	v_lshlrev_b32_e32 v165, 1, v5
	v_add_u32_e32 v5, s9, v7
	v_mul_u32_u24_e32 v13, 0x210, v12
	v_mad_u32_u24 v167, v12, s42, v8
	v_cmp_lt_u32_e64 s[8:9], v12, v1
	v_cmp_gt_u32_e64 s[10:11], v12, v1
	v_cmp_lt_u32_e64 s[12:13], v12, v15
	v_cmp_lt_u32_e64 s[14:15], v12, v16
	v_or_b32_e32 v169, v12, v3
	v_mul_u32_u24_e32 v3, 0x90, v12
	v_cmp_lt_u32_e64 s[16:17], v14, v1
	v_cmp_gt_u32_e64 s[18:19], v14, v1
	v_cmp_lt_u32_e64 s[20:21], v14, v15
	v_cmp_lt_u32_e64 s[22:23], v14, v16
	v_mov_b32_e32 v12, 0x2100
	v_mov_b32_e32 v14, 0x4200
	v_mov_b32_e32 v15, 0x6300
	v_mul_u32_u24_e32 v1, 0x210, v130
	v_mad_u32_u24 v12, v130, s42, v12
	v_mad_u32_u24 v14, v130, s42, v14
	v_mad_u32_u24 v15, v130, s42, v15
	v_add3_u32 v170, s38, v1, v164
	v_add3_u32 v171, s38, v12, v164
	v_add3_u32 v172, s38, v14, v164
	v_add3_u32 v173, s38, v15, v164
	s_add_i32 s38, 0, 0x10880
	v_add3_u32 v174, s38, v1, v164
	v_add3_u32 v175, s38, v12, v164
	v_add3_u32 v177, s38, v14, v164
	v_add3_u32 v178, s38, v15, v164
	s_add_i32 s38, 0, 0x108c0
	v_add3_u32 v179, s38, v1, v164
	v_add3_u32 v180, s38, v12, v164
	v_add3_u32 v181, s38, v14, v164
	v_add3_u32 v182, s38, v15, v164
	s_add_i32 s38, 0, 0x10900
	v_add3_u32 v183, s38, v1, v164
	v_add3_u32 v184, s38, v12, v164
	v_add3_u32 v185, s38, v14, v164
	v_add3_u32 v186, s38, v15, v164
	s_add_i32 s38, 0, 0x10940
	v_bfe_u32 v9, v176, 2, 2
	v_add3_u32 v187, s38, v1, v164
	v_add3_u32 v188, s38, v12, v164
	v_add3_u32 v189, s38, v14, v164
	v_add3_u32 v190, s38, v15, v164
	s_add_i32 s38, 0, 0x10980
	v_lshlrev_b32_e32 v0, 3, v224
	v_or_b32_e32 v9, v164, v9
	v_lshrrev_b32_e32 v134, 1, v176
	v_add3_u32 v191, s38, v1, v164
	v_add3_u32 v192, s38, v12, v164
	v_add3_u32 v193, s38, v14, v164
	v_add3_u32 v194, s38, v15, v164
	s_add_i32 s38, 0, 0x109c0
	v_add3_u32 v201, 0, v163, v7
	v_lshlrev_b32_e32 v7, 13, v130
	v_mov_b32_e32 v133, 0
	s_movk_i32 s4, 0x80
	v_add3_u32 v195, s38, v1, v164
	v_add3_u32 v196, s38, v12, v164
	v_add3_u32 v197, s38, v14, v164
	v_add3_u32 v198, s38, v15, v164
	v_mul_u32_u24_e32 v1, 0x90, v130
	v_mul_u32_u24_e32 v12, 0x110, v9
	v_lshl_or_b32 v138, v128, 13, v2
	v_or3_b32 v142, v7, v10, v164
	v_lshlrev_b32_e32 v7, 5, v134
	s_mov_b32 s38, 0x180000
	v_lshlrev_b32_e32 v146, 1, v0
	v_mbcnt_lo_u32_b32 v0, -1, 0
	s_mov_b32 s39, 0
	v_cmp_gt_u32_e64 s[4:5], s4, v176
	v_cmp_gt_u32_e64 s[6:7], 16, v128
	v_lshlrev_b32_e32 v166, 3, v130
	v_lshl_add_u64 v[136:137], s[0:1], 0, v[132:133]
	v_add_u32_e32 v168, 0x2100, v167
	v_mul_u32_u24_e32 v199, 0x210, v9
	v_add3_u32 v200, v11, v165, v12
	v_mov_b32_e32 v139, v133
	v_or_b32_e32 v140, 0xe300800, v138
	v_mov_b32_e32 v141, v133
	v_mov_b32_e32 v143, v133
	s_lshl_b32 s73, s2, 4
	s_lshl_b32 s74, s54, 4
	v_or3_b32 v144, v7, v132, s38
	v_mov_b32_e32 v145, v133
	s_mov_b64 s[42:43], 0x41000
	s_movk_i32 s75, 0x1000
	s_mov_b64 s[52:53], 0x80000
	s_mov_b32 s76, 0x80000
	s_mov_b64 s[54:55], 0x81000
	v_mbcnt_hi_u32_b32 v202, -1, v0
	s_mov_b64 s[56:57], 0x800
	v_lshlrev_b32_e32 v132, 1, v2
	v_lshlrev_b32_e32 v148, 1, v4
	v_add_u32_e32 v203, v8, v13
	v_add_u32_e32 v204, v6, v3
	v_add_u32_e32 v205, v5, v1
	s_mov_b32 s77, s2
	s_mov_b32 s78, s2
	v_lshrrev_b32_e32 v129, 5, v176
	v_mul_u32_u24_e32 v129, 0x210, v129
	v_and_b32_e32 v255, 31, v176
	v_lshl_add_u32 v129, v255, 4, v129
	v_mov_b32_e32 v131, v129
	v_add_u32_e32 v129, 0x10800, v129
	v_lshrrev_b32_e32 v135, 4, v176
	v_mul_u32_u24_e32 v135, 0x110, v135
	v_lshl_add_u32 v135, v130, 4, v135
	v_add_u32_e32 v135, 0x18c00, v135
	v_lshrrev_b32_e32 v146, 5, v176
	v_lshlrev_b32_e32 v255, 4, v255
	v_lshl_or_b32 v146, v146, 13, v255
	v_or_b32_e32 v140, 0xe300800, v146
	v_lshrrev_b32_e32 v138, 4, v176
	v_lshlrev_b32_e32 v255, 4, v130
	v_lshl_or_b32 v138, v138, 13, v255
	s_mov_b64 s[84:85], 0x20000
	s_mov_b64 s[86:87], 0x40000
	v_and_b32_e32 v255, 16, v176
	v_lshlrev_b32_e32 v255, 4, v255
	v_and_b32_e32 v0, 32, v176
	v_lshl_or_b32 v255, v0, 2, v255
	v_lshl_or_b32 v255, v130, 3, v255
	v_add_u32_e32 v255, 0x23800, v255
	v_lshrrev_b32_e32 v129, 5, v176
	v_mul_u32_u24_e32 v129, 0x210, v129
	v_and_b32_e32 v0, 28, v176
	v_lshl_add_u32 v129, v0, 4, v129
	v_and_b32_e32 v0, 1, v176
	v_lshl_add_u32 v129, v0, 5, v129
	v_and_b32_e32 v0, 2, v176
	v_lshl_add_u32 v129, v0, 2, v129
	v_add_u32_e32 v129, 0x10800, v129
	v_mul_u32_u24_e32 v170, 0x210, v130
	v_lshl_add_u32 v170, v164, 1, v170
	v_add_u32_e32 v170, 0x10800, v170
	v_add_u32_e32 v201, 0x8400, v163
	v_add_u32_e32 v201, v201, v164
	s_branch .LBB0_1133

; __device__ __forceinline__ float rms_r(float ss) { return __builtin_amdgcn_rsqf(ss * (1.0f / DM) + RMS_EPS); }
; #define LDS_BAR() do { asm volatile("s_waitcnt lgkmcnt(0)" ::: "memory"); __builtin_amdgcn_s_barrier(); asm volatile("" ::: "memory"); } while (0)
; #define RET_STAGE(Kd, Vd) do { _Pragma("unroll") for (int uu = 0; uu < 4; ++uu) { const int c8 = lc8 + 8 * uu; *(LAS u32x4*)(Ql + ls * 264 + 8 * c8) = pq[uu]; *(LAS u32x4*)((Kd) + ls * 264 + 8 * c8) = pkv[uu]; } \
;         _Pragma("unroll") for (int uu = 0; uu < 2; ++uu) { const int c8 = lc8 + 8 * uu; *(LAS u32x4*)((Vd) + ls * 136 + 8 * c8) = pv[uu]; } } while (0)
; __device__ __forceinline__ void ret_unit(LAS unsigned char* lds, bf16_t* QKV, float* gn, int b, int h, int vs, bool commit, const float* s00p, const float* ss3, bool skel = false) {
;     ...
;     const float l2g = __builtin_amdgcn_logf(1.0f - __builtin_amdgcn_exp2f(-5.0f - (float)h));
;     const float cd = __builtin_amdgcn_exp2f(64.f * l2g);
;     f32x4 state[16];
; #pragma unroll
;     for (int m = 0; m < 16; ++m) state[m] = (f32x4){0.f, 0.f, 0.f, 0.f};
;     const float s00 = s00p[b * 4 + h] * rms_r(ss3[(size_t)b * SEQ]) * rms_r(ss3[(size_t)b * SEQ]) * 0.0625f;
;     const int si = w & 3, ti0 = 2 * (w >> 2);
;     u32x4 pq[4], pkv[4], pv[2];
;     const int ls = tid & 63, lc8 = tid >> 6;
;     ...
;     RET_LOAD(0);
;     LDS_BAR();
;     RET_STAGE(Kb, Vb);
;     RET_LOAD(1);
;     if (tid < 128) st[tid] = 0.f;
;     LDS_BAR();
.LBB0_1133:
	s_ashr_i32 s58, s78, 2
	s_and_b32 s38, s78, 4
	s_and_b32 s58, s58, -8
	s_or_b32 s38, s58, s38
	s_and_b32 s79, s78, 3
	s_or_b32 s58, s38, s79
	s_ashr_i32 s59, s58, 31
	s_ashr_i32 s64, s38, 2
	s_lshl_b64 s[58:59], s[58:59], 2
	s_add_u32 s62, s3, s58
	s_addc_u32 s63, s72, s59
	s_ashr_i32 s65, s64, 31
	s_lshl_b64 s[58:59], s[64:65], 11
	s_lshl_b64 s[68:69], s[64:65], 13
	s_add_u32 s68, s33, s68
	v_mov_b32_e32 v3, s59
	v_mov_b32_e32 v2, s58
	s_addc_u32 s69, s70, s69
	global_load_dword v0, v133, s[62:63]
	global_load_dword v1, v133, s[68:69]
	v_lshlrev_b64 v[2:3], 13, v[2:3]
	s_lshl_b32 s62, s78, 4
	v_lshl_add_u64 v[34:35], s[26:27], 0, v[2:3]
	s_lshl_b32 s38, s79, 9
	s_lshl_b32 s68, s79, 10
	s_mov_b32 s69, s39
	s_and_b32 s62, s62, 0x180
	v_lshl_add_u64 v[2:3], v[34:35], 0, s[38:39]
	s_lshl_b32 s62, s62, 1
	s_mov_b32 s63, s39
	v_lshl_add_u64 v[34:35], v[34:35], 0, s[68:69]
	v_mov_b32_e32 v147, v133
	v_lshl_add_u64 v[34:35], v[34:35], 0, s[62:63]
	v_lshl_add_u64 v[44:45], v[34:35], 0, v[138:139]
	v_add_co_u32_e32 v34, vcc, s75, v44
	v_lshl_add_u64 v[42:43], v[2:3], 0, v[146:147]
	v_lshl_add_u64 v[38:39], v[44:45], 0, s[42:43]
	v_addc_co_u32_e32 v35, vcc, 0, v45, vcc
	s_waitcnt lgkmcnt(0)
	v_lshl_add_u64 v[14:15], v[42:43], 0, s[84:85]
	v_lshl_add_u64 v[26:27], v[14:15], 0, s[84:85]
	v_lshl_add_u64 v[30:31], v[26:27], 0, s[84:85]
	global_load_dwordx4 v[2:5], v[42:43], off
	global_load_dwordx4 v[6:9], v[14:15], off
	global_load_dwordx4 v[10:13], v[42:43], off offset:2048
	global_load_dwordx4 v[14:17], v[14:15], off offset:2048
	global_load_dwordx4 v[18:21], v[26:27], off
	global_load_dwordx4 v[22:25], v[30:31], off
	global_load_dwordx4 v[26:29], v[26:27], off offset:2048
	global_load_dwordx4 v[30:33], v[30:31], off offset:2048
	global_load_dwordx4 v[34:37], v[34:35], off
	global_load_dwordx4 v[38:41], v[38:39], off
	s_waitcnt lgkmcnt(0)
	s_barrier
	v_lshl_add_u64 v[80:81], v[42:43], 0, s[52:53]
	v_lshl_add_u64 v[76:77], v[80:81], 0, s[84:85]
	v_lshl_add_u64 v[84:85], v[76:77], 0, s[84:85]
	v_lshl_add_u64 v[92:93], v[84:85], 0, s[84:85]
	global_load_dwordx4 v[64:67], v[76:77], off
	global_load_dwordx4 v[68:71], v[84:85], off
	global_load_dwordx4 v[72:75], v[80:81], off
	global_load_dwordx4 v[88:91], v[92:93], off
	global_load_dwordx4 v[76:79], v[76:77], off offset:2048
	global_load_dwordx4 v[84:87], v[84:85], off offset:2048
	global_load_dwordx4 v[80:83], v[80:81], off offset:2048
	global_load_dwordx4 v[92:95], v[92:93], off offset:2048
	v_lshl_add_u64 v[98:99], v[44:45], 0, s[54:55]
	v_lshl_add_u64 v[100:101], v[98:99], 0, s[86:87]
	global_load_dwordx4 v[96:99], v[98:99], off
	global_load_dwordx4 v[100:103], v[100:101], off
	s_waitcnt vmcnt(19)
	ds_write_b64 v129, v[2:3]
	ds_write_b64 v129, v[4:5] offset:16
	s_waitcnt vmcnt(17)
	ds_write_b128 v131, v[10:13]
	ds_write_b64 v129, v[6:7] offset:8448
	ds_write_b64 v129, v[8:9] offset:8464
	s_waitcnt vmcnt(16)
	ds_write_b128 v131, v[14:17] offset:8448
	s_waitcnt vmcnt(15)
	ds_write_b64 v129, v[18:19] offset:16896
	ds_write_b64 v129, v[20:21] offset:16912
	s_waitcnt vmcnt(13)
	ds_write_b128 v131, v[26:29] offset:16896
	ds_write_b64 v129, v[22:23] offset:25344
	ds_write_b64 v129, v[24:25] offset:25360
	s_waitcnt vmcnt(12)
	ds_write_b128 v131, v[30:33] offset:25344
	s_waitcnt vmcnt(11)
	ds_write_b128 v135, v[34:37]
	s_waitcnt vmcnt(10)
	ds_write_b128 v135, v[38:41] offset:8704
	s_and_saveexec_b64 s[68:69], s[4:5]
	ds_write_b32 v162, v133
	s_or_b64 exec, exec, s[68:69]
	v_cvt_f32_ubyte0_e32 v2, s79
	v_sub_f32_e32 v2, 0xc0a00000, v2
	v_exp_f32_e32 v2, v2
	v_mov_b32_e32 v3, 0x358637bd
	v_fmamk_f32 v1, v1, 0x3a800000, v3
	v_rsq_f32_e32 v1, v1
	v_sub_f32_e32 v2, 1.0, v2
	v_log_f32_e32 v2, v2
	s_and_b32 s63, s77, 3
	s_lshl_b32 s68, s73, 1
	s_lshl_b32 s80, s63, 9
	v_mul_f32_e32 v2, 0x42800000, v2
	s_and_b32 s83, s68, 0x300
	v_exp_f32_e32 v150, v2
	s_lshl_b64 s[68:69], s[64:65], 24
	s_lshl_b32 s82, s63, 10
	s_or_b32 s80, s68, s80
	s_mov_b32 s81, s69
	s_lshl_b32 s63, s63, 3
	v_mul_f32_e32 v0, v0, v1
	s_waitcnt lgkmcnt(0)
	s_barrier
	v_lshl_add_u64 v[154:155], s[80:81], 0, v[140:141]
	s_or_b32 s80, s83, s82
	s_lshl_b64 s[64:65], s[64:65], 16
	v_mul_f32_e32 v0, v1, v0
	s_or_b32 s68, s68, s80
	s_or_b32 s64, s64, s63
	v_mov_b32_e32 v40, 0
	v_mul_f32_e32 v147, 0x3d800000, v0
	v_mov_b32_e32 v152, v150
	v_mov_b32_e32 v153, v150
	v_lshl_add_u64 v[156:157], s[68:69], 0, v[142:143]
	v_lshl_add_u64 v[158:159], s[64:65], 0, v[144:145]
	v_lshl_add_u64 v[160:161], s[68:69], 0, v[138:139]
	s_mov_b32 s63, 0
	v_mov_b32_e32 v41, v40
	v_mov_b32_e32 v42, v40
	v_mov_b32_e32 v43, v40
	v_mov_b32_e32 v44, v40
	v_mov_b32_e32 v45, v40
	v_mov_b32_e32 v46, v40
	v_mov_b32_e32 v47, v40
	v_mov_b32_e32 v48, v40
	v_mov_b32_e32 v49, v40
	v_mov_b32_e32 v50, v40
	v_mov_b32_e32 v51, v40
	v_mov_b32_e32 v52, v40
	v_mov_b32_e32 v53, v40
	v_mov_b32_e32 v54, v40
	v_mov_b32_e32 v55, v40
	v_mov_b32_e32 v56, v40
	v_mov_b32_e32 v57, v40
	v_mov_b32_e32 v58, v40
	v_mov_b32_e32 v59, v40
	v_mov_b32_e32 v60, v40
	v_mov_b32_e32 v61, v40
	v_mov_b32_e32 v62, v40
	v_mov_b32_e32 v63, v40
	v_mov_b32_e32 v36, v40
	v_mov_b32_e32 v37, v40
	v_mov_b32_e32 v38, v40
	v_mov_b32_e32 v39, v40
	v_mov_b32_e32 v32, v40
	v_mov_b32_e32 v33, v40
	v_mov_b32_e32 v34, v40
	v_mov_b32_e32 v35, v40
	v_mov_b32_e32 v28, v40
	v_mov_b32_e32 v29, v40
	v_mov_b32_e32 v30, v40
	v_mov_b32_e32 v31, v40
	v_mov_b32_e32 v24, v40
	v_mov_b32_e32 v25, v40
	v_mov_b32_e32 v26, v40
	v_mov_b32_e32 v27, v40
	v_mov_b32_e32 v20, v40
	v_mov_b32_e32 v21, v40
	v_mov_b32_e32 v22, v40
	v_mov_b32_e32 v23, v40
	v_mov_b32_e32 v16, v40
	v_mov_b32_e32 v17, v40
	v_mov_b32_e32 v18, v40
	v_mov_b32_e32 v19, v40
	v_mov_b32_e32 v12, v40
	v_mov_b32_e32 v13, v40
	v_mov_b32_e32 v14, v40
	v_mov_b32_e32 v15, v40
	v_mov_b32_e32 v8, v40
	v_mov_b32_e32 v9, v40
	v_mov_b32_e32 v10, v40
	v_mov_b32_e32 v11, v40
	v_mov_b32_e32 v4, v40
	v_mov_b32_e32 v5, v40
	v_mov_b32_e32 v6, v40
	v_mov_b32_e32 v7, v40
	v_mov_b32_e32 v0, v40
	v_mov_b32_e32 v1, v40
	v_mov_b32_e32 v2, v40
	v_mov_b32_e32 v3, v40
	s_waitcnt vmcnt(0)
	s_branch .LBB0_1137

; #define LAS __attribute__((address_space(3)))
; __device__ __forceinline__ u32x2 pack4(f32x4 v) { return (u32x2){pk2(v[0], v[1]), pk2(v[2], v[3])}; }
; #define SB0 __builtin_amdgcn_sched_barrier(0)
; #define SB0 __builtin_amdgcn_sched_barrier(0)
; #define RA_LOAD(ks_) do { ka[(ks_) % 3] = *(const LAS bf16x8*)(Kl + (16 * si + fr) * 264 + 32 * (ks_) + 8 * fq); \
;               _Pragma("unroll") for (int tt = 0; tt < 2; ++tt) qb[(ks_) % 3][tt] = *(const LAS bf16x8*)(Ql + (16 * (ti0 + tt) + fr) * 264 + 32 * (ks_) + 8 * fq); } while (0)
; __device__ __forceinline__ void ret_unit(LAS unsigned char* lds, bf16_t* QKV, float* gn, int b, int h, int vs, bool commit, const float* s00p, const float* ss3, bool skel = false) {
;     ...
;         if (!skel) {
;         { f32x4 sv[2] = {(f32x4){0.f, 0.f, 0.f, 0.f}, (f32x4){0.f, 0.f, 0.f, 0.f}};
;           bf16x8 ka[3], qb[3][2];
;     ...
;           RA_LOAD(0); RA_LOAD(1); SB0;
; #pragma unroll
;           for (int ks = 0; ks < 8; ++ks) { if (ks + 2 < 8) RA_LOAD(ks + 2); SB0;
; #pragma unroll
;               for (int tt = 0; tt < 2; ++tt) sv[tt] = __builtin_amdgcn_mfma_f32_16x16x32_bf16(ka[ks % 3], qb[ks % 3][tt], sv[tt], 0, 0, 0);
;               SB0; }
;     ...
; #pragma unroll
;           for (int tt = 0; tt < 2; ++tt) { const int t = 16 * (ti0 + tt) + fr; f32x4 pvv;
; #pragma unroll
;               for (int r = 0; r < 4; ++r) { const int sidx = 16 * si + 4 * fq + r; pvv[r] = t >= sidx ? sv[tt][r] : 0.f; }
;               if (c == 0 && t == 0 && si == 0 && fq == 0) pvv[0] = s00;
;               *(LAS u32x2*)(Pl + t * 72 + 16 * si + 4 * fq) = pack4(pvv); } }
;         { u32x4 qf[3][4];
;     ...
;           RC_LOAD(0); RC_LOAD(1); SB0;
; #pragma unroll
;           for (int kk = 0; kk < 8; ++kk) { if (kk + 2 < 8) RC_LOAD(kk + 2);
;               const u32x2 s0 = pack4(state[2 * kk]), s1 = pack4(state[2 * kk + 1]);
;               const u32x4 aw = (u32x4){s0.x, s0.y, s1.x, s1.y}; const bf16x8 afrag = __builtin_bit_cast(bf16x8, aw);
;               SB0;
; #pragma unroll
;               for (int n = 0; n < 4; ++n) oacc[n] = __builtin_amdgcn_mfma_f32_16x16x32_bf16(afrag, __builtin_bit_cast(bf16x8, qf[kk % 3][n]), oacc[n], 0, 0, 0);
;               SB0; }
.LBB0_1137:
	s_and_b32 s65, s63, 1
	s_mul_i32 s64, s65, 0x8400
	s_add_i32 s64, s64, 0
	v_lshlrev_b32_e32 v104, 1, v164
	v_add3_u32 v149, s64, v163, v164
	ds_read_b128 v[104:107], v203
	s_waitcnt lgkmcnt(1)
	ds_read_b128 v[108:111], v203 offset:8448
	ds_read2_b64 v[112:115], v149 offset1:4
	ds_read2_b64 v[116:119], v149 offset0:8 offset1:12
	ds_read_b128 v[120:123], v167 offset:64
	ds_read_b128 v[124:127], v168 offset:64
	ds_read2_b64 v[206:209], v149 offset0:16 offset1:20
	ds_read_b128 v[210:213], v203 offset:128
	ds_read_b128 v[214:217], v203 offset:8576
	s_waitcnt lgkmcnt(6)
	v_mfma_f32_16x16x32_bf16 v[104:107], v[112:115], v[104:107], 0
	v_mfma_f32_16x16x32_bf16 v[108:111], v[112:115], v[108:111], 0
	ds_read2_b64 v[112:115], v149 offset0:24 offset1:28
	ds_read_b128 v[218:221], v203 offset:192
	ds_read_b128 v[222:225], v203 offset:8640
	s_waitcnt lgkmcnt(7)
	v_mfma_f32_16x16x32_bf16 v[104:107], v[116:119], v[120:123], v[104:107]
	s_waitcnt lgkmcnt(6)
	v_mfma_f32_16x16x32_bf16 v[108:111], v[116:119], v[124:127], v[108:111]
	ds_read2_b64 v[116:119], v149 offset0:32 offset1:36
	ds_read_b128 v[120:123], v203 offset:256
	ds_read_b128 v[124:127], v203 offset:8704
	s_waitcnt lgkmcnt(7)
	v_mfma_f32_16x16x32_bf16 v[104:107], v[206:209], v[210:213], v[104:107]
	s_waitcnt lgkmcnt(6)
	v_mfma_f32_16x16x32_bf16 v[108:111], v[206:209], v[214:217], v[108:111]
	ds_read2_b64 v[206:209], v149 offset0:40 offset1:44
	ds_read_b128 v[210:213], v203 offset:320
	ds_read_b128 v[214:217], v203 offset:8768
	s_waitcnt lgkmcnt(7)
	v_mfma_f32_16x16x32_bf16 v[104:107], v[112:115], v[218:221], v[104:107]
	s_waitcnt lgkmcnt(6)
	v_mfma_f32_16x16x32_bf16 v[108:111], v[112:115], v[222:225], v[108:111]
	ds_read2_b64 v[112:115], v149 offset0:48 offset1:52
	ds_read_b128 v[218:221], v203 offset:384
	ds_read_b128 v[222:225], v203 offset:8832
	s_waitcnt lgkmcnt(7)
	v_mfma_f32_16x16x32_bf16 v[104:107], v[116:119], v[120:123], v[104:107]
	s_waitcnt lgkmcnt(6)
	v_mfma_f32_16x16x32_bf16 v[108:111], v[116:119], v[124:127], v[108:111]
	ds_read2_b64 v[116:119], v149 offset0:56 offset1:60
	ds_read_b128 v[120:123], v203 offset:448
	ds_read_b128 v[124:127], v203 offset:8896
	s_waitcnt lgkmcnt(7)
	v_mfma_f32_16x16x32_bf16 v[104:107], v[206:209], v[210:213], v[104:107]
	s_waitcnt lgkmcnt(6)
	v_mfma_f32_16x16x32_bf16 v[108:111], v[206:209], v[214:217], v[108:111]
	s_waitcnt lgkmcnt(4)
	v_mfma_f32_16x16x32_bf16 v[104:107], v[112:115], v[218:221], v[104:107]
	s_waitcnt lgkmcnt(3)
	v_mfma_f32_16x16x32_bf16 v[108:111], v[112:115], v[222:225], v[108:111]
	s_waitcnt lgkmcnt(1)
	v_mfma_f32_16x16x32_bf16 v[104:107], v[116:119], v[120:123], v[104:107]
	s_waitcnt lgkmcnt(0)
	v_mfma_f32_16x16x32_bf16 v[108:111], v[116:119], v[124:127], v[108:111]
	v_or_b32_e32 v112, s63, v169
	v_cmp_eq_u32_e32 vcc, 0, v112
	s_nop 3
	v_cndmask_b32_e64 v104, v104, 0, s[8:9]
	s_and_b64 vcc, vcc, s[6:7]
	v_cndmask_b32_e64 v105, 0, v105, s[10:11]
	v_cndmask_b32_e32 v104, v104, v147, vcc
	v_cndmask_b32_e64 v106, v106, 0, s[12:13]
	v_cndmask_b32_e64 v107, v107, 0, s[14:15]
	v_cvt_pk_bf16_f32 v104, v104, v105
	v_cvt_pk_bf16_f32 v105, v106, v107
	ds_write_b64 v204, v[104:105]
	v_cndmask_b32_e64 v104, v108, 0, s[16:17]
	v_cndmask_b32_e64 v105, 0, v109, s[18:19]
	v_cndmask_b32_e64 v106, v110, 0, s[20:21]
	v_cndmask_b32_e64 v107, v111, 0, s[22:23]
	v_cvt_pk_bf16_f32 v104, v104, v105
	v_cvt_pk_bf16_f32 v105, v106, v107
	ds_write_b64 v204, v[104:105] offset:2304
	ds_read_b128 v[104:107], v170
	ds_read_b128 v[108:111], v170 offset:8448
	ds_read_b128 v[112:115], v170 offset:16896
	ds_read_b128 v[116:119], v170 offset:25344
	ds_read_b128 v[120:123], v170 offset:64
	ds_read_b128 v[124:127], v170 offset:8512
	ds_read_b128 v[206:209], v170 offset:16960
	ds_read_b128 v[210:213], v170 offset:25408
	ds_read_b128 v[214:217], v170 offset:128
	ds_read_b128 v[218:221], v170 offset:8576
	ds_read_b128 v[222:225], v170 offset:17024
	ds_read_b128 v[226:229], v170 offset:25472
	v_cvt_pk_bf16_f32 v230, v60, v61
	v_cvt_pk_bf16_f32 v231, v62, v63
	v_cvt_pk_bf16_f32 v232, v56, v57
	v_cvt_pk_bf16_f32 v233, v58, v59
	s_waitcnt lgkmcnt(11)
	v_mfma_f32_16x16x32_bf16 v[104:107], v[230:233], v[104:107], 0
	s_waitcnt lgkmcnt(10)
	v_mfma_f32_16x16x32_bf16 v[108:111], v[230:233], v[108:111], 0
	s_waitcnt lgkmcnt(9)
	v_mfma_f32_16x16x32_bf16 v[112:115], v[230:233], v[112:115], 0
	s_waitcnt lgkmcnt(8)
	v_mfma_f32_16x16x32_bf16 v[116:119], v[230:233], v[116:119], 0
	ds_read_b128 v[230:233], v170 offset:192
	ds_read_b128 v[234:237], v170 offset:8640
	ds_read_b128 v[238:241], v170 offset:17088
	ds_read_b128 v[242:245], v170 offset:25536
	v_cvt_pk_bf16_f32 v246, v52, v53
	v_cvt_pk_bf16_f32 v247, v54, v55
	v_cvt_pk_bf16_f32 v248, v48, v49
	v_cvt_pk_bf16_f32 v249, v50, v51
	s_waitcnt lgkmcnt(11)
	v_mfma_f32_16x16x32_bf16 v[104:107], v[246:249], v[120:123], v[104:107]
	s_waitcnt lgkmcnt(10)
	v_mfma_f32_16x16x32_bf16 v[108:111], v[246:249], v[124:127], v[108:111]
	s_waitcnt lgkmcnt(9)
	v_mfma_f32_16x16x32_bf16 v[112:115], v[246:249], v[206:209], v[112:115]
	s_waitcnt lgkmcnt(8)
	v_mfma_f32_16x16x32_bf16 v[116:119], v[246:249], v[210:213], v[116:119]
	ds_read_b128 v[120:123], v170 offset:256
	ds_read_b128 v[124:127], v170 offset:8704
	ds_read_b128 v[206:209], v170 offset:17152
	ds_read_b128 v[210:213], v170 offset:25600
	v_cvt_pk_bf16_f32 v246, v44, v45
	v_cvt_pk_bf16_f32 v247, v46, v47
	v_cvt_pk_bf16_f32 v248, v40, v41
	v_cvt_pk_bf16_f32 v249, v42, v43
	s_waitcnt lgkmcnt(11)
; __device__ __forceinline__ u32x2 pack4(f32x4 v) { return (u32x2){pk2(v[0], v[1]), pk2(v[2], v[3])}; }
; #define LDS_BAR() do { asm volatile("s_waitcnt lgkmcnt(0)" ::: "memory"); __builtin_amdgcn_s_barrier(); asm volatile("" ::: "memory"); } while (0)
; #define SB0 __builtin_amdgcn_sched_barrier(0)
; #define RET_STAGE(Kd, Vd) do { _Pragma("unroll") for (int uu = 0; uu < 4; ++uu) { const int c8 = lc8 + 8 * uu; *(LAS u32x4*)(Ql + ls * 264 + 8 * c8) = pq[uu]; *(LAS u32x4*)((Kd) + ls * 264 + 8 * c8) = pkv[uu]; } \
;         _Pragma("unroll") for (int uu = 0; uu < 2; ++uu) { const int c8 = lc8 + 8 * uu; *(LAS u32x4*)((Vd) + ls * 136 + 8 * c8) = pv[uu]; } } while (0)
; #define SB0 __builtin_amdgcn_sched_barrier(0)
; #define RC_LOAD(kk_) do { _Pragma("unroll") for (int n = 0; n < 4; ++n) { const u32x2 lo = *(const LAS u32x2*)(Ql + (16 * n + fr) * 264 + 32 * (kk_) + 4 * fq), hi = *(const LAS u32x2*)(Ql + (16 * n + fr) * 264 + 32 * (kk_) + 16 + 4 * fq); \
;               qf[(kk_) % 3][n] = (u32x4){lo.x, lo.y, hi.x, hi.y}; } } while (0)
; __device__ __forceinline__ void ret_unit(LAS unsigned char* lds, bf16_t* QKV, float* gn, int b, int h, int vs, bool commit, const float* s00p, const float* ss3, bool skel = false) {
;     ...
;           for (int kk = 0; kk < 8; ++kk) { if (kk + 2 < 8) RC_LOAD(kk + 2);
;               const u32x2 s0 = pack4(state[2 * kk]), s1 = pack4(state[2 * kk + 1]);
;               const u32x4 aw = (u32x4){s0.x, s0.y, s1.x, s1.y}; const bf16x8 afrag = __builtin_bit_cast(bf16x8, aw);
;               SB0;
; #pragma unroll
;               for (int n = 0; n < 4; ++n) oacc[n] = __builtin_amdgcn_mfma_f32_16x16x32_bf16(afrag, __builtin_bit_cast(bf16x8, qf[kk % 3][n]), oacc[n], 0, 0, 0);
;               SB0; }
;     ...
;         }
; #pragma unroll
;         for (int n = 0; n < 4; ++n) oacc[n] = oacc[n] * cd;
;         }
;         LDS_BAR();
;         if (c + 1 < 32) { RET_STAGE(Kn, Vn); if (c + 2 < 32) RET_LOAD(c + 2); }
	v_mfma_f32_16x16x32_bf16 v[104:107], v[246:249], v[214:217], v[104:107]
	s_waitcnt lgkmcnt(10)
	v_mfma_f32_16x16x32_bf16 v[108:111], v[246:249], v[218:221], v[108:111]
	s_waitcnt lgkmcnt(9)
	v_mfma_f32_16x16x32_bf16 v[112:115], v[246:249], v[222:225], v[112:115]
	s_waitcnt lgkmcnt(8)
	v_mfma_f32_16x16x32_bf16 v[116:119], v[246:249], v[226:229], v[116:119]
	ds_read_b128 v[214:217], v170 offset:320
	ds_read_b128 v[218:221], v170 offset:8768
	ds_read_b128 v[222:225], v170 offset:17216
	ds_read_b128 v[226:229], v170 offset:25664
	v_cvt_pk_bf16_f32 v246, v36, v37
	v_cvt_pk_bf16_f32 v247, v38, v39
	v_cvt_pk_bf16_f32 v248, v32, v33
	v_cvt_pk_bf16_f32 v249, v34, v35
	s_waitcnt lgkmcnt(11)
	v_mfma_f32_16x16x32_bf16 v[104:107], v[246:249], v[230:233], v[104:107]
	s_waitcnt lgkmcnt(10)
	v_mfma_f32_16x16x32_bf16 v[108:111], v[246:249], v[234:237], v[108:111]
	s_waitcnt lgkmcnt(9)
	v_mfma_f32_16x16x32_bf16 v[112:115], v[246:249], v[238:241], v[112:115]
	s_waitcnt lgkmcnt(8)
	v_mfma_f32_16x16x32_bf16 v[116:119], v[246:249], v[242:245], v[116:119]
	ds_read_b128 v[230:233], v170 offset:384
	ds_read_b128 v[234:237], v170 offset:8832
	ds_read_b128 v[238:241], v170 offset:17280
	ds_read_b128 v[242:245], v170 offset:25728
	v_cvt_pk_bf16_f32 v246, v28, v29
	v_cvt_pk_bf16_f32 v247, v30, v31
	v_cvt_pk_bf16_f32 v248, v24, v25
	v_cvt_pk_bf16_f32 v249, v26, v27
	s_waitcnt lgkmcnt(11)
	v_mfma_f32_16x16x32_bf16 v[104:107], v[246:249], v[120:123], v[104:107]
	s_waitcnt lgkmcnt(10)
	v_mfma_f32_16x16x32_bf16 v[108:111], v[246:249], v[124:127], v[108:111]
	s_waitcnt lgkmcnt(9)
	v_mfma_f32_16x16x32_bf16 v[112:115], v[246:249], v[206:209], v[112:115]
	s_waitcnt lgkmcnt(8)
	v_mfma_f32_16x16x32_bf16 v[116:119], v[246:249], v[210:213], v[116:119]
	ds_read_b128 v[120:123], v170 offset:448
	ds_read_b128 v[124:127], v170 offset:8896
	ds_read_b128 v[206:209], v170 offset:17344
	ds_read_b128 v[210:213], v170 offset:25792
	v_cvt_pk_bf16_f32 v246, v20, v21
	v_cvt_pk_bf16_f32 v247, v22, v23
	v_cvt_pk_bf16_f32 v248, v16, v17
	v_cvt_pk_bf16_f32 v249, v18, v19
	s_waitcnt lgkmcnt(11)
	v_mfma_f32_16x16x32_bf16 v[104:107], v[246:249], v[214:217], v[104:107]
	s_waitcnt lgkmcnt(10)
	v_mfma_f32_16x16x32_bf16 v[108:111], v[246:249], v[218:221], v[108:111]
	s_waitcnt lgkmcnt(9)
	v_mfma_f32_16x16x32_bf16 v[112:115], v[246:249], v[222:225], v[112:115]
	s_waitcnt lgkmcnt(8)
	v_mfma_f32_16x16x32_bf16 v[116:119], v[246:249], v[226:229], v[116:119]
	v_cvt_pk_bf16_f32 v214, v12, v13
	v_cvt_pk_bf16_f32 v215, v14, v15
	v_cvt_pk_bf16_f32 v216, v8, v9
	v_cvt_pk_bf16_f32 v217, v10, v11
	s_waitcnt lgkmcnt(7)
	v_mfma_f32_16x16x32_bf16 v[104:107], v[214:217], v[230:233], v[104:107]
	s_waitcnt lgkmcnt(6)
	v_mfma_f32_16x16x32_bf16 v[108:111], v[214:217], v[234:237], v[108:111]
	s_waitcnt lgkmcnt(5)
	v_mfma_f32_16x16x32_bf16 v[218:221], v[214:217], v[238:241], v[112:115]
	s_waitcnt lgkmcnt(4)
	v_mfma_f32_16x16x32_bf16 v[214:217], v[214:217], v[242:245], v[116:119]
	v_cvt_pk_bf16_f32 v222, v4, v5
	v_cvt_pk_bf16_f32 v223, v6, v7
	v_cvt_pk_bf16_f32 v224, v0, v1
	v_cvt_pk_bf16_f32 v225, v2, v3
	s_waitcnt lgkmcnt(3)
	v_mfma_f32_16x16x32_bf16 v[116:119], v[222:225], v[120:123], v[104:107]
	s_waitcnt lgkmcnt(2)
	v_mfma_f32_16x16x32_bf16 v[112:115], v[222:225], v[124:127], v[108:111]
	s_waitcnt lgkmcnt(1)
	v_mfma_f32_16x16x32_bf16 v[108:111], v[222:225], v[206:209], v[218:221]
	s_waitcnt lgkmcnt(0)
	v_mfma_f32_16x16x32_bf16 v[104:107], v[222:225], v[210:213], v[214:217]
	s_xor_b32 s68, s65, 1
	s_waitcnt lgkmcnt(0)
	s_barrier
	s_mul_i32 s69, s68, 0x8400
	s_mulk_i32 s68, 0x4400
	v_add_u32_e32 v120, s69, v131
	s_waitcnt vmcnt(7)
	ds_write_b64 v129, v[72:73]
	ds_write_b64 v129, v[74:75] offset:16
	ds_write_b128 v120, v[80:83]
	ds_write_b64 v129, v[64:65] offset:8448
	ds_write_b64 v129, v[66:67] offset:8464
	ds_write_b128 v120, v[76:79] offset:8448
	ds_write_b64 v129, v[68:69] offset:16896
	ds_write_b64 v129, v[70:71] offset:16912
	ds_write_b128 v120, v[84:87] offset:16896
	ds_write_b64 v129, v[88:89] offset:25344
	ds_write_b64 v129, v[90:91] offset:25360
	s_waitcnt vmcnt(6)
	ds_write_b128 v120, v[92:95] offset:25344
	v_add_u32_e32 v120, s68, v135
	s_cmp_gt_u32 s63, 29
	s_waitcnt vmcnt(5)
	ds_write_b128 v120, v[96:99]
	s_waitcnt vmcnt(4)
	ds_write_b128 v120, v[100:103] offset:8704
	s_cbranch_scc1 .LBB0_1139
	v_lshl_add_u64 v[80:81], s[50:51], 0, v[154:155]
	v_lshl_add_u64 v[76:77], v[80:81], 0, s[84:85]
	v_lshl_add_u64 v[84:85], v[76:77], 0, s[84:85]
	v_lshl_add_u64 v[92:93], v[84:85], 0, s[84:85]
	global_load_dwordx4 v[72:75], v[80:81], off offset:-2048
	global_load_dwordx4 v[64:67], v[76:77], off offset:-2048
	global_load_dwordx4 v[80:83], v[80:81], off
	global_load_dwordx4 v[76:79], v[76:77], off
	global_load_dwordx4 v[68:71], v[84:85], off offset:-2048
	global_load_dwordx4 v[88:91], v[92:93], off offset:-2048
	global_load_dwordx4 v[84:87], v[84:85], off
	global_load_dwordx4 v[92:95], v[92:93], off
	v_lshl_add_u64 v[96:97], s[50:51], 0, v[160:161]
	v_add_co_u32_e32 v98, vcc, 0xe301000, v96
	s_nop 1
	v_addc_co_u32_e32 v99, vcc, 0, v97, vcc
	v_lshl_add_u64 v[100:101], v[98:99], 0, s[86:87]
	global_load_dwordx4 v[96:99], v[98:99], off
	global_load_dwordx4 v[100:103], v[100:101], off

; __device__ __forceinline__ u32x2 pack4(f32x4 v) { return (u32x2){pk2(v[0], v[1]), pk2(v[2], v[3])}; }
; #define EPI_LOAD_RR(ssp) float rr[8]; _Pragma("unroll") for (int it = 0; it < 8; ++it) rr[it] = (ssp)[EPI_IT_ROW(it)]; _Pragma("unroll") for (int it = 0; it < 8; ++it) rr[it] = rms_r(rr[it])
;     __device__ __forceinline__ void operator()(AccRef acc, const Unit& u, int wr, int wc, int fr, int fq) const {
;     ...
;         const int j0 = u.pn * 128 + wc * 32 + 8 * fq;
;         u32x2 pa[2][2][4][2];
;         { EPI_LOAD_RR(ss);
; #pragma unroll
;           for (int it = 0; it < 8; ++it)
; #pragma unroll
;               for (int bj = 0; bj < 2; ++bj)
; #pragma unroll
;                   for (int n = 0; n < 2; ++n) pa[it >> 2][bj][it & 3][n] = pack4(acc[it >> 2][bj][it & 3][n] * rr[it]); }
.LBB0_1406:
	s_lshl_b32 s65, s6, 8
	v_mov_b32_e32 v166, v151
	v_mov_b32_e32 v185, v153
	s_add_i32 s65, s65, s63
	s_lshl_b32 s0, s0, 7
	v_add_u32_e32 v146, s65, v166
	v_ashrrev_i32_e32 v147, 31, v146
	v_lshl_add_u64 v[148:149], v[146:147], 2, s[18:19]
	global_load_dword v136, v[148:149], off
	v_add_u32_e32 v148, 16, v146
	v_add_u32_e32 v170, 32, v146
	v_ashrrev_i32_e32 v149, 31, v148
	v_ashrrev_i32_e32 v171, 31, v170
	v_add_u32_e32 v172, 48, v146
	v_add_u32_e32 v174, 0x80, v146
	v_add_u32_e32 v178, 0x90, v146
	v_add_u32_e32 v180, 0xa0, v146
	v_add_u32_e32 v182, 0xb0, v146
	v_lshl_add_u64 v[168:169], v[148:149], 2, s[18:19]
	v_lshl_add_u64 v[170:171], v[170:171], 2, s[18:19]
	v_ashrrev_i32_e32 v173, 31, v172
	v_ashrrev_i32_e32 v175, 31, v174
	v_ashrrev_i32_e32 v179, 31, v178
	v_ashrrev_i32_e32 v181, 31, v180
	v_ashrrev_i32_e32 v183, 31, v182
	v_lshl_add_u64 v[172:173], v[172:173], 2, s[18:19]
	v_lshl_add_u64 v[174:175], v[174:175], 2, s[18:19]
	v_lshl_add_u64 v[178:179], v[178:179], 2, s[18:19]
	v_lshl_add_u64 v[180:181], v[180:181], 2, s[18:19]
	v_lshl_add_u64 v[182:183], v[182:183], 2, s[18:19]
	global_load_dword v147, v[168:169], off
	global_load_dword v149, v[170:171], off
	global_load_dword v150, v[172:173], off
	global_load_dword v152, v[174:175], off
	global_load_dword v167, v[178:179], off
	s_nop 0
	global_load_dword v169, v[180:181], off
	global_load_dword v170, v[182:183], off
	s_or_b32 s0, s0, s76
	s_waitcnt vmcnt(0)
	v_fmamk_f32 v136, v136, 0x3a800000, v165
	v_rsq_f32_e32 v168, v136
	v_fmamk_f32 v136, v147, 0x3a800000, v165
	v_fmamk_f32 v147, v149, 0x3a800000, v165
	v_fmamk_f32 v149, v150, 0x3a800000, v165
	v_fmamk_f32 v150, v152, 0x3a800000, v165
	v_fmamk_f32 v152, v167, 0x3a800000, v165
	v_fmamk_f32 v167, v169, 0x3a800000, v165
	v_fmamk_f32 v169, v170, 0x3a800000, v165
	v_rsq_f32_e32 v170, v136
	v_rsq_f32_e32 v180, v147
	v_rsq_f32_e32 v184, v150
	v_rsq_f32_e32 v150, v167
	v_rsq_f32_e32 v182, v149
	v_rsq_f32_e32 v152, v152
	v_rsq_f32_e32 v136, v169
	v_pk_mul_f32 v[108:109], v[108:109], v[168:169] op_sel_hi:[1,0]
	v_pk_mul_f32 v[122:123], v[122:123], v[168:169] op_sel_hi:[1,0]
	v_pk_mul_f32 v[116:117], v[116:117], v[168:169] op_sel_hi:[1,0]
	v_pk_mul_f32 v[110:111], v[110:111], v[168:169] op_sel_hi:[1,0]
	v_cvt_pk_bf16_f32 v171, v122, v123
	v_cvt_pk_bf16_f32 v181, v116, v117
	v_cvt_pk_bf16_f32 v173, v108, v109
	v_pk_mul_f32 v[42:43], v[42:43], v[184:185] op_sel_hi:[1,0]
	v_pk_mul_f32 v[108:109], v[114:115], v[170:171] op_sel_hi:[1,0]
	v_pk_mul_f32 v[104:105], v[104:105], v[170:171] op_sel_hi:[1,0]
	v_pk_mul_f32 v[80:81], v[80:81], v[180:181] op_sel_hi:[1,0]
	v_pk_mul_f32 v[72:73], v[72:73], v[180:181] op_sel_hi:[1,0]
	v_pk_mul_f32 v[10:11], v[10:11], v[150:151] op_sel_hi:[1,0]
	v_pk_mul_f32 v[8:9], v[8:9], v[150:151] op_sel_hi:[1,0]
	v_pk_mul_f32 v[118:119], v[118:119], v[168:169] op_sel_hi:[1,0]
	v_cvt_pk_bf16_f32 v174, v110, v111
	v_pk_mul_f32 v[110:111], v[112:113], v[170:171] op_sel_hi:[1,0]
	v_cvt_pk_bf16_f32 v183, v118, v119
	v_pk_mul_f32 v[106:107], v[106:107], v[170:171] op_sel_hi:[1,0]
	v_pk_mul_f32 v[98:99], v[98:99], v[170:171] op_sel_hi:[1,0]
	v_pk_mul_f32 v[96:97], v[96:97], v[170:171] op_sel_hi:[1,0]
	v_pk_mul_f32 v[90:91], v[90:91], v[170:171] op_sel_hi:[1,0]
	v_pk_mul_f32 v[88:89], v[88:89], v[170:171] op_sel_hi:[1,0]
	v_pk_mul_f32 v[112:113], v[94:95], v[180:181] op_sel_hi:[1,0]
	v_pk_mul_f32 v[114:115], v[92:93], v[180:181] op_sel_hi:[1,0]
	v_cvt_pk_bf16_f32 v93, v108, v109
	v_cvt_pk_bf16_f32 v170, v104, v105
	v_pk_mul_f32 v[82:83], v[82:83], v[180:181] op_sel_hi:[1,0]
	v_cvt_pk_bf16_f32 v95, v80, v81
	v_pk_mul_f32 v[74:75], v[74:75], v[180:181] op_sel_hi:[1,0]
	v_cvt_pk_bf16_f32 v80, v72, v73
	v_pk_mul_f32 v[72:73], v[86:87], v[182:183] op_sel_hi:[1,0]
	v_pk_mul_f32 v[40:41], v[40:41], v[184:185] op_sel_hi:[1,0]
	v_cvt_pk_bf16_f32 v105, v42, v43
	v_pk_mul_f32 v[42:43], v[52:53], v[152:153] op_sel_hi:[1,0]
	v_pk_mul_f32 v[26:27], v[26:27], v[152:153] op_sel_hi:[1,0]
	v_pk_mul_f32 v[24:25], v[24:25], v[152:153] op_sel_hi:[1,0]
	v_cvt_pk_bf16_f32 v108, v8, v9
	v_cvt_pk_bf16_f32 v109, v10, v11
	v_pk_mul_f32 v[8:9], v[22:23], v[136:137] op_sel_hi:[1,0]
	v_pk_mul_f32 v[10:11], v[20:21], v[136:137] op_sel_hi:[1,0]
	v_pk_mul_f32 v[126:127], v[126:127], v[168:169] op_sel_hi:[1,0]
	v_pk_mul_f32 v[124:125], v[124:125], v[168:169] op_sel_hi:[1,0]
	v_pk_mul_f32 v[120:121], v[120:121], v[168:169] op_sel_hi:[1,0]
	v_pk_mul_f32 v[102:103], v[102:103], v[180:181] op_sel_hi:[1,0]
	v_pk_mul_f32 v[100:101], v[100:101], v[180:181] op_sel_hi:[1,0]
	v_cvt_pk_bf16_f32 v169, v106, v107
	v_cvt_pk_bf16_f32 v168, v112, v113
	v_cvt_pk_bf16_f32 v178, v82, v83
	v_cvt_pk_bf16_f32 v81, v74, v75
	v_pk_mul_f32 v[74:75], v[84:85], v[182:183] op_sel_hi:[1,0]
	v_cvt_pk_bf16_f32 v83, v72, v73
	v_pk_mul_f32 v[72:73], v[78:79], v[182:183] op_sel_hi:[1,0]
	v_pk_mul_f32 v[50:51], v[50:51], v[184:185] op_sel_hi:[1,0]
	v_pk_mul_f32 v[48:49], v[48:49], v[184:185] op_sel_hi:[1,0]
	v_cvt_pk_bf16_f32 v104, v40, v41
	v_pk_mul_f32 v[40:41], v[54:55], v[152:153] op_sel_hi:[1,0]
	v_cvt_pk_bf16_f32 v116, v42, v43
	v_pk_mul_f32 v[42:43], v[44:45], v[152:153] op_sel_hi:[1,0]
	v_cvt_pk_bf16_f32 v106, v24, v25
	v_cvt_pk_bf16_f32 v107, v26, v27
	v_pk_mul_f32 v[24:25], v[38:39], v[150:151] op_sel_hi:[1,0]
	v_pk_mul_f32 v[26:27], v[36:37], v[150:151] op_sel_hi:[1,0]
	v_cvt_pk_bf16_f32 v112, v10, v11
	v_cvt_pk_bf16_f32 v113, v8, v9
	v_pk_mul_f32 v[8:9], v[14:15], v[136:137] op_sel_hi:[1,0]
	v_pk_mul_f32 v[10:11], v[12:13], v[136:137] op_sel_hi:[1,0]
	v_pk_mul_f32 v[6:7], v[6:7], v[136:137] op_sel_hi:[1,0]
	v_pk_mul_f32 v[4:5], v[4:5], v[136:137] op_sel_hi:[1,0]
; __device__ __forceinline__ f32x4 ror1v(f32x4 v) { return (f32x4){dpp_ror1(v[0]), dpp_ror1(v[1]), dpp_ror1(v[2]), dpp_ror1(v[3])}; }
; __device__ __forceinline__ f32x4 ror2v(f32x4 v) { return (f32x4){dpp_ror2(v[0]), dpp_ror2(v[1]), dpp_ror2(v[2]), dpp_ror2(v[3])}; }
; __device__ __forceinline__ u32x2 pack4(f32x4 v) { return (u32x2){pk2(v[0], v[1]), pk2(v[2], v[3])}; }
; __device__ __forceinline__ f32x4 unpack4(u32x2 w) { return (f32x4){bflo(w.x), bfhi(w.x), bflo(w.y), bfhi(w.y)}; }
; #define EPI_LOAD_RR(ssp) float rr[8]; _Pragma("unroll") for (int it = 0; it < 8; ++it) rr[it] = (ssp)[EPI_IT_ROW(it)]; _Pragma("unroll") for (int it = 0; it < 8; ++it) rr[it] = rms_r(rr[it])
;     __device__ __forceinline__ void operator()(AccRef acc, const Unit& u, int wr, int wc, int fr, int fq) const {
;     ...
;         { EPI_LOAD_RR(ss);
; #pragma unroll
;           for (int it = 0; it < 8; ++it)
; #pragma unroll
;               for (int bj = 0; bj < 2; ++bj)
; #pragma unroll
;                   for (int n = 0; n < 2; ++n) pa[it >> 2][bj][it & 3][n] = pack4(acc[it >> 2][bj][it & 3][n] * rr[it]); }
;         __builtin_amdgcn_sched_barrier(0);
; #pragma unroll
;         for (int ai = 0; ai < 2; ++ai) {
;             const int rowg = u.pm * 256 + ai * 128 + wr * 64; const int grp = rowg >> 6;
; #pragma unroll
;             for (int n = 0; n < 2; ++n) { const unsigned jn = (unsigned)(j0 + 4 * n);
;                 f32x4 cu[4];
;                 {
;                     const f32x4 wu0 = *(const f32x4*)(cw + (DFF + jn)), wu1 = *(const f32x4*)(cw + (UPN + DFF + jn)), wu2 = *(const f32x4*)(cw + (2 * UPN + DFF + jn)), bu = *(const f32x4*)(cb + (DFF + jn));
;                     f32x4 pu1 = (f32x4){0.f, 0.f, 0.f, 0.f}, pu2 = pu1;
; #pragma unroll
;                     for (int m = 0; m < 4; ++m) {
;                         const f32x4 au = unpack4(pa[ai][1][m][n]);
;                         const f32x4 ru1 = ror1v(au), ru2 = ror2v(au);
;                         const f32x4 u1 = fr >= 1 ? ru1 : pu1, u2 = fr >= 2 ? ru2 : pu2;
;                         if (m == 0 && fr < 2) *(f32x4*)(edge + (unsigned)((grp * 4 + fr) * UPN + DFF + jn)) = au;
;                         if (m == 3 && fr >= 14) *(f32x4*)(edge + (unsigned)((grp * 4 + (fr - 12)) * UPN + DFF + jn)) = au;
;                         cu[m] = bu + wu0 * u2 + wu1 * u1 + wu2 * au;
;                         pu1 = ru1; pu2 = ru2; }
	v_pk_mul_f32 v[2:3], v[2:3], v[136:137] op_sel_hi:[1,0]
	v_pk_mul_f32 v[0:1], v[0:1], v[136:137] op_sel_hi:[1,0]
	v_lshl_add_u32 v44, v185, 3, s0
	v_cvt_pk_bf16_f32 v190, v124, v125
	v_cvt_pk_bf16_f32 v189, v126, v127
	v_cvt_pk_bf16_f32 v172, v120, v121
	v_cvt_pk_bf16_f32 v94, v110, v111
	v_cvt_pk_bf16_f32 v179, v96, v97
	v_cvt_pk_bf16_f32 v177, v98, v99
	v_cvt_pk_bf16_f32 v89, v88, v89
	v_cvt_pk_bf16_f32 v88, v90, v91
	v_cvt_pk_bf16_f32 v92, v100, v101
	v_cvt_pk_bf16_f32 v91, v102, v103
	v_cvt_pk_bf16_f32 v167, v114, v115
	v_cvt_pk_bf16_f32 v82, v74, v75
	v_pk_mul_f32 v[74:75], v[76:77], v[182:183] op_sel_hi:[1,0]
	v_cvt_pk_bf16_f32 v149, v72, v73
	v_pk_mul_f32 v[72:73], v[70:71], v[182:183] op_sel_hi:[1,0]
	v_cvt_pk_bf16_f32 v147, v74, v75
	v_pk_mul_f32 v[68:69], v[68:69], v[182:183] op_sel_hi:[1,0]
	v_cvt_pk_bf16_f32 v71, v72, v73
	v_pk_mul_f32 v[66:67], v[66:67], v[182:183] op_sel_hi:[1,0]
	v_cvt_pk_bf16_f32 v70, v68, v69
	v_pk_mul_f32 v[64:65], v[64:65], v[182:183] op_sel_hi:[1,0]
	v_cvt_pk_bf16_f32 v79, v66, v67
	v_pk_mul_f32 v[62:63], v[62:63], v[184:185] op_sel_hi:[1,0]
	v_cvt_pk_bf16_f32 v78, v64, v65
	v_pk_mul_f32 v[60:61], v[60:61], v[184:185] op_sel_hi:[1,0]
	v_cvt_pk_bf16_f32 v119, v62, v63
	v_pk_mul_f32 v[58:59], v[58:59], v[184:185] op_sel_hi:[1,0]
	v_cvt_pk_bf16_f32 v118, v60, v61
	v_pk_mul_f32 v[56:57], v[56:57], v[184:185] op_sel_hi:[1,0]
	v_cvt_pk_bf16_f32 v103, v58, v59
	v_cvt_pk_bf16_f32 v120, v48, v49
	v_cvt_pk_bf16_f32 v121, v50, v51
	v_cvt_pk_bf16_f32 v117, v40, v41
	v_pk_mul_f32 v[40:41], v[46:47], v[152:153] op_sel_hi:[1,0]
	v_cvt_pk_bf16_f32 v102, v56, v57
	v_cvt_pk_bf16_f32 v100, v42, v43
	v_pk_mul_f32 v[34:35], v[34:35], v[152:153] op_sel_hi:[1,0]
	v_cvt_pk_bf16_f32 v101, v40, v41
	v_pk_mul_f32 v[32:33], v[32:33], v[152:153] op_sel_hi:[1,0]
	v_cvt_pk_bf16_f32 v123, v34, v35
	v_cvt_pk_bf16_f32 v114, v26, v27
	v_cvt_pk_bf16_f32 v115, v24, v25
	v_pk_mul_f32 v[24:25], v[30:31], v[150:151] op_sel_hi:[1,0]
	v_cvt_pk_bf16_f32 v122, v32, v33
	v_pk_mul_f32 v[26:27], v[28:29], v[150:151] op_sel_hi:[1,0]
	v_cvt_pk_bf16_f32 v99, v24, v25
	v_pk_mul_f32 v[18:19], v[18:19], v[150:151] op_sel_hi:[1,0]
	v_cvt_pk_bf16_f32 v98, v26, v27
	v_pk_mul_f32 v[16:17], v[16:17], v[150:151] op_sel_hi:[1,0]
	v_cvt_pk_bf16_f32 v125, v18, v19
	v_cvt_pk_bf16_f32 v96, v10, v11
	v_cvt_pk_bf16_f32 v97, v8, v9
	v_cvt_pk_bf16_f32 v126, v4, v5
	v_cvt_pk_bf16_f32 v127, v6, v7
	s_nop 0
	v_cvt_pk_bf16_f32 v124, v16, v17
	v_cvt_pk_bf16_f32 v110, v0, v1
	v_cvt_pk_bf16_f32 v111, v2, v3
	v_add_u32_e32 v136, 0xb00, v44
	v_lshlrev_b64 v[12:13], 2, v[136:137]
	v_add_u32_e32 v136, 0x2100, v44
	v_lshl_add_u64 v[50:51], v[136:137], 2, s[20:21]
	v_add_u32_e32 v136, 0x3700, v44
	v_lshl_add_u64 v[48:49], s[20:21], 0, v[12:13]
	v_lshl_add_u64 v[52:53], v[136:137], 2, s[20:21]
	v_lshl_add_u64 v[54:55], s[22:23], 0, v[12:13]
	global_load_dwordx4 v[8:11], v[48:49], off
	global_load_dwordx4 v[0:3], v[50:51], off
	global_load_dwordx4 v[4:7], v[52:53], off
	global_load_dwordx4 v[12:15], v[54:55], off
	s_ashr_i32 s6, s65, 4
	v_add_u32_e32 v16, s6, v166
	v_mul_lo_u32 v175, v16, s85
	v_lshlrev_b32_e32 v36, 16, v181
	v_and_b32_e32 v37, 0xffff0000, v181
	v_lshlrev_b32_e32 v38, 16, v183
	v_and_b32_e32 v39, 0xffff0000, v183
	s_nop 1
	v_cmp_lt_i32_e64 s[10:11], 1, v166
	v_cmp_gt_i32_e64 s[12:13], 2, v166
	v_add_u32_e32 v84, 0xb00, v175
	v_mov_b32_dpp v191, v36 row_ror:1 row_mask:0xf bank_mask:0xf
	v_mov_b32_dpp v194, v37 row_ror:1 row_mask:0xf bank_mask:0xf
	v_mov_b32_dpp v192, v38 row_ror:1 row_mask:0xf bank_mask:0xf
	v_mov_b32_dpp v196, v39 row_ror:1 row_mask:0xf bank_mask:0xf
	v_mov_b32_dpp v193, v36 row_ror:2 row_mask:0xf bank_mask:0xf
	v_mov_b32_dpp v197, v37 row_ror:2 row_mask:0xf bank_mask:0xf
	v_mov_b32_dpp v201, v38 row_ror:2 row_mask:0xf bank_mask:0xf
	v_mov_b32_dpp v204, v39 row_ror:2 row_mask:0xf bank_mask:0xf
	s_and_saveexec_b64 s[0:1], s[12:13]
	s_cbranch_execz .LBB0_1408
	v_add_u32_e32 v136, v84, v44
	v_lshl_add_u64 v[16:17], v[136:137], 2, s[28:29]
	global_store_dwordx4 v[16:17], v[36:39], off
.LBB0_1408:
	s_or_b64 exec, exec, s[0:1]
	v_add_u32_e32 v150, -12, v166
	v_add_u32_e32 v16, s6, v150
	v_mul_lo_u32 v152, v16, s85
	v_lshlrev_b32_e32 v68, 16, v179
	v_and_b32_e32 v69, 0xffff0000, v179
	v_lshlrev_b32_e32 v66, 16, v177
	v_and_b32_e32 v67, 0xffff0000, v177
	s_nop 1
	v_lshlrev_b32_e32 v60, 16, v95
	v_and_b32_e32 v61, 0xffff0000, v95
	v_lshlrev_b32_e32 v46, 16, v178
	v_and_b32_e32 v47, 0xffff0000, v178
	s_nop 1
	v_lshlrev_b32_e32 v16, 16, v70
	v_and_b32_e32 v17, 0xffff0000, v70
	v_lshlrev_b32_e32 v18, 16, v71
	v_and_b32_e32 v19, 0xffff0000, v71
	s_nop 1
	v_cmp_lt_i32_e32 vcc, 13, v166
	v_add_u32_e32 v90, 0xb00, v152
	v_mov_b32_dpp v195, v68 row_ror:1 row_mask:0xf bank_mask:0xf
	v_mov_b32_dpp v200, v69 row_ror:1 row_mask:0xf bank_mask:0xf
	v_mov_b32_dpp v198, v66 row_ror:1 row_mask:0xf bank_mask:0xf
	v_mov_b32_dpp v202, v67 row_ror:1 row_mask:0xf bank_mask:0xf
	v_mov_b32_dpp v199, v68 row_ror:2 row_mask:0xf bank_mask:0xf
	v_mov_b32_dpp v203, v69 row_ror:2 row_mask:0xf bank_mask:0xf
	v_mov_b32_dpp v205, v66 row_ror:2 row_mask:0xf bank_mask:0xf
	v_mov_b32_dpp v206, v67 row_ror:2 row_mask:0xf bank_mask:0xf
	v_mov_b32_dpp v85, v60 row_ror:1 row_mask:0xf bank_mask:0xf
	v_mov_b32_dpp v95, v61 row_ror:1 row_mask:0xf bank_mask:0xf
	v_mov_b32_dpp v86, v46 row_ror:1 row_mask:0xf bank_mask:0xf
	v_mov_b32_dpp v177, v47 row_ror:1 row_mask:0xf bank_mask:0xf
	v_mov_b32_dpp v87, v60 row_ror:2 row_mask:0xf bank_mask:0xf
	v_mov_b32_dpp v178, v61 row_ror:2 row_mask:0xf bank_mask:0xf
	v_mov_b32_dpp v179, v46 row_ror:2 row_mask:0xf bank_mask:0xf
	v_mov_b32_dpp v180, v47 row_ror:2 row_mask:0xf bank_mask:0xf
	v_mov_b32_dpp v181, v16 row_ror:1 row_mask:0xf bank_mask:0xf
	v_mov_b32_dpp v184, v17 row_ror:1 row_mask:0xf bank_mask:0xf
	v_mov_b32_dpp v182, v18 row_ror:1 row_mask:0xf bank_mask:0xf
	v_mov_b32_dpp v185, v19 row_ror:1 row_mask:0xf bank_mask:0xf
	v_mov_b32_dpp v183, v16 row_ror:2 row_mask:0xf bank_mask:0xf
	v_mov_b32_dpp v186, v17 row_ror:2 row_mask:0xf bank_mask:0xf
	v_mov_b32_dpp v187, v18 row_ror:2 row_mask:0xf bank_mask:0xf
	v_mov_b32_dpp v188, v19 row_ror:2 row_mask:0xf bank_mask:0xf
	s_and_saveexec_b64 s[0:1], vcc
	s_cbranch_execz .LBB0_1410
	v_add_u32_e32 v136, v90, v44
	v_lshl_add_u64 v[20:21], v[136:137], 2, s[28:29]
	global_store_dwordx4 v[20:21], v[16:19], off
; __device__ __forceinline__ f32x4 gelu4(f32x4 v) { const f32x2 a = gelu_pk((f32x2){v[0], v[1]}), b = gelu_pk((f32x2){v[2], v[3]}); return (f32x4){a.x, a.y, b.x, b.y}; }
; __device__ __forceinline__ f32x4 ror1v(f32x4 v) { return (f32x4){dpp_ror1(v[0]), dpp_ror1(v[1]), dpp_ror1(v[2]), dpp_ror1(v[3])}; }
; __device__ __forceinline__ f32x4 ror2v(f32x4 v) { return (f32x4){dpp_ror2(v[0]), dpp_ror2(v[1]), dpp_ror2(v[2]), dpp_ror2(v[3])}; }
; __device__ __forceinline__ u32x2 pack4(f32x4 v) { return (u32x2){pk2(v[0], v[1]), pk2(v[2], v[3])}; }
; __device__ __forceinline__ f32x2 gelu_pk(f32x2 v) {
;     const f32x2 av = __builtin_elementwise_abs(v), d = av * 0.2316418882f + 1.0f;
;     f32x2 t; t.x = __builtin_amdgcn_rcpf(d.x); t.y = __builtin_amdgcn_rcpf(d.y);
;     f32x2 q = t * 0.5307027145f + (-0.7265760135f); q = q * t + 0.7107068705f; q = q * t + (-0.142248368f); q = q * t + 0.127414796f; q = q * t;
;     const f32x2 s = (v * v) * (-0.72134752044f);
;     f32x2 e; e.x = __builtin_amdgcn_exp2f(s.x); e.y = __builtin_amdgcn_exp2f(s.y);
;     const f32x2 m = v * (q * e), r = v - m;
;     f32x2 o; o.x = v.x < 0.f ? m.x : r.x; o.y = v.y < 0.f ? m.y : r.y; return o;
; }
;     __device__ __forceinline__ void operator()(AccRef acc, const Unit& u, int wr, int wc, int fr, int fq) const {
;     ...
;                 {
;                     const f32x4 wg0 = *(const f32x4*)(cw + jn), wg1 = *(const f32x4*)(cw + (UPN + jn)), wg2 = *(const f32x4*)(cw + (2 * UPN + jn)), bg = *(const f32x4*)(cb + jn);
;                     f32x4 pg1 = (f32x4){0.f, 0.f, 0.f, 0.f}, pg2 = pg1;
; #pragma unroll
;                     for (int m = 0; m < 4; ++m) { const int row = rowg + m * 16 + fr;
;                         const f32x4 ag = unpack4(pa[ai][0][m][n]);
;                         const f32x4 rg1 = ror1v(ag), rg2 = ror2v(ag);
;                         const f32x4 g1 = fr >= 1 ? rg1 : pg1, g2 = fr >= 2 ? rg2 : pg2;
;                         if (m == 0 && fr < 2) *(f32x4*)(edge + (unsigned)((grp * 4 + fr) * UPN + jn)) = ag;
;                         if (m == 3 && fr >= 14) *(f32x4*)(edge + (unsigned)((grp * 4 + (fr - 12)) * UPN + jn)) = ag;
;                         const f32x4 o = gelu4(bg + wg0 * g2 + wg1 * g1 + wg2 * ag) * cu[m];
;                         if (!(m == 0 && fr < 2)) *(u32x2*)(act + (unsigned)(row * DFF + jn)) = pack4(o);
;                         pg1 = rg1; pg2 = rg2; }
.LBB0_1410:
	s_or_b64 exec, exec, s[0:1]
	v_mov_b32_e32 v45, v137
	v_add_u32_e32 v136, 0x1600, v44
	v_lshlrev_b64 v[32:33], 2, v[44:45]
	v_lshl_add_u64 v[58:59], v[136:137], 2, s[20:21]
	v_add_u32_e32 v136, 0x2c00, v44
	v_lshl_add_u64 v[56:57], s[20:21], 0, v[32:33]
	v_lshl_add_u64 v[62:63], v[136:137], 2, s[20:21]
	v_lshl_add_u64 v[64:65], s[22:23], 0, v[32:33]
	global_load_dwordx4 v[28:31], v[56:57], off
	global_load_dwordx4 v[20:23], v[58:59], off
	global_load_dwordx4 v[24:27], v[62:63], off
	global_load_dwordx4 v[32:35], v[64:65], off
	v_lshlrev_b32_e32 v40, 16, v190
	v_and_b32_e32 v41, 0xffff0000, v190
	v_lshlrev_b32_e32 v42, 16, v189
	v_and_b32_e32 v43, 0xffff0000, v189
	s_nop 1
	v_cmp_lt_i32_e64 s[8:9], 0, v166
	v_cmp_lt_i32_e64 s[6:7], 1, v166
	v_mov_b32_dpp v70, v40 row_ror:1 row_mask:0xf bank_mask:0xf
	v_mov_b32_dpp v71, v41 row_ror:1 row_mask:0xf bank_mask:0xf
	v_mov_b32_dpp v72, v42 row_ror:1 row_mask:0xf bank_mask:0xf
	v_mov_b32_dpp v73, v43 row_ror:1 row_mask:0xf bank_mask:0xf
	v_mov_b32_dpp v74, v40 row_ror:2 row_mask:0xf bank_mask:0xf
	v_mov_b32_dpp v75, v41 row_ror:2 row_mask:0xf bank_mask:0xf
	v_mov_b32_dpp v76, v42 row_ror:2 row_mask:0xf bank_mask:0xf
	v_mov_b32_dpp v77, v43 row_ror:2 row_mask:0xf bank_mask:0xf
	s_and_saveexec_b64 s[0:1], s[10:11]
	s_xor_b64 s[74:75], exec, s[0:1]
	s_cbranch_execz .LBB0_1412
	v_cndmask_b32_e64 v213, 0, v204, s[6:7]
	v_cndmask_b32_e64 v212, 0, v201, s[6:7]
	v_cndmask_b32_e64 v211, 0, v196, s[8:9]
	v_cndmask_b32_e64 v210, 0, v192, s[8:9]
	s_waitcnt vmcnt(4)
	v_pk_fma_f32 v[212:213], v[10:11], v[212:213], v[14:15]
	v_cndmask_b32_e64 v215, 0, v197, s[6:7]
	v_pk_fma_f32 v[210:211], v[2:3], v[210:211], v[212:213]
	v_cndmask_b32_e64 v214, 0, v193, s[6:7]
	v_pk_fma_f32 v[38:39], v[6:7], v[38:39], v[210:211]
	s_waitcnt vmcnt(0)
	v_pk_fma_f32 v[210:211], v[28:29], v[74:75], v[32:33]
	v_cndmask_b32_e64 v209, 0, v194, s[8:9]
	v_pk_fma_f32 v[210:211], v[20:21], v[70:71], v[210:211]
	v_cndmask_b32_e64 v208, 0, v191, s[8:9]
	v_pk_fma_f32 v[40:41], v[24:25], v[40:41], v[210:211]
	v_pk_fma_f32 v[214:215], v[8:9], v[214:215], v[12:13]
	v_and_b32_e32 v213, 0x7fffffff, v41
	v_and_b32_e32 v212, 0x7fffffff, v40
	v_pk_fma_f32 v[212:213], v[212:213], s[52:53], 1.0 op_sel_hi:[1,0,0]
	v_pk_fma_f32 v[208:209], v[0:1], v[208:209], v[214:215]
	v_rcp_f32_e32 v212, v212
	v_rcp_f32_e32 v213, v213
	v_pk_mul_f32 v[210:211], v[40:41], v[40:41]
	v_mov_b64_e32 v[214:215], s[56:57]
	v_pk_mul_f32 v[210:211], v[210:211], s[42:43] op_sel_hi:[1,0]
	v_pk_fma_f32 v[216:217], v[212:213], s[54:55], v[214:215] op_sel_hi:[1,0,0]
	v_exp_f32_e32 v210, v210
	v_exp_f32_e32 v211, v211
	v_pk_fma_f32 v[216:217], v[212:213], v[216:217], s[58:59] op_sel_hi:[1,1,0]
	v_pk_fma_f32 v[36:37], v[4:5], v[36:37], v[208:209]
	v_pk_fma_f32 v[216:217], v[212:213], v[216:217], s[60:61] op_sel_hi:[1,1,0]
	v_pk_fma_f32 v[208:209], v[30:31], v[76:77], v[34:35]
	v_pk_fma_f32 v[216:217], v[212:213], v[216:217], s[62:63] op_sel_hi:[1,1,0]
	v_pk_fma_f32 v[208:209], v[22:23], v[72:73], v[208:209]
	v_pk_mul_f32 v[212:213], v[212:213], v[216:217]
	v_cmp_gt_f32_e64 s[0:1], 0, v40
	v_pk_mul_f32 v[210:211], v[210:211], v[212:213]
	v_pk_fma_f32 v[42:43], v[26:27], v[42:43], v[208:209]
	v_pk_mul_f32 v[212:213], v[40:41], v[210:211]
	v_pk_fma_f32 v[210:211], v[40:41], v[210:211], v[40:41] neg_lo:[1,0,0] neg_hi:[1,0,0]
	v_pk_mul_f32 v[208:209], v[42:43], v[42:43]
	v_cndmask_b32_e64 v40, v210, v212, s[0:1]
	v_cmp_gt_f32_e64 s[0:1], 0, v41
	v_and_b32_e32 v210, 0x7fffffff, v42
	v_pk_mul_f32 v[208:209], v[208:209], s[42:43] op_sel_hi:[1,0]
	v_cndmask_b32_e64 v41, v211, v213, s[0:1]
	v_and_b32_e32 v211, 0x7fffffff, v43
	v_pk_fma_f32 v[210:211], v[210:211], s[52:53], 1.0 op_sel_hi:[1,0,0]
	v_exp_f32_e32 v208, v208
	v_rcp_f32_e32 v210, v210
	v_rcp_f32_e32 v211, v211
	v_exp_f32_e32 v209, v209
	v_cmp_gt_f32_e64 s[0:1], 0, v42
	v_pk_mul_f32 v[36:37], v[36:37], v[40:41]
	v_pk_fma_f32 v[212:213], v[210:211], s[54:55], v[214:215] op_sel_hi:[1,0,0]
	v_cvt_pk_bf16_f32 v36, v36, v37
	s_nop 0
	v_pk_fma_f32 v[212:213], v[210:211], v[212:213], s[58:59] op_sel_hi:[1,1,0]
	s_nop 0
	v_pk_fma_f32 v[212:213], v[210:211], v[212:213], s[60:61] op_sel_hi:[1,1,0]
	s_nop 0
	v_pk_fma_f32 v[212:213], v[210:211], v[212:213], s[62:63] op_sel_hi:[1,1,0]
	s_nop 0
	v_pk_mul_f32 v[210:211], v[210:211], v[212:213]
	s_nop 0
	v_pk_mul_f32 v[208:209], v[208:209], v[210:211]
	s_nop 0
	v_pk_mul_f32 v[210:211], v[42:43], v[208:209]
	v_pk_fma_f32 v[208:209], v[42:43], v[208:209], v[42:43] neg_lo:[1,0,0] neg_hi:[1,0,0]
	s_nop 0
	v_cndmask_b32_e64 v42, v208, v210, s[0:1]
	v_cmp_gt_f32_e64 s[0:1], 0, v43
	s_nop 1
	v_cndmask_b32_e64 v43, v209, v211, s[0:1]
	v_pk_mul_f32 v[38:39], v[38:39], v[42:43]
	s_nop 0
	v_cvt_pk_bf16_f32 v37, v38, v39
	v_mad_u64_u32 v[38:39], s[0:1], v146, s86, v[44:45]
	v_mov_b32_e32 v39, v137
	v_lshl_add_u64 v[38:39], v[38:39], 1, s[26:27]
	global_store_dwordx2 v[38:39], v[36:37], off

;     __device__ __forceinline__ void operator()(AccRef acc, const Unit& u, int wr, int wc, int fr, int fq) const {
;     ...
;             for (int n = 0; n < 2; ++n) { const unsigned jn = (unsigned)(j0 + 4 * n);
;                 f32x4 cu[4];
;                 {
;                     const f32x4 wu0 = *(const f32x4*)(cw + (DFF + jn)), wu1 = *(const f32x4*)(cw + (UPN + DFF + jn)), wu2 = *(const f32x4*)(cw + (2 * UPN + DFF + jn)), bu = *(const f32x4*)(cb + (DFF + jn));
;                     f32x4 pu1 = (f32x4){0.f, 0.f, 0.f, 0.f}, pu2 = pu1;
; #pragma unroll
;                     for (int m = 0; m < 4; ++m) {
;                         const f32x4 au = unpack4(pa[ai][1][m][n]);
;                         const f32x4 ru1 = ror1v(au), ru2 = ror2v(au);
;                         const f32x4 u1 = fr >= 1 ? ru1 : pu1, u2 = fr >= 2 ? ru2 : pu2;
;                         if (m == 0 && fr < 2) *(f32x4*)(edge + (unsigned)((grp * 4 + fr) * UPN + DFF + jn)) = au;
;                         if (m == 3 && fr >= 14) *(f32x4*)(edge + (unsigned)((grp * 4 + (fr - 12)) * UPN + DFF + jn)) = au;
;                         cu[m] = bu + wu0 * u2 + wu1 * u1 + wu2 * au;
;                         pu1 = ru1; pu2 = ru2; }
;                 }
;                 {
;                     const f32x4 wg0 = *(const f32x4*)(cw + jn), wg1 = *(const f32x4*)(cw + (UPN + jn)), wg2 = *(const f32x4*)(cw + (2 * UPN + jn)), bg = *(const f32x4*)(cb + jn);
;                     f32x4 pg1 = (f32x4){0.f, 0.f, 0.f, 0.f}, pg2 = pg1;
; #pragma unroll
;                     for (int m = 0; m < 4; ++m) { const int row = rowg + m * 16 + fr;
;                         const f32x4 ag = unpack4(pa[ai][0][m][n]);
;                         const f32x4 rg1 = ror1v(ag), rg2 = ror2v(ag);
;                         const f32x4 g1 = fr >= 1 ? rg1 : pg1, g2 = fr >= 2 ? rg2 : pg2;
;                         if (m == 0 && fr < 2) *(f32x4*)(edge + (unsigned)((grp * 4 + fr) * UPN + jn)) = ag;
;                         if (m == 3 && fr >= 14) *(f32x4*)(edge + (unsigned)((grp * 4 + (fr - 12)) * UPN + jn)) = ag;
;                         const f32x4 o = gelu4(bg + wg0 * g2 + wg1 * g1 + wg2 * ag) * cu[m];
;                         if (!(m == 0 && fr < 2)) *(u32x2*)(act + (unsigned)(row * DFF + jn)) = pack4(o);
;                         pg1 = rg1; pg2 = rg2; }
.LBB0_1414:
	s_or_b64 exec, exec, s[0:1]
	s_nop 0
	v_cndmask_b32_e64 v41, v204, v206, s[6:7]
	v_cndmask_b32_e64 v40, v201, v205, s[6:7]
	v_cndmask_b32_e64 v43, v197, v203, s[6:7]
	v_cndmask_b32_e64 v42, v193, v199, s[6:7]
	v_cndmask_b32_e64 v37, v194, v200, s[8:9]
	v_cndmask_b32_e64 v36, v191, v195, s[8:9]
	v_cndmask_b32_e64 v39, v196, v202, s[8:9]
	v_cndmask_b32_e64 v38, v192, v198, s[8:9]
	s_waitcnt vmcnt(4)
	v_pk_fma_f32 v[42:43], v[8:9], v[42:43], v[12:13]
	v_pk_fma_f32 v[40:41], v[10:11], v[40:41], v[14:15]
	v_pk_fma_f32 v[36:37], v[0:1], v[36:37], v[42:43]
	v_pk_fma_f32 v[38:39], v[2:3], v[38:39], v[40:41]
	v_pk_fma_f32 v[36:37], v[4:5], v[68:69], v[36:37]
	v_pk_fma_f32 v[38:39], v[6:7], v[66:67], v[38:39]
	v_cndmask_b32_e64 v67, v206, v180, s[6:7]
	v_cndmask_b32_e64 v66, v205, v179, s[6:7]
	v_cndmask_b32_e64 v69, v203, v178, s[6:7]
	v_cndmask_b32_e64 v68, v199, v87, s[6:7]
	v_cndmask_b32_e64 v41, v200, v95, s[8:9]
	v_cndmask_b32_e64 v40, v195, v85, s[8:9]
	v_cndmask_b32_e64 v43, v202, v177, s[8:9]
	v_cndmask_b32_e64 v42, v198, v86, s[8:9]
	v_pk_fma_f32 v[68:69], v[8:9], v[68:69], v[12:13]
	v_pk_fma_f32 v[66:67], v[10:11], v[66:67], v[14:15]
	v_pk_fma_f32 v[40:41], v[0:1], v[40:41], v[68:69]
	v_pk_fma_f32 v[42:43], v[2:3], v[42:43], v[66:67]
	v_pk_fma_f32 v[66:67], v[4:5], v[60:61], v[40:41]
	v_pk_fma_f32 v[68:69], v[6:7], v[46:47], v[42:43]
	v_lshlrev_b32_e32 v40, 16, v94
	v_and_b32_e32 v41, 0xffff0000, v94
	v_lshlrev_b32_e32 v42, 16, v93
	v_and_b32_e32 v43, 0xffff0000, v93
	v_mov_b32_e32 v93, v137
	v_mov_b32_e32 v94, v137
	v_mov_b32_e32 v191, v137
	v_mov_b32_e32 v192, v137
	v_mov_b32_dpp v93, v40 row_ror:1 row_mask:0xf bank_mask:0xf
	v_mov_b32_dpp v94, v41 row_ror:1 row_mask:0xf bank_mask:0xf
	v_mov_b32_dpp v191, v40 row_ror:2 row_mask:0xf bank_mask:0xf
	v_mov_b32_dpp v192, v41 row_ror:2 row_mask:0xf bank_mask:0xf
	v_cndmask_b32_e64 v61, v71, v94, s[8:9]
	v_cndmask_b32_e64 v60, v70, v93, s[8:9]
	v_cndmask_b32_e64 v71, v75, v192, s[6:7]
	v_cndmask_b32_e64 v70, v74, v191, s[6:7]
	s_waitcnt vmcnt(0)
	v_pk_fma_f32 v[70:71], v[28:29], v[70:71], v[32:33]
	v_mov_b32_e32 v189, v137
	v_pk_fma_f32 v[60:61], v[20:21], v[60:61], v[70:71]
	v_mov_b32_e32 v190, v137
	v_pk_fma_f32 v[40:41], v[24:25], v[40:41], v[60:61]
	v_mov_b32_e32 v193, v137
	v_and_b32_e32 v71, 0x7fffffff, v41
	v_and_b32_e32 v70, 0x7fffffff, v40
	v_mov_b32_e32 v194, v137
	v_pk_fma_f32 v[70:71], v[70:71], s[52:53], 1.0 op_sel_hi:[1,0,0]
	v_mov_b32_dpp v189, v42 row_ror:1 row_mask:0xf bank_mask:0xf
	v_mov_b32_dpp v190, v43 row_ror:1 row_mask:0xf bank_mask:0xf
	v_mov_b32_dpp v193, v42 row_ror:2 row_mask:0xf bank_mask:0xf
	v_mov_b32_dpp v194, v43 row_ror:2 row_mask:0xf bank_mask:0xf
	v_rcp_f32_e32 v70, v70
	v_rcp_f32_e32 v71, v71
	v_cndmask_b32_e64 v47, v73, v190, s[8:9]
	v_cndmask_b32_e64 v46, v72, v189, s[8:9]
	v_cndmask_b32_e64 v73, v77, v194, s[6:7]
	v_cndmask_b32_e64 v72, v76, v193, s[6:7]
	v_pk_fma_f32 v[72:73], v[30:31], v[72:73], v[34:35]
	v_pk_mul_f32 v[60:61], v[40:41], v[40:41]
	v_pk_fma_f32 v[46:47], v[22:23], v[46:47], v[72:73]
	v_mov_b64_e32 v[72:73], s[56:57]
	v_pk_mul_f32 v[60:61], v[60:61], s[42:43] op_sel_hi:[1,0]
	v_pk_fma_f32 v[74:75], v[70:71], s[54:55], v[72:73] op_sel_hi:[1,0,0]
	v_exp_f32_e32 v60, v60
	v_exp_f32_e32 v61, v61
	v_pk_fma_f32 v[74:75], v[70:71], v[74:75], s[58:59] op_sel_hi:[1,1,0]
	v_cmp_gt_f32_e64 s[0:1], 0, v40
	v_pk_fma_f32 v[74:75], v[70:71], v[74:75], s[60:61] op_sel_hi:[1,1,0]
	v_pk_fma_f32 v[42:43], v[26:27], v[42:43], v[46:47]
	v_pk_fma_f32 v[74:75], v[70:71], v[74:75], s[62:63] op_sel_hi:[1,1,0]
	v_pk_mul_f32 v[46:47], v[42:43], v[42:43]
	v_pk_mul_f32 v[70:71], v[70:71], v[74:75]
	v_pk_mul_f32 v[46:47], v[46:47], s[42:43] op_sel_hi:[1,0]
	v_pk_mul_f32 v[60:61], v[60:61], v[70:71]
	v_exp_f32_e32 v46, v46
	v_pk_mul_f32 v[70:71], v[40:41], v[60:61]
	v_pk_fma_f32 v[60:61], v[40:41], v[60:61], v[40:41] neg_lo:[1,0,0] neg_hi:[1,0,0]
	v_exp_f32_e32 v47, v47
	v_cndmask_b32_e64 v40, v60, v70, s[0:1]
	v_cmp_gt_f32_e64 s[0:1], 0, v41
	v_and_b32_e32 v60, 0x7fffffff, v42
	v_mul_lo_u32 v45, v148, s86
	v_cndmask_b32_e64 v41, v61, v71, s[0:1]
	v_and_b32_e32 v61, 0x7fffffff, v43
	v_pk_fma_f32 v[60:61], v[60:61], s[52:53], 1.0 op_sel_hi:[1,0,0]
	v_cmp_gt_f32_e64 s[0:1], 0, v42
	v_rcp_f32_e32 v60, v60
	v_rcp_f32_e32 v61, v61
	v_pk_mul_f32 v[36:37], v[36:37], v[40:41]
	v_add_u32_e32 v136, v45, v44
	v_cvt_pk_bf16_f32 v36, v36, v37
	v_pk_fma_f32 v[70:71], v[60:61], s[54:55], v[72:73] op_sel_hi:[1,0,0]
	s_nop 1
	v_pk_fma_f32 v[70:71], v[60:61], v[70:71], s[58:59] op_sel_hi:[1,1,0]
	s_nop 1
	v_pk_fma_f32 v[70:71], v[60:61], v[70:71], s[60:61] op_sel_hi:[1,1,0]
	v_add_u32_e32 v148, 0xb000, v45
	v_pk_fma_f32 v[70:71], v[60:61], v[70:71], s[62:63] op_sel_hi:[1,1,0]
	s_nop 0
	v_pk_mul_f32 v[60:61], v[60:61], v[70:71]
	s_nop 0
	v_pk_mul_f32 v[46:47], v[46:47], v[60:61]
	s_nop 0
	v_pk_mul_f32 v[60:61], v[42:43], v[46:47]
	v_pk_fma_f32 v[46:47], v[42:43], v[46:47], v[42:43] neg_lo:[1,0,0] neg_hi:[1,0,0]
	s_nop 0
	v_cndmask_b32_e64 v42, v46, v60, s[0:1]
	v_cmp_gt_f32_e64 s[0:1], 0, v43
	s_nop 1
	v_cndmask_b32_e64 v43, v47, v61, s[0:1]
	v_pk_mul_f32 v[38:39], v[38:39], v[42:43]
	s_nop 1
	v_cvt_pk_bf16_f32 v37, v38, v39
	v_lshl_add_u64 v[38:39], v[136:137], 1, s[26:27]
	global_store_dwordx2 v[38:39], v[36:37], off
	v_lshlrev_b32_e32 v36, 16, v92
	v_and_b32_e32 v37, 0xffff0000, v92
	v_lshlrev_b32_e32 v38, 16, v91
	v_mov_b32_dpp v43, v36 row_ror:2 row_mask:0xf bank_mask:0xf
	v_mov_b32_dpp v60, v37 row_ror:2 row_mask:0xf bank_mask:0xf
	v_mov_b32_dpp v40, v36 row_ror:1 row_mask:0xf bank_mask:0xf
	v_mov_b32_dpp v41, v37 row_ror:1 row_mask:0xf bank_mask:0xf
;     __device__ __forceinline__ void operator()(AccRef acc, const Unit& u, int wr, int wc, int fr, int fq) const {
;     ...
;             for (int n = 0; n < 2; ++n) { const unsigned jn = (unsigned)(j0 + 4 * n);
;                 f32x4 cu[4];
;                 {
;                     const f32x4 wu0 = *(const f32x4*)(cw + (DFF + jn)), wu1 = *(const f32x4*)(cw + (UPN + DFF + jn)), wu2 = *(const f32x4*)(cw + (2 * UPN + DFF + jn)), bu = *(const f32x4*)(cb + (DFF + jn));
;                     f32x4 pu1 = (f32x4){0.f, 0.f, 0.f, 0.f}, pu2 = pu1;
; #pragma unroll
;                     for (int m = 0; m < 4; ++m) {
;                         const f32x4 au = unpack4(pa[ai][1][m][n]);
;                         const f32x4 ru1 = ror1v(au), ru2 = ror2v(au);
;                         const f32x4 u1 = fr >= 1 ? ru1 : pu1, u2 = fr >= 2 ? ru2 : pu2;
;                         if (m == 0 && fr < 2) *(f32x4*)(edge + (unsigned)((grp * 4 + fr) * UPN + DFF + jn)) = au;
;                         if (m == 3 && fr >= 14) *(f32x4*)(edge + (unsigned)((grp * 4 + (fr - 12)) * UPN + DFF + jn)) = au;
;                         cu[m] = bu + wu0 * u2 + wu1 * u1 + wu2 * au;
;                         pu1 = ru1; pu2 = ru2; }
;                 }
;                 {
;                     const f32x4 wg0 = *(const f32x4*)(cw + jn), wg1 = *(const f32x4*)(cw + (UPN + jn)), wg2 = *(const f32x4*)(cw + (2 * UPN + jn)), bg = *(const f32x4*)(cb + jn);
;                     f32x4 pg1 = (f32x4){0.f, 0.f, 0.f, 0.f}, pg2 = pg1;
; #pragma unroll
;                     for (int m = 0; m < 4; ++m) { const int row = rowg + m * 16 + fr;
;                         const f32x4 ag = unpack4(pa[ai][0][m][n]);
;                         const f32x4 rg1 = ror1v(ag), rg2 = ror2v(ag);
;                         const f32x4 g1 = fr >= 1 ? rg1 : pg1, g2 = fr >= 2 ? rg2 : pg2;
;                         if (m == 0 && fr < 2) *(f32x4*)(edge + (unsigned)((grp * 4 + fr) * UPN + jn)) = ag;
;                         if (m == 3 && fr >= 14) *(f32x4*)(edge + (unsigned)((grp * 4 + (fr - 12)) * UPN + jn)) = ag;
;                         const f32x4 o = gelu4(bg + wg0 * g2 + wg1 * g1 + wg2 * ag) * cu[m];
;                         if (!(m == 0 && fr < 2)) *(u32x2*)(act + (unsigned)(row * DFF + jn)) = pack4(o);
;                         pg1 = rg1; pg2 = rg2; }
	v_cndmask_b32_e64 v77, v192, v60, s[6:7]
	v_cndmask_b32_e64 v76, v191, v43, s[6:7]
	v_cndmask_b32_e64 v75, v94, v41, s[8:9]
	v_cndmask_b32_e64 v74, v93, v40, s[8:9]
	v_pk_fma_f32 v[76:77], v[28:29], v[76:77], v[32:33]
	v_and_b32_e32 v39, 0xffff0000, v91
	v_pk_fma_f32 v[74:75], v[20:21], v[74:75], v[76:77]
	s_nop 1
	v_pk_fma_f32 v[36:37], v[24:25], v[36:37], v[74:75]
	s_nop 1
	v_and_b32_e32 v77, 0x7fffffff, v37
	v_and_b32_e32 v76, 0x7fffffff, v36
	v_pk_fma_f32 v[76:77], v[76:77], s[52:53], 1.0 op_sel_hi:[1,0,0]
	s_nop 1
	v_rcp_f32_e32 v76, v76
	v_rcp_f32_e32 v77, v77
	v_mov_b32_dpp v46, v38 row_ror:2 row_mask:0xf bank_mask:0xf
	v_mov_b32_dpp v61, v39 row_ror:2 row_mask:0xf bank_mask:0xf
	v_mov_b32_dpp v42, v38 row_ror:1 row_mask:0xf bank_mask:0xf
	v_mov_b32_dpp v47, v39 row_ror:1 row_mask:0xf bank_mask:0xf
	v_cndmask_b32_e64 v93, v194, v61, s[6:7]
	v_cndmask_b32_e64 v92, v193, v46, s[6:7]
	v_cndmask_b32_e64 v71, v190, v47, s[8:9]
	v_cndmask_b32_e64 v70, v189, v42, s[8:9]
	v_pk_fma_f32 v[92:93], v[30:31], v[92:93], v[34:35]
	v_pk_mul_f32 v[74:75], v[36:37], v[36:37]
	v_pk_fma_f32 v[70:71], v[22:23], v[70:71], v[92:93]
	v_pk_mul_f32 v[74:75], v[74:75], s[42:43] op_sel_hi:[1,0]
	v_pk_fma_f32 v[92:93], v[76:77], s[54:55], v[72:73] op_sel_hi:[1,0,0]
	v_exp_f32_e32 v74, v74
	v_exp_f32_e32 v75, v75
	v_pk_fma_f32 v[92:93], v[76:77], v[92:93], s[58:59] op_sel_hi:[1,1,0]
	v_cmp_gt_f32_e64 s[0:1], 0, v36
	v_pk_fma_f32 v[92:93], v[76:77], v[92:93], s[60:61] op_sel_hi:[1,1,0]
	v_pk_fma_f32 v[38:39], v[26:27], v[38:39], v[70:71]
	v_pk_fma_f32 v[92:93], v[76:77], v[92:93], s[62:63] op_sel_hi:[1,1,0]
	v_pk_mul_f32 v[70:71], v[38:39], v[38:39]
	v_pk_mul_f32 v[76:77], v[76:77], v[92:93]
	v_pk_mul_f32 v[70:71], v[70:71], s[42:43] op_sel_hi:[1,0]
	v_pk_mul_f32 v[74:75], v[74:75], v[76:77]
	v_exp_f32_e32 v70, v70
	v_pk_mul_f32 v[76:77], v[36:37], v[74:75]
	v_pk_fma_f32 v[74:75], v[36:37], v[74:75], v[36:37] neg_lo:[1,0,0] neg_hi:[1,0,0]
	v_exp_f32_e32 v71, v71
	v_cndmask_b32_e64 v36, v74, v76, s[0:1]
	v_cmp_gt_f32_e64 s[0:1], 0, v37
	v_and_b32_e32 v74, 0x7fffffff, v38
	v_add_u32_e32 v136, v148, v44
	v_cndmask_b32_e64 v37, v75, v77, s[0:1]
	v_and_b32_e32 v75, 0x7fffffff, v39
	v_pk_fma_f32 v[74:75], v[74:75], s[52:53], 1.0 op_sel_hi:[1,0,0]
	v_cmp_gt_f32_e64 s[0:1], 0, v38
	v_rcp_f32_e32 v74, v74
	v_rcp_f32_e32 v75, v75
	v_pk_mul_f32 v[36:37], v[66:67], v[36:37]
	s_nop 1
	v_cvt_pk_bf16_f32 v36, v36, v37
	v_pk_fma_f32 v[72:73], v[74:75], s[54:55], v[72:73] op_sel_hi:[1,0,0]
	s_nop 1
	v_pk_fma_f32 v[72:73], v[74:75], v[72:73], s[58:59] op_sel_hi:[1,1,0]
	s_nop 0
	v_pk_fma_f32 v[72:73], v[74:75], v[72:73], s[60:61] op_sel_hi:[1,1,0]
	s_nop 0
	v_pk_fma_f32 v[72:73], v[74:75], v[72:73], s[62:63] op_sel_hi:[1,1,0]
	s_nop 0
	v_pk_mul_f32 v[72:73], v[74:75], v[72:73]
	s_nop 0
	v_pk_mul_f32 v[70:71], v[70:71], v[72:73]
	s_nop 0
	v_pk_mul_f32 v[72:73], v[38:39], v[70:71]
	v_pk_fma_f32 v[70:71], v[38:39], v[70:71], v[38:39] neg_lo:[1,0,0] neg_hi:[1,0,0]
	s_nop 0
	v_cndmask_b32_e64 v38, v70, v72, s[0:1]
	v_cmp_gt_f32_e64 s[0:1], 0, v39
	s_nop 1
	v_cndmask_b32_e64 v39, v71, v73, s[0:1]
	v_pk_mul_f32 v[38:39], v[68:69], v[38:39]
	s_nop 1
	v_cvt_pk_bf16_f32 v37, v38, v39
	v_lshl_add_u64 v[38:39], v[136:137], 1, s[26:27]
	global_store_dwordx2 v[38:39], v[36:37], off
	v_lshlrev_b32_e32 v36, 16, v82
	v_and_b32_e32 v37, 0xffff0000, v82
	v_lshlrev_b32_e32 v38, 16, v83
	v_and_b32_e32 v39, 0xffff0000, v83
	s_nop 1
	v_mov_b32_dpp v66, v36 row_ror:1 row_mask:0xf bank_mask:0xf
	v_mov_b32_dpp v67, v37 row_ror:1 row_mask:0xf bank_mask:0xf
	v_mov_b32_dpp v68, v38 row_ror:1 row_mask:0xf bank_mask:0xf
	v_mov_b32_dpp v71, v39 row_ror:1 row_mask:0xf bank_mask:0xf
	v_mov_b32_dpp v69, v36 row_ror:2 row_mask:0xf bank_mask:0xf
	v_mov_b32_dpp v72, v37 row_ror:2 row_mask:0xf bank_mask:0xf
	v_mov_b32_dpp v70, v38 row_ror:2 row_mask:0xf bank_mask:0xf
	v_mov_b32_dpp v73, v39 row_ror:2 row_mask:0xf bank_mask:0xf
	s_and_saveexec_b64 s[0:1], vcc
	s_cbranch_execz .LBB0_1416
	v_add_u32_e32 v136, v152, v44
	v_lshl_add_u64 v[74:75], v[136:137], 2, s[28:29]
	global_store_dwordx4 v[74:75], v[36:39], off
.LBB0_1416:
	s_or_b64 exec, exec, s[0:1]
	v_cndmask_b32_e64 v74, v42, v68, s[8:9]
	v_cndmask_b32_e64 v40, v40, v66, s[8:9]
	v_cndmask_b32_e64 v66, v43, v69, s[6:7]
	v_cndmask_b32_e64 v69, v180, v188, s[6:7]
	v_cndmask_b32_e64 v68, v179, v187, s[6:7]
	v_cndmask_b32_e64 v41, v41, v67, s[8:9]
	v_cndmask_b32_e64 v67, v60, v72, s[6:7]
	v_cndmask_b32_e64 v43, v61, v73, s[6:7]
	v_cndmask_b32_e64 v61, v177, v185, s[8:9]
	v_cndmask_b32_e64 v60, v86, v182, s[8:9]
	v_pk_fma_f32 v[10:11], v[10:11], v[68:69], v[14:15]
	v_cndmask_b32_e64 v75, v47, v71, s[8:9]
	v_pk_fma_f32 v[2:3], v[2:3], v[60:61], v[10:11]
	v_cndmask_b32_e64 v42, v46, v70, s[6:7]
	v_pk_fma_f32 v[2:3], v[6:7], v[18:19], v[2:3]
	v_pk_fma_f32 v[6:7], v[28:29], v[66:67], v[32:33]
	v_cndmask_b32_e64 v71, v178, v186, s[6:7]
	v_pk_fma_f32 v[6:7], v[20:21], v[40:41], v[6:7]
	v_cndmask_b32_e64 v70, v87, v183, s[6:7]
	v_pk_fma_f32 v[6:7], v[24:25], v[36:37], v[6:7]
	v_pk_fma_f32 v[8:9], v[8:9], v[70:71], v[12:13]
	v_and_b32_e32 v13, 0x7fffffff, v7
	v_and_b32_e32 v12, 0x7fffffff, v6
	v_pk_fma_f32 v[12:13], v[12:13], s[52:53], 1.0 op_sel_hi:[1,0,0]
	v_cndmask_b32_e64 v47, v95, v184, s[8:9]
	v_rcp_f32_e32 v12, v12
	v_rcp_f32_e32 v13, v13
	v_cndmask_b32_e64 v46, v85, v181, s[8:9]
	v_pk_fma_f32 v[0:1], v[0:1], v[46:47], v[8:9]
	v_pk_mul_f32 v[10:11], v[6:7], v[6:7]
	v_mov_b64_e32 v[14:15], s[56:57]
	v_pk_fma_f32 v[0:1], v[4:5], v[16:17], v[0:1]
	v_pk_mul_f32 v[10:11], v[10:11], s[42:43] op_sel_hi:[1,0]
	v_pk_fma_f32 v[16:17], v[12:13], s[54:55], v[14:15] op_sel_hi:[1,0,0]
;     __device__ __forceinline__ void operator()(AccRef acc, const Unit& u, int wr, int wc, int fr, int fq) const {
;     ...
;             for (int n = 0; n < 2; ++n) { const unsigned jn = (unsigned)(j0 + 4 * n);
;                 f32x4 cu[4];
;                 {
;                     const f32x4 wu0 = *(const f32x4*)(cw + (DFF + jn)), wu1 = *(const f32x4*)(cw + (UPN + DFF + jn)), wu2 = *(const f32x4*)(cw + (2 * UPN + DFF + jn)), bu = *(const f32x4*)(cb + (DFF + jn));
;                     f32x4 pu1 = (f32x4){0.f, 0.f, 0.f, 0.f}, pu2 = pu1;
; #pragma unroll
;                     for (int m = 0; m < 4; ++m) {
;                         const f32x4 au = unpack4(pa[ai][1][m][n]);
;                         const f32x4 ru1 = ror1v(au), ru2 = ror2v(au);
;                         const f32x4 u1 = fr >= 1 ? ru1 : pu1, u2 = fr >= 2 ? ru2 : pu2;
;                         if (m == 0 && fr < 2) *(f32x4*)(edge + (unsigned)((grp * 4 + fr) * UPN + DFF + jn)) = au;
;                         if (m == 3 && fr >= 14) *(f32x4*)(edge + (unsigned)((grp * 4 + (fr - 12)) * UPN + DFF + jn)) = au;
;                         cu[m] = bu + wu0 * u2 + wu1 * u1 + wu2 * au;
;                         pu1 = ru1; pu2 = ru2; }
;                 }
;                 {
;                     const f32x4 wg0 = *(const f32x4*)(cw + jn), wg1 = *(const f32x4*)(cw + (UPN + jn)), wg2 = *(const f32x4*)(cw + (2 * UPN + jn)), bg = *(const f32x4*)(cb + jn);
;                     f32x4 pg1 = (f32x4){0.f, 0.f, 0.f, 0.f}, pg2 = pg1;
; #pragma unroll
;                     for (int m = 0; m < 4; ++m) { const int row = rowg + m * 16 + fr;
;                         const f32x4 ag = unpack4(pa[ai][0][m][n]);
;                         const f32x4 rg1 = ror1v(ag), rg2 = ror2v(ag);
;                         const f32x4 g1 = fr >= 1 ? rg1 : pg1, g2 = fr >= 2 ? rg2 : pg2;
;                         if (m == 0 && fr < 2) *(f32x4*)(edge + (unsigned)((grp * 4 + fr) * UPN + jn)) = ag;
;                         if (m == 3 && fr >= 14) *(f32x4*)(edge + (unsigned)((grp * 4 + (fr - 12)) * UPN + jn)) = ag;
;                         const f32x4 o = gelu4(bg + wg0 * g2 + wg1 * g1 + wg2 * ag) * cu[m];
;                         if (!(m == 0 && fr < 2)) *(u32x2*)(act + (unsigned)(row * DFF + jn)) = pack4(o);
;                         pg1 = rg1; pg2 = rg2; }
	v_exp_f32_e32 v10, v10
	v_exp_f32_e32 v11, v11
	v_pk_fma_f32 v[16:17], v[12:13], v[16:17], s[58:59] op_sel_hi:[1,1,0]
	v_pk_fma_f32 v[4:5], v[30:31], v[42:43], v[34:35]
	v_pk_fma_f32 v[16:17], v[12:13], v[16:17], s[60:61] op_sel_hi:[1,1,0]
	v_pk_fma_f32 v[4:5], v[22:23], v[74:75], v[4:5]
	v_pk_fma_f32 v[16:17], v[12:13], v[16:17], s[62:63] op_sel_hi:[1,1,0]
	v_cmp_gt_f32_e64 s[0:1], 0, v6
	v_pk_mul_f32 v[12:13], v[12:13], v[16:17]
	v_pk_fma_f32 v[4:5], v[26:27], v[38:39], v[4:5]
	v_pk_mul_f32 v[10:11], v[10:11], v[12:13]
	v_pk_mul_f32 v[8:9], v[4:5], v[4:5]
	v_pk_mul_f32 v[12:13], v[6:7], v[10:11]
	v_pk_fma_f32 v[10:11], v[6:7], v[10:11], v[6:7] neg_lo:[1,0,0] neg_hi:[1,0,0]
	v_pk_mul_f32 v[8:9], v[8:9], s[42:43] op_sel_hi:[1,0]
	v_cndmask_b32_e64 v6, v10, v12, s[0:1]
	v_cmp_gt_f32_e64 s[0:1], 0, v7
	v_and_b32_e32 v10, 0x7fffffff, v4
	v_exp_f32_e32 v8, v8
	v_cndmask_b32_e64 v7, v11, v13, s[0:1]
	v_and_b32_e32 v11, 0x7fffffff, v5
	v_pk_fma_f32 v[10:11], v[10:11], s[52:53], 1.0 op_sel_hi:[1,0,0]
	v_exp_f32_e32 v9, v9
	v_rcp_f32_e32 v10, v10
	v_rcp_f32_e32 v11, v11
	v_cmp_gt_f32_e64 s[0:1], 0, v4
	v_add_u32_e32 v177, 0xb000, v148
	v_pk_mul_f32 v[0:1], v[0:1], v[6:7]
	v_pk_fma_f32 v[12:13], v[10:11], s[54:55], v[14:15] op_sel_hi:[1,0,0]
	v_add_u32_e32 v136, v177, v44
	v_pk_fma_f32 v[12:13], v[10:11], v[12:13], s[58:59] op_sel_hi:[1,1,0]
	v_cvt_pk_bf16_f32 v0, v0, v1
	v_lshlrev_b32_e32 v36, 16, v173
	v_pk_fma_f32 v[12:13], v[10:11], v[12:13], s[60:61] op_sel_hi:[1,1,0]
	v_and_b32_e32 v37, 0xffff0000, v173
	v_pk_fma_f32 v[12:13], v[10:11], v[12:13], s[62:63] op_sel_hi:[1,1,0]
	v_lshlrev_b32_e32 v38, 16, v174
	v_pk_mul_f32 v[10:11], v[10:11], v[12:13]
	v_and_b32_e32 v39, 0xffff0000, v174
	v_pk_mul_f32 v[8:9], v[8:9], v[10:11]
	s_nop 1
	v_pk_mul_f32 v[10:11], v[4:5], v[8:9]
	v_pk_fma_f32 v[8:9], v[4:5], v[8:9], v[4:5] neg_lo:[1,0,0] neg_hi:[1,0,0]
	s_nop 1
	v_cndmask_b32_e64 v4, v8, v10, s[0:1]
	v_cmp_gt_f32_e64 s[0:1], 0, v5
	s_nop 1
	v_cndmask_b32_e64 v5, v9, v11, s[0:1]
	v_pk_mul_f32 v[2:3], v[2:3], v[4:5]
	s_nop 1
	v_cvt_pk_bf16_f32 v1, v2, v3
	v_lshl_add_u64 v[2:3], v[136:137], 1, s[26:27]
	v_add_u32_e32 v136, 0xb04, v44
	v_lshlrev_b64 v[12:13], 2, v[136:137]
	v_add_u32_e32 v136, 0x2104, v44
	v_lshl_add_u64 v[66:67], v[136:137], 2, s[20:21]
	v_add_u32_e32 v136, 0x3704, v44
	global_store_dwordx2 v[2:3], v[0:1], off
	v_lshl_add_u64 v[60:61], s[20:21], 0, v[12:13]
	v_lshl_add_u64 v[68:69], v[136:137], 2, s[20:21]
	v_lshl_add_u64 v[70:71], s[22:23], 0, v[12:13]
	global_load_dwordx4 v[8:11], v[60:61], off
	global_load_dwordx4 v[0:3], v[66:67], off
	global_load_dwordx4 v[4:7], v[68:69], off
	global_load_dwordx4 v[12:15], v[70:71], off
	s_nop 1
	v_or_b32_e32 v46, 4, v44
	v_mov_b32_dpp v193, v36 row_ror:1 row_mask:0xf bank_mask:0xf
	v_mov_b32_dpp v199, v37 row_ror:1 row_mask:0xf bank_mask:0xf
	v_mov_b32_dpp v196, v38 row_ror:1 row_mask:0xf bank_mask:0xf
	v_mov_b32_dpp v202, v39 row_ror:1 row_mask:0xf bank_mask:0xf
	v_mov_b32_dpp v197, v36 row_ror:2 row_mask:0xf bank_mask:0xf
	v_mov_b32_dpp v203, v37 row_ror:2 row_mask:0xf bank_mask:0xf
	v_mov_b32_dpp v205, v38 row_ror:2 row_mask:0xf bank_mask:0xf
	v_mov_b32_dpp v207, v39 row_ror:2 row_mask:0xf bank_mask:0xf
	s_and_saveexec_b64 s[0:1], s[12:13]
	s_cbranch_execz .LBB0_1418
	v_add_u32_e32 v136, v46, v84
	v_lshl_add_u64 v[16:17], v[136:137], 2, s[28:29]
	global_store_dwordx4 v[16:17], v[36:39], off
.LBB0_1418:
	s_or_b64 exec, exec, s[0:1]
	v_lshlrev_b32_e32 v86, 16, v89
	v_and_b32_e32 v87, 0xffff0000, v89
	v_lshlrev_b32_e32 v84, 16, v88
	v_and_b32_e32 v85, 0xffff0000, v88
	s_nop 1
	v_lshlrev_b32_e32 v82, 16, v80
	v_and_b32_e32 v83, 0xffff0000, v80
	v_lshlrev_b32_e32 v80, 16, v81
	v_and_b32_e32 v81, 0xffff0000, v81
	s_nop 1
	v_lshlrev_b32_e32 v16, 16, v78
	v_and_b32_e32 v17, 0xffff0000, v78
	v_lshlrev_b32_e32 v18, 16, v79
	v_and_b32_e32 v19, 0xffff0000, v79
	s_nop 1
	v_mov_b32_dpp v192, v86 row_ror:1 row_mask:0xf bank_mask:0xf
	v_mov_b32_dpp v198, v87 row_ror:1 row_mask:0xf bank_mask:0xf
	v_mov_b32_dpp v194, v84 row_ror:1 row_mask:0xf bank_mask:0xf
	v_mov_b32_dpp v200, v85 row_ror:1 row_mask:0xf bank_mask:0xf
	v_mov_b32_dpp v195, v86 row_ror:2 row_mask:0xf bank_mask:0xf
	v_mov_b32_dpp v201, v87 row_ror:2 row_mask:0xf bank_mask:0xf
	v_mov_b32_dpp v204, v84 row_ror:2 row_mask:0xf bank_mask:0xf
	v_mov_b32_dpp v206, v85 row_ror:2 row_mask:0xf bank_mask:0xf
	v_mov_b32_dpp v173, v82 row_ror:1 row_mask:0xf bank_mask:0xf
	v_mov_b32_dpp v179, v83 row_ror:1 row_mask:0xf bank_mask:0xf
	v_mov_b32_dpp v174, v80 row_ror:1 row_mask:0xf bank_mask:0xf
	v_mov_b32_dpp v180, v81 row_ror:1 row_mask:0xf bank_mask:0xf
	v_mov_b32_dpp v178, v82 row_ror:2 row_mask:0xf bank_mask:0xf
	v_mov_b32_dpp v181, v83 row_ror:2 row_mask:0xf bank_mask:0xf
	v_mov_b32_dpp v182, v80 row_ror:2 row_mask:0xf bank_mask:0xf
	v_mov_b32_dpp v183, v81 row_ror:2 row_mask:0xf bank_mask:0xf
	v_mov_b32_dpp v184, v16 row_ror:1 row_mask:0xf bank_mask:0xf
	v_mov_b32_dpp v187, v17 row_ror:1 row_mask:0xf bank_mask:0xf
	v_mov_b32_dpp v185, v18 row_ror:1 row_mask:0xf bank_mask:0xf
	v_mov_b32_dpp v188, v19 row_ror:1 row_mask:0xf bank_mask:0xf
	v_mov_b32_dpp v186, v16 row_ror:2 row_mask:0xf bank_mask:0xf
	v_mov_b32_dpp v189, v17 row_ror:2 row_mask:0xf bank_mask:0xf
	v_mov_b32_dpp v190, v18 row_ror:2 row_mask:0xf bank_mask:0xf
	v_mov_b32_dpp v191, v19 row_ror:2 row_mask:0xf bank_mask:0xf
	s_and_saveexec_b64 s[0:1], vcc
	s_cbranch_execz .LBB0_1420
	v_add_u32_e32 v136, v90, v46
	v_lshl_add_u64 v[20:21], v[136:137], 2, s[28:29]
	global_store_dwordx4 v[20:21], v[16:19], off
; __device__ __forceinline__ f32x4 gelu4(f32x4 v) { const f32x2 a = gelu_pk((f32x2){v[0], v[1]}), b = gelu_pk((f32x2){v[2], v[3]}); return (f32x4){a.x, a.y, b.x, b.y}; }
; __device__ __forceinline__ f32x4 ror1v(f32x4 v) { return (f32x4){dpp_ror1(v[0]), dpp_ror1(v[1]), dpp_ror1(v[2]), dpp_ror1(v[3])}; }
; __device__ __forceinline__ f32x4 ror2v(f32x4 v) { return (f32x4){dpp_ror2(v[0]), dpp_ror2(v[1]), dpp_ror2(v[2]), dpp_ror2(v[3])}; }
; __device__ __forceinline__ u32x2 pack4(f32x4 v) { return (u32x2){pk2(v[0], v[1]), pk2(v[2], v[3])}; }
; __device__ __forceinline__ f32x2 gelu_pk(f32x2 v) {
;     const f32x2 av = __builtin_elementwise_abs(v), d = av * 0.2316418882f + 1.0f;
;     f32x2 t; t.x = __builtin_amdgcn_rcpf(d.x); t.y = __builtin_amdgcn_rcpf(d.y);
;     f32x2 q = t * 0.5307027145f + (-0.7265760135f); q = q * t + 0.7107068705f; q = q * t + (-0.142248368f); q = q * t + 0.127414796f; q = q * t;
;     const f32x2 s = (v * v) * (-0.72134752044f);
;     f32x2 e; e.x = __builtin_amdgcn_exp2f(s.x); e.y = __builtin_amdgcn_exp2f(s.y);
;     const f32x2 m = v * (q * e), r = v - m;
;     f32x2 o; o.x = v.x < 0.f ? m.x : r.x; o.y = v.y < 0.f ? m.y : r.y; return o;
;     __device__ __forceinline__ void operator()(AccRef acc, const Unit& u, int wr, int wc, int fr, int fq) const {
;     ...
;                     const f32x4 wg0 = *(const f32x4*)(cw + jn), wg1 = *(const f32x4*)(cw + (UPN + jn)), wg2 = *(const f32x4*)(cw + (2 * UPN + jn)), bg = *(const f32x4*)(cb + jn);
;                     f32x4 pg1 = (f32x4){0.f, 0.f, 0.f, 0.f}, pg2 = pg1;
; #pragma unroll
;                     for (int m = 0; m < 4; ++m) { const int row = rowg + m * 16 + fr;
;                         const f32x4 ag = unpack4(pa[ai][0][m][n]);
;                         const f32x4 rg1 = ror1v(ag), rg2 = ror2v(ag);
;                         const f32x4 g1 = fr >= 1 ? rg1 : pg1, g2 = fr >= 2 ? rg2 : pg2;
;                         if (m == 0 && fr < 2) *(f32x4*)(edge + (unsigned)((grp * 4 + fr) * UPN + jn)) = ag;
;                         if (m == 3 && fr >= 14) *(f32x4*)(edge + (unsigned)((grp * 4 + (fr - 12)) * UPN + jn)) = ag;
;                         const f32x4 o = gelu4(bg + wg0 * g2 + wg1 * g1 + wg2 * ag) * cu[m];
;                         if (!(m == 0 && fr < 2)) *(u32x2*)(act + (unsigned)(row * DFF + jn)) = pack4(o);
;                         pg1 = rg1; pg2 = rg2; }
.LBB0_1420:
	s_or_b64 exec, exec, s[0:1]
	v_mov_b32_e32 v47, v137
	v_add_u32_e32 v136, 0x1604, v44
	v_lshlrev_b64 v[32:33], 2, v[46:47]
	v_lshl_add_u64 v[74:75], v[136:137], 2, s[20:21]
	v_add_u32_e32 v136, 0x2c04, v44
	v_lshl_add_u64 v[72:73], s[20:21], 0, v[32:33]
	v_lshl_add_u64 v[76:77], v[136:137], 2, s[20:21]
	v_lshl_add_u64 v[78:79], s[22:23], 0, v[32:33]
	global_load_dwordx4 v[28:31], v[72:73], off
	global_load_dwordx4 v[20:23], v[74:75], off
	global_load_dwordx4 v[24:27], v[76:77], off
	global_load_dwordx4 v[32:35], v[78:79], off
	v_lshlrev_b32_e32 v40, 16, v172
	v_and_b32_e32 v41, 0xffff0000, v172
	v_lshlrev_b32_e32 v42, 16, v171
	v_and_b32_e32 v43, 0xffff0000, v171
	s_nop 1
	v_mov_b32_dpp v88, v40 row_ror:1 row_mask:0xf bank_mask:0xf
	v_mov_b32_dpp v89, v41 row_ror:1 row_mask:0xf bank_mask:0xf
	v_mov_b32_dpp v90, v42 row_ror:1 row_mask:0xf bank_mask:0xf
	v_mov_b32_dpp v91, v43 row_ror:1 row_mask:0xf bank_mask:0xf
	v_mov_b32_dpp v92, v40 row_ror:2 row_mask:0xf bank_mask:0xf
	v_mov_b32_dpp v93, v41 row_ror:2 row_mask:0xf bank_mask:0xf
	v_mov_b32_dpp v94, v42 row_ror:2 row_mask:0xf bank_mask:0xf
	v_mov_b32_dpp v95, v43 row_ror:2 row_mask:0xf bank_mask:0xf
	s_and_saveexec_b64 s[0:1], s[10:11]
	s_xor_b64 s[74:75], exec, s[0:1]
	s_cbranch_execz .LBB0_1422
	v_cndmask_b32_e64 v213, 0, v207, s[6:7]
	v_cndmask_b32_e64 v212, 0, v205, s[6:7]
	v_cndmask_b32_e64 v211, 0, v202, s[8:9]
	v_cndmask_b32_e64 v210, 0, v196, s[8:9]
	s_waitcnt vmcnt(4)
	v_pk_fma_f32 v[212:213], v[10:11], v[212:213], v[14:15]
	v_cndmask_b32_e64 v215, 0, v203, s[6:7]
	v_pk_fma_f32 v[210:211], v[2:3], v[210:211], v[212:213]
	v_cndmask_b32_e64 v214, 0, v197, s[6:7]
	v_pk_fma_f32 v[38:39], v[6:7], v[38:39], v[210:211]
	s_waitcnt vmcnt(0)
	v_pk_fma_f32 v[210:211], v[28:29], v[92:93], v[32:33]
	v_cndmask_b32_e64 v209, 0, v199, s[8:9]
	v_pk_fma_f32 v[210:211], v[20:21], v[88:89], v[210:211]
	v_cndmask_b32_e64 v208, 0, v193, s[8:9]
	v_pk_fma_f32 v[40:41], v[24:25], v[40:41], v[210:211]
	v_pk_fma_f32 v[214:215], v[8:9], v[214:215], v[12:13]
	v_and_b32_e32 v213, 0x7fffffff, v41
	v_and_b32_e32 v212, 0x7fffffff, v40
	v_pk_fma_f32 v[212:213], v[212:213], s[52:53], 1.0 op_sel_hi:[1,0,0]
	v_pk_fma_f32 v[208:209], v[0:1], v[208:209], v[214:215]
	v_rcp_f32_e32 v212, v212
	v_rcp_f32_e32 v213, v213
	v_pk_mul_f32 v[210:211], v[40:41], v[40:41]
	v_mov_b64_e32 v[214:215], s[56:57]
	v_pk_mul_f32 v[210:211], v[210:211], s[42:43] op_sel_hi:[1,0]
	v_pk_fma_f32 v[216:217], v[212:213], s[54:55], v[214:215] op_sel_hi:[1,0,0]
	v_exp_f32_e32 v210, v210
	v_exp_f32_e32 v211, v211
	v_pk_fma_f32 v[216:217], v[212:213], v[216:217], s[58:59] op_sel_hi:[1,1,0]
	v_pk_fma_f32 v[36:37], v[4:5], v[36:37], v[208:209]
	v_pk_fma_f32 v[216:217], v[212:213], v[216:217], s[60:61] op_sel_hi:[1,1,0]
	v_pk_fma_f32 v[208:209], v[30:31], v[94:95], v[34:35]
	v_pk_fma_f32 v[216:217], v[212:213], v[216:217], s[62:63] op_sel_hi:[1,1,0]
	v_pk_fma_f32 v[208:209], v[22:23], v[90:91], v[208:209]
	v_pk_mul_f32 v[212:213], v[212:213], v[216:217]
	v_cmp_gt_f32_e64 s[0:1], 0, v40
	v_pk_mul_f32 v[210:211], v[210:211], v[212:213]
	v_pk_fma_f32 v[42:43], v[26:27], v[42:43], v[208:209]
	v_pk_mul_f32 v[212:213], v[40:41], v[210:211]
	v_pk_fma_f32 v[210:211], v[40:41], v[210:211], v[40:41] neg_lo:[1,0,0] neg_hi:[1,0,0]
	v_pk_mul_f32 v[208:209], v[42:43], v[42:43]
	v_cndmask_b32_e64 v40, v210, v212, s[0:1]
	v_cmp_gt_f32_e64 s[0:1], 0, v41
	v_and_b32_e32 v210, 0x7fffffff, v42
	v_pk_mul_f32 v[208:209], v[208:209], s[42:43] op_sel_hi:[1,0]
	v_cndmask_b32_e64 v41, v211, v213, s[0:1]
	v_and_b32_e32 v211, 0x7fffffff, v43
	v_pk_fma_f32 v[210:211], v[210:211], s[52:53], 1.0 op_sel_hi:[1,0,0]
	v_exp_f32_e32 v208, v208
	v_rcp_f32_e32 v210, v210
	v_rcp_f32_e32 v211, v211
	v_exp_f32_e32 v209, v209
	v_cmp_gt_f32_e64 s[0:1], 0, v42
	v_pk_mul_f32 v[36:37], v[36:37], v[40:41]
	v_pk_fma_f32 v[212:213], v[210:211], s[54:55], v[214:215] op_sel_hi:[1,0,0]
	v_cvt_pk_bf16_f32 v36, v36, v37
	s_nop 0
	v_pk_fma_f32 v[212:213], v[210:211], v[212:213], s[58:59] op_sel_hi:[1,1,0]
	s_nop 0
	v_pk_fma_f32 v[212:213], v[210:211], v[212:213], s[60:61] op_sel_hi:[1,1,0]
	s_nop 0
	v_pk_fma_f32 v[212:213], v[210:211], v[212:213], s[62:63] op_sel_hi:[1,1,0]
	s_nop 0
	v_pk_mul_f32 v[210:211], v[210:211], v[212:213]
	s_nop 0
	v_pk_mul_f32 v[208:209], v[208:209], v[210:211]
	s_nop 0
	v_pk_mul_f32 v[210:211], v[42:43], v[208:209]
	v_pk_fma_f32 v[208:209], v[42:43], v[208:209], v[42:43] neg_lo:[1,0,0] neg_hi:[1,0,0]
	s_nop 0
	v_cndmask_b32_e64 v42, v208, v210, s[0:1]
	v_cmp_gt_f32_e64 s[0:1], 0, v43
	s_nop 1
	v_cndmask_b32_e64 v43, v209, v211, s[0:1]
	v_pk_mul_f32 v[38:39], v[38:39], v[42:43]
	s_nop 0
	v_cvt_pk_bf16_f32 v37, v38, v39
	v_mad_u64_u32 v[38:39], s[0:1], v146, s86, v[46:47]
	v_mov_b32_e32 v39, v137
	v_lshl_add_u64 v[38:39], v[38:39], 1, s[26:27]
	global_store_dwordx2 v[38:39], v[36:37], off

;     __device__ __forceinline__ void operator()(AccRef acc, const Unit& u, int wr, int wc, int fr, int fq) const {
;     ...
;             for (int n = 0; n < 2; ++n) { const unsigned jn = (unsigned)(j0 + 4 * n);
;                 f32x4 cu[4];
;                 {
;                     const f32x4 wu0 = *(const f32x4*)(cw + (DFF + jn)), wu1 = *(const f32x4*)(cw + (UPN + DFF + jn)), wu2 = *(const f32x4*)(cw + (2 * UPN + DFF + jn)), bu = *(const f32x4*)(cb + (DFF + jn));
;                     f32x4 pu1 = (f32x4){0.f, 0.f, 0.f, 0.f}, pu2 = pu1;
; #pragma unroll
;                     for (int m = 0; m < 4; ++m) {
;                         const f32x4 au = unpack4(pa[ai][1][m][n]);
;                         const f32x4 ru1 = ror1v(au), ru2 = ror2v(au);
;                         const f32x4 u1 = fr >= 1 ? ru1 : pu1, u2 = fr >= 2 ? ru2 : pu2;
;                         if (m == 0 && fr < 2) *(f32x4*)(edge + (unsigned)((grp * 4 + fr) * UPN + DFF + jn)) = au;
;                         if (m == 3 && fr >= 14) *(f32x4*)(edge + (unsigned)((grp * 4 + (fr - 12)) * UPN + DFF + jn)) = au;
;                         cu[m] = bu + wu0 * u2 + wu1 * u1 + wu2 * au;
;                         pu1 = ru1; pu2 = ru2; }
;                 }
;                 {
;                     const f32x4 wg0 = *(const f32x4*)(cw + jn), wg1 = *(const f32x4*)(cw + (UPN + jn)), wg2 = *(const f32x4*)(cw + (2 * UPN + jn)), bg = *(const f32x4*)(cb + jn);
;                     f32x4 pg1 = (f32x4){0.f, 0.f, 0.f, 0.f}, pg2 = pg1;
; #pragma unroll
;                     for (int m = 0; m < 4; ++m) { const int row = rowg + m * 16 + fr;
;                         const f32x4 ag = unpack4(pa[ai][0][m][n]);
;                         const f32x4 rg1 = ror1v(ag), rg2 = ror2v(ag);
;                         const f32x4 g1 = fr >= 1 ? rg1 : pg1, g2 = fr >= 2 ? rg2 : pg2;
;                         if (m == 0 && fr < 2) *(f32x4*)(edge + (unsigned)((grp * 4 + fr) * UPN + jn)) = ag;
;                         if (m == 3 && fr >= 14) *(f32x4*)(edge + (unsigned)((grp * 4 + (fr - 12)) * UPN + jn)) = ag;
;                         const f32x4 o = gelu4(bg + wg0 * g2 + wg1 * g1 + wg2 * ag) * cu[m];
;                         if (!(m == 0 && fr < 2)) *(u32x2*)(act + (unsigned)(row * DFF + jn)) = pack4(o);
;                         pg1 = rg1; pg2 = rg2; }
.LBB0_1424:
	s_or_b64 exec, exec, s[0:1]
	s_nop 0
	v_cndmask_b32_e64 v41, v207, v206, s[6:7]
	v_cndmask_b32_e64 v40, v205, v204, s[6:7]
	v_cndmask_b32_e64 v43, v203, v201, s[6:7]
	v_cndmask_b32_e64 v42, v197, v195, s[6:7]
	v_cndmask_b32_e64 v37, v199, v198, s[8:9]
	v_cndmask_b32_e64 v36, v193, v192, s[8:9]
	v_cndmask_b32_e64 v39, v202, v200, s[8:9]
	v_cndmask_b32_e64 v38, v196, v194, s[8:9]
	s_waitcnt vmcnt(4)
	v_pk_fma_f32 v[42:43], v[8:9], v[42:43], v[12:13]
	v_pk_fma_f32 v[40:41], v[10:11], v[40:41], v[14:15]
	v_pk_fma_f32 v[36:37], v[0:1], v[36:37], v[42:43]
	v_pk_fma_f32 v[38:39], v[2:3], v[38:39], v[40:41]
	v_pk_fma_f32 v[36:37], v[4:5], v[86:87], v[36:37]
	v_pk_fma_f32 v[38:39], v[6:7], v[84:85], v[38:39]
	v_cndmask_b32_e64 v85, v206, v183, s[6:7]
	v_cndmask_b32_e64 v84, v204, v182, s[6:7]
	v_cndmask_b32_e64 v87, v201, v181, s[6:7]
	v_cndmask_b32_e64 v86, v195, v178, s[6:7]
	v_cndmask_b32_e64 v41, v198, v179, s[8:9]
	v_cndmask_b32_e64 v40, v192, v173, s[8:9]
	v_cndmask_b32_e64 v43, v200, v180, s[8:9]
	v_cndmask_b32_e64 v42, v194, v174, s[8:9]
	v_pk_fma_f32 v[86:87], v[8:9], v[86:87], v[12:13]
	v_pk_fma_f32 v[84:85], v[10:11], v[84:85], v[14:15]
	v_pk_fma_f32 v[40:41], v[0:1], v[40:41], v[86:87]
	v_pk_fma_f32 v[42:43], v[2:3], v[42:43], v[84:85]
	v_pk_fma_f32 v[82:83], v[4:5], v[82:83], v[40:41]
	v_pk_fma_f32 v[84:85], v[6:7], v[80:81], v[42:43]
	v_lshlrev_b32_e32 v40, 16, v170
	v_and_b32_e32 v41, 0xffff0000, v170
	v_lshlrev_b32_e32 v42, 16, v169
	v_and_b32_e32 v43, 0xffff0000, v169
	v_mov_b32_e32 v146, v137
	v_mov_b32_e32 v169, v137
	v_mov_b32_e32 v172, v137
	v_mov_b32_e32 v175, v137
	v_mov_b32_dpp v146, v40 row_ror:1 row_mask:0xf bank_mask:0xf
	v_mov_b32_dpp v169, v41 row_ror:1 row_mask:0xf bank_mask:0xf
	v_mov_b32_dpp v172, v40 row_ror:2 row_mask:0xf bank_mask:0xf
	v_mov_b32_dpp v175, v41 row_ror:2 row_mask:0xf bank_mask:0xf
	v_cndmask_b32_e64 v87, v89, v169, s[8:9]
	v_cndmask_b32_e64 v86, v88, v146, s[8:9]
	v_cndmask_b32_e64 v89, v93, v175, s[6:7]
	v_cndmask_b32_e64 v88, v92, v172, s[6:7]
	s_waitcnt vmcnt(0)
	v_pk_fma_f32 v[88:89], v[28:29], v[88:89], v[32:33]
	v_mov_b32_e32 v170, v137
	v_pk_fma_f32 v[86:87], v[20:21], v[86:87], v[88:89]
	v_mov_b32_e32 v171, v137
	v_pk_fma_f32 v[40:41], v[24:25], v[40:41], v[86:87]
	v_mov_b32_e32 v192, v137
	v_and_b32_e32 v89, 0x7fffffff, v41
	v_and_b32_e32 v88, 0x7fffffff, v40
	v_mov_b32_e32 v193, v137
	v_pk_fma_f32 v[88:89], v[88:89], s[52:53], 1.0 op_sel_hi:[1,0,0]
	v_mov_b32_dpp v170, v42 row_ror:1 row_mask:0xf bank_mask:0xf
	v_mov_b32_dpp v171, v43 row_ror:1 row_mask:0xf bank_mask:0xf
	v_mov_b32_dpp v192, v42 row_ror:2 row_mask:0xf bank_mask:0xf
	v_mov_b32_dpp v193, v43 row_ror:2 row_mask:0xf bank_mask:0xf
	v_rcp_f32_e32 v88, v88
	v_rcp_f32_e32 v89, v89
	v_cndmask_b32_e64 v81, v91, v171, s[8:9]
	v_cndmask_b32_e64 v80, v90, v170, s[8:9]
	v_cndmask_b32_e64 v91, v95, v193, s[6:7]
	v_cndmask_b32_e64 v90, v94, v192, s[6:7]
	v_pk_fma_f32 v[90:91], v[30:31], v[90:91], v[34:35]
	v_pk_mul_f32 v[86:87], v[40:41], v[40:41]
	v_pk_fma_f32 v[80:81], v[22:23], v[80:81], v[90:91]
	v_mov_b64_e32 v[90:91], s[56:57]
	v_pk_mul_f32 v[86:87], v[86:87], s[42:43] op_sel_hi:[1,0]
	v_pk_fma_f32 v[92:93], v[88:89], s[54:55], v[90:91] op_sel_hi:[1,0,0]
	v_exp_f32_e32 v86, v86
	v_exp_f32_e32 v87, v87
	v_pk_fma_f32 v[92:93], v[88:89], v[92:93], s[58:59] op_sel_hi:[1,1,0]
	v_cmp_gt_f32_e64 s[0:1], 0, v40
	v_pk_fma_f32 v[92:93], v[88:89], v[92:93], s[60:61] op_sel_hi:[1,1,0]
	v_pk_fma_f32 v[42:43], v[26:27], v[42:43], v[80:81]
	v_pk_fma_f32 v[92:93], v[88:89], v[92:93], s[62:63] op_sel_hi:[1,1,0]
	v_pk_mul_f32 v[80:81], v[42:43], v[42:43]
	v_pk_mul_f32 v[88:89], v[88:89], v[92:93]
	v_pk_mul_f32 v[80:81], v[80:81], s[42:43] op_sel_hi:[1,0]
	v_pk_mul_f32 v[86:87], v[86:87], v[88:89]
	v_exp_f32_e32 v80, v80
	v_pk_mul_f32 v[88:89], v[40:41], v[86:87]
	v_pk_fma_f32 v[86:87], v[40:41], v[86:87], v[40:41] neg_lo:[1,0,0] neg_hi:[1,0,0]
	v_exp_f32_e32 v81, v81
	v_cndmask_b32_e64 v40, v86, v88, s[0:1]
	v_cmp_gt_f32_e64 s[0:1], 0, v41
	v_and_b32_e32 v86, 0x7fffffff, v42
	v_add_u32_e32 v136, v45, v46
	v_cndmask_b32_e64 v41, v87, v89, s[0:1]
	v_and_b32_e32 v87, 0x7fffffff, v43
	v_pk_fma_f32 v[86:87], v[86:87], s[52:53], 1.0 op_sel_hi:[1,0,0]
	v_cmp_gt_f32_e64 s[0:1], 0, v42
	v_rcp_f32_e32 v86, v86
	v_rcp_f32_e32 v87, v87
	v_pk_mul_f32 v[36:37], v[36:37], v[40:41]
	s_nop 1
	v_cvt_pk_bf16_f32 v36, v36, v37
	v_pk_fma_f32 v[88:89], v[86:87], s[54:55], v[90:91] op_sel_hi:[1,0,0]
	s_nop 1
	v_pk_fma_f32 v[88:89], v[86:87], v[88:89], s[58:59] op_sel_hi:[1,1,0]
	s_nop 1
	v_pk_fma_f32 v[88:89], v[86:87], v[88:89], s[60:61] op_sel_hi:[1,1,0]
	s_nop 1
	v_pk_fma_f32 v[88:89], v[86:87], v[88:89], s[62:63] op_sel_hi:[1,1,0]
	s_nop 0
	v_pk_mul_f32 v[86:87], v[86:87], v[88:89]
	s_nop 0
	v_pk_mul_f32 v[80:81], v[80:81], v[86:87]
	s_nop 0
	v_pk_mul_f32 v[86:87], v[42:43], v[80:81]
	v_pk_fma_f32 v[80:81], v[42:43], v[80:81], v[42:43] neg_lo:[1,0,0] neg_hi:[1,0,0]
	s_nop 0
	v_cndmask_b32_e64 v42, v80, v86, s[0:1]
	v_cmp_gt_f32_e64 s[0:1], 0, v43
	s_nop 1
	s_nop 0
	v_cndmask_b32_e64 v43, v81, v87, s[0:1]
	v_pk_mul_f32 v[38:39], v[38:39], v[42:43]
	s_nop 1
	v_cvt_pk_bf16_f32 v37, v38, v39
	v_lshl_add_u64 v[38:39], v[136:137], 1, s[26:27]
	global_store_dwordx2 v[38:39], v[36:37], off
	v_lshlrev_b32_e32 v36, 16, v167
	v_and_b32_e32 v37, 0xffff0000, v167
	v_lshlrev_b32_e32 v38, 16, v168
	v_mov_b32_dpp v43, v36 row_ror:2 row_mask:0xf bank_mask:0xf
	v_mov_b32_dpp v80, v37 row_ror:2 row_mask:0xf bank_mask:0xf
	v_mov_b32_dpp v40, v36 row_ror:1 row_mask:0xf bank_mask:0xf
	v_mov_b32_dpp v41, v37 row_ror:1 row_mask:0xf bank_mask:0xf
	v_cndmask_b32_e64 v93, v175, v80, s[6:7]
;     __device__ __forceinline__ void operator()(AccRef acc, const Unit& u, int wr, int wc, int fr, int fq) const {
;     ...
;             for (int n = 0; n < 2; ++n) { const unsigned jn = (unsigned)(j0 + 4 * n);
;                 f32x4 cu[4];
;                 {
;                     const f32x4 wu0 = *(const f32x4*)(cw + (DFF + jn)), wu1 = *(const f32x4*)(cw + (UPN + DFF + jn)), wu2 = *(const f32x4*)(cw + (2 * UPN + DFF + jn)), bu = *(const f32x4*)(cb + (DFF + jn));
;                     f32x4 pu1 = (f32x4){0.f, 0.f, 0.f, 0.f}, pu2 = pu1;
; #pragma unroll
;                     for (int m = 0; m < 4; ++m) {
;                         const f32x4 au = unpack4(pa[ai][1][m][n]);
;                         const f32x4 ru1 = ror1v(au), ru2 = ror2v(au);
;                         const f32x4 u1 = fr >= 1 ? ru1 : pu1, u2 = fr >= 2 ? ru2 : pu2;
;                         if (m == 0 && fr < 2) *(f32x4*)(edge + (unsigned)((grp * 4 + fr) * UPN + DFF + jn)) = au;
;                         if (m == 3 && fr >= 14) *(f32x4*)(edge + (unsigned)((grp * 4 + (fr - 12)) * UPN + DFF + jn)) = au;
;                         cu[m] = bu + wu0 * u2 + wu1 * u1 + wu2 * au;
;                         pu1 = ru1; pu2 = ru2; }
;                 }
;                 {
;                     const f32x4 wg0 = *(const f32x4*)(cw + jn), wg1 = *(const f32x4*)(cw + (UPN + jn)), wg2 = *(const f32x4*)(cw + (2 * UPN + jn)), bg = *(const f32x4*)(cb + jn);
;                     f32x4 pg1 = (f32x4){0.f, 0.f, 0.f, 0.f}, pg2 = pg1;
; #pragma unroll
;                     for (int m = 0; m < 4; ++m) { const int row = rowg + m * 16 + fr;
;                         const f32x4 ag = unpack4(pa[ai][0][m][n]);
;                         const f32x4 rg1 = ror1v(ag), rg2 = ror2v(ag);
;                         const f32x4 g1 = fr >= 1 ? rg1 : pg1, g2 = fr >= 2 ? rg2 : pg2;
;                         if (m == 0 && fr < 2) *(f32x4*)(edge + (unsigned)((grp * 4 + fr) * UPN + jn)) = ag;
;                         if (m == 3 && fr >= 14) *(f32x4*)(edge + (unsigned)((grp * 4 + (fr - 12)) * UPN + jn)) = ag;
;                         const f32x4 o = gelu4(bg + wg0 * g2 + wg1 * g1 + wg2 * ag) * cu[m];
;                         if (!(m == 0 && fr < 2)) *(u32x2*)(act + (unsigned)(row * DFF + jn)) = pack4(o);
;                         pg1 = rg1; pg2 = rg2; }
	v_cndmask_b32_e64 v92, v172, v43, s[6:7]
	v_cndmask_b32_e64 v89, v169, v41, s[8:9]
	v_cndmask_b32_e64 v88, v146, v40, s[8:9]
	v_pk_fma_f32 v[92:93], v[28:29], v[92:93], v[32:33]
	v_and_b32_e32 v39, 0xffff0000, v168
	v_pk_fma_f32 v[88:89], v[20:21], v[88:89], v[92:93]
	s_nop 1
	v_pk_fma_f32 v[36:37], v[24:25], v[36:37], v[88:89]
	s_nop 1
	v_and_b32_e32 v93, 0x7fffffff, v37
	v_and_b32_e32 v92, 0x7fffffff, v36
	v_pk_fma_f32 v[92:93], v[92:93], s[52:53], 1.0 op_sel_hi:[1,0,0]
	v_mov_b32_dpp v45, v38 row_ror:2 row_mask:0xf bank_mask:0xf
	v_rcp_f32_e32 v92, v92
	v_rcp_f32_e32 v93, v93
	v_mov_b32_dpp v81, v39 row_ror:2 row_mask:0xf bank_mask:0xf
	v_mov_b32_dpp v42, v38 row_ror:1 row_mask:0xf bank_mask:0xf
	v_mov_b32_dpp v47, v39 row_ror:1 row_mask:0xf bank_mask:0xf
	v_cndmask_b32_e64 v95, v193, v81, s[6:7]
	v_cndmask_b32_e64 v94, v192, v45, s[6:7]
	v_cndmask_b32_e64 v87, v171, v47, s[8:9]
	v_cndmask_b32_e64 v86, v170, v42, s[8:9]
	v_pk_fma_f32 v[94:95], v[30:31], v[94:95], v[34:35]
	v_pk_mul_f32 v[88:89], v[36:37], v[36:37]
	v_pk_fma_f32 v[86:87], v[22:23], v[86:87], v[94:95]
	v_pk_mul_f32 v[88:89], v[88:89], s[42:43] op_sel_hi:[1,0]
	v_pk_fma_f32 v[94:95], v[92:93], s[54:55], v[90:91] op_sel_hi:[1,0,0]
	v_exp_f32_e32 v88, v88
	v_exp_f32_e32 v89, v89
	v_pk_fma_f32 v[94:95], v[92:93], v[94:95], s[58:59] op_sel_hi:[1,1,0]
	v_cmp_gt_f32_e64 s[0:1], 0, v36
	v_pk_fma_f32 v[94:95], v[92:93], v[94:95], s[60:61] op_sel_hi:[1,1,0]
	v_pk_fma_f32 v[38:39], v[26:27], v[38:39], v[86:87]
	v_pk_fma_f32 v[94:95], v[92:93], v[94:95], s[62:63] op_sel_hi:[1,1,0]
	v_pk_mul_f32 v[86:87], v[38:39], v[38:39]
	v_pk_mul_f32 v[92:93], v[92:93], v[94:95]
	v_pk_mul_f32 v[86:87], v[86:87], s[42:43] op_sel_hi:[1,0]
	v_pk_mul_f32 v[88:89], v[88:89], v[92:93]
	v_exp_f32_e32 v86, v86
	v_pk_mul_f32 v[92:93], v[36:37], v[88:89]
	v_pk_fma_f32 v[88:89], v[36:37], v[88:89], v[36:37] neg_lo:[1,0,0] neg_hi:[1,0,0]
	v_exp_f32_e32 v87, v87
	v_cndmask_b32_e64 v36, v88, v92, s[0:1]
	v_cmp_gt_f32_e64 s[0:1], 0, v37
	v_and_b32_e32 v88, 0x7fffffff, v38
	v_add_u32_e32 v136, v148, v46
	v_cndmask_b32_e64 v37, v89, v93, s[0:1]
	v_and_b32_e32 v89, 0x7fffffff, v39
	v_pk_fma_f32 v[88:89], v[88:89], s[52:53], 1.0 op_sel_hi:[1,0,0]
	v_cmp_gt_f32_e64 s[0:1], 0, v38
	v_rcp_f32_e32 v88, v88
	v_rcp_f32_e32 v89, v89
	v_pk_mul_f32 v[36:37], v[82:83], v[36:37]
	s_nop 1
	v_cvt_pk_bf16_f32 v36, v36, v37
	v_pk_fma_f32 v[90:91], v[88:89], s[54:55], v[90:91] op_sel_hi:[1,0,0]
	s_nop 1
	v_pk_fma_f32 v[90:91], v[88:89], v[90:91], s[58:59] op_sel_hi:[1,1,0]
	s_nop 0
	v_pk_fma_f32 v[90:91], v[88:89], v[90:91], s[60:61] op_sel_hi:[1,1,0]
	s_nop 0
	v_pk_fma_f32 v[90:91], v[88:89], v[90:91], s[62:63] op_sel_hi:[1,1,0]
	s_nop 0
	v_pk_mul_f32 v[88:89], v[88:89], v[90:91]
	s_nop 0
	v_pk_mul_f32 v[86:87], v[86:87], v[88:89]
	s_nop 0
	v_pk_mul_f32 v[88:89], v[38:39], v[86:87]
	v_pk_fma_f32 v[86:87], v[38:39], v[86:87], v[38:39] neg_lo:[1,0,0] neg_hi:[1,0,0]
	s_nop 0
	v_cndmask_b32_e64 v38, v86, v88, s[0:1]
	v_cmp_gt_f32_e64 s[0:1], 0, v39
	s_nop 1
	v_cndmask_b32_e64 v39, v87, v89, s[0:1]
	v_pk_mul_f32 v[38:39], v[84:85], v[38:39]
	s_nop 1
	v_cvt_pk_bf16_f32 v37, v38, v39
	v_lshl_add_u64 v[38:39], v[136:137], 1, s[26:27]
	global_store_dwordx2 v[38:39], v[36:37], off
	v_lshlrev_b32_e32 v36, 16, v147
	v_and_b32_e32 v37, 0xffff0000, v147
	v_lshlrev_b32_e32 v38, 16, v149
	v_and_b32_e32 v39, 0xffff0000, v149
	s_nop 1
	v_mov_b32_dpp v82, v36 row_ror:1 row_mask:0xf bank_mask:0xf
	v_mov_b32_dpp v83, v37 row_ror:1 row_mask:0xf bank_mask:0xf
	v_mov_b32_dpp v84, v38 row_ror:1 row_mask:0xf bank_mask:0xf
	v_mov_b32_dpp v87, v39 row_ror:1 row_mask:0xf bank_mask:0xf
	v_mov_b32_dpp v85, v36 row_ror:2 row_mask:0xf bank_mask:0xf
	v_mov_b32_dpp v88, v37 row_ror:2 row_mask:0xf bank_mask:0xf
	v_mov_b32_dpp v86, v38 row_ror:2 row_mask:0xf bank_mask:0xf
	v_mov_b32_dpp v89, v39 row_ror:2 row_mask:0xf bank_mask:0xf
	s_and_saveexec_b64 s[0:1], vcc
	s_cbranch_execz .LBB0_1426
	v_add_u32_e32 v136, v46, v152
	v_lshl_add_u64 v[90:91], v[136:137], 2, s[28:29]
	global_store_dwordx4 v[90:91], v[36:39], off
.LBB0_1426:
	s_or_b64 exec, exec, s[0:1]
	v_cndmask_b32_e64 v91, v47, v87, s[8:9]
	v_cndmask_b32_e64 v90, v42, v84, s[8:9]
	v_cndmask_b32_e64 v42, v45, v86, s[6:7]
	v_cndmask_b32_e64 v87, v183, v191, s[6:7]
	v_cndmask_b32_e64 v86, v182, v190, s[6:7]
	v_cndmask_b32_e64 v40, v40, v82, s[8:9]
	v_cndmask_b32_e64 v82, v43, v85, s[6:7]
	v_cndmask_b32_e64 v85, v180, v188, s[8:9]
	v_cndmask_b32_e64 v84, v174, v185, s[8:9]
	v_pk_fma_f32 v[10:11], v[10:11], v[86:87], v[14:15]
	v_cndmask_b32_e64 v41, v41, v83, s[8:9]
	v_cndmask_b32_e64 v83, v80, v88, s[6:7]
	v_pk_fma_f32 v[2:3], v[2:3], v[84:85], v[10:11]
	v_cndmask_b32_e64 v43, v81, v89, s[6:7]
	v_pk_fma_f32 v[2:3], v[6:7], v[18:19], v[2:3]
	v_pk_fma_f32 v[6:7], v[28:29], v[82:83], v[32:33]
	v_cndmask_b32_e64 v89, v181, v189, s[6:7]
	v_pk_fma_f32 v[6:7], v[20:21], v[40:41], v[6:7]
	v_cndmask_b32_e64 v88, v178, v186, s[6:7]
	v_pk_fma_f32 v[6:7], v[24:25], v[36:37], v[6:7]
	v_pk_fma_f32 v[8:9], v[8:9], v[88:89], v[12:13]
	v_and_b32_e32 v13, 0x7fffffff, v7
	v_and_b32_e32 v12, 0x7fffffff, v6
	v_pk_fma_f32 v[12:13], v[12:13], s[52:53], 1.0 op_sel_hi:[1,0,0]
	v_cndmask_b32_e64 v81, v179, v187, s[8:9]
	v_rcp_f32_e32 v12, v12
	v_rcp_f32_e32 v13, v13
	v_cndmask_b32_e64 v80, v173, v184, s[8:9]
	v_pk_fma_f32 v[0:1], v[0:1], v[80:81], v[8:9]
	v_pk_mul_f32 v[10:11], v[6:7], v[6:7]
	v_mov_b64_e32 v[14:15], s[56:57]
	v_pk_fma_f32 v[0:1], v[4:5], v[16:17], v[0:1]
	v_pk_mul_f32 v[10:11], v[10:11], s[42:43] op_sel_hi:[1,0]
	v_pk_fma_f32 v[16:17], v[12:13], s[54:55], v[14:15] op_sel_hi:[1,0,0]
	v_exp_f32_e32 v10, v10
;     __device__ __forceinline__ void operator()(AccRef acc, const Unit& u, int wr, int wc, int fr, int fq) const {
;     ...
;         for (int ai = 0; ai < 2; ++ai) {
;             const int rowg = u.pm * 256 + ai * 128 + wr * 64; const int grp = rowg >> 6;
; #pragma unroll
;             for (int n = 0; n < 2; ++n) { const unsigned jn = (unsigned)(j0 + 4 * n);
;                 f32x4 cu[4];
;                 {
;                     const f32x4 wu0 = *(const f32x4*)(cw + (DFF + jn)), wu1 = *(const f32x4*)(cw + (UPN + DFF + jn)), wu2 = *(const f32x4*)(cw + (2 * UPN + DFF + jn)), bu = *(const f32x4*)(cb + (DFF + jn));
;                     f32x4 pu1 = (f32x4){0.f, 0.f, 0.f, 0.f}, pu2 = pu1;
; #pragma unroll
;                     for (int m = 0; m < 4; ++m) {
;                         const f32x4 au = unpack4(pa[ai][1][m][n]);
;                         const f32x4 ru1 = ror1v(au), ru2 = ror2v(au);
;                         const f32x4 u1 = fr >= 1 ? ru1 : pu1, u2 = fr >= 2 ? ru2 : pu2;
;                         if (m == 0 && fr < 2) *(f32x4*)(edge + (unsigned)((grp * 4 + fr) * UPN + DFF + jn)) = au;
;                         if (m == 3 && fr >= 14) *(f32x4*)(edge + (unsigned)((grp * 4 + (fr - 12)) * UPN + DFF + jn)) = au;
;                         cu[m] = bu + wu0 * u2 + wu1 * u1 + wu2 * au;
;                         pu1 = ru1; pu2 = ru2; }
;                 }
;                 {
;                     const f32x4 wg0 = *(const f32x4*)(cw + jn), wg1 = *(const f32x4*)(cw + (UPN + jn)), wg2 = *(const f32x4*)(cw + (2 * UPN + jn)), bg = *(const f32x4*)(cb + jn);
;                     f32x4 pg1 = (f32x4){0.f, 0.f, 0.f, 0.f}, pg2 = pg1;
; #pragma unroll
;                     for (int m = 0; m < 4; ++m) { const int row = rowg + m * 16 + fr;
;                         const f32x4 ag = unpack4(pa[ai][0][m][n]);
;                         const f32x4 rg1 = ror1v(ag), rg2 = ror2v(ag);
;                         const f32x4 g1 = fr >= 1 ? rg1 : pg1, g2 = fr >= 2 ? rg2 : pg2;
;                         if (m == 0 && fr < 2) *(f32x4*)(edge + (unsigned)((grp * 4 + fr) * UPN + jn)) = ag;
;                         if (m == 3 && fr >= 14) *(f32x4*)(edge + (unsigned)((grp * 4 + (fr - 12)) * UPN + jn)) = ag;
;                         const f32x4 o = gelu4(bg + wg0 * g2 + wg1 * g1 + wg2 * ag) * cu[m];
	v_exp_f32_e32 v11, v11
	v_pk_fma_f32 v[16:17], v[12:13], v[16:17], s[58:59] op_sel_hi:[1,1,0]
	v_pk_fma_f32 v[4:5], v[30:31], v[42:43], v[34:35]
	v_pk_fma_f32 v[16:17], v[12:13], v[16:17], s[60:61] op_sel_hi:[1,1,0]
	v_pk_fma_f32 v[4:5], v[22:23], v[90:91], v[4:5]
	v_pk_fma_f32 v[16:17], v[12:13], v[16:17], s[62:63] op_sel_hi:[1,1,0]
	v_cmp_gt_f32_e64 s[0:1], 0, v6
	v_pk_mul_f32 v[12:13], v[12:13], v[16:17]
	v_pk_fma_f32 v[4:5], v[26:27], v[38:39], v[4:5]
	v_pk_mul_f32 v[10:11], v[10:11], v[12:13]
	v_pk_mul_f32 v[8:9], v[4:5], v[4:5]
	v_pk_mul_f32 v[12:13], v[6:7], v[10:11]
	v_pk_fma_f32 v[10:11], v[6:7], v[10:11], v[6:7] neg_lo:[1,0,0] neg_hi:[1,0,0]
	v_pk_mul_f32 v[8:9], v[8:9], s[42:43] op_sel_hi:[1,0]
	v_cndmask_b32_e64 v6, v10, v12, s[0:1]
	v_cmp_gt_f32_e64 s[0:1], 0, v7
	v_and_b32_e32 v10, 0x7fffffff, v4
	v_exp_f32_e32 v8, v8
	v_cndmask_b32_e64 v7, v11, v13, s[0:1]
	v_and_b32_e32 v11, 0x7fffffff, v5
	v_pk_fma_f32 v[10:11], v[10:11], s[52:53], 1.0 op_sel_hi:[1,0,0]
	v_exp_f32_e32 v9, v9
	v_rcp_f32_e32 v10, v10
	v_rcp_f32_e32 v11, v11
	v_cmp_gt_f32_e64 s[0:1], 0, v4
	v_pk_mul_f32 v[0:1], v[0:1], v[6:7]
	v_add_u32_e32 v136, v177, v46
	v_pk_fma_f32 v[12:13], v[10:11], s[54:55], v[14:15] op_sel_hi:[1,0,0]
	v_cvt_pk_bf16_f32 v0, v0, v1
	s_addk_i32 s65, 0x80
	v_pk_fma_f32 v[12:13], v[10:11], v[12:13], s[58:59] op_sel_hi:[1,1,0]
	s_ashr_i32 s69, s65, 4
	v_pk_fma_f32 v[12:13], v[10:11], v[12:13], s[60:61] op_sel_hi:[1,1,0]
	v_add_u32_e32 v16, s69, v166
	v_pk_fma_f32 v[12:13], v[10:11], v[12:13], s[62:63] op_sel_hi:[1,1,0]
	v_mul_lo_u32 v80, v16, s85
	v_pk_mul_f32 v[10:11], v[10:11], v[12:13]
	v_lshlrev_b32_e32 v36, 16, v120
	v_pk_mul_f32 v[8:9], v[8:9], v[10:11]
	v_and_b32_e32 v37, 0xffff0000, v120
	v_pk_mul_f32 v[10:11], v[4:5], v[8:9]
	v_pk_fma_f32 v[8:9], v[4:5], v[8:9], v[4:5] neg_lo:[1,0,0] neg_hi:[1,0,0]
	v_lshlrev_b32_e32 v38, 16, v121
	v_cndmask_b32_e64 v4, v8, v10, s[0:1]
	v_cmp_gt_f32_e64 s[0:1], 0, v5
	v_and_b32_e32 v39, 0xffff0000, v121
	s_nop 1
	v_cndmask_b32_e64 v5, v9, v11, s[0:1]
	v_pk_mul_f32 v[2:3], v[2:3], v[4:5]
	s_nop 1
	v_cvt_pk_bf16_f32 v1, v2, v3
	v_lshl_add_u64 v[2:3], v[136:137], 1, s[26:27]
	global_store_dwordx2 v[2:3], v[0:1], off
	global_load_dwordx4 v[8:11], v[48:49], off
	global_load_dwordx4 v[4:7], v[50:51], off
	s_nop 0
	global_load_dwordx4 v[0:3], v[52:53], off
	global_load_dwordx4 v[12:15], v[54:55], off
	s_nop 1
	v_add_u32_e32 v45, 0xb00, v80
	v_mov_b32_dpp v146, v36 row_ror:1 row_mask:0xf bank_mask:0xf
	v_mov_b32_dpp v149, v37 row_ror:1 row_mask:0xf bank_mask:0xf
	v_mov_b32_dpp v147, v38 row_ror:1 row_mask:0xf bank_mask:0xf
	v_mov_b32_dpp v167, v39 row_ror:1 row_mask:0xf bank_mask:0xf
	v_mov_b32_dpp v148, v36 row_ror:2 row_mask:0xf bank_mask:0xf
	v_mov_b32_dpp v168, v37 row_ror:2 row_mask:0xf bank_mask:0xf
	v_mov_b32_dpp v172, v38 row_ror:2 row_mask:0xf bank_mask:0xf
	v_mov_b32_dpp v174, v39 row_ror:2 row_mask:0xf bank_mask:0xf
	s_and_saveexec_b64 s[0:1], s[12:13]
	s_cbranch_execz .LBB0_1428
	v_add_u32_e32 v136, v45, v44
	v_lshl_add_u64 v[16:17], v[136:137], 2, s[28:29]
	global_store_dwordx4 v[16:17], v[36:39], off
.LBB0_1428:
	s_or_b64 exec, exec, s[0:1]
	v_add_u32_e32 v16, s69, v150
	v_mul_lo_u32 v47, v16, s85
	v_lshlrev_b32_e32 v54, 16, v122
	v_and_b32_e32 v55, 0xffff0000, v122
	v_lshlrev_b32_e32 v52, 16, v123
	v_and_b32_e32 v53, 0xffff0000, v123
	s_nop 1
	v_lshlrev_b32_e32 v50, 16, v124
	v_and_b32_e32 v51, 0xffff0000, v124
	v_lshlrev_b32_e32 v48, 16, v125
	v_and_b32_e32 v49, 0xffff0000, v125
	s_nop 1
	v_lshlrev_b32_e32 v16, 16, v126
	v_and_b32_e32 v17, 0xffff0000, v126
	v_lshlrev_b32_e32 v18, 16, v127
	v_and_b32_e32 v19, 0xffff0000, v127
	s_nop 1
	v_add_u32_e32 v81, 0xb00, v47
	v_mov_b32_dpp v123, v54 row_ror:1 row_mask:0xf bank_mask:0xf
	v_mov_b32_dpp v169, v55 row_ror:1 row_mask:0xf bank_mask:0xf
	v_mov_b32_dpp v150, v52 row_ror:1 row_mask:0xf bank_mask:0xf
	v_mov_b32_dpp v170, v53 row_ror:1 row_mask:0xf bank_mask:0xf
	v_mov_b32_dpp v152, v54 row_ror:2 row_mask:0xf bank_mask:0xf
	v_mov_b32_dpp v171, v55 row_ror:2 row_mask:0xf bank_mask:0xf
	v_mov_b32_dpp v173, v52 row_ror:2 row_mask:0xf bank_mask:0xf
	v_mov_b32_dpp v175, v53 row_ror:2 row_mask:0xf bank_mask:0xf
	v_mov_b32_dpp v83, v50 row_ror:1 row_mask:0xf bank_mask:0xf
	v_mov_b32_dpp v86, v51 row_ror:1 row_mask:0xf bank_mask:0xf
	v_mov_b32_dpp v84, v48 row_ror:1 row_mask:0xf bank_mask:0xf
	v_mov_b32_dpp v87, v49 row_ror:1 row_mask:0xf bank_mask:0xf
	v_mov_b32_dpp v85, v50 row_ror:2 row_mask:0xf bank_mask:0xf
	v_mov_b32_dpp v88, v51 row_ror:2 row_mask:0xf bank_mask:0xf
	v_mov_b32_dpp v89, v48 row_ror:2 row_mask:0xf bank_mask:0xf
	v_mov_b32_dpp v90, v49 row_ror:2 row_mask:0xf bank_mask:0xf
	v_mov_b32_dpp v91, v16 row_ror:1 row_mask:0xf bank_mask:0xf
	v_mov_b32_dpp v94, v17 row_ror:1 row_mask:0xf bank_mask:0xf
	v_mov_b32_dpp v92, v18 row_ror:1 row_mask:0xf bank_mask:0xf
	v_mov_b32_dpp v95, v19 row_ror:1 row_mask:0xf bank_mask:0xf
	v_mov_b32_dpp v93, v16 row_ror:2 row_mask:0xf bank_mask:0xf
	v_mov_b32_dpp v120, v17 row_ror:2 row_mask:0xf bank_mask:0xf
	v_mov_b32_dpp v121, v18 row_ror:2 row_mask:0xf bank_mask:0xf
	v_mov_b32_dpp v122, v19 row_ror:2 row_mask:0xf bank_mask:0xf
	s_and_saveexec_b64 s[0:1], vcc
	s_cbranch_execz .LBB0_1430
	v_add_u32_e32 v136, v81, v44
	v_lshl_add_u64 v[20:21], v[136:137], 2, s[28:29]
	global_store_dwordx4 v[20:21], v[16:19], off
; __device__ __forceinline__ f32x4 gelu4(f32x4 v) { const f32x2 a = gelu_pk((f32x2){v[0], v[1]}), b = gelu_pk((f32x2){v[2], v[3]}); return (f32x4){a.x, a.y, b.x, b.y}; }
; __device__ __forceinline__ f32x4 ror1v(f32x4 v) { return (f32x4){dpp_ror1(v[0]), dpp_ror1(v[1]), dpp_ror1(v[2]), dpp_ror1(v[3])}; }
; __device__ __forceinline__ f32x4 ror2v(f32x4 v) { return (f32x4){dpp_ror2(v[0]), dpp_ror2(v[1]), dpp_ror2(v[2]), dpp_ror2(v[3])}; }
; __device__ __forceinline__ u32x2 pack4(f32x4 v) { return (u32x2){pk2(v[0], v[1]), pk2(v[2], v[3])}; }
; __device__ __forceinline__ f32x2 gelu_pk(f32x2 v) {
;     const f32x2 av = __builtin_elementwise_abs(v), d = av * 0.2316418882f + 1.0f;
;     f32x2 t; t.x = __builtin_amdgcn_rcpf(d.x); t.y = __builtin_amdgcn_rcpf(d.y);
;     f32x2 q = t * 0.5307027145f + (-0.7265760135f); q = q * t + 0.7107068705f; q = q * t + (-0.142248368f); q = q * t + 0.127414796f; q = q * t;
;     const f32x2 s = (v * v) * (-0.72134752044f);
;     f32x2 e; e.x = __builtin_amdgcn_exp2f(s.x); e.y = __builtin_amdgcn_exp2f(s.y);
;     const f32x2 m = v * (q * e), r = v - m;
;     f32x2 o; o.x = v.x < 0.f ? m.x : r.x; o.y = v.y < 0.f ? m.y : r.y; return o;
;     __device__ __forceinline__ void operator()(AccRef acc, const Unit& u, int wr, int wc, int fr, int fq) const {
;     ...
;                     const f32x4 wg0 = *(const f32x4*)(cw + jn), wg1 = *(const f32x4*)(cw + (UPN + jn)), wg2 = *(const f32x4*)(cw + (2 * UPN + jn)), bg = *(const f32x4*)(cb + jn);
;                     f32x4 pg1 = (f32x4){0.f, 0.f, 0.f, 0.f}, pg2 = pg1;
; #pragma unroll
;                     for (int m = 0; m < 4; ++m) { const int row = rowg + m * 16 + fr;
;                         const f32x4 ag = unpack4(pa[ai][0][m][n]);
;                         const f32x4 rg1 = ror1v(ag), rg2 = ror2v(ag);
;                         const f32x4 g1 = fr >= 1 ? rg1 : pg1, g2 = fr >= 2 ? rg2 : pg2;
;                         if (m == 0 && fr < 2) *(f32x4*)(edge + (unsigned)((grp * 4 + fr) * UPN + jn)) = ag;
;                         if (m == 3 && fr >= 14) *(f32x4*)(edge + (unsigned)((grp * 4 + (fr - 12)) * UPN + jn)) = ag;
;                         const f32x4 o = gelu4(bg + wg0 * g2 + wg1 * g1 + wg2 * ag) * cu[m];
;                         if (!(m == 0 && fr < 2)) *(u32x2*)(act + (unsigned)(row * DFF + jn)) = pack4(o);
;                         pg1 = rg1; pg2 = rg2; }
.LBB0_1430:
	s_or_b64 exec, exec, s[0:1]
	global_load_dwordx4 v[28:31], v[56:57], off
	global_load_dwordx4 v[24:27], v[58:59], off
	global_load_dwordx4 v[20:23], v[62:63], off
	global_load_dwordx4 v[32:35], v[64:65], off
	v_add_u32_e32 v124, s65, v166
	v_lshlrev_b32_e32 v40, 16, v118
	v_and_b32_e32 v41, 0xffff0000, v118
	v_lshlrev_b32_e32 v42, 16, v119
	v_and_b32_e32 v43, 0xffff0000, v119
	s_nop 1
	v_mov_b32_dpp v56, v40 row_ror:1 row_mask:0xf bank_mask:0xf
	v_mov_b32_dpp v57, v41 row_ror:1 row_mask:0xf bank_mask:0xf
	v_mov_b32_dpp v58, v42 row_ror:1 row_mask:0xf bank_mask:0xf
	v_mov_b32_dpp v59, v43 row_ror:1 row_mask:0xf bank_mask:0xf
	v_mov_b32_dpp v62, v40 row_ror:2 row_mask:0xf bank_mask:0xf
	v_mov_b32_dpp v63, v41 row_ror:2 row_mask:0xf bank_mask:0xf
	v_mov_b32_dpp v64, v42 row_ror:2 row_mask:0xf bank_mask:0xf
	v_mov_b32_dpp v65, v43 row_ror:2 row_mask:0xf bank_mask:0xf
	v_mul_lo_u32 v82, v124, s86
	s_and_saveexec_b64 s[0:1], s[10:11]
	s_xor_b64 s[74:75], exec, s[0:1]
	s_cbranch_execz .LBB0_1432
	v_cndmask_b32_e64 v179, 0, v174, s[6:7]
	v_cndmask_b32_e64 v178, 0, v172, s[6:7]
	v_cndmask_b32_e64 v127, 0, v167, s[8:9]
	v_cndmask_b32_e64 v126, 0, v147, s[8:9]
	s_waitcnt vmcnt(4)
	v_pk_fma_f32 v[178:179], v[10:11], v[178:179], v[14:15]
	v_cndmask_b32_e64 v181, 0, v168, s[6:7]
	v_pk_fma_f32 v[126:127], v[6:7], v[126:127], v[178:179]
	v_cndmask_b32_e64 v180, 0, v148, s[6:7]
	v_pk_fma_f32 v[38:39], v[2:3], v[38:39], v[126:127]
	s_waitcnt vmcnt(0)
	v_pk_fma_f32 v[126:127], v[28:29], v[62:63], v[32:33]
	v_cndmask_b32_e64 v119, 0, v149, s[8:9]
	v_pk_fma_f32 v[126:127], v[24:25], v[56:57], v[126:127]
	v_cndmask_b32_e64 v118, 0, v146, s[8:9]
	v_pk_fma_f32 v[40:41], v[20:21], v[40:41], v[126:127]
	v_pk_fma_f32 v[180:181], v[8:9], v[180:181], v[12:13]
	v_and_b32_e32 v179, 0x7fffffff, v41
	v_and_b32_e32 v178, 0x7fffffff, v40
	v_pk_fma_f32 v[178:179], v[178:179], s[52:53], 1.0 op_sel_hi:[1,0,0]
	v_pk_fma_f32 v[118:119], v[4:5], v[118:119], v[180:181]
	v_rcp_f32_e32 v178, v178
	v_rcp_f32_e32 v179, v179
	v_pk_mul_f32 v[126:127], v[40:41], v[40:41]
	v_mov_b64_e32 v[180:181], s[56:57]
	v_pk_mul_f32 v[126:127], v[126:127], s[42:43] op_sel_hi:[1,0]
	v_pk_fma_f32 v[182:183], v[178:179], s[54:55], v[180:181] op_sel_hi:[1,0,0]
	v_exp_f32_e32 v126, v126
	v_exp_f32_e32 v127, v127
	v_pk_fma_f32 v[182:183], v[178:179], v[182:183], s[58:59] op_sel_hi:[1,1,0]
	v_pk_fma_f32 v[36:37], v[0:1], v[36:37], v[118:119]
	v_pk_fma_f32 v[182:183], v[178:179], v[182:183], s[60:61] op_sel_hi:[1,1,0]
	v_pk_fma_f32 v[118:119], v[30:31], v[64:65], v[34:35]
	v_pk_fma_f32 v[182:183], v[178:179], v[182:183], s[62:63] op_sel_hi:[1,1,0]
	v_pk_fma_f32 v[118:119], v[26:27], v[58:59], v[118:119]
	v_pk_mul_f32 v[178:179], v[178:179], v[182:183]
	v_cmp_gt_f32_e64 s[0:1], 0, v40
	v_pk_mul_f32 v[126:127], v[126:127], v[178:179]
	v_pk_fma_f32 v[42:43], v[22:23], v[42:43], v[118:119]
	v_pk_mul_f32 v[178:179], v[40:41], v[126:127]
	v_pk_fma_f32 v[126:127], v[40:41], v[126:127], v[40:41] neg_lo:[1,0,0] neg_hi:[1,0,0]
	v_pk_mul_f32 v[118:119], v[42:43], v[42:43]
	v_cndmask_b32_e64 v40, v126, v178, s[0:1]
	v_cmp_gt_f32_e64 s[0:1], 0, v41
	v_and_b32_e32 v126, 0x7fffffff, v42
	v_pk_mul_f32 v[118:119], v[118:119], s[42:43] op_sel_hi:[1,0]
	v_cndmask_b32_e64 v41, v127, v179, s[0:1]
	v_and_b32_e32 v127, 0x7fffffff, v43
	v_pk_fma_f32 v[126:127], v[126:127], s[52:53], 1.0 op_sel_hi:[1,0,0]
	v_exp_f32_e32 v118, v118
	v_rcp_f32_e32 v126, v126
	v_rcp_f32_e32 v127, v127
	v_exp_f32_e32 v119, v119
	v_cmp_gt_f32_e64 s[0:1], 0, v42
	v_mul_lo_u32 v82, v124, s86
	v_pk_fma_f32 v[178:179], v[126:127], s[54:55], v[180:181] op_sel_hi:[1,0,0]
	v_pk_mul_f32 v[36:37], v[36:37], v[40:41]
	v_pk_fma_f32 v[178:179], v[126:127], v[178:179], s[58:59] op_sel_hi:[1,1,0]
	v_add_u32_e32 v136, v82, v44
	v_pk_fma_f32 v[178:179], v[126:127], v[178:179], s[60:61] op_sel_hi:[1,1,0]
	v_cvt_pk_bf16_f32 v36, v36, v37
	s_nop 0
	v_pk_fma_f32 v[178:179], v[126:127], v[178:179], s[62:63] op_sel_hi:[1,1,0]
	s_nop 0
	v_pk_mul_f32 v[126:127], v[126:127], v[178:179]
	s_nop 0
	v_pk_mul_f32 v[118:119], v[118:119], v[126:127]
	s_nop 0
	v_pk_mul_f32 v[126:127], v[42:43], v[118:119]
	v_pk_fma_f32 v[118:119], v[42:43], v[118:119], v[42:43] neg_lo:[1,0,0] neg_hi:[1,0,0]
	s_nop 0
	v_cndmask_b32_e64 v42, v118, v126, s[0:1]
	v_cmp_gt_f32_e64 s[0:1], 0, v43
	s_nop 1
	v_cndmask_b32_e64 v43, v119, v127, s[0:1]
	v_pk_mul_f32 v[38:39], v[38:39], v[42:43]
	s_nop 0
	v_cvt_pk_bf16_f32 v37, v38, v39
	v_lshl_add_u64 v[38:39], v[136:137], 1, s[26:27]
	global_store_dwordx2 v[38:39], v[36:37], off

;     __device__ __forceinline__ void operator()(AccRef acc, const Unit& u, int wr, int wc, int fr, int fq) const {
;     ...
;             for (int n = 0; n < 2; ++n) { const unsigned jn = (unsigned)(j0 + 4 * n);
;                 f32x4 cu[4];
;                 {
;                     const f32x4 wu0 = *(const f32x4*)(cw + (DFF + jn)), wu1 = *(const f32x4*)(cw + (UPN + DFF + jn)), wu2 = *(const f32x4*)(cw + (2 * UPN + DFF + jn)), bu = *(const f32x4*)(cb + (DFF + jn));
;                     f32x4 pu1 = (f32x4){0.f, 0.f, 0.f, 0.f}, pu2 = pu1;
; #pragma unroll
;                     for (int m = 0; m < 4; ++m) {
;                         const f32x4 au = unpack4(pa[ai][1][m][n]);
;                         const f32x4 ru1 = ror1v(au), ru2 = ror2v(au);
;                         const f32x4 u1 = fr >= 1 ? ru1 : pu1, u2 = fr >= 2 ? ru2 : pu2;
;                         if (m == 0 && fr < 2) *(f32x4*)(edge + (unsigned)((grp * 4 + fr) * UPN + DFF + jn)) = au;
;                         if (m == 3 && fr >= 14) *(f32x4*)(edge + (unsigned)((grp * 4 + (fr - 12)) * UPN + DFF + jn)) = au;
;                         cu[m] = bu + wu0 * u2 + wu1 * u1 + wu2 * au;
;                         pu1 = ru1; pu2 = ru2; }
;                 }
;                 {
;                     const f32x4 wg0 = *(const f32x4*)(cw + jn), wg1 = *(const f32x4*)(cw + (UPN + jn)), wg2 = *(const f32x4*)(cw + (2 * UPN + jn)), bg = *(const f32x4*)(cb + jn);
;                     f32x4 pg1 = (f32x4){0.f, 0.f, 0.f, 0.f}, pg2 = pg1;
; #pragma unroll
;                     for (int m = 0; m < 4; ++m) { const int row = rowg + m * 16 + fr;
;                         const f32x4 ag = unpack4(pa[ai][0][m][n]);
;                         const f32x4 rg1 = ror1v(ag), rg2 = ror2v(ag);
;                         const f32x4 g1 = fr >= 1 ? rg1 : pg1, g2 = fr >= 2 ? rg2 : pg2;
;                         if (m == 0 && fr < 2) *(f32x4*)(edge + (unsigned)((grp * 4 + fr) * UPN + jn)) = ag;
;                         if (m == 3 && fr >= 14) *(f32x4*)(edge + (unsigned)((grp * 4 + (fr - 12)) * UPN + jn)) = ag;
;                         const f32x4 o = gelu4(bg + wg0 * g2 + wg1 * g1 + wg2 * ag) * cu[m];
;                         if (!(m == 0 && fr < 2)) *(u32x2*)(act + (unsigned)(row * DFF + jn)) = pack4(o);
;                         pg1 = rg1; pg2 = rg2; }
.LBB0_1434:
	s_or_b64 exec, exec, s[0:1]
	s_nop 0
	v_cndmask_b32_e64 v41, v174, v175, s[6:7]
	v_cndmask_b32_e64 v40, v172, v173, s[6:7]
	v_cndmask_b32_e64 v43, v168, v171, s[6:7]
	v_cndmask_b32_e64 v42, v148, v152, s[6:7]
	v_cndmask_b32_e64 v37, v149, v169, s[8:9]
	v_cndmask_b32_e64 v36, v146, v123, s[8:9]
	v_cndmask_b32_e64 v39, v167, v170, s[8:9]
	v_cndmask_b32_e64 v38, v147, v150, s[8:9]
	s_waitcnt vmcnt(4)
	v_pk_fma_f32 v[42:43], v[8:9], v[42:43], v[12:13]
	v_pk_fma_f32 v[40:41], v[10:11], v[40:41], v[14:15]
	v_pk_fma_f32 v[36:37], v[4:5], v[36:37], v[42:43]
	v_pk_fma_f32 v[38:39], v[6:7], v[38:39], v[40:41]
	v_pk_fma_f32 v[36:37], v[0:1], v[54:55], v[36:37]
	v_pk_fma_f32 v[38:39], v[2:3], v[52:53], v[38:39]
	v_cndmask_b32_e64 v53, v175, v90, s[6:7]
	v_cndmask_b32_e64 v52, v173, v89, s[6:7]
	v_cndmask_b32_e64 v55, v171, v88, s[6:7]
	v_cndmask_b32_e64 v54, v152, v85, s[6:7]
	v_cndmask_b32_e64 v41, v169, v86, s[8:9]
	v_cndmask_b32_e64 v40, v123, v83, s[8:9]
	v_cndmask_b32_e64 v43, v170, v87, s[8:9]
	v_cndmask_b32_e64 v42, v150, v84, s[8:9]
	v_pk_fma_f32 v[54:55], v[8:9], v[54:55], v[12:13]
	v_pk_fma_f32 v[52:53], v[10:11], v[52:53], v[14:15]
	v_pk_fma_f32 v[40:41], v[4:5], v[40:41], v[54:55]
	v_pk_fma_f32 v[42:43], v[6:7], v[42:43], v[52:53]
	v_pk_fma_f32 v[52:53], v[0:1], v[50:51], v[40:41]
	v_pk_fma_f32 v[54:55], v[2:3], v[48:49], v[42:43]
	v_lshlrev_b32_e32 v40, 16, v116
	v_and_b32_e32 v41, 0xffff0000, v116
	v_lshlrev_b32_e32 v42, 16, v117
	v_and_b32_e32 v43, 0xffff0000, v117
	v_mov_b32_e32 v116, v137
	v_mov_b32_e32 v117, v137
	v_mov_b32_e32 v123, v137
	v_mov_b32_e32 v124, v137
	v_mov_b32_dpp v116, v40 row_ror:1 row_mask:0xf bank_mask:0xf
	v_mov_b32_dpp v117, v41 row_ror:1 row_mask:0xf bank_mask:0xf
	v_mov_b32_dpp v123, v40 row_ror:2 row_mask:0xf bank_mask:0xf
	v_mov_b32_dpp v124, v41 row_ror:2 row_mask:0xf bank_mask:0xf
	v_cndmask_b32_e64 v51, v57, v117, s[8:9]
	v_cndmask_b32_e64 v50, v56, v116, s[8:9]
	v_cndmask_b32_e64 v57, v63, v124, s[6:7]
	v_cndmask_b32_e64 v56, v62, v123, s[6:7]
	s_waitcnt vmcnt(0)
	v_pk_fma_f32 v[56:57], v[28:29], v[56:57], v[32:33]
	v_mov_b32_e32 v118, v137
	v_pk_fma_f32 v[50:51], v[24:25], v[50:51], v[56:57]
	v_mov_b32_e32 v119, v137
	v_pk_fma_f32 v[40:41], v[20:21], v[40:41], v[50:51]
	v_mov_b32_e32 v125, v137
	v_and_b32_e32 v57, 0x7fffffff, v41
	v_and_b32_e32 v56, 0x7fffffff, v40
	v_mov_b32_e32 v126, v137
	v_pk_fma_f32 v[56:57], v[56:57], s[52:53], 1.0 op_sel_hi:[1,0,0]
	v_mov_b32_dpp v118, v42 row_ror:1 row_mask:0xf bank_mask:0xf
	v_mov_b32_dpp v119, v43 row_ror:1 row_mask:0xf bank_mask:0xf
	v_mov_b32_dpp v125, v42 row_ror:2 row_mask:0xf bank_mask:0xf
	v_mov_b32_dpp v126, v43 row_ror:2 row_mask:0xf bank_mask:0xf
	v_rcp_f32_e32 v56, v56
	v_rcp_f32_e32 v57, v57
	v_cndmask_b32_e64 v49, v59, v119, s[8:9]
	v_cndmask_b32_e64 v48, v58, v118, s[8:9]
	v_cndmask_b32_e64 v59, v65, v126, s[6:7]
	v_cndmask_b32_e64 v58, v64, v125, s[6:7]
	v_pk_fma_f32 v[58:59], v[30:31], v[58:59], v[34:35]
	v_pk_mul_f32 v[50:51], v[40:41], v[40:41]
	v_pk_fma_f32 v[48:49], v[26:27], v[48:49], v[58:59]
	v_mov_b64_e32 v[58:59], s[56:57]
	v_pk_mul_f32 v[50:51], v[50:51], s[42:43] op_sel_hi:[1,0]
	v_pk_fma_f32 v[62:63], v[56:57], s[54:55], v[58:59] op_sel_hi:[1,0,0]
	v_exp_f32_e32 v50, v50
	v_exp_f32_e32 v51, v51
	v_pk_fma_f32 v[62:63], v[56:57], v[62:63], s[58:59] op_sel_hi:[1,1,0]
	v_cmp_gt_f32_e64 s[0:1], 0, v40
	v_pk_fma_f32 v[62:63], v[56:57], v[62:63], s[60:61] op_sel_hi:[1,1,0]
	v_pk_fma_f32 v[42:43], v[22:23], v[42:43], v[48:49]
	v_pk_fma_f32 v[62:63], v[56:57], v[62:63], s[62:63] op_sel_hi:[1,1,0]
	v_pk_mul_f32 v[48:49], v[42:43], v[42:43]
	v_pk_mul_f32 v[56:57], v[56:57], v[62:63]
	v_pk_mul_f32 v[48:49], v[48:49], s[42:43] op_sel_hi:[1,0]
	v_pk_mul_f32 v[50:51], v[50:51], v[56:57]
	v_exp_f32_e32 v48, v48
	v_pk_mul_f32 v[56:57], v[40:41], v[50:51]
	v_pk_fma_f32 v[50:51], v[40:41], v[50:51], v[40:41] neg_lo:[1,0,0] neg_hi:[1,0,0]
	v_exp_f32_e32 v49, v49
	v_cndmask_b32_e64 v40, v50, v56, s[0:1]
	v_cmp_gt_f32_e64 s[0:1], 0, v41
	v_and_b32_e32 v50, 0x7fffffff, v42
	v_add_u32_e32 v62, 0xb000, v82
	v_cndmask_b32_e64 v41, v51, v57, s[0:1]
	v_and_b32_e32 v51, 0x7fffffff, v43
	v_pk_fma_f32 v[50:51], v[50:51], s[52:53], 1.0 op_sel_hi:[1,0,0]
	v_cmp_gt_f32_e64 s[0:1], 0, v42
	v_rcp_f32_e32 v50, v50
	v_rcp_f32_e32 v51, v51
	v_pk_mul_f32 v[36:37], v[36:37], v[40:41]
	v_add_u32_e32 v136, v62, v44
	v_cvt_pk_bf16_f32 v36, v36, v37
	v_pk_fma_f32 v[56:57], v[50:51], s[54:55], v[58:59] op_sel_hi:[1,0,0]
	s_nop 1
	v_pk_fma_f32 v[56:57], v[50:51], v[56:57], s[58:59] op_sel_hi:[1,1,0]
	s_nop 1
	v_pk_fma_f32 v[56:57], v[50:51], v[56:57], s[60:61] op_sel_hi:[1,1,0]
	v_add_u32_e32 v63, 0x16000, v82
	v_pk_fma_f32 v[56:57], v[50:51], v[56:57], s[62:63] op_sel_hi:[1,1,0]
	s_nop 0
	v_pk_mul_f32 v[50:51], v[50:51], v[56:57]
	s_nop 0
	v_pk_mul_f32 v[48:49], v[48:49], v[50:51]
	s_nop 0
	v_pk_mul_f32 v[50:51], v[42:43], v[48:49]
	v_pk_fma_f32 v[48:49], v[42:43], v[48:49], v[42:43] neg_lo:[1,0,0] neg_hi:[1,0,0]
	s_nop 0
	v_cndmask_b32_e64 v42, v48, v50, s[0:1]
	v_cmp_gt_f32_e64 s[0:1], 0, v43
	s_nop 1
	v_cndmask_b32_e64 v43, v49, v51, s[0:1]
	v_pk_mul_f32 v[38:39], v[38:39], v[42:43]
	s_nop 1
	v_cvt_pk_bf16_f32 v37, v38, v39
	v_lshl_add_u64 v[38:39], v[136:137], 1, s[26:27]
	global_store_dwordx2 v[38:39], v[36:37], off
	v_lshlrev_b32_e32 v36, 16, v114
	v_and_b32_e32 v37, 0xffff0000, v114
	v_lshlrev_b32_e32 v38, 16, v115
	v_mov_b32_dpp v43, v36 row_ror:2 row_mask:0xf bank_mask:0xf
	v_mov_b32_dpp v50, v37 row_ror:2 row_mask:0xf bank_mask:0xf
	v_and_b32_e32 v39, 0xffff0000, v115
	v_mov_b32_dpp v40, v36 row_ror:1 row_mask:0xf bank_mask:0xf
;     __device__ __forceinline__ void operator()(AccRef acc, const Unit& u, int wr, int wc, int fr, int fq) const {
;     ...
;             for (int n = 0; n < 2; ++n) { const unsigned jn = (unsigned)(j0 + 4 * n);
;                 f32x4 cu[4];
;                 {
;                     const f32x4 wu0 = *(const f32x4*)(cw + (DFF + jn)), wu1 = *(const f32x4*)(cw + (UPN + DFF + jn)), wu2 = *(const f32x4*)(cw + (2 * UPN + DFF + jn)), bu = *(const f32x4*)(cb + (DFF + jn));
;                     f32x4 pu1 = (f32x4){0.f, 0.f, 0.f, 0.f}, pu2 = pu1;
; #pragma unroll
;                     for (int m = 0; m < 4; ++m) {
;                         const f32x4 au = unpack4(pa[ai][1][m][n]);
;                         const f32x4 ru1 = ror1v(au), ru2 = ror2v(au);
;                         const f32x4 u1 = fr >= 1 ? ru1 : pu1, u2 = fr >= 2 ? ru2 : pu2;
;                         if (m == 0 && fr < 2) *(f32x4*)(edge + (unsigned)((grp * 4 + fr) * UPN + DFF + jn)) = au;
;                         if (m == 3 && fr >= 14) *(f32x4*)(edge + (unsigned)((grp * 4 + (fr - 12)) * UPN + DFF + jn)) = au;
;                         cu[m] = bu + wu0 * u2 + wu1 * u1 + wu2 * au;
;                         pu1 = ru1; pu2 = ru2; }
;                 }
;                 {
;                     const f32x4 wg0 = *(const f32x4*)(cw + jn), wg1 = *(const f32x4*)(cw + (UPN + jn)), wg2 = *(const f32x4*)(cw + (2 * UPN + jn)), bg = *(const f32x4*)(cb + jn);
;                     f32x4 pg1 = (f32x4){0.f, 0.f, 0.f, 0.f}, pg2 = pg1;
; #pragma unroll
;                     for (int m = 0; m < 4; ++m) { const int row = rowg + m * 16 + fr;
;                         const f32x4 ag = unpack4(pa[ai][0][m][n]);
;                         const f32x4 rg1 = ror1v(ag), rg2 = ror2v(ag);
;                         const f32x4 g1 = fr >= 1 ? rg1 : pg1, g2 = fr >= 2 ? rg2 : pg2;
;                         if (m == 0 && fr < 2) *(f32x4*)(edge + (unsigned)((grp * 4 + fr) * UPN + jn)) = ag;
;                         if (m == 3 && fr >= 14) *(f32x4*)(edge + (unsigned)((grp * 4 + (fr - 12)) * UPN + jn)) = ag;
;                         const f32x4 o = gelu4(bg + wg0 * g2 + wg1 * g1 + wg2 * ag) * cu[m];
;                         if (!(m == 0 && fr < 2)) *(u32x2*)(act + (unsigned)(row * DFF + jn)) = pack4(o);
;                         pg1 = rg1; pg2 = rg2; }
	v_mov_b32_dpp v41, v37 row_ror:1 row_mask:0xf bank_mask:0xf
	v_cndmask_b32_e64 v115, v124, v50, s[6:7]
	v_cndmask_b32_e64 v114, v123, v43, s[6:7]
	v_cndmask_b32_e64 v65, v117, v41, s[8:9]
	v_cndmask_b32_e64 v64, v116, v40, s[8:9]
	v_pk_fma_f32 v[114:115], v[28:29], v[114:115], v[32:33]
	s_nop 1
	v_pk_fma_f32 v[64:65], v[24:25], v[64:65], v[114:115]
	s_nop 1
	v_pk_fma_f32 v[36:37], v[20:21], v[36:37], v[64:65]
	s_nop 1
	v_and_b32_e32 v115, 0x7fffffff, v37
	v_and_b32_e32 v114, 0x7fffffff, v36
	v_pk_fma_f32 v[114:115], v[114:115], s[52:53], 1.0 op_sel_hi:[1,0,0]
	v_mov_b32_dpp v48, v38 row_ror:2 row_mask:0xf bank_mask:0xf
	v_rcp_f32_e32 v114, v114
	v_rcp_f32_e32 v115, v115
	v_mov_b32_dpp v51, v39 row_ror:2 row_mask:0xf bank_mask:0xf
	v_mov_b32_dpp v42, v38 row_ror:1 row_mask:0xf bank_mask:0xf
	v_mov_b32_dpp v49, v39 row_ror:1 row_mask:0xf bank_mask:0xf
	v_cndmask_b32_e64 v117, v126, v51, s[6:7]
	v_cndmask_b32_e64 v116, v125, v48, s[6:7]
	v_cndmask_b32_e64 v57, v119, v49, s[8:9]
	v_cndmask_b32_e64 v56, v118, v42, s[8:9]
	v_pk_fma_f32 v[116:117], v[30:31], v[116:117], v[34:35]
	v_pk_mul_f32 v[64:65], v[36:37], v[36:37]
	v_pk_fma_f32 v[56:57], v[26:27], v[56:57], v[116:117]
	v_pk_mul_f32 v[64:65], v[64:65], s[42:43] op_sel_hi:[1,0]
	v_pk_fma_f32 v[116:117], v[114:115], s[54:55], v[58:59] op_sel_hi:[1,0,0]
	v_exp_f32_e32 v64, v64
	v_exp_f32_e32 v65, v65
	v_pk_fma_f32 v[116:117], v[114:115], v[116:117], s[58:59] op_sel_hi:[1,1,0]
	v_cmp_gt_f32_e64 s[0:1], 0, v36
	v_pk_fma_f32 v[116:117], v[114:115], v[116:117], s[60:61] op_sel_hi:[1,1,0]
	v_pk_fma_f32 v[38:39], v[22:23], v[38:39], v[56:57]
	v_pk_fma_f32 v[116:117], v[114:115], v[116:117], s[62:63] op_sel_hi:[1,1,0]
	v_pk_mul_f32 v[56:57], v[38:39], v[38:39]
	v_pk_mul_f32 v[114:115], v[114:115], v[116:117]
	v_pk_mul_f32 v[56:57], v[56:57], s[42:43] op_sel_hi:[1,0]
	v_pk_mul_f32 v[64:65], v[64:65], v[114:115]
	v_exp_f32_e32 v56, v56
	v_pk_mul_f32 v[114:115], v[36:37], v[64:65]
	v_pk_fma_f32 v[64:65], v[36:37], v[64:65], v[36:37] neg_lo:[1,0,0] neg_hi:[1,0,0]
	v_exp_f32_e32 v57, v57
	v_cndmask_b32_e64 v36, v64, v114, s[0:1]
	v_cmp_gt_f32_e64 s[0:1], 0, v37
	v_and_b32_e32 v64, 0x7fffffff, v38
	v_add_u32_e32 v136, v63, v44
	v_cndmask_b32_e64 v37, v65, v115, s[0:1]
	v_and_b32_e32 v65, 0x7fffffff, v39
	v_pk_fma_f32 v[64:65], v[64:65], s[52:53], 1.0 op_sel_hi:[1,0,0]
	v_cmp_gt_f32_e64 s[0:1], 0, v38
	v_rcp_f32_e32 v64, v64
	v_rcp_f32_e32 v65, v65
	v_pk_mul_f32 v[36:37], v[52:53], v[36:37]
	s_nop 1
	v_cvt_pk_bf16_f32 v36, v36, v37
	v_pk_fma_f32 v[58:59], v[64:65], s[54:55], v[58:59] op_sel_hi:[1,0,0]
	s_nop 1
	v_pk_fma_f32 v[58:59], v[64:65], v[58:59], s[58:59] op_sel_hi:[1,1,0]
	s_nop 0
	v_pk_fma_f32 v[58:59], v[64:65], v[58:59], s[60:61] op_sel_hi:[1,1,0]
	s_nop 0
	v_pk_fma_f32 v[58:59], v[64:65], v[58:59], s[62:63] op_sel_hi:[1,1,0]
	s_nop 0
	v_pk_mul_f32 v[58:59], v[64:65], v[58:59]
	s_nop 0
	v_pk_mul_f32 v[56:57], v[56:57], v[58:59]
	s_nop 0
	v_pk_mul_f32 v[58:59], v[38:39], v[56:57]
	v_pk_fma_f32 v[56:57], v[38:39], v[56:57], v[38:39] neg_lo:[1,0,0] neg_hi:[1,0,0]
	s_nop 0
	v_cndmask_b32_e64 v38, v56, v58, s[0:1]
	v_cmp_gt_f32_e64 s[0:1], 0, v39
	s_nop 1
	v_cndmask_b32_e64 v39, v57, v59, s[0:1]
	v_pk_mul_f32 v[38:39], v[54:55], v[38:39]
	s_nop 1
	v_cvt_pk_bf16_f32 v37, v38, v39
	v_lshl_add_u64 v[38:39], v[136:137], 1, s[26:27]
	global_store_dwordx2 v[38:39], v[36:37], off
	v_lshlrev_b32_e32 v36, 16, v112
	v_and_b32_e32 v37, 0xffff0000, v112
	v_lshlrev_b32_e32 v38, 16, v113
	v_and_b32_e32 v39, 0xffff0000, v113
	s_nop 1
	v_mov_b32_dpp v52, v36 row_ror:1 row_mask:0xf bank_mask:0xf
	v_mov_b32_dpp v53, v37 row_ror:1 row_mask:0xf bank_mask:0xf
	v_mov_b32_dpp v54, v38 row_ror:1 row_mask:0xf bank_mask:0xf
	v_mov_b32_dpp v57, v39 row_ror:1 row_mask:0xf bank_mask:0xf
	v_mov_b32_dpp v55, v36 row_ror:2 row_mask:0xf bank_mask:0xf
	v_mov_b32_dpp v58, v37 row_ror:2 row_mask:0xf bank_mask:0xf
	v_mov_b32_dpp v56, v38 row_ror:2 row_mask:0xf bank_mask:0xf
	v_mov_b32_dpp v59, v39 row_ror:2 row_mask:0xf bank_mask:0xf
	s_and_saveexec_b64 s[0:1], vcc
	s_cbranch_execz .LBB0_1436
	v_add_u32_e32 v136, v47, v44
	v_lshl_add_u64 v[64:65], v[136:137], 2, s[28:29]
	global_store_dwordx4 v[64:65], v[36:39], off
.LBB0_1436:
	s_or_b64 exec, exec, s[0:1]
	v_cndmask_b32_e64 v64, v42, v54, s[8:9]
	v_cndmask_b32_e64 v40, v40, v52, s[8:9]
	v_cndmask_b32_e64 v52, v43, v55, s[6:7]
	v_cndmask_b32_e64 v55, v90, v122, s[6:7]
	v_cndmask_b32_e64 v54, v89, v121, s[6:7]
	v_cndmask_b32_e64 v41, v41, v53, s[8:9]
	v_cndmask_b32_e64 v53, v50, v58, s[6:7]
	v_cndmask_b32_e64 v43, v51, v59, s[6:7]
	v_cndmask_b32_e64 v51, v87, v95, s[8:9]
	v_cndmask_b32_e64 v50, v84, v92, s[8:9]
	v_pk_fma_f32 v[10:11], v[10:11], v[54:55], v[14:15]
	v_cndmask_b32_e64 v65, v49, v57, s[8:9]
	v_pk_fma_f32 v[6:7], v[6:7], v[50:51], v[10:11]
	v_cndmask_b32_e64 v42, v48, v56, s[6:7]
	v_pk_fma_f32 v[2:3], v[2:3], v[18:19], v[6:7]
	v_pk_fma_f32 v[6:7], v[28:29], v[52:53], v[32:33]
	v_cndmask_b32_e64 v57, v88, v120, s[6:7]
	v_pk_fma_f32 v[6:7], v[24:25], v[40:41], v[6:7]
	v_cndmask_b32_e64 v56, v85, v93, s[6:7]
	v_pk_fma_f32 v[6:7], v[20:21], v[36:37], v[6:7]
	v_pk_fma_f32 v[8:9], v[8:9], v[56:57], v[12:13]
	v_and_b32_e32 v13, 0x7fffffff, v7
	v_and_b32_e32 v12, 0x7fffffff, v6
	v_pk_fma_f32 v[12:13], v[12:13], s[52:53], 1.0 op_sel_hi:[1,0,0]
	v_cndmask_b32_e64 v49, v86, v94, s[8:9]
	v_rcp_f32_e32 v12, v12
	v_rcp_f32_e32 v13, v13
	v_cndmask_b32_e64 v48, v83, v91, s[8:9]
	v_pk_fma_f32 v[4:5], v[4:5], v[48:49], v[8:9]
	v_pk_mul_f32 v[10:11], v[6:7], v[6:7]
	v_mov_b64_e32 v[14:15], s[56:57]
	v_pk_fma_f32 v[0:1], v[0:1], v[16:17], v[4:5]
	v_pk_mul_f32 v[10:11], v[10:11], s[42:43] op_sel_hi:[1,0]
;     __device__ __forceinline__ void operator()(AccRef acc, const Unit& u, int wr, int wc, int fr, int fq) const {
;     ...
;         for (int ai = 0; ai < 2; ++ai) {
;             const int rowg = u.pm * 256 + ai * 128 + wr * 64; const int grp = rowg >> 6;
; #pragma unroll
;             for (int n = 0; n < 2; ++n) { const unsigned jn = (unsigned)(j0 + 4 * n);
;                 f32x4 cu[4];
;                 {
;                     const f32x4 wu0 = *(const f32x4*)(cw + (DFF + jn)), wu1 = *(const f32x4*)(cw + (UPN + DFF + jn)), wu2 = *(const f32x4*)(cw + (2 * UPN + DFF + jn)), bu = *(const f32x4*)(cb + (DFF + jn));
;                     f32x4 pu1 = (f32x4){0.f, 0.f, 0.f, 0.f}, pu2 = pu1;
; #pragma unroll
;                     for (int m = 0; m < 4; ++m) {
;                         const f32x4 au = unpack4(pa[ai][1][m][n]);
;                         const f32x4 ru1 = ror1v(au), ru2 = ror2v(au);
;                         const f32x4 u1 = fr >= 1 ? ru1 : pu1, u2 = fr >= 2 ? ru2 : pu2;
;                         if (m == 0 && fr < 2) *(f32x4*)(edge + (unsigned)((grp * 4 + fr) * UPN + DFF + jn)) = au;
;                         if (m == 3 && fr >= 14) *(f32x4*)(edge + (unsigned)((grp * 4 + (fr - 12)) * UPN + DFF + jn)) = au;
;                         cu[m] = bu + wu0 * u2 + wu1 * u1 + wu2 * au;
;                         pu1 = ru1; pu2 = ru2; }
;                 }
;                 {
;                     const f32x4 wg0 = *(const f32x4*)(cw + jn), wg1 = *(const f32x4*)(cw + (UPN + jn)), wg2 = *(const f32x4*)(cw + (2 * UPN + jn)), bg = *(const f32x4*)(cb + jn);
;                     f32x4 pg1 = (f32x4){0.f, 0.f, 0.f, 0.f}, pg2 = pg1;
; #pragma unroll
;                     for (int m = 0; m < 4; ++m) { const int row = rowg + m * 16 + fr;
;                         const f32x4 ag = unpack4(pa[ai][0][m][n]);
;                         const f32x4 rg1 = ror1v(ag), rg2 = ror2v(ag);
;                         const f32x4 g1 = fr >= 1 ? rg1 : pg1, g2 = fr >= 2 ? rg2 : pg2;
;                         if (m == 0 && fr < 2) *(f32x4*)(edge + (unsigned)((grp * 4 + fr) * UPN + jn)) = ag;
;                         if (m == 3 && fr >= 14) *(f32x4*)(edge + (unsigned)((grp * 4 + (fr - 12)) * UPN + jn)) = ag;
;                         const f32x4 o = gelu4(bg + wg0 * g2 + wg1 * g1 + wg2 * ag) * cu[m];
	v_pk_fma_f32 v[16:17], v[12:13], s[54:55], v[14:15] op_sel_hi:[1,0,0]
	v_exp_f32_e32 v10, v10
	v_exp_f32_e32 v11, v11
	v_pk_fma_f32 v[16:17], v[12:13], v[16:17], s[58:59] op_sel_hi:[1,1,0]
	v_pk_fma_f32 v[4:5], v[30:31], v[42:43], v[34:35]
	v_pk_fma_f32 v[16:17], v[12:13], v[16:17], s[60:61] op_sel_hi:[1,1,0]
	v_pk_fma_f32 v[4:5], v[26:27], v[64:65], v[4:5]
	v_pk_fma_f32 v[16:17], v[12:13], v[16:17], s[62:63] op_sel_hi:[1,1,0]
	v_cmp_gt_f32_e64 s[0:1], 0, v6
	v_pk_mul_f32 v[12:13], v[12:13], v[16:17]
	v_pk_fma_f32 v[4:5], v[22:23], v[38:39], v[4:5]
	v_pk_mul_f32 v[10:11], v[10:11], v[12:13]
	v_pk_mul_f32 v[8:9], v[4:5], v[4:5]
	v_pk_mul_f32 v[12:13], v[6:7], v[10:11]
	v_pk_fma_f32 v[10:11], v[6:7], v[10:11], v[6:7] neg_lo:[1,0,0] neg_hi:[1,0,0]
	v_pk_mul_f32 v[8:9], v[8:9], s[42:43] op_sel_hi:[1,0]
	v_cndmask_b32_e64 v6, v10, v12, s[0:1]
	v_cmp_gt_f32_e64 s[0:1], 0, v7
	v_and_b32_e32 v10, 0x7fffffff, v4
	v_exp_f32_e32 v8, v8
	v_cndmask_b32_e64 v7, v11, v13, s[0:1]
	v_and_b32_e32 v11, 0x7fffffff, v5
	v_pk_fma_f32 v[10:11], v[10:11], s[52:53], 1.0 op_sel_hi:[1,0,0]
	v_exp_f32_e32 v9, v9
	v_rcp_f32_e32 v10, v10
	v_rcp_f32_e32 v11, v11
	v_cmp_gt_f32_e64 s[0:1], 0, v4
	v_add_u32_e32 v64, 0x21000, v82
	v_pk_mul_f32 v[0:1], v[0:1], v[6:7]
	v_pk_fma_f32 v[12:13], v[10:11], s[54:55], v[14:15] op_sel_hi:[1,0,0]
	v_add_u32_e32 v136, v64, v44
	v_pk_fma_f32 v[12:13], v[10:11], v[12:13], s[58:59] op_sel_hi:[1,1,0]
	v_cvt_pk_bf16_f32 v0, v0, v1
	v_lshlrev_b32_e32 v36, 16, v104
	v_pk_fma_f32 v[12:13], v[10:11], v[12:13], s[60:61] op_sel_hi:[1,1,0]
	v_and_b32_e32 v37, 0xffff0000, v104
	v_pk_fma_f32 v[12:13], v[10:11], v[12:13], s[62:63] op_sel_hi:[1,1,0]
	v_lshlrev_b32_e32 v38, 16, v105
	v_pk_mul_f32 v[10:11], v[10:11], v[12:13]
	v_and_b32_e32 v39, 0xffff0000, v105
	v_pk_mul_f32 v[8:9], v[8:9], v[10:11]
	s_nop 1
	v_pk_mul_f32 v[10:11], v[4:5], v[8:9]
	v_pk_fma_f32 v[8:9], v[4:5], v[8:9], v[4:5] neg_lo:[1,0,0] neg_hi:[1,0,0]
	s_nop 1
	v_cndmask_b32_e64 v4, v8, v10, s[0:1]
	v_cmp_gt_f32_e64 s[0:1], 0, v5
	s_nop 1
	v_cndmask_b32_e64 v5, v9, v11, s[0:1]
	v_pk_mul_f32 v[2:3], v[2:3], v[4:5]
	s_nop 1
	v_cvt_pk_bf16_f32 v1, v2, v3
	v_lshl_add_u64 v[2:3], v[136:137], 1, s[26:27]
	global_store_dwordx2 v[2:3], v[0:1], off
	global_load_dwordx4 v[8:11], v[60:61], off
	global_load_dwordx4 v[4:7], v[66:67], off
	s_nop 0
	global_load_dwordx4 v[0:3], v[68:69], off
	global_load_dwordx4 v[12:15], v[70:71], off
	s_nop 1
	v_mov_b32_dpp v93, v36 row_ror:1 row_mask:0xf bank_mask:0xf
	v_mov_b32_dpp v112, v37 row_ror:1 row_mask:0xf bank_mask:0xf
	v_mov_b32_dpp v104, v38 row_ror:1 row_mask:0xf bank_mask:0xf
	v_mov_b32_dpp v114, v39 row_ror:1 row_mask:0xf bank_mask:0xf
	v_mov_b32_dpp v105, v36 row_ror:2 row_mask:0xf bank_mask:0xf
	v_mov_b32_dpp v115, v37 row_ror:2 row_mask:0xf bank_mask:0xf
	v_mov_b32_dpp v117, v38 row_ror:2 row_mask:0xf bank_mask:0xf
	v_mov_b32_dpp v119, v39 row_ror:2 row_mask:0xf bank_mask:0xf
	s_and_saveexec_b64 s[0:1], s[12:13]
	s_cbranch_execz .LBB0_1438
	v_add_u32_e32 v136, v46, v45
	v_lshl_add_u64 v[16:17], v[136:137], 2, s[28:29]
	global_store_dwordx4 v[16:17], v[36:39], off
.LBB0_1438:
	s_or_b64 exec, exec, s[0:1]
	v_lshlrev_b32_e32 v52, 16, v106
	v_and_b32_e32 v53, 0xffff0000, v106
	v_lshlrev_b32_e32 v50, 16, v107
	v_and_b32_e32 v51, 0xffff0000, v107
	s_nop 1
	v_lshlrev_b32_e32 v48, 16, v108
	v_and_b32_e32 v49, 0xffff0000, v108
	v_lshlrev_b32_e32 v44, 16, v109
	v_and_b32_e32 v45, 0xffff0000, v109
	s_nop 1
	v_lshlrev_b32_e32 v16, 16, v110
	v_and_b32_e32 v17, 0xffff0000, v110
	v_lshlrev_b32_e32 v18, 16, v111
	v_and_b32_e32 v19, 0xffff0000, v111
	s_nop 1
	v_mov_b32_dpp v92, v52 row_ror:1 row_mask:0xf bank_mask:0xf
	v_mov_b32_dpp v106, v53 row_ror:1 row_mask:0xf bank_mask:0xf
	v_mov_b32_dpp v94, v50 row_ror:1 row_mask:0xf bank_mask:0xf
	v_mov_b32_dpp v107, v51 row_ror:1 row_mask:0xf bank_mask:0xf
	v_mov_b32_dpp v95, v52 row_ror:2 row_mask:0xf bank_mask:0xf
	v_mov_b32_dpp v113, v53 row_ror:2 row_mask:0xf bank_mask:0xf
	v_mov_b32_dpp v116, v50 row_ror:2 row_mask:0xf bank_mask:0xf
	v_mov_b32_dpp v118, v51 row_ror:2 row_mask:0xf bank_mask:0xf
	v_mov_b32_dpp v65, v48 row_ror:1 row_mask:0xf bank_mask:0xf
	v_mov_b32_dpp v68, v49 row_ror:1 row_mask:0xf bank_mask:0xf
	v_mov_b32_dpp v66, v44 row_ror:1 row_mask:0xf bank_mask:0xf
	v_mov_b32_dpp v69, v45 row_ror:1 row_mask:0xf bank_mask:0xf
	v_mov_b32_dpp v67, v48 row_ror:2 row_mask:0xf bank_mask:0xf
	v_mov_b32_dpp v70, v49 row_ror:2 row_mask:0xf bank_mask:0xf
	v_mov_b32_dpp v71, v44 row_ror:2 row_mask:0xf bank_mask:0xf
	v_mov_b32_dpp v83, v45 row_ror:2 row_mask:0xf bank_mask:0xf
	v_mov_b32_dpp v84, v16 row_ror:1 row_mask:0xf bank_mask:0xf
	v_mov_b32_dpp v87, v17 row_ror:1 row_mask:0xf bank_mask:0xf
	v_mov_b32_dpp v85, v18 row_ror:1 row_mask:0xf bank_mask:0xf
	v_mov_b32_dpp v88, v19 row_ror:1 row_mask:0xf bank_mask:0xf
	v_mov_b32_dpp v86, v16 row_ror:2 row_mask:0xf bank_mask:0xf
	v_mov_b32_dpp v89, v17 row_ror:2 row_mask:0xf bank_mask:0xf
	v_mov_b32_dpp v90, v18 row_ror:2 row_mask:0xf bank_mask:0xf
	v_mov_b32_dpp v91, v19 row_ror:2 row_mask:0xf bank_mask:0xf
	s_and_saveexec_b64 s[0:1], vcc
	s_cbranch_execz .LBB0_1440
	v_add_u32_e32 v136, v81, v46
	v_lshl_add_u64 v[20:21], v[136:137], 2, s[28:29]
	global_store_dwordx4 v[20:21], v[16:19], off
; __device__ __forceinline__ f32x4 gelu4(f32x4 v) { const f32x2 a = gelu_pk((f32x2){v[0], v[1]}), b = gelu_pk((f32x2){v[2], v[3]}); return (f32x4){a.x, a.y, b.x, b.y}; }
; __device__ __forceinline__ f32x4 ror1v(f32x4 v) { return (f32x4){dpp_ror1(v[0]), dpp_ror1(v[1]), dpp_ror1(v[2]), dpp_ror1(v[3])}; }
; __device__ __forceinline__ f32x4 ror2v(f32x4 v) { return (f32x4){dpp_ror2(v[0]), dpp_ror2(v[1]), dpp_ror2(v[2]), dpp_ror2(v[3])}; }
; __device__ __forceinline__ u32x2 pack4(f32x4 v) { return (u32x2){pk2(v[0], v[1]), pk2(v[2], v[3])}; }
; __device__ __forceinline__ f32x2 gelu_pk(f32x2 v) {
;     const f32x2 av = __builtin_elementwise_abs(v), d = av * 0.2316418882f + 1.0f;
;     f32x2 t; t.x = __builtin_amdgcn_rcpf(d.x); t.y = __builtin_amdgcn_rcpf(d.y);
;     f32x2 q = t * 0.5307027145f + (-0.7265760135f); q = q * t + 0.7107068705f; q = q * t + (-0.142248368f); q = q * t + 0.127414796f; q = q * t;
;     const f32x2 s = (v * v) * (-0.72134752044f);
;     f32x2 e; e.x = __builtin_amdgcn_exp2f(s.x); e.y = __builtin_amdgcn_exp2f(s.y);
;     const f32x2 m = v * (q * e), r = v - m;
;     f32x2 o; o.x = v.x < 0.f ? m.x : r.x; o.y = v.y < 0.f ? m.y : r.y; return o;
;     __device__ __forceinline__ void operator()(AccRef acc, const Unit& u, int wr, int wc, int fr, int fq) const {
;     ...
;                     const f32x4 wg0 = *(const f32x4*)(cw + jn), wg1 = *(const f32x4*)(cw + (UPN + jn)), wg2 = *(const f32x4*)(cw + (2 * UPN + jn)), bg = *(const f32x4*)(cb + jn);
;                     f32x4 pg1 = (f32x4){0.f, 0.f, 0.f, 0.f}, pg2 = pg1;
; #pragma unroll
;                     for (int m = 0; m < 4; ++m) { const int row = rowg + m * 16 + fr;
;                         const f32x4 ag = unpack4(pa[ai][0][m][n]);
;                         const f32x4 rg1 = ror1v(ag), rg2 = ror2v(ag);
;                         const f32x4 g1 = fr >= 1 ? rg1 : pg1, g2 = fr >= 2 ? rg2 : pg2;
;                         if (m == 0 && fr < 2) *(f32x4*)(edge + (unsigned)((grp * 4 + fr) * UPN + jn)) = ag;
;                         if (m == 3 && fr >= 14) *(f32x4*)(edge + (unsigned)((grp * 4 + (fr - 12)) * UPN + jn)) = ag;
;                         const f32x4 o = gelu4(bg + wg0 * g2 + wg1 * g1 + wg2 * ag) * cu[m];
;                         if (!(m == 0 && fr < 2)) *(u32x2*)(act + (unsigned)(row * DFF + jn)) = pack4(o);
;                         pg1 = rg1; pg2 = rg2; }
.LBB0_1440:
	s_or_b64 exec, exec, s[0:1]
	global_load_dwordx4 v[28:31], v[72:73], off
	global_load_dwordx4 v[24:27], v[74:75], off
	global_load_dwordx4 v[20:23], v[76:77], off
	global_load_dwordx4 v[32:35], v[78:79], off
	v_lshlrev_b32_e32 v40, 16, v102
	v_and_b32_e32 v41, 0xffff0000, v102
	v_lshlrev_b32_e32 v42, 16, v103
	v_and_b32_e32 v43, 0xffff0000, v103
	s_nop 1
	v_mov_b32_dpp v54, v40 row_ror:1 row_mask:0xf bank_mask:0xf
	v_mov_b32_dpp v55, v41 row_ror:1 row_mask:0xf bank_mask:0xf
	v_mov_b32_dpp v56, v42 row_ror:1 row_mask:0xf bank_mask:0xf
	v_mov_b32_dpp v57, v43 row_ror:1 row_mask:0xf bank_mask:0xf
	v_mov_b32_dpp v58, v40 row_ror:2 row_mask:0xf bank_mask:0xf
	v_mov_b32_dpp v59, v41 row_ror:2 row_mask:0xf bank_mask:0xf
	v_mov_b32_dpp v60, v42 row_ror:2 row_mask:0xf bank_mask:0xf
	v_mov_b32_dpp v61, v43 row_ror:2 row_mask:0xf bank_mask:0xf
	s_and_saveexec_b64 s[0:1], s[10:11]
	s_xor_b64 s[10:11], exec, s[0:1]
	s_cbranch_execz .LBB0_1442
	v_cndmask_b32_e64 v77, 0, v119, s[6:7]
	v_cndmask_b32_e64 v76, 0, v117, s[6:7]
	v_cndmask_b32_e64 v75, 0, v114, s[8:9]
	v_cndmask_b32_e64 v74, 0, v104, s[8:9]
	s_waitcnt vmcnt(4)
	v_pk_fma_f32 v[76:77], v[10:11], v[76:77], v[14:15]
	v_cndmask_b32_e64 v79, 0, v115, s[6:7]
	v_pk_fma_f32 v[74:75], v[6:7], v[74:75], v[76:77]
	v_cndmask_b32_e64 v78, 0, v105, s[6:7]
	v_pk_fma_f32 v[38:39], v[2:3], v[38:39], v[74:75]
	s_waitcnt vmcnt(0)
	v_pk_fma_f32 v[74:75], v[28:29], v[58:59], v[32:33]
	v_cndmask_b32_e64 v73, 0, v112, s[8:9]
	v_pk_fma_f32 v[74:75], v[24:25], v[54:55], v[74:75]
	v_cndmask_b32_e64 v72, 0, v93, s[8:9]
	v_pk_fma_f32 v[40:41], v[20:21], v[40:41], v[74:75]
	v_pk_fma_f32 v[78:79], v[8:9], v[78:79], v[12:13]
	v_and_b32_e32 v77, 0x7fffffff, v41
	v_and_b32_e32 v76, 0x7fffffff, v40
	v_pk_fma_f32 v[76:77], v[76:77], s[52:53], 1.0 op_sel_hi:[1,0,0]
	v_pk_fma_f32 v[72:73], v[4:5], v[72:73], v[78:79]
	v_rcp_f32_e32 v76, v76
	v_rcp_f32_e32 v77, v77
	v_pk_mul_f32 v[74:75], v[40:41], v[40:41]
	v_mov_b64_e32 v[78:79], s[56:57]
	v_pk_mul_f32 v[74:75], v[74:75], s[42:43] op_sel_hi:[1,0]
	v_pk_fma_f32 v[80:81], v[76:77], s[54:55], v[78:79] op_sel_hi:[1,0,0]
	v_exp_f32_e32 v74, v74
	v_exp_f32_e32 v75, v75
	v_pk_fma_f32 v[80:81], v[76:77], v[80:81], s[58:59] op_sel_hi:[1,1,0]
	v_pk_fma_f32 v[36:37], v[0:1], v[36:37], v[72:73]
	v_pk_fma_f32 v[80:81], v[76:77], v[80:81], s[60:61] op_sel_hi:[1,1,0]
	v_pk_fma_f32 v[72:73], v[30:31], v[60:61], v[34:35]
	v_pk_fma_f32 v[80:81], v[76:77], v[80:81], s[62:63] op_sel_hi:[1,1,0]
	v_pk_fma_f32 v[72:73], v[26:27], v[56:57], v[72:73]
	v_pk_mul_f32 v[76:77], v[76:77], v[80:81]
	v_cmp_gt_f32_e64 s[0:1], 0, v40
	v_pk_mul_f32 v[74:75], v[74:75], v[76:77]
	v_pk_fma_f32 v[42:43], v[22:23], v[42:43], v[72:73]
	v_pk_mul_f32 v[76:77], v[40:41], v[74:75]
	v_pk_fma_f32 v[74:75], v[40:41], v[74:75], v[40:41] neg_lo:[1,0,0] neg_hi:[1,0,0]
	v_pk_mul_f32 v[72:73], v[42:43], v[42:43]
	v_cndmask_b32_e64 v40, v74, v76, s[0:1]
	v_cmp_gt_f32_e64 s[0:1], 0, v41
	v_and_b32_e32 v74, 0x7fffffff, v42
	v_pk_mul_f32 v[72:73], v[72:73], s[42:43] op_sel_hi:[1,0]
	v_cndmask_b32_e64 v41, v75, v77, s[0:1]
	v_and_b32_e32 v75, 0x7fffffff, v43
	v_pk_fma_f32 v[74:75], v[74:75], s[52:53], 1.0 op_sel_hi:[1,0,0]
	v_exp_f32_e32 v72, v72
	v_rcp_f32_e32 v74, v74
	v_rcp_f32_e32 v75, v75
	v_exp_f32_e32 v73, v73
	v_cmp_gt_f32_e64 s[0:1], 0, v42
	v_pk_mul_f32 v[36:37], v[36:37], v[40:41]
	v_pk_fma_f32 v[76:77], v[74:75], s[54:55], v[78:79] op_sel_hi:[1,0,0]
	v_add_u32_e32 v136, v82, v46
	v_pk_fma_f32 v[76:77], v[74:75], v[76:77], s[58:59] op_sel_hi:[1,1,0]
	v_cvt_pk_bf16_f32 v36, v36, v37
	s_nop 0
	v_pk_fma_f32 v[76:77], v[74:75], v[76:77], s[60:61] op_sel_hi:[1,1,0]
	s_nop 0
	v_pk_fma_f32 v[76:77], v[74:75], v[76:77], s[62:63] op_sel_hi:[1,1,0]
	s_nop 0
	v_pk_mul_f32 v[74:75], v[74:75], v[76:77]
	s_nop 0
	v_pk_mul_f32 v[72:73], v[72:73], v[74:75]
	s_nop 0
	v_pk_mul_f32 v[74:75], v[42:43], v[72:73]
	v_pk_fma_f32 v[72:73], v[42:43], v[72:73], v[42:43] neg_lo:[1,0,0] neg_hi:[1,0,0]
	s_nop 0
	v_cndmask_b32_e64 v42, v72, v74, s[0:1]
	v_cmp_gt_f32_e64 s[0:1], 0, v43
	s_nop 1
	v_cndmask_b32_e64 v43, v73, v75, s[0:1]
	v_pk_mul_f32 v[38:39], v[38:39], v[42:43]
	s_nop 0
	v_cvt_pk_bf16_f32 v37, v38, v39
	v_lshl_add_u64 v[38:39], v[136:137], 1, s[26:27]
	global_store_dwordx2 v[38:39], v[36:37], off

;     __device__ __forceinline__ void operator()(AccRef acc, const Unit& u, int wr, int wc, int fr, int fq) const {
;     ...
;             for (int n = 0; n < 2; ++n) { const unsigned jn = (unsigned)(j0 + 4 * n);
;                 f32x4 cu[4];
;                 {
;                     const f32x4 wu0 = *(const f32x4*)(cw + (DFF + jn)), wu1 = *(const f32x4*)(cw + (UPN + DFF + jn)), wu2 = *(const f32x4*)(cw + (2 * UPN + DFF + jn)), bu = *(const f32x4*)(cb + (DFF + jn));
;                     f32x4 pu1 = (f32x4){0.f, 0.f, 0.f, 0.f}, pu2 = pu1;
; #pragma unroll
;                     for (int m = 0; m < 4; ++m) {
;                         const f32x4 au = unpack4(pa[ai][1][m][n]);
;                         const f32x4 ru1 = ror1v(au), ru2 = ror2v(au);
;                         const f32x4 u1 = fr >= 1 ? ru1 : pu1, u2 = fr >= 2 ? ru2 : pu2;
;                         if (m == 0 && fr < 2) *(f32x4*)(edge + (unsigned)((grp * 4 + fr) * UPN + DFF + jn)) = au;
;                         if (m == 3 && fr >= 14) *(f32x4*)(edge + (unsigned)((grp * 4 + (fr - 12)) * UPN + DFF + jn)) = au;
;                         cu[m] = bu + wu0 * u2 + wu1 * u1 + wu2 * au;
;                         pu1 = ru1; pu2 = ru2; }
;                 }
;                 {
;                     const f32x4 wg0 = *(const f32x4*)(cw + jn), wg1 = *(const f32x4*)(cw + (UPN + jn)), wg2 = *(const f32x4*)(cw + (2 * UPN + jn)), bg = *(const f32x4*)(cb + jn);
;                     f32x4 pg1 = (f32x4){0.f, 0.f, 0.f, 0.f}, pg2 = pg1;
; #pragma unroll
;                     for (int m = 0; m < 4; ++m) { const int row = rowg + m * 16 + fr;
;                         const f32x4 ag = unpack4(pa[ai][0][m][n]);
;                         const f32x4 rg1 = ror1v(ag), rg2 = ror2v(ag);
;                         const f32x4 g1 = fr >= 1 ? rg1 : pg1, g2 = fr >= 2 ? rg2 : pg2;
;                         if (m == 0 && fr < 2) *(f32x4*)(edge + (unsigned)((grp * 4 + fr) * UPN + jn)) = ag;
;                         if (m == 3 && fr >= 14) *(f32x4*)(edge + (unsigned)((grp * 4 + (fr - 12)) * UPN + jn)) = ag;
;                         const f32x4 o = gelu4(bg + wg0 * g2 + wg1 * g1 + wg2 * ag) * cu[m];
;                         if (!(m == 0 && fr < 2)) *(u32x2*)(act + (unsigned)(row * DFF + jn)) = pack4(o);
;                         pg1 = rg1; pg2 = rg2; }
.LBB0_1444:
	s_or_b64 exec, exec, s[0:1]
	s_nop 0
	v_cndmask_b32_e64 v43, v115, v113, s[6:7]
	v_cndmask_b32_e64 v42, v105, v95, s[6:7]
	v_cndmask_b32_e64 v37, v112, v106, s[8:9]
	v_cndmask_b32_e64 v36, v93, v92, s[8:9]
	v_cndmask_b32_e64 v41, v119, v118, s[6:7]
	v_cndmask_b32_e64 v40, v117, v116, s[6:7]
	s_waitcnt vmcnt(4)
	v_pk_fma_f32 v[42:43], v[8:9], v[42:43], v[12:13]
	v_cndmask_b32_e64 v39, v114, v107, s[8:9]
	v_cndmask_b32_e64 v38, v104, v94, s[8:9]
	v_pk_fma_f32 v[40:41], v[10:11], v[40:41], v[14:15]
	v_pk_fma_f32 v[36:37], v[4:5], v[36:37], v[42:43]
	v_pk_fma_f32 v[38:39], v[6:7], v[38:39], v[40:41]
	v_pk_fma_f32 v[36:37], v[0:1], v[52:53], v[36:37]
	v_cndmask_b32_e64 v53, v113, v70, s[6:7]
	v_cndmask_b32_e64 v52, v95, v67, s[6:7]
	v_pk_fma_f32 v[38:39], v[2:3], v[50:51], v[38:39]
	v_cndmask_b32_e64 v41, v106, v68, s[8:9]
	v_cndmask_b32_e64 v40, v92, v65, s[8:9]
	v_cndmask_b32_e64 v51, v118, v83, s[6:7]
	v_cndmask_b32_e64 v50, v116, v71, s[6:7]
	v_pk_fma_f32 v[52:53], v[8:9], v[52:53], v[12:13]
	v_cndmask_b32_e64 v43, v107, v69, s[8:9]
	v_cndmask_b32_e64 v42, v94, v66, s[8:9]
	v_pk_fma_f32 v[50:51], v[10:11], v[50:51], v[14:15]
	v_pk_fma_f32 v[40:41], v[4:5], v[40:41], v[52:53]
	v_pk_fma_f32 v[42:43], v[6:7], v[42:43], v[50:51]
	v_pk_fma_f32 v[50:51], v[0:1], v[48:49], v[40:41]
	v_lshlrev_b32_e32 v40, 16, v100
	v_and_b32_e32 v41, 0xffff0000, v100
	v_mov_b32_e32 v72, v137
	v_mov_b32_e32 v73, v137
	v_mov_b32_e32 v76, v137
	v_mov_b32_e32 v77, v137
	v_mov_b32_dpp v72, v40 row_ror:1 row_mask:0xf bank_mask:0xf
	v_mov_b32_dpp v73, v41 row_ror:1 row_mask:0xf bank_mask:0xf
	v_mov_b32_dpp v76, v40 row_ror:2 row_mask:0xf bank_mask:0xf
	v_mov_b32_dpp v77, v41 row_ror:2 row_mask:0xf bank_mask:0xf
	v_cndmask_b32_e64 v49, v55, v73, s[8:9]
	v_cndmask_b32_e64 v48, v54, v72, s[8:9]
	v_cndmask_b32_e64 v55, v59, v77, s[6:7]
	v_cndmask_b32_e64 v54, v58, v76, s[6:7]
	s_waitcnt vmcnt(0)
	v_pk_fma_f32 v[54:55], v[28:29], v[54:55], v[32:33]
	v_pk_fma_f32 v[52:53], v[2:3], v[44:45], v[42:43]
	v_pk_fma_f32 v[48:49], v[24:25], v[48:49], v[54:55]
	v_lshlrev_b32_e32 v42, 16, v101
	v_pk_fma_f32 v[40:41], v[20:21], v[40:41], v[48:49]
	v_and_b32_e32 v43, 0xffff0000, v101
	v_and_b32_e32 v55, 0x7fffffff, v41
	v_and_b32_e32 v54, 0x7fffffff, v40
	v_mov_b32_e32 v74, v137
	v_mov_b32_e32 v75, v137
	v_mov_b32_e32 v78, v137
	v_mov_b32_e32 v79, v137
	v_pk_fma_f32 v[54:55], v[54:55], s[52:53], 1.0 op_sel_hi:[1,0,0]
	v_mov_b32_dpp v74, v42 row_ror:1 row_mask:0xf bank_mask:0xf
	v_mov_b32_dpp v75, v43 row_ror:1 row_mask:0xf bank_mask:0xf
	v_mov_b32_dpp v78, v42 row_ror:2 row_mask:0xf bank_mask:0xf
	v_mov_b32_dpp v79, v43 row_ror:2 row_mask:0xf bank_mask:0xf
	v_rcp_f32_e32 v54, v54
	v_rcp_f32_e32 v55, v55
	v_cndmask_b32_e64 v45, v57, v75, s[8:9]
	v_cndmask_b32_e64 v44, v56, v74, s[8:9]
	v_cndmask_b32_e64 v57, v61, v79, s[6:7]
	v_cndmask_b32_e64 v56, v60, v78, s[6:7]
	v_pk_fma_f32 v[56:57], v[30:31], v[56:57], v[34:35]
	v_pk_mul_f32 v[48:49], v[40:41], v[40:41]
	v_pk_fma_f32 v[44:45], v[26:27], v[44:45], v[56:57]
	v_mov_b64_e32 v[56:57], s[56:57]
	v_pk_mul_f32 v[48:49], v[48:49], s[42:43] op_sel_hi:[1,0]
	v_pk_fma_f32 v[58:59], v[54:55], s[54:55], v[56:57] op_sel_hi:[1,0,0]
	v_exp_f32_e32 v48, v48
	v_exp_f32_e32 v49, v49
	v_pk_fma_f32 v[58:59], v[54:55], v[58:59], s[58:59] op_sel_hi:[1,1,0]
	v_cmp_gt_f32_e64 s[0:1], 0, v40
	v_pk_fma_f32 v[58:59], v[54:55], v[58:59], s[60:61] op_sel_hi:[1,1,0]
	v_pk_fma_f32 v[42:43], v[22:23], v[42:43], v[44:45]
	v_pk_fma_f32 v[58:59], v[54:55], v[58:59], s[62:63] op_sel_hi:[1,1,0]
	v_pk_mul_f32 v[44:45], v[42:43], v[42:43]
	v_pk_mul_f32 v[54:55], v[54:55], v[58:59]
	v_pk_mul_f32 v[44:45], v[44:45], s[42:43] op_sel_hi:[1,0]
	v_pk_mul_f32 v[48:49], v[48:49], v[54:55]
	v_exp_f32_e32 v44, v44
	v_pk_mul_f32 v[54:55], v[40:41], v[48:49]
	v_pk_fma_f32 v[48:49], v[40:41], v[48:49], v[40:41] neg_lo:[1,0,0] neg_hi:[1,0,0]
	v_exp_f32_e32 v45, v45
	v_cndmask_b32_e64 v40, v48, v54, s[0:1]
	v_cmp_gt_f32_e64 s[0:1], 0, v41
	v_and_b32_e32 v48, 0x7fffffff, v42
	v_add_u32_e32 v136, v62, v46
	v_cndmask_b32_e64 v41, v49, v55, s[0:1]
	v_and_b32_e32 v49, 0x7fffffff, v43
	v_pk_fma_f32 v[48:49], v[48:49], s[52:53], 1.0 op_sel_hi:[1,0,0]
	v_cmp_gt_f32_e64 s[0:1], 0, v42
	v_rcp_f32_e32 v48, v48
	v_rcp_f32_e32 v49, v49
	v_pk_mul_f32 v[36:37], v[36:37], v[40:41]
	s_nop 1
	v_cvt_pk_bf16_f32 v36, v36, v37
	v_pk_fma_f32 v[54:55], v[48:49], s[54:55], v[56:57] op_sel_hi:[1,0,0]
	s_nop 1
	v_pk_fma_f32 v[54:55], v[48:49], v[54:55], s[58:59] op_sel_hi:[1,1,0]
	s_nop 0
	v_pk_fma_f32 v[54:55], v[48:49], v[54:55], s[60:61] op_sel_hi:[1,1,0]
	s_nop 0
	v_pk_fma_f32 v[54:55], v[48:49], v[54:55], s[62:63] op_sel_hi:[1,1,0]
	s_nop 0
	v_pk_mul_f32 v[48:49], v[48:49], v[54:55]
	s_nop 0
	v_pk_mul_f32 v[44:45], v[44:45], v[48:49]
	s_nop 0
	v_pk_mul_f32 v[48:49], v[42:43], v[44:45]
;     __device__ __forceinline__ void operator()(AccRef acc, const Unit& u, int wr, int wc, int fr, int fq) const {
;     ...
;             for (int n = 0; n < 2; ++n) { const unsigned jn = (unsigned)(j0 + 4 * n);
;                 f32x4 cu[4];
;                 {
;                     const f32x4 wu0 = *(const f32x4*)(cw + (DFF + jn)), wu1 = *(const f32x4*)(cw + (UPN + DFF + jn)), wu2 = *(const f32x4*)(cw + (2 * UPN + DFF + jn)), bu = *(const f32x4*)(cb + (DFF + jn));
;                     f32x4 pu1 = (f32x4){0.f, 0.f, 0.f, 0.f}, pu2 = pu1;
; #pragma unroll
;                     for (int m = 0; m < 4; ++m) {
;                         const f32x4 au = unpack4(pa[ai][1][m][n]);
;                         const f32x4 ru1 = ror1v(au), ru2 = ror2v(au);
;                         const f32x4 u1 = fr >= 1 ? ru1 : pu1, u2 = fr >= 2 ? ru2 : pu2;
;                         if (m == 0 && fr < 2) *(f32x4*)(edge + (unsigned)((grp * 4 + fr) * UPN + DFF + jn)) = au;
;                         if (m == 3 && fr >= 14) *(f32x4*)(edge + (unsigned)((grp * 4 + (fr - 12)) * UPN + DFF + jn)) = au;
;                         cu[m] = bu + wu0 * u2 + wu1 * u1 + wu2 * au;
;                         pu1 = ru1; pu2 = ru2; }
;                 }
;                 {
;                     const f32x4 wg0 = *(const f32x4*)(cw + jn), wg1 = *(const f32x4*)(cw + (UPN + jn)), wg2 = *(const f32x4*)(cw + (2 * UPN + jn)), bg = *(const f32x4*)(cb + jn);
;                     f32x4 pg1 = (f32x4){0.f, 0.f, 0.f, 0.f}, pg2 = pg1;
; #pragma unroll
;                     for (int m = 0; m < 4; ++m) { const int row = rowg + m * 16 + fr;
;                         const f32x4 ag = unpack4(pa[ai][0][m][n]);
;                         const f32x4 rg1 = ror1v(ag), rg2 = ror2v(ag);
;                         const f32x4 g1 = fr >= 1 ? rg1 : pg1, g2 = fr >= 2 ? rg2 : pg2;
;                         if (m == 0 && fr < 2) *(f32x4*)(edge + (unsigned)((grp * 4 + fr) * UPN + jn)) = ag;
;                         if (m == 3 && fr >= 14) *(f32x4*)(edge + (unsigned)((grp * 4 + (fr - 12)) * UPN + jn)) = ag;
;                         const f32x4 o = gelu4(bg + wg0 * g2 + wg1 * g1 + wg2 * ag) * cu[m];
;                         if (!(m == 0 && fr < 2)) *(u32x2*)(act + (unsigned)(row * DFF + jn)) = pack4(o);
;                         pg1 = rg1; pg2 = rg2; }
	v_pk_fma_f32 v[44:45], v[42:43], v[44:45], v[42:43] neg_lo:[1,0,0] neg_hi:[1,0,0]
	s_nop 0
	v_cndmask_b32_e64 v42, v44, v48, s[0:1]
	v_cmp_gt_f32_e64 s[0:1], 0, v43
	s_nop 1
	v_cndmask_b32_e64 v43, v45, v49, s[0:1]
	v_pk_mul_f32 v[38:39], v[38:39], v[42:43]
	s_nop 1
	v_cvt_pk_bf16_f32 v37, v38, v39
	v_lshl_add_u64 v[38:39], v[136:137], 1, s[26:27]
	global_store_dwordx2 v[38:39], v[36:37], off
	v_lshlrev_b32_e32 v36, 16, v98
	v_and_b32_e32 v37, 0xffff0000, v98
	v_lshlrev_b32_e32 v38, 16, v99
	v_mov_b32_dpp v44, v36 row_ror:2 row_mask:0xf bank_mask:0xf
	v_mov_b32_dpp v48, v37 row_ror:2 row_mask:0xf bank_mask:0xf
	v_mov_b32_dpp v40, v36 row_ror:1 row_mask:0xf bank_mask:0xf
	v_mov_b32_dpp v41, v37 row_ror:1 row_mask:0xf bank_mask:0xf
	v_cndmask_b32_e64 v61, v77, v48, s[6:7]
	v_cndmask_b32_e64 v60, v76, v44, s[6:7]
	v_cndmask_b32_e64 v59, v73, v41, s[8:9]
	v_cndmask_b32_e64 v58, v72, v40, s[8:9]
	v_pk_fma_f32 v[60:61], v[28:29], v[60:61], v[32:33]
	v_and_b32_e32 v39, 0xffff0000, v99
	v_pk_fma_f32 v[58:59], v[24:25], v[58:59], v[60:61]
	s_nop 1
	v_pk_fma_f32 v[36:37], v[20:21], v[36:37], v[58:59]
	s_nop 1
	v_and_b32_e32 v61, 0x7fffffff, v37
	v_and_b32_e32 v60, 0x7fffffff, v36
	v_pk_fma_f32 v[60:61], v[60:61], s[52:53], 1.0 op_sel_hi:[1,0,0]
	s_nop 1
	v_rcp_f32_e32 v60, v60
	v_rcp_f32_e32 v61, v61
	v_mov_b32_dpp v45, v38 row_ror:2 row_mask:0xf bank_mask:0xf
	v_mov_b32_dpp v49, v39 row_ror:2 row_mask:0xf bank_mask:0xf
	v_mov_b32_dpp v42, v38 row_ror:1 row_mask:0xf bank_mask:0xf
	v_mov_b32_dpp v43, v39 row_ror:1 row_mask:0xf bank_mask:0xf
	v_cndmask_b32_e64 v73, v79, v49, s[6:7]
	v_cndmask_b32_e64 v72, v78, v45, s[6:7]
	v_cndmask_b32_e64 v55, v75, v43, s[8:9]
	v_cndmask_b32_e64 v54, v74, v42, s[8:9]
	v_pk_fma_f32 v[72:73], v[30:31], v[72:73], v[34:35]
	v_pk_mul_f32 v[58:59], v[36:37], v[36:37]
	v_pk_fma_f32 v[54:55], v[26:27], v[54:55], v[72:73]
	v_pk_mul_f32 v[58:59], v[58:59], s[42:43] op_sel_hi:[1,0]
	v_pk_fma_f32 v[72:73], v[60:61], s[54:55], v[56:57] op_sel_hi:[1,0,0]
	v_exp_f32_e32 v58, v58
	v_exp_f32_e32 v59, v59
	v_pk_fma_f32 v[72:73], v[60:61], v[72:73], s[58:59] op_sel_hi:[1,1,0]
	v_cmp_gt_f32_e64 s[0:1], 0, v36
	v_pk_fma_f32 v[72:73], v[60:61], v[72:73], s[60:61] op_sel_hi:[1,1,0]
	v_pk_fma_f32 v[38:39], v[22:23], v[38:39], v[54:55]
	v_pk_fma_f32 v[72:73], v[60:61], v[72:73], s[62:63] op_sel_hi:[1,1,0]
	v_pk_mul_f32 v[54:55], v[38:39], v[38:39]
	v_pk_mul_f32 v[60:61], v[60:61], v[72:73]
	v_pk_mul_f32 v[54:55], v[54:55], s[42:43] op_sel_hi:[1,0]
	v_pk_mul_f32 v[58:59], v[58:59], v[60:61]
	v_exp_f32_e32 v54, v54
	v_pk_mul_f32 v[60:61], v[36:37], v[58:59]
	v_pk_fma_f32 v[58:59], v[36:37], v[58:59], v[36:37] neg_lo:[1,0,0] neg_hi:[1,0,0]
	v_exp_f32_e32 v55, v55
	v_cndmask_b32_e64 v36, v58, v60, s[0:1]
	v_cmp_gt_f32_e64 s[0:1], 0, v37
	v_and_b32_e32 v58, 0x7fffffff, v38
	v_add_u32_e32 v136, v63, v46
	v_cndmask_b32_e64 v37, v59, v61, s[0:1]
	v_and_b32_e32 v59, 0x7fffffff, v39
	v_pk_fma_f32 v[58:59], v[58:59], s[52:53], 1.0 op_sel_hi:[1,0,0]
	v_cmp_gt_f32_e64 s[0:1], 0, v38
	v_rcp_f32_e32 v58, v58
	v_rcp_f32_e32 v59, v59
	v_pk_mul_f32 v[36:37], v[50:51], v[36:37]
	s_nop 1
	v_cvt_pk_bf16_f32 v36, v36, v37
	v_pk_fma_f32 v[56:57], v[58:59], s[54:55], v[56:57] op_sel_hi:[1,0,0]
	s_nop 1
	v_pk_fma_f32 v[56:57], v[58:59], v[56:57], s[58:59] op_sel_hi:[1,1,0]
	s_nop 0
	v_pk_fma_f32 v[56:57], v[58:59], v[56:57], s[60:61] op_sel_hi:[1,1,0]
	s_nop 0
	v_pk_fma_f32 v[56:57], v[58:59], v[56:57], s[62:63] op_sel_hi:[1,1,0]
	s_nop 0
	v_pk_mul_f32 v[56:57], v[58:59], v[56:57]
	s_nop 0
	v_pk_mul_f32 v[54:55], v[54:55], v[56:57]
	s_nop 0
	v_pk_mul_f32 v[56:57], v[38:39], v[54:55]
	v_pk_fma_f32 v[54:55], v[38:39], v[54:55], v[38:39] neg_lo:[1,0,0] neg_hi:[1,0,0]
	s_nop 0
	v_cndmask_b32_e64 v38, v54, v56, s[0:1]
	v_cmp_gt_f32_e64 s[0:1], 0, v39
	s_nop 1
	v_cndmask_b32_e64 v39, v55, v57, s[0:1]
	v_pk_mul_f32 v[38:39], v[52:53], v[38:39]
	s_nop 1
	v_cvt_pk_bf16_f32 v37, v38, v39
	v_lshl_add_u64 v[38:39], v[136:137], 1, s[26:27]
	global_store_dwordx2 v[38:39], v[36:37], off
	v_lshlrev_b32_e32 v36, 16, v96
	v_and_b32_e32 v37, 0xffff0000, v96
	v_lshlrev_b32_e32 v38, 16, v97
	v_and_b32_e32 v39, 0xffff0000, v97
	s_nop 1
	v_mov_b32_dpp v50, v36 row_ror:1 row_mask:0xf bank_mask:0xf
	v_mov_b32_dpp v51, v37 row_ror:1 row_mask:0xf bank_mask:0xf
	v_mov_b32_dpp v52, v38 row_ror:1 row_mask:0xf bank_mask:0xf
	v_mov_b32_dpp v53, v39 row_ror:1 row_mask:0xf bank_mask:0xf
	v_mov_b32_dpp v54, v36 row_ror:2 row_mask:0xf bank_mask:0xf
	v_mov_b32_dpp v56, v37 row_ror:2 row_mask:0xf bank_mask:0xf
	v_mov_b32_dpp v55, v38 row_ror:2 row_mask:0xf bank_mask:0xf
	v_mov_b32_dpp v57, v39 row_ror:2 row_mask:0xf bank_mask:0xf
	s_and_saveexec_b64 s[0:1], vcc
	s_cbranch_execz .LBB0_1446
	v_add_u32_e32 v136, v46, v47
	v_lshl_add_u64 v[58:59], v[136:137], 2, s[28:29]
	global_store_dwordx4 v[58:59], v[36:39], off

; __device__ __forceinline__ float sigmoid_f(float z) { return __builtin_amdgcn_rcpf(1.f + fexp(-z)); }
; __device__ __forceinline__ float rms_r(float ss) { return __builtin_amdgcn_rsqf(ss * (1.0f / DM) + RMS_EPS); }
; #define EPI_IT_ROW(it) EPI_ROW((it) >> 2, (it) & 3)
; #define EPI_PACK8(v0, v1) (u32x4){pk2((v0)[0], (v0)[1]), pk2((v0)[2], (v0)[3]), pk2((v1)[0], (v1)[1]), pk2((v1)[2], (v1)[3])}
;     __device__ __forceinline__ void operator()(AccRef acc, const Unit& u, int wr, int wc, int fr, int fq) const {
;     ...
;         for (int st = 0; st < 16; ++st) { const int it = st >> 1, bj = st & 1, ai = it >> 2, m = it & 3, row = EPI_IT_ROW(it);
;             if (st + 1 < 16) { const int it1 = (st + 1) >> 1, bj1 = (st + 1) & 1; const size_t p = (size_t)EPI_IT_ROW(it1) * DM + EPI_COL(bj1);
;                 xn0 = *(const f32x4*)(x + p); xn1 = *(const f32x4*)(x + p + 4); pn = *(const u32x4*)(pp + p);
;                 if (bj1 == 0) { sn_ = ssin[EPI_IT_ROW(it1)]; qn = ppss[EPI_IT_ROW(it1)]; } }
;             const float r = rms_r(sc), rp = rms_r(qc);
;             const size_t p = (size_t)row * DM + EPI_COL(bj);
;             const f32x4 p0 = (f32x4){bflo(pc.x), bfhi(pc.x), bflo(pc.y), bfhi(pc.y)}, p1 = (f32x4){bflo(pc.z), bfhi(pc.z), bflo(pc.w), bfhi(pc.w)};
;             const f32x4 z0 = acc[ai][bj][m][0] * r, z1 = acc[ai][bj][m][1] * r;
;             f32x4 g0, g1;
; #pragma unroll
;             for (int e = 0; e < 4; ++e) { g0[e] = sigmoid_f(z0[e]); g1[e] = sigmoid_f(z1[e]); }
;             const f32x4 x0 = xc0 + g0 * (p0 * rp) * pg[bj][0], x1 = xc1 + g1 * (p1 * rp) * pg[bj][1];
;             if (xo) { __builtin_nontemporal_store(x0, (f32x4*)(xo + p)); __builtin_nontemporal_store(x1, (f32x4*)(xo + p + 4)); }
;             *(u32x4*)(xb + p) = EPI_PACK8(x0, x1);
;             q += EPI_SQ8(x0, x1);
;             if (bj == 1) { q += __shfl_xor(q, 16); q += __shfl_xor(q, 32); if (fq == 0) atomicAdd(ssout + row, q); q = 0.f; sc = sn_; qc = qn; }
;             xc0 = xn0; xc1 = xn1; pc = pn; }
.LBB0_1751:
	v_add_u32_e32 v192, 16, v190
	v_ashrrev_i32_e32 v193, 31, v192
	v_lshlrev_b64 v[202:203], 10, v[192:193]
	v_lshl_add_u64 v[140:141], v[152:153], 1, s[24:25]
	v_lshl_add_u64 v[196:197], v[202:203], 0, v[188:189]
	v_lshlrev_b64 v[154:155], 2, v[192:193]
	v_cvt_pk_bf16_f32 v136, v164, v165
	v_cvt_pk_bf16_f32 v137, v166, v167
	v_cvt_pk_bf16_f32 v138, v160, v161
	v_cvt_pk_bf16_f32 v139, v162, v163
	s_nop 0
	v_lshl_add_u64 v[198:199], v[196:197], 2, s[48:49]
	v_lshl_add_u64 v[152:153], v[196:197], 1, s[40:41]
	v_lshl_add_u64 v[214:215], s[12:13], 0, v[154:155]
	global_load_dwordx4 v[136:139], v[198:199], off offset:16
	global_load_dwordx4 v[140:143], v[198:199], off
	v_lshl_add_u64 v[218:219], s[16:17], 0, v[154:155]
	global_load_dwordx4 v[152:155], v[152:153], off
	s_nop 0
	global_load_dword v215, v[214:215], off
	s_nop 0
	global_load_dword v214, v[218:219], off
	v_mul_f32_e32 v132, v132, v216
	v_mul_f32_e32 v128, v128, v216
	v_mul_f32_e32 v132, 0xbfb8aa3b, v132
	v_mul_f32_e32 v128, 0xbfb8aa3b, v128
	v_exp_f32_e32 v132, v132
	v_exp_f32_e32 v217, v128
	v_mul_f32_e32 v133, v133, v216
	v_mul_f32_e32 v129, v129, v216
	v_mul_f32_e32 v133, 0xbfb8aa3b, v133
	v_mul_f32_e32 v129, 0xbfb8aa3b, v129
	v_add_f32_e32 v128, 1.0, v132
	v_add_f32_e32 v132, 1.0, v217
	v_exp_f32_e32 v133, v133
	v_exp_f32_e32 v217, v129
	v_mul_f32_e32 v134, v134, v216
	v_mul_f32_e32 v135, v135, v216
	v_mul_f32_e32 v134, 0xbfb8aa3b, v134
	v_mul_f32_e32 v135, 0xbfb8aa3b, v135
	v_exp_f32_e32 v134, v134
	v_mul_f32_e32 v130, v130, v216
	v_exp_f32_e32 v135, v135
	v_mul_f32_e32 v131, v131, v216
	v_mul_f32_e32 v130, 0xbfb8aa3b, v130
	v_mul_f32_e32 v131, 0xbfb8aa3b, v131
	v_add_f32_e32 v129, 1.0, v133
	v_add_f32_e32 v133, 1.0, v217
	v_exp_f32_e32 v217, v130
	v_exp_f32_e32 v216, v131
	v_add_f32_e32 v130, 1.0, v134
	v_add_f32_e32 v131, 1.0, v135
	v_rcp_f32_e32 v128, v128
	v_rcp_f32_e32 v129, v129
	v_rcp_f32_e32 v130, v130
	v_rcp_f32_e32 v131, v131
	v_add_f32_e32 v134, 1.0, v217
	v_add_f32_e32 v135, 1.0, v216
	v_mov_b32_e32 v205, v204
	v_lshlrev_b32_e32 v218, 16, v156
	v_and_b32_e32 v219, 0xffff0000, v156
	v_lshlrev_b32_e32 v156, 16, v157
	v_and_b32_e32 v157, 0xffff0000, v157
	v_rcp_f32_e32 v132, v132
	v_rcp_f32_e32 v133, v133
	v_rcp_f32_e32 v134, v134
	v_rcp_f32_e32 v135, v135
	v_mov_b32_e32 v216, v204
	v_mov_b32_e32 v217, v204
	v_pk_mul_f32 v[156:157], v[216:217], v[156:157]
	v_pk_mul_f32 v[218:219], v[204:205], v[218:219]
	v_lshlrev_b32_e32 v220, 16, v158
	v_and_b32_e32 v221, 0xffff0000, v158
	v_lshlrev_b32_e32 v158, 16, v159
	v_and_b32_e32 v159, 0xffff0000, v159
	v_pk_mul_f32 v[128:129], v[218:219], v[128:129]
	v_pk_mul_f32 v[130:131], v[156:157], v[130:131]
	v_pk_fma_f32 v[128:129], v[44:45], v[128:129], v[148:149]
	v_pk_fma_f32 v[130:131], v[46:47], v[130:131], v[150:151]
	v_pk_mul_f32 v[148:149], v[216:217], v[158:159]
	v_pk_mul_f32 v[150:151], v[204:205], v[220:221]
	v_pk_mul_f32 v[134:135], v[148:149], v[134:135]
	v_pk_mul_f32 v[132:133], v[150:151], v[132:133]
	v_pk_fma_f32 v[134:135], v[42:43], v[134:135], v[146:147]
	s_and_b64 vcc, exec, s[6:7]
	v_pk_fma_f32 v[132:133], v[40:41], v[132:133], v[144:145]
	s_cbranch_vccnz .LBB0_1753
	global_store_dwordx4 v[200:201], v[128:131], off nt
	global_store_dwordx4 v[200:201], v[132:135], off offset:16 nt
.LBB0_1753:
	v_mul_f32_e32 v144, v165, v165
	v_mul_f32_e32 v145, v167, v167
	v_fmac_f32_e32 v144, v164, v164
	v_fmac_f32_e32 v145, v166, v166
	v_add_f32_e32 v144, v144, v145
	v_mul_f32_e32 v145, v161, v161
	v_fmac_f32_e32 v145, v160, v160
	v_mul_f32_e32 v146, v129, v129
	v_mul_f32_e32 v147, v131, v131
	v_add_f32_e32 v144, v145, v144
	v_mul_f32_e32 v145, v163, v163
	v_fmac_f32_e32 v146, v128, v128
	v_fmac_f32_e32 v147, v130, v130
	v_fmac_f32_e32 v145, v162, v162
	v_add_f32_e32 v146, v146, v147
	v_mul_f32_e32 v147, v133, v133
	v_add_f32_e32 v144, v145, v144
	v_mul_f32_e32 v145, v135, v135
	v_fmac_f32_e32 v147, v132, v132
	v_fmac_f32_e32 v145, v134, v134
	v_add_f32_e32 v146, v147, v146
	v_add_f32_e32 v145, v145, v146
	v_add_f32_e32 v146, v144, v145
	v_and_b32_e32 v145, 64, v212
	v_xor_b32_e32 v144, 16, v212
	v_add_u32_e32 v147, 64, v145
	v_cmp_lt_i32_e32 vcc, v144, v147
	v_cmp_eq_u32_e64 s[8:9], 0, v213
	v_cvt_pk_bf16_f32 v145, v130, v131
	v_lshl_add_u64 v[130:131], v[194:195], 1, s[24:25]
	v_cndmask_b32_e32 v144, v212, v144, vcc
	v_lshlrev_b32_e32 v166, 2, v144
	ds_bpermute_b32 v148, v166, v146
	v_cvt_pk_bf16_f32 v144, v128, v129
	v_xor_b32_e32 v129, 32, v212
	v_cmp_lt_i32_e32 vcc, v129, v147
	v_cvt_pk_bf16_f32 v147, v134, v135
	s_waitcnt lgkmcnt(0)
	v_add_f32_e32 v128, v146, v148
	v_cvt_pk_bf16_f32 v146, v132, v133
	s_nop 0
	v_cndmask_b32_e32 v129, v212, v129, vcc
	v_lshlrev_b32_e32 v167, 2, v129
	ds_bpermute_b32 v129, v167, v128
	s_and_saveexec_b64 s[42:43], s[8:9]
	v_readlane_b32 s72, v254, 6
	v_readlane_b32 s73, v254, 7
	v_readlane_b32 s74, v254, 8
	v_readlane_b32 s75, v254, 9
	s_cbranch_execz .LBB0_1755
	v_lshl_add_u64 v[130:131], v[190:191], 2, s[14:15]
	s_waitcnt lgkmcnt(0)
	v_add_f32_e32 v128, v128, v129
	global_atomic_add_f32 v[130:131], v128, off

; __device__ __forceinline__ float sigmoid_f(float z) { return __builtin_amdgcn_rcpf(1.f + fexp(-z)); }
; __device__ __forceinline__ float rms_r(float ss) { return __builtin_amdgcn_rsqf(ss * (1.0f / DM) + RMS_EPS); }
; #define EPI_IT_ROW(it) EPI_ROW((it) >> 2, (it) & 3)
; #define EPI_PACK8(v0, v1) (u32x4){pk2((v0)[0], (v0)[1]), pk2((v0)[2], (v0)[3]), pk2((v1)[0], (v1)[1]), pk2((v1)[2], (v1)[3])}
;     __device__ __forceinline__ void operator()(AccRef acc, const Unit& u, int wr, int wc, int fr, int fq) const {
;     ...
;         for (int st = 0; st < 16; ++st) { const int it = st >> 1, bj = st & 1, ai = it >> 2, m = it & 3, row = EPI_IT_ROW(it);
;             if (st + 1 < 16) { const int it1 = (st + 1) >> 1, bj1 = (st + 1) & 1; const size_t p = (size_t)EPI_IT_ROW(it1) * DM + EPI_COL(bj1);
;                 xn0 = *(const f32x4*)(x + p); xn1 = *(const f32x4*)(x + p + 4); pn = *(const u32x4*)(pp + p);
;                 if (bj1 == 0) { sn_ = ssin[EPI_IT_ROW(it1)]; qn = ppss[EPI_IT_ROW(it1)]; } }
;             const float r = rms_r(sc), rp = rms_r(qc);
;             const size_t p = (size_t)row * DM + EPI_COL(bj);
;             const f32x4 p0 = (f32x4){bflo(pc.x), bfhi(pc.x), bflo(pc.y), bfhi(pc.y)}, p1 = (f32x4){bflo(pc.z), bfhi(pc.z), bflo(pc.w), bfhi(pc.w)};
;             const f32x4 z0 = acc[ai][bj][m][0] * r, z1 = acc[ai][bj][m][1] * r;
;             f32x4 g0, g1;
; #pragma unroll
;             for (int e = 0; e < 4; ++e) { g0[e] = sigmoid_f(z0[e]); g1[e] = sigmoid_f(z1[e]); }
;             const f32x4 x0 = xc0 + g0 * (p0 * rp) * pg[bj][0], x1 = xc1 + g1 * (p1 * rp) * pg[bj][1];
;             if (xo) { __builtin_nontemporal_store(x0, (f32x4*)(xo + p)); __builtin_nontemporal_store(x1, (f32x4*)(xo + p + 4)); }
;             *(u32x4*)(xb + p) = EPI_PACK8(x0, x1);
;             q += EPI_SQ8(x0, x1);
;             if (bj == 1) { q += __shfl_xor(q, 16); q += __shfl_xor(q, 32); if (fq == 0) atomicAdd(ssout + row, q); q = 0.f; sc = sn_; qc = qn; }
;             xc0 = xn0; xc1 = xn1; pc = pn; }
.LBB0_1757:
	v_add_u32_e32 v152, 32, v190
	v_ashrrev_i32_e32 v153, 31, v152
	v_lshlrev_b64 v[162:163], 10, v[152:153]
	v_lshl_add_u64 v[124:125], v[196:197], 1, s[24:25]
	v_lshl_add_u64 v[154:155], v[162:163], 0, v[188:189]
	v_lshlrev_b64 v[138:139], 2, v[152:153]
	v_cvt_pk_bf16_f32 v120, v140, v141
	v_cvt_pk_bf16_f32 v121, v142, v143
	v_cvt_pk_bf16_f32 v122, v144, v145
	v_cvt_pk_bf16_f32 v123, v146, v147
	s_nop 0
	v_lshl_add_u64 v[158:159], v[154:155], 2, s[48:49]
	v_lshl_add_u64 v[136:137], v[154:155], 1, s[40:41]
	v_lshl_add_u64 v[194:195], s[12:13], 0, v[138:139]
	global_load_dwordx4 v[120:123], v[158:159], off offset:16
	global_load_dwordx4 v[124:127], v[158:159], off
	v_lshl_add_u64 v[196:197], s[16:17], 0, v[138:139]
	global_load_dwordx4 v[136:139], v[136:137], off
	s_nop 0
	global_load_dword v195, v[194:195], off
	s_nop 0
	global_load_dword v194, v[196:197], off
	v_mul_f32_e32 v116, v116, v191
	v_mul_f32_e32 v112, v112, v191
	v_mul_f32_e32 v116, 0xbfb8aa3b, v116
	v_mul_f32_e32 v112, 0xbfb8aa3b, v112
	v_exp_f32_e32 v116, v116
	v_exp_f32_e32 v200, v112
	v_mul_f32_e32 v117, v117, v191
	v_mul_f32_e32 v113, v113, v191
	v_mul_f32_e32 v117, 0xbfb8aa3b, v117
	v_mul_f32_e32 v113, 0xbfb8aa3b, v113
	v_add_f32_e32 v112, 1.0, v116
	v_add_f32_e32 v116, 1.0, v200
	v_exp_f32_e32 v117, v117
	v_exp_f32_e32 v200, v113
	v_mul_f32_e32 v118, v118, v191
	v_mul_f32_e32 v119, v119, v191
	v_mul_f32_e32 v118, 0xbfb8aa3b, v118
	v_mul_f32_e32 v119, 0xbfb8aa3b, v119
	v_exp_f32_e32 v118, v118
	v_mul_f32_e32 v114, v114, v191
	v_exp_f32_e32 v119, v119
	v_mul_f32_e32 v115, v115, v191
	v_mul_f32_e32 v114, 0xbfb8aa3b, v114
	v_mul_f32_e32 v115, 0xbfb8aa3b, v115
	v_add_f32_e32 v113, 1.0, v117
	v_add_f32_e32 v117, 1.0, v200
	v_exp_f32_e32 v200, v114
	v_exp_f32_e32 v191, v115
	v_add_f32_e32 v114, 1.0, v118
	v_add_f32_e32 v115, 1.0, v119
	v_rcp_f32_e32 v112, v112
	v_rcp_f32_e32 v113, v113
	v_rcp_f32_e32 v114, v114
	v_rcp_f32_e32 v115, v115
	v_add_f32_e32 v118, 1.0, v200
	v_add_f32_e32 v119, 1.0, v191
	v_mov_b32_e32 v165, v164
	s_waitcnt vmcnt(6)
	v_lshlrev_b32_e32 v196, 16, v148
	v_and_b32_e32 v197, 0xffff0000, v148
	v_lshlrev_b32_e32 v148, 16, v149
	v_and_b32_e32 v149, 0xffff0000, v149
	v_rcp_f32_e32 v116, v116
	v_rcp_f32_e32 v117, v117
	v_rcp_f32_e32 v118, v118
	v_rcp_f32_e32 v119, v119
	v_mov_b32_e32 v200, v164
	v_mov_b32_e32 v201, v164
	v_pk_mul_f32 v[148:149], v[200:201], v[148:149]
	v_pk_mul_f32 v[196:197], v[164:165], v[196:197]
	v_lshlrev_b32_e32 v198, 16, v150
	v_and_b32_e32 v199, 0xffff0000, v150
	v_lshlrev_b32_e32 v150, 16, v151
	v_and_b32_e32 v151, 0xffff0000, v151
	v_pk_mul_f32 v[112:113], v[112:113], v[196:197]
	v_pk_mul_f32 v[114:115], v[114:115], v[148:149]
	v_pk_fma_f32 v[112:113], v[44:45], v[112:113], v[132:133]
	v_pk_fma_f32 v[114:115], v[46:47], v[114:115], v[134:135]
	v_pk_mul_f32 v[132:133], v[200:201], v[150:151]
	v_pk_mul_f32 v[134:135], v[164:165], v[198:199]
	v_pk_mul_f32 v[118:119], v[118:119], v[132:133]
	v_pk_mul_f32 v[116:117], v[116:117], v[134:135]
	v_pk_fma_f32 v[118:119], v[42:43], v[118:119], v[130:131]
	s_and_b64 vcc, exec, s[6:7]
	v_pk_fma_f32 v[116:117], v[40:41], v[116:117], v[128:129]
	s_cbranch_vccnz .LBB0_1759
	global_store_dwordx4 v[160:161], v[112:115], off nt
	global_store_dwordx4 v[160:161], v[116:119], off offset:16 nt
.LBB0_1759:
	v_mul_f32_e32 v128, v141, v141
	v_mul_f32_e32 v129, v143, v143
	v_fmac_f32_e32 v128, v140, v140
	v_fmac_f32_e32 v129, v142, v142
	v_add_f32_e32 v128, v128, v129
	v_mul_f32_e32 v129, v145, v145
	v_fmac_f32_e32 v129, v144, v144
	v_mul_f32_e32 v130, v113, v113
	v_mul_f32_e32 v131, v115, v115
	v_add_f32_e32 v128, v129, v128
	v_mul_f32_e32 v129, v147, v147
	v_fmac_f32_e32 v130, v112, v112
	v_fmac_f32_e32 v131, v114, v114
	v_fmac_f32_e32 v129, v146, v146
	v_add_f32_e32 v130, v130, v131
	v_mul_f32_e32 v131, v117, v117
	v_add_f32_e32 v128, v129, v128
	v_mul_f32_e32 v129, v119, v119
	v_fmac_f32_e32 v131, v116, v116
	v_fmac_f32_e32 v129, v118, v118
	v_add_f32_e32 v130, v131, v130
	v_add_f32_e32 v129, v129, v130
	v_add_f32_e32 v130, v128, v129
	ds_bpermute_b32 v131, v166, v130
	v_cvt_pk_bf16_f32 v128, v112, v113
	v_cvt_pk_bf16_f32 v129, v114, v115
	v_lshl_add_u64 v[114:115], v[156:157], 1, s[24:25]
	s_waitcnt lgkmcnt(0)
	v_add_f32_e32 v112, v130, v131
	ds_bpermute_b32 v113, v167, v112
	v_cvt_pk_bf16_f32 v130, v116, v117
	v_cvt_pk_bf16_f32 v131, v118, v119
	s_nop 0
	s_and_saveexec_b64 s[42:43], s[8:9]
	s_cbranch_execz .LBB0_1761
	v_lshl_add_u64 v[114:115], v[192:193], 2, s[14:15]
	s_waitcnt lgkmcnt(0)
	v_add_f32_e32 v112, v112, v113
	global_atomic_add_f32 v[114:115], v112, off

; __device__ __forceinline__ float sigmoid_f(float z) { return __builtin_amdgcn_rcpf(1.f + fexp(-z)); }
; __device__ __forceinline__ float rms_r(float ss) { return __builtin_amdgcn_rsqf(ss * (1.0f / DM) + RMS_EPS); }
; #define EPI_IT_ROW(it) EPI_ROW((it) >> 2, (it) & 3)
; #define EPI_PACK8(v0, v1) (u32x4){pk2((v0)[0], (v0)[1]), pk2((v0)[2], (v0)[3]), pk2((v1)[0], (v1)[1]), pk2((v1)[2], (v1)[3])}
;     __device__ __forceinline__ void operator()(AccRef acc, const Unit& u, int wr, int wc, int fr, int fq) const {
;     ...
;         for (int st = 0; st < 16; ++st) { const int it = st >> 1, bj = st & 1, ai = it >> 2, m = it & 3, row = EPI_IT_ROW(it);
;             if (st + 1 < 16) { const int it1 = (st + 1) >> 1, bj1 = (st + 1) & 1; const size_t p = (size_t)EPI_IT_ROW(it1) * DM + EPI_COL(bj1);
;                 xn0 = *(const f32x4*)(x + p); xn1 = *(const f32x4*)(x + p + 4); pn = *(const u32x4*)(pp + p);
;                 if (bj1 == 0) { sn_ = ssin[EPI_IT_ROW(it1)]; qn = ppss[EPI_IT_ROW(it1)]; } }
;             const float r = rms_r(sc), rp = rms_r(qc);
;             const size_t p = (size_t)row * DM + EPI_COL(bj);
;             const f32x4 p0 = (f32x4){bflo(pc.x), bfhi(pc.x), bflo(pc.y), bfhi(pc.y)}, p1 = (f32x4){bflo(pc.z), bfhi(pc.z), bflo(pc.w), bfhi(pc.w)};
;             const f32x4 z0 = acc[ai][bj][m][0] * r, z1 = acc[ai][bj][m][1] * r;
;             f32x4 g0, g1;
; #pragma unroll
;             for (int e = 0; e < 4; ++e) { g0[e] = sigmoid_f(z0[e]); g1[e] = sigmoid_f(z1[e]); }
;             const f32x4 x0 = xc0 + g0 * (p0 * rp) * pg[bj][0], x1 = xc1 + g1 * (p1 * rp) * pg[bj][1];
;             if (xo) { __builtin_nontemporal_store(x0, (f32x4*)(xo + p)); __builtin_nontemporal_store(x1, (f32x4*)(xo + p + 4)); }
;             *(u32x4*)(xb + p) = EPI_PACK8(x0, x1);
;             q += EPI_SQ8(x0, x1);
;             if (bj == 1) { q += __shfl_xor(q, 16); q += __shfl_xor(q, 32); if (fq == 0) atomicAdd(ssout + row, q); q = 0.f; sc = sn_; qc = qn; }
;             xc0 = xn0; xc1 = xn1; pc = pn; }
.LBB0_1763:
	v_add_u32_e32 v136, 48, v190
	v_ashrrev_i32_e32 v137, 31, v136
	v_lshlrev_b64 v[146:147], 10, v[136:137]
	v_lshl_add_u64 v[108:109], v[154:155], 1, s[24:25]
	v_lshl_add_u64 v[138:139], v[146:147], 0, v[188:189]
	v_lshlrev_b64 v[122:123], 2, v[136:137]
	v_cvt_pk_bf16_f32 v104, v124, v125
	v_cvt_pk_bf16_f32 v105, v126, v127
	v_cvt_pk_bf16_f32 v106, v128, v129
	v_cvt_pk_bf16_f32 v107, v130, v131
	s_nop 0
	v_lshl_add_u64 v[142:143], v[138:139], 2, s[48:49]
	v_lshl_add_u64 v[120:121], v[138:139], 1, s[40:41]
	v_lshl_add_u64 v[154:155], s[12:13], 0, v[122:123]
	global_load_dwordx4 v[104:107], v[142:143], off offset:16
	global_load_dwordx4 v[108:111], v[142:143], off
	v_lshl_add_u64 v[156:157], s[16:17], 0, v[122:123]
	global_load_dwordx4 v[120:123], v[120:121], off
	s_nop 0
	global_load_dword v154, v[154:155], off
	s_nop 0
	global_load_dword v151, v[156:157], off
	v_mul_f32_e32 v100, v100, v150
	v_mul_f32_e32 v96, v96, v150
	v_mul_f32_e32 v100, 0xbfb8aa3b, v100
	v_mul_f32_e32 v96, 0xbfb8aa3b, v96
	v_exp_f32_e32 v100, v100
	v_exp_f32_e32 v155, v96
	v_mul_f32_e32 v101, v101, v150
	v_mul_f32_e32 v97, v97, v150
	v_mul_f32_e32 v101, 0xbfb8aa3b, v101
	v_mul_f32_e32 v97, 0xbfb8aa3b, v97
	v_add_f32_e32 v96, 1.0, v100
	v_add_f32_e32 v100, 1.0, v155
	v_exp_f32_e32 v101, v101
	v_exp_f32_e32 v155, v97
	v_mul_f32_e32 v102, v102, v150
	v_mul_f32_e32 v103, v103, v150
	v_mul_f32_e32 v102, 0xbfb8aa3b, v102
	v_mul_f32_e32 v103, 0xbfb8aa3b, v103
	v_exp_f32_e32 v102, v102
	v_mul_f32_e32 v98, v98, v150
	v_exp_f32_e32 v103, v103
	v_mul_f32_e32 v99, v99, v150
	v_mul_f32_e32 v98, 0xbfb8aa3b, v98
	v_mul_f32_e32 v99, 0xbfb8aa3b, v99
	v_add_f32_e32 v97, 1.0, v101
	v_add_f32_e32 v101, 1.0, v155
	v_exp_f32_e32 v155, v98
	v_exp_f32_e32 v150, v99
	v_add_f32_e32 v98, 1.0, v102
	v_add_f32_e32 v99, 1.0, v103
	v_rcp_f32_e32 v96, v96
	v_rcp_f32_e32 v97, v97
	v_rcp_f32_e32 v98, v98
	v_rcp_f32_e32 v99, v99
	v_add_f32_e32 v102, 1.0, v155
	v_add_f32_e32 v103, 1.0, v150
	v_mov_b32_e32 v149, v148
	s_waitcnt vmcnt(6)
	v_lshlrev_b32_e32 v156, 16, v132
	v_and_b32_e32 v157, 0xffff0000, v132
	v_lshlrev_b32_e32 v132, 16, v133
	v_and_b32_e32 v133, 0xffff0000, v133
	v_rcp_f32_e32 v100, v100
	v_rcp_f32_e32 v101, v101
	v_rcp_f32_e32 v102, v102
	v_rcp_f32_e32 v103, v103
	v_mov_b32_e32 v160, v148
	v_mov_b32_e32 v161, v148
	v_pk_mul_f32 v[132:133], v[160:161], v[132:133]
	v_pk_mul_f32 v[156:157], v[148:149], v[156:157]
	v_lshlrev_b32_e32 v158, 16, v134
	v_and_b32_e32 v159, 0xffff0000, v134
	v_lshlrev_b32_e32 v134, 16, v135
	v_and_b32_e32 v135, 0xffff0000, v135
	v_pk_mul_f32 v[96:97], v[96:97], v[156:157]
	v_pk_mul_f32 v[98:99], v[98:99], v[132:133]
	v_pk_fma_f32 v[96:97], v[44:45], v[96:97], v[116:117]
	v_pk_fma_f32 v[98:99], v[46:47], v[98:99], v[118:119]
	v_pk_mul_f32 v[116:117], v[160:161], v[134:135]
	v_pk_mul_f32 v[118:119], v[148:149], v[158:159]
	v_pk_mul_f32 v[102:103], v[102:103], v[116:117]
	v_pk_mul_f32 v[100:101], v[100:101], v[118:119]
	v_pk_fma_f32 v[102:103], v[42:43], v[102:103], v[114:115]
	s_and_b64 vcc, exec, s[6:7]
	v_pk_fma_f32 v[100:101], v[40:41], v[100:101], v[112:113]
	s_cbranch_vccnz .LBB0_1765
	global_store_dwordx4 v[144:145], v[96:99], off nt
	global_store_dwordx4 v[144:145], v[100:103], off offset:16 nt
.LBB0_1765:
	v_mul_f32_e32 v112, v125, v125
	v_mul_f32_e32 v113, v127, v127
	v_fmac_f32_e32 v112, v124, v124
	v_fmac_f32_e32 v113, v126, v126
	v_add_f32_e32 v112, v112, v113
	v_mul_f32_e32 v113, v129, v129
	v_fmac_f32_e32 v113, v128, v128
	v_mul_f32_e32 v114, v97, v97
	v_mul_f32_e32 v115, v99, v99
	v_add_f32_e32 v112, v113, v112
	v_mul_f32_e32 v113, v131, v131
	v_fmac_f32_e32 v114, v96, v96
	v_fmac_f32_e32 v115, v98, v98
	v_fmac_f32_e32 v113, v130, v130
	v_add_f32_e32 v114, v114, v115
	v_mul_f32_e32 v115, v101, v101
	v_add_f32_e32 v112, v113, v112
	v_mul_f32_e32 v113, v103, v103
	v_fmac_f32_e32 v115, v100, v100
	v_fmac_f32_e32 v113, v102, v102
	v_add_f32_e32 v114, v115, v114
	v_add_f32_e32 v113, v113, v114
	v_add_f32_e32 v114, v112, v113
	ds_bpermute_b32 v115, v166, v114
	v_cvt_pk_bf16_f32 v112, v96, v97
	v_cvt_pk_bf16_f32 v113, v98, v99
	v_lshl_add_u64 v[98:99], v[140:141], 1, s[24:25]
	s_waitcnt lgkmcnt(0)
	v_add_f32_e32 v96, v114, v115
	ds_bpermute_b32 v97, v167, v96
	v_cvt_pk_bf16_f32 v114, v100, v101
	v_cvt_pk_bf16_f32 v115, v102, v103
	s_nop 0
	s_and_saveexec_b64 s[42:43], s[8:9]
	s_cbranch_execz .LBB0_1767
	v_lshl_add_u64 v[98:99], v[152:153], 2, s[14:15]
	s_waitcnt lgkmcnt(0)
	v_add_f32_e32 v96, v96, v97
	global_atomic_add_f32 v[98:99], v96, off

; __device__ __forceinline__ float sigmoid_f(float z) { return __builtin_amdgcn_rcpf(1.f + fexp(-z)); }
; __device__ __forceinline__ float rms_r(float ss) { return __builtin_amdgcn_rsqf(ss * (1.0f / DM) + RMS_EPS); }
; #define EPI_IT_ROW(it) EPI_ROW((it) >> 2, (it) & 3)
; #define EPI_PACK8(v0, v1) (u32x4){pk2((v0)[0], (v0)[1]), pk2((v0)[2], (v0)[3]), pk2((v1)[0], (v1)[1]), pk2((v1)[2], (v1)[3])}
;     __device__ __forceinline__ void operator()(AccRef acc, const Unit& u, int wr, int wc, int fr, int fq) const {
;     ...
;         for (int st = 0; st < 16; ++st) { const int it = st >> 1, bj = st & 1, ai = it >> 2, m = it & 3, row = EPI_IT_ROW(it);
;             if (st + 1 < 16) { const int it1 = (st + 1) >> 1, bj1 = (st + 1) & 1; const size_t p = (size_t)EPI_IT_ROW(it1) * DM + EPI_COL(bj1);
;                 xn0 = *(const f32x4*)(x + p); xn1 = *(const f32x4*)(x + p + 4); pn = *(const u32x4*)(pp + p);
;                 if (bj1 == 0) { sn_ = ssin[EPI_IT_ROW(it1)]; qn = ppss[EPI_IT_ROW(it1)]; } }
;             const float r = rms_r(sc), rp = rms_r(qc);
;             const size_t p = (size_t)row * DM + EPI_COL(bj);
;             const f32x4 p0 = (f32x4){bflo(pc.x), bfhi(pc.x), bflo(pc.y), bfhi(pc.y)}, p1 = (f32x4){bflo(pc.z), bfhi(pc.z), bflo(pc.w), bfhi(pc.w)};
;             const f32x4 z0 = acc[ai][bj][m][0] * r, z1 = acc[ai][bj][m][1] * r;
;             f32x4 g0, g1;
; #pragma unroll
;             for (int e = 0; e < 4; ++e) { g0[e] = sigmoid_f(z0[e]); g1[e] = sigmoid_f(z1[e]); }
;             const f32x4 x0 = xc0 + g0 * (p0 * rp) * pg[bj][0], x1 = xc1 + g1 * (p1 * rp) * pg[bj][1];
;             if (xo) { __builtin_nontemporal_store(x0, (f32x4*)(xo + p)); __builtin_nontemporal_store(x1, (f32x4*)(xo + p + 4)); }
;             *(u32x4*)(xb + p) = EPI_PACK8(x0, x1);
;             q += EPI_SQ8(x0, x1);
;             if (bj == 1) { q += __shfl_xor(q, 16); q += __shfl_xor(q, 32); if (fq == 0) atomicAdd(ssout + row, q); q = 0.f; sc = sn_; qc = qn; }
;             xc0 = xn0; xc1 = xn1; pc = pn; }
.LBB0_1769:
	v_add_u32_e32 v120, 0x80, v190
	v_ashrrev_i32_e32 v121, 31, v120
	v_lshlrev_b64 v[130:131], 10, v[120:121]
	v_lshl_add_u64 v[92:93], v[138:139], 1, s[24:25]
	v_lshl_add_u64 v[122:123], v[130:131], 0, v[188:189]
	v_lshlrev_b64 v[106:107], 2, v[120:121]
	v_cvt_pk_bf16_f32 v88, v108, v109
	v_cvt_pk_bf16_f32 v89, v110, v111
	v_cvt_pk_bf16_f32 v90, v112, v113
	v_cvt_pk_bf16_f32 v91, v114, v115
	s_nop 0
	v_lshl_add_u64 v[126:127], v[122:123], 2, s[48:49]
	v_lshl_add_u64 v[104:105], v[122:123], 1, s[40:41]
	v_lshl_add_u64 v[138:139], s[12:13], 0, v[106:107]
	global_load_dwordx4 v[88:91], v[126:127], off offset:16
	global_load_dwordx4 v[92:95], v[126:127], off
	v_lshl_add_u64 v[140:141], s[16:17], 0, v[106:107]
	global_load_dwordx4 v[104:107], v[104:105], off
	s_nop 0
	global_load_dword v138, v[138:139], off
	s_nop 0
	global_load_dword v135, v[140:141], off
	v_mul_f32_e32 v84, v84, v134
	v_mul_f32_e32 v80, v80, v134
	v_mul_f32_e32 v84, 0xbfb8aa3b, v84
	v_mul_f32_e32 v80, 0xbfb8aa3b, v80
	v_exp_f32_e32 v84, v84
	v_exp_f32_e32 v139, v80
	v_mul_f32_e32 v85, v85, v134
	v_mul_f32_e32 v81, v81, v134
	v_mul_f32_e32 v85, 0xbfb8aa3b, v85
	v_mul_f32_e32 v81, 0xbfb8aa3b, v81
	v_add_f32_e32 v80, 1.0, v84
	v_add_f32_e32 v84, 1.0, v139
	v_exp_f32_e32 v85, v85
	v_exp_f32_e32 v139, v81
	v_mul_f32_e32 v86, v86, v134
	v_mul_f32_e32 v87, v87, v134
	v_mul_f32_e32 v86, 0xbfb8aa3b, v86
	v_mul_f32_e32 v87, 0xbfb8aa3b, v87
	v_exp_f32_e32 v86, v86
	v_mul_f32_e32 v82, v82, v134
	v_exp_f32_e32 v87, v87
	v_mul_f32_e32 v83, v83, v134
	v_mul_f32_e32 v82, 0xbfb8aa3b, v82
	v_mul_f32_e32 v83, 0xbfb8aa3b, v83
	v_add_f32_e32 v81, 1.0, v85
	v_add_f32_e32 v85, 1.0, v139
	v_exp_f32_e32 v139, v82
	v_exp_f32_e32 v134, v83
	v_add_f32_e32 v82, 1.0, v86
	v_add_f32_e32 v83, 1.0, v87
	v_rcp_f32_e32 v80, v80
	v_rcp_f32_e32 v81, v81
	v_rcp_f32_e32 v82, v82
	v_rcp_f32_e32 v83, v83
	v_add_f32_e32 v86, 1.0, v139
	v_add_f32_e32 v87, 1.0, v134
	v_mov_b32_e32 v133, v132
	s_waitcnt vmcnt(6)
	v_lshlrev_b32_e32 v140, 16, v116
	v_and_b32_e32 v141, 0xffff0000, v116
	v_lshlrev_b32_e32 v116, 16, v117
	v_and_b32_e32 v117, 0xffff0000, v117
	v_rcp_f32_e32 v84, v84
	v_rcp_f32_e32 v85, v85
	v_rcp_f32_e32 v86, v86
	v_rcp_f32_e32 v87, v87
	v_mov_b32_e32 v144, v132
	v_mov_b32_e32 v145, v132
	v_pk_mul_f32 v[116:117], v[144:145], v[116:117]
	v_pk_mul_f32 v[140:141], v[132:133], v[140:141]
	v_lshlrev_b32_e32 v142, 16, v118
	v_and_b32_e32 v143, 0xffff0000, v118
	v_lshlrev_b32_e32 v118, 16, v119
	v_and_b32_e32 v119, 0xffff0000, v119
	v_pk_mul_f32 v[80:81], v[80:81], v[140:141]
	v_pk_mul_f32 v[82:83], v[82:83], v[116:117]
	v_pk_fma_f32 v[80:81], v[44:45], v[80:81], v[100:101]
	v_pk_fma_f32 v[82:83], v[46:47], v[82:83], v[102:103]
	v_pk_mul_f32 v[100:101], v[144:145], v[118:119]
	v_pk_mul_f32 v[102:103], v[132:133], v[142:143]
	v_pk_mul_f32 v[86:87], v[86:87], v[100:101]
	v_pk_mul_f32 v[84:85], v[84:85], v[102:103]
	v_pk_fma_f32 v[86:87], v[42:43], v[86:87], v[98:99]
	s_and_b64 vcc, exec, s[6:7]
	v_pk_fma_f32 v[84:85], v[40:41], v[84:85], v[96:97]
	s_cbranch_vccnz .LBB0_1771
	global_store_dwordx4 v[128:129], v[80:83], off nt
	global_store_dwordx4 v[128:129], v[84:87], off offset:16 nt
.LBB0_1771:
	v_mul_f32_e32 v96, v109, v109
	v_mul_f32_e32 v97, v111, v111
	v_fmac_f32_e32 v96, v108, v108
	v_fmac_f32_e32 v97, v110, v110
	v_add_f32_e32 v96, v96, v97
	v_mul_f32_e32 v97, v113, v113
	v_fmac_f32_e32 v97, v112, v112
	v_mul_f32_e32 v98, v81, v81
	v_mul_f32_e32 v99, v83, v83
	v_add_f32_e32 v96, v97, v96
	v_mul_f32_e32 v97, v115, v115
	v_fmac_f32_e32 v98, v80, v80
	v_fmac_f32_e32 v99, v82, v82
	v_fmac_f32_e32 v97, v114, v114
	v_add_f32_e32 v98, v98, v99
	v_mul_f32_e32 v99, v85, v85
	v_add_f32_e32 v96, v97, v96
	v_mul_f32_e32 v97, v87, v87
	v_fmac_f32_e32 v99, v84, v84
	v_fmac_f32_e32 v97, v86, v86
	v_add_f32_e32 v98, v99, v98
	v_add_f32_e32 v97, v97, v98
	v_add_f32_e32 v98, v96, v97
	ds_bpermute_b32 v99, v166, v98
	v_cvt_pk_bf16_f32 v96, v80, v81
	v_cvt_pk_bf16_f32 v97, v82, v83
	v_lshl_add_u64 v[82:83], v[124:125], 1, s[24:25]
	s_waitcnt lgkmcnt(0)
	v_add_f32_e32 v80, v98, v99
	ds_bpermute_b32 v81, v167, v80
	v_cvt_pk_bf16_f32 v98, v84, v85
	v_cvt_pk_bf16_f32 v99, v86, v87
	s_nop 0
	s_and_saveexec_b64 s[42:43], s[8:9]
	s_cbranch_execz .LBB0_1773
	v_lshl_add_u64 v[82:83], v[136:137], 2, s[14:15]
	s_waitcnt lgkmcnt(0)
	v_add_f32_e32 v80, v80, v81
	global_atomic_add_f32 v[82:83], v80, off

; __device__ __forceinline__ float sigmoid_f(float z) { return __builtin_amdgcn_rcpf(1.f + fexp(-z)); }
; __device__ __forceinline__ float rms_r(float ss) { return __builtin_amdgcn_rsqf(ss * (1.0f / DM) + RMS_EPS); }
; #define EPI_IT_ROW(it) EPI_ROW((it) >> 2, (it) & 3)
; #define EPI_PACK8(v0, v1) (u32x4){pk2((v0)[0], (v0)[1]), pk2((v0)[2], (v0)[3]), pk2((v1)[0], (v1)[1]), pk2((v1)[2], (v1)[3])}
;     __device__ __forceinline__ void operator()(AccRef acc, const Unit& u, int wr, int wc, int fr, int fq) const {
;     ...
;         for (int st = 0; st < 16; ++st) { const int it = st >> 1, bj = st & 1, ai = it >> 2, m = it & 3, row = EPI_IT_ROW(it);
;             if (st + 1 < 16) { const int it1 = (st + 1) >> 1, bj1 = (st + 1) & 1; const size_t p = (size_t)EPI_IT_ROW(it1) * DM + EPI_COL(bj1);
;                 xn0 = *(const f32x4*)(x + p); xn1 = *(const f32x4*)(x + p + 4); pn = *(const u32x4*)(pp + p);
;                 if (bj1 == 0) { sn_ = ssin[EPI_IT_ROW(it1)]; qn = ppss[EPI_IT_ROW(it1)]; } }
;             const float r = rms_r(sc), rp = rms_r(qc);
;             const size_t p = (size_t)row * DM + EPI_COL(bj);
;             const f32x4 p0 = (f32x4){bflo(pc.x), bfhi(pc.x), bflo(pc.y), bfhi(pc.y)}, p1 = (f32x4){bflo(pc.z), bfhi(pc.z), bflo(pc.w), bfhi(pc.w)};
;             const f32x4 z0 = acc[ai][bj][m][0] * r, z1 = acc[ai][bj][m][1] * r;
;             f32x4 g0, g1;
; #pragma unroll
;             for (int e = 0; e < 4; ++e) { g0[e] = sigmoid_f(z0[e]); g1[e] = sigmoid_f(z1[e]); }
;             const f32x4 x0 = xc0 + g0 * (p0 * rp) * pg[bj][0], x1 = xc1 + g1 * (p1 * rp) * pg[bj][1];
;             if (xo) { __builtin_nontemporal_store(x0, (f32x4*)(xo + p)); __builtin_nontemporal_store(x1, (f32x4*)(xo + p + 4)); }
;             *(u32x4*)(xb + p) = EPI_PACK8(x0, x1);
;             q += EPI_SQ8(x0, x1);
;             if (bj == 1) { q += __shfl_xor(q, 16); q += __shfl_xor(q, 32); if (fq == 0) atomicAdd(ssout + row, q); q = 0.f; sc = sn_; qc = qn; }
;             xc0 = xn0; xc1 = xn1; pc = pn; }
.LBB0_1775:
	v_add_u32_e32 v104, 0x90, v190
	v_ashrrev_i32_e32 v105, 31, v104
	v_lshlrev_b64 v[114:115], 10, v[104:105]
	v_lshl_add_u64 v[76:77], v[122:123], 1, s[24:25]
	v_lshl_add_u64 v[106:107], v[114:115], 0, v[188:189]
	v_lshlrev_b64 v[90:91], 2, v[104:105]
	v_cvt_pk_bf16_f32 v72, v92, v93
	v_cvt_pk_bf16_f32 v73, v94, v95
	v_cvt_pk_bf16_f32 v74, v96, v97
	v_cvt_pk_bf16_f32 v75, v98, v99
	s_nop 0
	v_lshl_add_u64 v[110:111], v[106:107], 2, s[48:49]
	v_lshl_add_u64 v[88:89], v[106:107], 1, s[40:41]
	v_lshl_add_u64 v[122:123], s[12:13], 0, v[90:91]
	global_load_dwordx4 v[72:75], v[110:111], off offset:16
	global_load_dwordx4 v[76:79], v[110:111], off
	v_lshl_add_u64 v[124:125], s[16:17], 0, v[90:91]
	global_load_dwordx4 v[88:91], v[88:89], off
	s_nop 0
	global_load_dword v122, v[122:123], off
	s_nop 0
	global_load_dword v119, v[124:125], off
	v_mul_f32_e32 v68, v68, v118
	v_mul_f32_e32 v64, v64, v118
	v_mul_f32_e32 v68, 0xbfb8aa3b, v68
	v_mul_f32_e32 v64, 0xbfb8aa3b, v64
	v_exp_f32_e32 v68, v68
	v_exp_f32_e32 v123, v64
	v_mul_f32_e32 v69, v69, v118
	v_mul_f32_e32 v65, v65, v118
	v_mul_f32_e32 v69, 0xbfb8aa3b, v69
	v_mul_f32_e32 v65, 0xbfb8aa3b, v65
	v_add_f32_e32 v64, 1.0, v68
	v_add_f32_e32 v68, 1.0, v123
	v_exp_f32_e32 v69, v69
	v_exp_f32_e32 v123, v65
	v_mul_f32_e32 v70, v70, v118
	v_mul_f32_e32 v71, v71, v118
	v_mul_f32_e32 v70, 0xbfb8aa3b, v70
	v_mul_f32_e32 v71, 0xbfb8aa3b, v71
	v_exp_f32_e32 v70, v70
	v_mul_f32_e32 v66, v66, v118
	v_exp_f32_e32 v71, v71
	v_mul_f32_e32 v67, v67, v118
	v_mul_f32_e32 v66, 0xbfb8aa3b, v66
	v_mul_f32_e32 v67, 0xbfb8aa3b, v67
	v_add_f32_e32 v65, 1.0, v69
	v_add_f32_e32 v69, 1.0, v123
	v_exp_f32_e32 v123, v66
	v_exp_f32_e32 v118, v67
	v_add_f32_e32 v66, 1.0, v70
	v_add_f32_e32 v67, 1.0, v71
	v_rcp_f32_e32 v64, v64
	v_rcp_f32_e32 v65, v65
	v_rcp_f32_e32 v66, v66
	v_rcp_f32_e32 v67, v67
	v_add_f32_e32 v70, 1.0, v123
	v_add_f32_e32 v71, 1.0, v118
	v_mov_b32_e32 v117, v116
	s_waitcnt vmcnt(6)
	v_lshlrev_b32_e32 v124, 16, v100
	v_and_b32_e32 v125, 0xffff0000, v100
	v_lshlrev_b32_e32 v100, 16, v101
	v_and_b32_e32 v101, 0xffff0000, v101
	v_rcp_f32_e32 v68, v68
	v_rcp_f32_e32 v69, v69
	v_rcp_f32_e32 v70, v70
	v_rcp_f32_e32 v71, v71
	v_mov_b32_e32 v128, v116
	v_mov_b32_e32 v129, v116
	v_pk_mul_f32 v[100:101], v[128:129], v[100:101]
	v_pk_mul_f32 v[124:125], v[116:117], v[124:125]
	v_lshlrev_b32_e32 v126, 16, v102
	v_and_b32_e32 v127, 0xffff0000, v102
	v_lshlrev_b32_e32 v102, 16, v103
	v_and_b32_e32 v103, 0xffff0000, v103
	v_pk_mul_f32 v[64:65], v[64:65], v[124:125]
	v_pk_mul_f32 v[66:67], v[66:67], v[100:101]
	v_pk_fma_f32 v[64:65], v[44:45], v[64:65], v[84:85]
	v_pk_fma_f32 v[66:67], v[46:47], v[66:67], v[86:87]
	v_pk_mul_f32 v[84:85], v[128:129], v[102:103]
	v_pk_mul_f32 v[86:87], v[116:117], v[126:127]
	v_pk_mul_f32 v[70:71], v[70:71], v[84:85]
	v_pk_mul_f32 v[68:69], v[68:69], v[86:87]
	v_pk_fma_f32 v[70:71], v[42:43], v[70:71], v[82:83]
	s_and_b64 vcc, exec, s[6:7]
	v_pk_fma_f32 v[68:69], v[40:41], v[68:69], v[80:81]
	s_cbranch_vccnz .LBB0_1777
	global_store_dwordx4 v[112:113], v[64:67], off nt
	global_store_dwordx4 v[112:113], v[68:71], off offset:16 nt
.LBB0_1777:
	v_mul_f32_e32 v80, v93, v93
	v_mul_f32_e32 v81, v95, v95
	v_fmac_f32_e32 v80, v92, v92
	v_fmac_f32_e32 v81, v94, v94
	v_add_f32_e32 v80, v80, v81
	v_mul_f32_e32 v81, v97, v97
	v_fmac_f32_e32 v81, v96, v96
	v_mul_f32_e32 v82, v65, v65
	v_mul_f32_e32 v83, v67, v67
	v_add_f32_e32 v80, v81, v80
	v_mul_f32_e32 v81, v99, v99
	v_fmac_f32_e32 v82, v64, v64
	v_fmac_f32_e32 v83, v66, v66
	v_fmac_f32_e32 v81, v98, v98
	v_add_f32_e32 v82, v82, v83
	v_mul_f32_e32 v83, v69, v69
	v_add_f32_e32 v80, v81, v80
	v_mul_f32_e32 v81, v71, v71
	v_fmac_f32_e32 v83, v68, v68
	v_fmac_f32_e32 v81, v70, v70
	v_add_f32_e32 v82, v83, v82
	v_add_f32_e32 v81, v81, v82
	v_add_f32_e32 v82, v80, v81
	ds_bpermute_b32 v83, v166, v82
	v_cvt_pk_bf16_f32 v80, v64, v65
	v_cvt_pk_bf16_f32 v81, v66, v67
	v_lshl_add_u64 v[66:67], v[108:109], 1, s[24:25]
	s_waitcnt lgkmcnt(0)
	v_add_f32_e32 v64, v82, v83
	ds_bpermute_b32 v65, v167, v64
	v_cvt_pk_bf16_f32 v82, v68, v69
	v_cvt_pk_bf16_f32 v83, v70, v71
	s_nop 0
	s_and_saveexec_b64 s[42:43], s[8:9]
	s_cbranch_execz .LBB0_1779
	v_lshl_add_u64 v[66:67], v[120:121], 2, s[14:15]
	s_waitcnt lgkmcnt(0)
	v_add_f32_e32 v64, v64, v65
	global_atomic_add_f32 v[66:67], v64, off

; __device__ __forceinline__ float sigmoid_f(float z) { return __builtin_amdgcn_rcpf(1.f + fexp(-z)); }
; __device__ __forceinline__ float rms_r(float ss) { return __builtin_amdgcn_rsqf(ss * (1.0f / DM) + RMS_EPS); }
; #define EPI_IT_ROW(it) EPI_ROW((it) >> 2, (it) & 3)
; #define EPI_PACK8(v0, v1) (u32x4){pk2((v0)[0], (v0)[1]), pk2((v0)[2], (v0)[3]), pk2((v1)[0], (v1)[1]), pk2((v1)[2], (v1)[3])}
;     __device__ __forceinline__ void operator()(AccRef acc, const Unit& u, int wr, int wc, int fr, int fq) const {
;     ...
;         for (int st = 0; st < 16; ++st) { const int it = st >> 1, bj = st & 1, ai = it >> 2, m = it & 3, row = EPI_IT_ROW(it);
;             if (st + 1 < 16) { const int it1 = (st + 1) >> 1, bj1 = (st + 1) & 1; const size_t p = (size_t)EPI_IT_ROW(it1) * DM + EPI_COL(bj1);
;                 xn0 = *(const f32x4*)(x + p); xn1 = *(const f32x4*)(x + p + 4); pn = *(const u32x4*)(pp + p);
;                 if (bj1 == 0) { sn_ = ssin[EPI_IT_ROW(it1)]; qn = ppss[EPI_IT_ROW(it1)]; } }
;             const float r = rms_r(sc), rp = rms_r(qc);
;             const size_t p = (size_t)row * DM + EPI_COL(bj);
;             const f32x4 p0 = (f32x4){bflo(pc.x), bfhi(pc.x), bflo(pc.y), bfhi(pc.y)}, p1 = (f32x4){bflo(pc.z), bfhi(pc.z), bflo(pc.w), bfhi(pc.w)};
;             const f32x4 z0 = acc[ai][bj][m][0] * r, z1 = acc[ai][bj][m][1] * r;
;             f32x4 g0, g1;
; #pragma unroll
;             for (int e = 0; e < 4; ++e) { g0[e] = sigmoid_f(z0[e]); g1[e] = sigmoid_f(z1[e]); }
;             const f32x4 x0 = xc0 + g0 * (p0 * rp) * pg[bj][0], x1 = xc1 + g1 * (p1 * rp) * pg[bj][1];
;             if (xo) { __builtin_nontemporal_store(x0, (f32x4*)(xo + p)); __builtin_nontemporal_store(x1, (f32x4*)(xo + p + 4)); }
;             *(u32x4*)(xb + p) = EPI_PACK8(x0, x1);
;             q += EPI_SQ8(x0, x1);
;             if (bj == 1) { q += __shfl_xor(q, 16); q += __shfl_xor(q, 32); if (fq == 0) atomicAdd(ssout + row, q); q = 0.f; sc = sn_; qc = qn; }
;             xc0 = xn0; xc1 = xn1; pc = pn; }
.LBB0_1781:
	v_add_u32_e32 v88, 0xa0, v190
	v_ashrrev_i32_e32 v89, 31, v88
	v_lshlrev_b64 v[98:99], 10, v[88:89]
	v_lshl_add_u64 v[52:53], v[106:107], 1, s[24:25]
	v_lshl_add_u64 v[90:91], v[98:99], 0, v[188:189]
	v_lshlrev_b64 v[74:75], 2, v[88:89]
	v_cvt_pk_bf16_f32 v48, v76, v77
	v_cvt_pk_bf16_f32 v49, v78, v79
	v_cvt_pk_bf16_f32 v50, v80, v81
	v_cvt_pk_bf16_f32 v51, v82, v83
	s_nop 0
	v_lshl_add_u64 v[94:95], v[90:91], 2, s[48:49]
	v_lshl_add_u64 v[72:73], v[90:91], 1, s[40:41]
	v_lshl_add_u64 v[106:107], s[12:13], 0, v[74:75]
	global_load_dwordx4 v[48:51], v[94:95], off offset:16
	global_load_dwordx4 v[52:55], v[94:95], off
	v_lshl_add_u64 v[108:109], s[16:17], 0, v[74:75]
	global_load_dwordx4 v[72:75], v[72:73], off
	s_nop 0
	global_load_dword v106, v[106:107], off
	s_nop 0
	global_load_dword v103, v[108:109], off
	v_mul_f32_e32 v36, v36, v102
	v_mul_f32_e32 v32, v32, v102
	v_mul_f32_e32 v36, 0xbfb8aa3b, v36
	v_mul_f32_e32 v32, 0xbfb8aa3b, v32
	v_exp_f32_e32 v36, v36
	v_exp_f32_e32 v107, v32
	v_mul_f32_e32 v37, v37, v102
	v_mul_f32_e32 v33, v33, v102
	v_mul_f32_e32 v37, 0xbfb8aa3b, v37
	v_mul_f32_e32 v33, 0xbfb8aa3b, v33
	v_add_f32_e32 v32, 1.0, v36
	v_add_f32_e32 v36, 1.0, v107
	v_exp_f32_e32 v37, v37
	v_exp_f32_e32 v107, v33
	v_mul_f32_e32 v38, v38, v102
	v_mul_f32_e32 v39, v39, v102
	v_mul_f32_e32 v38, 0xbfb8aa3b, v38
	v_mul_f32_e32 v39, 0xbfb8aa3b, v39
	v_exp_f32_e32 v38, v38
	v_mul_f32_e32 v34, v34, v102
	v_exp_f32_e32 v39, v39
	v_mul_f32_e32 v35, v35, v102
	v_mul_f32_e32 v34, 0xbfb8aa3b, v34
	v_mul_f32_e32 v35, 0xbfb8aa3b, v35
	v_add_f32_e32 v33, 1.0, v37
	v_add_f32_e32 v37, 1.0, v107
	v_exp_f32_e32 v107, v34
	v_exp_f32_e32 v102, v35
	v_add_f32_e32 v34, 1.0, v38
	v_add_f32_e32 v35, 1.0, v39
	v_rcp_f32_e32 v32, v32
	v_rcp_f32_e32 v33, v33
	v_rcp_f32_e32 v34, v34
	v_rcp_f32_e32 v35, v35
	v_add_f32_e32 v38, 1.0, v107
	v_add_f32_e32 v39, 1.0, v102
	v_mov_b32_e32 v101, v100
	s_waitcnt vmcnt(6)
	v_lshlrev_b32_e32 v108, 16, v84
	v_and_b32_e32 v109, 0xffff0000, v84
	v_lshlrev_b32_e32 v84, 16, v85
	v_and_b32_e32 v85, 0xffff0000, v85
	v_rcp_f32_e32 v36, v36
	v_rcp_f32_e32 v37, v37
	v_rcp_f32_e32 v38, v38
	v_rcp_f32_e32 v39, v39
	v_mov_b32_e32 v112, v100
	v_mov_b32_e32 v113, v100
	v_pk_mul_f32 v[84:85], v[112:113], v[84:85]
	v_pk_mul_f32 v[108:109], v[100:101], v[108:109]
	v_lshlrev_b32_e32 v110, 16, v86
	v_and_b32_e32 v111, 0xffff0000, v86
	v_lshlrev_b32_e32 v86, 16, v87
	v_and_b32_e32 v87, 0xffff0000, v87
	v_pk_mul_f32 v[32:33], v[32:33], v[108:109]
	v_pk_mul_f32 v[34:35], v[34:35], v[84:85]
	v_pk_fma_f32 v[32:33], v[44:45], v[32:33], v[68:69]
	v_pk_fma_f32 v[34:35], v[46:47], v[34:35], v[70:71]
	v_pk_mul_f32 v[68:69], v[112:113], v[86:87]
	v_pk_mul_f32 v[70:71], v[100:101], v[110:111]
	v_pk_mul_f32 v[38:39], v[38:39], v[68:69]
	v_pk_mul_f32 v[36:37], v[36:37], v[70:71]
	v_pk_fma_f32 v[38:39], v[42:43], v[38:39], v[66:67]
	s_and_b64 vcc, exec, s[6:7]
	v_pk_fma_f32 v[36:37], v[40:41], v[36:37], v[64:65]
	s_cbranch_vccnz .LBB0_1783
	global_store_dwordx4 v[96:97], v[32:35], off nt
	global_store_dwordx4 v[96:97], v[36:39], off offset:16 nt
.LBB0_1783:
	v_mul_f32_e32 v64, v77, v77
	v_mul_f32_e32 v65, v79, v79
	v_fmac_f32_e32 v64, v76, v76
	v_fmac_f32_e32 v65, v78, v78
	v_add_f32_e32 v64, v64, v65
	v_mul_f32_e32 v65, v81, v81
	v_fmac_f32_e32 v65, v80, v80
	v_mul_f32_e32 v66, v33, v33
	v_mul_f32_e32 v67, v35, v35
	v_add_f32_e32 v64, v65, v64
	v_mul_f32_e32 v65, v83, v83
	v_fmac_f32_e32 v66, v32, v32
	v_fmac_f32_e32 v67, v34, v34
	v_fmac_f32_e32 v65, v82, v82
	v_add_f32_e32 v66, v66, v67
	v_mul_f32_e32 v67, v37, v37
	v_add_f32_e32 v64, v65, v64
	v_mul_f32_e32 v65, v39, v39
	v_fmac_f32_e32 v67, v36, v36
	v_fmac_f32_e32 v65, v38, v38
	v_add_f32_e32 v66, v67, v66
	v_add_f32_e32 v65, v65, v66
	v_add_f32_e32 v66, v64, v65
	ds_bpermute_b32 v67, v166, v66
	v_cvt_pk_bf16_f32 v64, v32, v33
	v_cvt_pk_bf16_f32 v65, v34, v35
	v_lshl_add_u64 v[34:35], v[92:93], 1, s[24:25]
	s_waitcnt lgkmcnt(0)
	v_add_f32_e32 v32, v66, v67
	ds_bpermute_b32 v33, v167, v32
	v_cvt_pk_bf16_f32 v66, v36, v37
	v_cvt_pk_bf16_f32 v67, v38, v39
	s_nop 0
	s_and_saveexec_b64 s[42:43], s[8:9]
	s_cbranch_execz .LBB0_1785
	v_lshl_add_u64 v[34:35], v[104:105], 2, s[14:15]
	s_waitcnt lgkmcnt(0)
	v_add_f32_e32 v32, v32, v33
	global_atomic_add_f32 v[34:35], v32, off

; __device__ __forceinline__ float sigmoid_f(float z) { return __builtin_amdgcn_rcpf(1.f + fexp(-z)); }
; __device__ __forceinline__ float rms_r(float ss) { return __builtin_amdgcn_rsqf(ss * (1.0f / DM) + RMS_EPS); }
; #define EPI_IT_ROW(it) EPI_ROW((it) >> 2, (it) & 3)
; #define EPI_PACK8(v0, v1) (u32x4){pk2((v0)[0], (v0)[1]), pk2((v0)[2], (v0)[3]), pk2((v1)[0], (v1)[1]), pk2((v1)[2], (v1)[3])}
;     __device__ __forceinline__ void operator()(AccRef acc, const Unit& u, int wr, int wc, int fr, int fq) const {
;     ...
;         for (int st = 0; st < 16; ++st) { const int it = st >> 1, bj = st & 1, ai = it >> 2, m = it & 3, row = EPI_IT_ROW(it);
;             if (st + 1 < 16) { const int it1 = (st + 1) >> 1, bj1 = (st + 1) & 1; const size_t p = (size_t)EPI_IT_ROW(it1) * DM + EPI_COL(bj1);
;                 xn0 = *(const f32x4*)(x + p); xn1 = *(const f32x4*)(x + p + 4); pn = *(const u32x4*)(pp + p);
;                 if (bj1 == 0) { sn_ = ssin[EPI_IT_ROW(it1)]; qn = ppss[EPI_IT_ROW(it1)]; } }
;             const float r = rms_r(sc), rp = rms_r(qc);
;             const size_t p = (size_t)row * DM + EPI_COL(bj);
;             const f32x4 p0 = (f32x4){bflo(pc.x), bfhi(pc.x), bflo(pc.y), bfhi(pc.y)}, p1 = (f32x4){bflo(pc.z), bfhi(pc.z), bflo(pc.w), bfhi(pc.w)};
;             const f32x4 z0 = acc[ai][bj][m][0] * r, z1 = acc[ai][bj][m][1] * r;
;             f32x4 g0, g1;
; #pragma unroll
;             for (int e = 0; e < 4; ++e) { g0[e] = sigmoid_f(z0[e]); g1[e] = sigmoid_f(z1[e]); }
;             const f32x4 x0 = xc0 + g0 * (p0 * rp) * pg[bj][0], x1 = xc1 + g1 * (p1 * rp) * pg[bj][1];
;             if (xo) { __builtin_nontemporal_store(x0, (f32x4*)(xo + p)); __builtin_nontemporal_store(x1, (f32x4*)(xo + p + 4)); }
;             *(u32x4*)(xb + p) = EPI_PACK8(x0, x1);
;             q += EPI_SQ8(x0, x1);
;             if (bj == 1) { q += __shfl_xor(q, 16); q += __shfl_xor(q, 32); if (fq == 0) atomicAdd(ssout + row, q); q = 0.f; sc = sn_; qc = qn; }
;             xc0 = xn0; xc1 = xn1; pc = pn; }
.LBB0_1787:
	v_add_u32_e32 v72, 0xb0, v190
	v_ashrrev_i32_e32 v73, 31, v72
	v_lshlrev_b64 v[82:83], 10, v[72:73]
	v_lshl_add_u64 v[28:29], v[90:91], 1, s[24:25]
	v_lshl_add_u64 v[74:75], v[82:83], 0, v[188:189]
	v_lshlrev_b64 v[50:51], 2, v[72:73]
	v_cvt_pk_bf16_f32 v24, v52, v53
	v_cvt_pk_bf16_f32 v25, v54, v55
	v_cvt_pk_bf16_f32 v26, v64, v65
	v_cvt_pk_bf16_f32 v27, v66, v67
	s_nop 0
	v_lshl_add_u64 v[78:79], v[74:75], 2, s[48:49]
	v_lshl_add_u64 v[48:49], v[74:75], 1, s[40:41]
	v_lshl_add_u64 v[90:91], s[12:13], 0, v[50:51]
	global_load_dwordx4 v[24:27], v[78:79], off offset:16
	global_load_dwordx4 v[28:31], v[78:79], off
	v_lshl_add_u64 v[92:93], s[16:17], 0, v[50:51]
	global_load_dwordx4 v[48:51], v[48:49], off
	s_nop 0
	global_load_dword v90, v[90:91], off
	s_nop 0
	global_load_dword v87, v[92:93], off
	v_mul_f32_e32 v20, v20, v86
	v_mul_f32_e32 v16, v16, v86
	v_mul_f32_e32 v20, 0xbfb8aa3b, v20
	v_mul_f32_e32 v16, 0xbfb8aa3b, v16
	v_exp_f32_e32 v20, v20
	v_exp_f32_e32 v91, v16
	v_mul_f32_e32 v21, v21, v86
	v_mul_f32_e32 v17, v17, v86
	v_mul_f32_e32 v21, 0xbfb8aa3b, v21
	v_mul_f32_e32 v17, 0xbfb8aa3b, v17
	v_add_f32_e32 v16, 1.0, v20
	v_add_f32_e32 v20, 1.0, v91
	v_exp_f32_e32 v21, v21
	v_exp_f32_e32 v91, v17
	v_mul_f32_e32 v22, v22, v86
	v_mul_f32_e32 v23, v23, v86
	v_mul_f32_e32 v22, 0xbfb8aa3b, v22
	v_mul_f32_e32 v23, 0xbfb8aa3b, v23
	v_exp_f32_e32 v22, v22
	v_mul_f32_e32 v18, v18, v86
	v_exp_f32_e32 v23, v23
	v_mul_f32_e32 v19, v19, v86
	v_mul_f32_e32 v18, 0xbfb8aa3b, v18
	v_mul_f32_e32 v19, 0xbfb8aa3b, v19
	v_add_f32_e32 v17, 1.0, v21
	v_add_f32_e32 v21, 1.0, v91
	v_exp_f32_e32 v91, v18
	v_exp_f32_e32 v86, v19
	v_add_f32_e32 v18, 1.0, v22
	v_add_f32_e32 v19, 1.0, v23
	v_rcp_f32_e32 v16, v16
	v_rcp_f32_e32 v17, v17
	v_rcp_f32_e32 v18, v18
	v_rcp_f32_e32 v19, v19
	v_add_f32_e32 v22, 1.0, v91
	v_add_f32_e32 v23, 1.0, v86
	v_mov_b32_e32 v85, v84
	s_waitcnt vmcnt(6)
	v_lshlrev_b32_e32 v92, 16, v68
	v_and_b32_e32 v93, 0xffff0000, v68
	v_lshlrev_b32_e32 v68, 16, v69
	v_and_b32_e32 v69, 0xffff0000, v69
	v_rcp_f32_e32 v20, v20
	v_rcp_f32_e32 v21, v21
	v_rcp_f32_e32 v22, v22
	v_rcp_f32_e32 v23, v23
	v_mov_b32_e32 v96, v84
	v_mov_b32_e32 v97, v84
	v_pk_mul_f32 v[68:69], v[96:97], v[68:69]
	v_pk_mul_f32 v[92:93], v[84:85], v[92:93]
	v_lshlrev_b32_e32 v94, 16, v70
	v_and_b32_e32 v95, 0xffff0000, v70
	v_lshlrev_b32_e32 v70, 16, v71
	v_and_b32_e32 v71, 0xffff0000, v71
	v_pk_mul_f32 v[16:17], v[16:17], v[92:93]
	v_pk_mul_f32 v[18:19], v[18:19], v[68:69]
	v_pk_fma_f32 v[16:17], v[44:45], v[16:17], v[36:37]
	v_pk_fma_f32 v[18:19], v[46:47], v[18:19], v[38:39]
	v_pk_mul_f32 v[36:37], v[96:97], v[70:71]
	v_pk_mul_f32 v[38:39], v[84:85], v[94:95]
	v_pk_mul_f32 v[22:23], v[22:23], v[36:37]
	v_pk_mul_f32 v[20:21], v[20:21], v[38:39]
	v_pk_fma_f32 v[22:23], v[42:43], v[22:23], v[34:35]
	s_and_b64 vcc, exec, s[6:7]
	v_pk_fma_f32 v[20:21], v[40:41], v[20:21], v[32:33]
	s_cbranch_vccnz .LBB0_1789
	global_store_dwordx4 v[80:81], v[16:19], off nt
	global_store_dwordx4 v[80:81], v[20:23], off offset:16 nt
.LBB0_1789:
	v_mul_f32_e32 v32, v53, v53
	v_mul_f32_e32 v33, v55, v55
	v_fmac_f32_e32 v32, v52, v52
	v_fmac_f32_e32 v33, v54, v54
	v_add_f32_e32 v32, v32, v33
	v_mul_f32_e32 v33, v65, v65
	v_fmac_f32_e32 v33, v64, v64
	v_mul_f32_e32 v34, v17, v17
	v_mul_f32_e32 v35, v19, v19
	v_add_f32_e32 v32, v33, v32
	v_mul_f32_e32 v33, v67, v67
	v_fmac_f32_e32 v34, v16, v16
	v_fmac_f32_e32 v35, v18, v18
	v_fmac_f32_e32 v33, v66, v66
	v_add_f32_e32 v34, v34, v35
	v_mul_f32_e32 v35, v21, v21
	v_add_f32_e32 v32, v33, v32
	v_mul_f32_e32 v33, v23, v23
	v_fmac_f32_e32 v35, v20, v20
	v_fmac_f32_e32 v33, v22, v22
	v_add_f32_e32 v34, v35, v34
	v_add_f32_e32 v33, v33, v34
	v_add_f32_e32 v34, v32, v33
	ds_bpermute_b32 v35, v166, v34
	v_cvt_pk_bf16_f32 v32, v16, v17
	v_cvt_pk_bf16_f32 v33, v18, v19
	v_lshl_add_u64 v[18:19], v[76:77], 1, s[24:25]
	s_waitcnt lgkmcnt(0)
	v_add_f32_e32 v16, v34, v35
	ds_bpermute_b32 v17, v167, v16
	v_cvt_pk_bf16_f32 v34, v20, v21
	v_cvt_pk_bf16_f32 v35, v22, v23
	s_nop 0
	s_and_saveexec_b64 s[42:43], s[8:9]
	s_cbranch_execz .LBB0_1791
	v_lshl_add_u64 v[18:19], v[88:89], 2, s[14:15]
	s_waitcnt lgkmcnt(0)
	v_add_f32_e32 v16, v16, v17
	global_atomic_add_f32 v[18:19], v16, off

; __device__ __forceinline__ float sigmoid_f(float z) { return __builtin_amdgcn_rcpf(1.f + fexp(-z)); }
; __device__ __forceinline__ float rms_r(float ss) { return __builtin_amdgcn_rsqf(ss * (1.0f / DM) + RMS_EPS); }
; #define EPI_IT_ROW(it) EPI_ROW((it) >> 2, (it) & 3)
; #define EPI_PACK8(v0, v1) (u32x4){pk2((v0)[0], (v0)[1]), pk2((v0)[2], (v0)[3]), pk2((v1)[0], (v1)[1]), pk2((v1)[2], (v1)[3])}
;     __device__ __forceinline__ void operator()(AccRef acc, const Unit& u, int wr, int wc, int fr, int fq) const {
;     ...
;         for (int st = 0; st < 16; ++st) { const int it = st >> 1, bj = st & 1, ai = it >> 2, m = it & 3, row = EPI_IT_ROW(it);
;             if (st + 1 < 16) { const int it1 = (st + 1) >> 1, bj1 = (st + 1) & 1; const size_t p = (size_t)EPI_IT_ROW(it1) * DM + EPI_COL(bj1);
;                 xn0 = *(const f32x4*)(x + p); xn1 = *(const f32x4*)(x + p + 4); pn = *(const u32x4*)(pp + p);
;                 if (bj1 == 0) { sn_ = ssin[EPI_IT_ROW(it1)]; qn = ppss[EPI_IT_ROW(it1)]; } }
;             const float r = rms_r(sc), rp = rms_r(qc);
;             const size_t p = (size_t)row * DM + EPI_COL(bj);
;             const f32x4 p0 = (f32x4){bflo(pc.x), bfhi(pc.x), bflo(pc.y), bfhi(pc.y)}, p1 = (f32x4){bflo(pc.z), bfhi(pc.z), bflo(pc.w), bfhi(pc.w)};
;             const f32x4 z0 = acc[ai][bj][m][0] * r, z1 = acc[ai][bj][m][1] * r;
;             f32x4 g0, g1;
; #pragma unroll
;             for (int e = 0; e < 4; ++e) { g0[e] = sigmoid_f(z0[e]); g1[e] = sigmoid_f(z1[e]); }
;             const f32x4 x0 = xc0 + g0 * (p0 * rp) * pg[bj][0], x1 = xc1 + g1 * (p1 * rp) * pg[bj][1];
;             if (xo) { __builtin_nontemporal_store(x0, (f32x4*)(xo + p)); __builtin_nontemporal_store(x1, (f32x4*)(xo + p + 4)); }
;             *(u32x4*)(xb + p) = EPI_PACK8(x0, x1);
;             q += EPI_SQ8(x0, x1);
;             if (bj == 1) { q += __shfl_xor(q, 16); q += __shfl_xor(q, 32); if (fq == 0) atomicAdd(ssout + row, q); q = 0.f; sc = sn_; qc = qn; }
;             xc0 = xn0; xc1 = xn1; pc = pn; }
.LBB0_1793:
	v_mul_f32_e32 v4, v4, v52
	v_mul_f32_e32 v0, v0, v52
	v_cvt_pk_bf16_f32 v24, v8, v9
	v_cvt_pk_bf16_f32 v25, v10, v11
	v_lshl_add_u64 v[28:29], v[74:75], 1, s[24:25]
	v_mul_f32_e32 v4, 0xbfb8aa3b, v4
	v_mul_f32_e32 v0, 0xbfb8aa3b, v0
	v_cvt_pk_bf16_f32 v26, v12, v13
	v_cvt_pk_bf16_f32 v27, v14, v15
	s_nop 0
	v_exp_f32_e32 v4, v4
	v_mul_f32_e32 v5, v5, v52
	s_waitcnt vmcnt(1)
	v_lshlrev_b32_e32 v24, 16, v32
	v_and_b32_e32 v25, 0xffff0000, v32
	v_exp_f32_e32 v32, v0
	v_mul_f32_e32 v1, v1, v52
	v_mul_f32_e32 v5, 0xbfb8aa3b, v5
	v_mul_f32_e32 v1, 0xbfb8aa3b, v1
	v_add_f32_e32 v0, 1.0, v4
	v_add_f32_e32 v4, 1.0, v32
	v_exp_f32_e32 v5, v5
	v_exp_f32_e32 v32, v1
	v_mul_f32_e32 v6, v6, v52
	v_mul_f32_e32 v2, v2, v52
	v_mul_f32_e32 v6, 0xbfb8aa3b, v6
	v_mul_f32_e32 v2, 0xbfb8aa3b, v2
	v_add_f32_e32 v1, 1.0, v5
	v_add_f32_e32 v5, 1.0, v32
	v_exp_f32_e32 v6, v6
	v_exp_f32_e32 v32, v2
	v_mul_f32_e32 v7, v7, v52
	v_mul_f32_e32 v7, 0xbfb8aa3b, v7
	v_exp_f32_e32 v7, v7
	v_mul_f32_e32 v3, v3, v52
	v_mul_f32_e32 v3, 0xbfb8aa3b, v3
	v_add_f32_e32 v2, 1.0, v6
	v_add_f32_e32 v6, 1.0, v32
	v_exp_f32_e32 v32, v3
	v_add_f32_e32 v3, 1.0, v7
	v_rcp_f32_e32 v0, v0
	v_rcp_f32_e32 v1, v1
	v_rcp_f32_e32 v2, v2
	v_rcp_f32_e32 v3, v3
	v_add_f32_e32 v7, 1.0, v32
	v_mov_b32_e32 v49, v48
	v_lshlrev_b32_e32 v26, 16, v33
	v_and_b32_e32 v27, 0xffff0000, v33
	v_rcp_f32_e32 v4, v4
	v_rcp_f32_e32 v5, v5
	v_rcp_f32_e32 v6, v6
	v_rcp_f32_e32 v7, v7
	v_mov_b32_e32 v32, v48
	v_mov_b32_e32 v33, v48
	v_pk_mul_f32 v[26:27], v[32:33], v[26:27]
	v_pk_mul_f32 v[24:25], v[48:49], v[24:25]
	v_lshlrev_b32_e32 v28, 16, v34
	v_and_b32_e32 v29, 0xffff0000, v34
	v_lshlrev_b32_e32 v30, 16, v35
	v_and_b32_e32 v31, 0xffff0000, v35
	v_pk_mul_f32 v[0:1], v[0:1], v[24:25]
	v_pk_mul_f32 v[2:3], v[2:3], v[26:27]
	v_pk_fma_f32 v[0:1], v[44:45], v[0:1], v[20:21]
	v_pk_fma_f32 v[2:3], v[46:47], v[2:3], v[22:23]
	v_pk_mul_f32 v[20:21], v[32:33], v[30:31]
	v_pk_mul_f32 v[22:23], v[48:49], v[28:29]
	v_pk_mul_f32 v[6:7], v[6:7], v[20:21]
	v_pk_mul_f32 v[4:5], v[4:5], v[22:23]
	v_pk_fma_f32 v[6:7], v[42:43], v[6:7], v[18:19]
	s_and_b64 vcc, exec, s[6:7]
	v_pk_fma_f32 v[4:5], v[40:41], v[4:5], v[16:17]
	s_cbranch_vccnz .LBB0_1795
	global_store_dwordx4 v[38:39], v[0:3], off nt
	global_store_dwordx4 v[38:39], v[4:7], off offset:16 nt
.LBB0_1795:
	v_mul_f32_e32 v9, v9, v9
	v_fmac_f32_e32 v9, v8, v8
	v_mul_f32_e32 v8, v11, v11
	v_fmac_f32_e32 v8, v10, v10
	v_add_f32_e32 v8, v9, v8
	v_mul_f32_e32 v9, v13, v13
	v_fmac_f32_e32 v9, v12, v12
	v_mul_f32_e32 v10, v1, v1
	v_mul_f32_e32 v11, v3, v3
	v_add_f32_e32 v8, v9, v8
	v_mul_f32_e32 v9, v15, v15
	v_fmac_f32_e32 v10, v0, v0
	v_fmac_f32_e32 v11, v2, v2
	v_fmac_f32_e32 v9, v14, v14
	v_add_f32_e32 v10, v10, v11
	v_mul_f32_e32 v11, v5, v5
	v_add_f32_e32 v8, v9, v8
	v_mul_f32_e32 v9, v7, v7
	v_fmac_f32_e32 v11, v4, v4
	v_fmac_f32_e32 v9, v6, v6
	v_add_f32_e32 v10, v11, v10
	v_add_f32_e32 v9, v9, v10
	v_add_f32_e32 v10, v8, v9
	ds_bpermute_b32 v11, v166, v10
	v_cvt_pk_bf16_f32 v8, v0, v1
	v_cvt_pk_bf16_f32 v9, v2, v3
	v_lshl_add_u64 v[2:3], v[36:37], 1, s[24:25]
	s_waitcnt lgkmcnt(0)
	v_add_f32_e32 v0, v10, v11
	ds_bpermute_b32 v1, v167, v0
	v_cvt_pk_bf16_f32 v10, v4, v5
	v_cvt_pk_bf16_f32 v11, v6, v7
	s_nop 0
	s_and_saveexec_b64 s[6:7], s[8:9]
	s_cbranch_execz .LBB0_1797
	v_lshl_add_u64 v[2:3], v[72:73], 2, s[14:15]
	s_waitcnt lgkmcnt(0)
	v_add_f32_e32 v0, v0, v1
	global_atomic_add_f32 v[2:3], v0, off
